# K-loop MFMA issue order: snake over (A,B) fragment pairs so one operand changes per MFMA
# baseline (speedup 1.0000x reference)
; #define PG8_STAGE(bufoff, gbase, voff) do { _Pragma("unroll") for (int _i = 0; _i < 2; ++_i) \
;         __builtin_amdgcn_global_load_lds((const unsigned*)((const char*)(gbase) + (voff)[_i]), (PG8_LAS unsigned*)(lds + (bufoff) + ldsw + _i * 8192), 16, 0, 0); } while (0)
; #define PG8_LDA(dst, b, h) do { _Pragma("unroll") for (int m = 0; m < 4; ++m) _Pragma("unroll") for (int k = 0; k < 2; ++k) dst[m][k] = *(const PG8_LAS bf16x8*)(lds + PG8_SA(b, h) + aoff + m * 2048 + k * 1024); } while (0)
; #define PG8_LDB(dst, b, h) do { _Pragma("unroll") for (int n = 0; n < 2; ++n) _Pragma("unroll") for (int k = 0; k < 2; ++k) dst[n][k] = *(const PG8_LAS bf16x8*)(lds + PG8_SB(b, h) + boff + n * 2048 + k * 1024); } while (0)
; #define PG8_WAIT_V(n) asm volatile("s_waitcnt vmcnt(" #n ")" ::: "memory")
; #define PG8_WAIT_L(n) asm volatile("s_waitcnt lgkmcnt(" #n ")" ::: "memory")
; #define PG8_BAR __builtin_amdgcn_s_barrier()
; #define PG8_SCHED __builtin_amdgcn_sched_barrier(0)
; template <class Epi, class Sched, bool ALIGN_EPI = false, bool SP2 = false>
; __device__ __forceinline__ void gemm_phase(PG8_LAS unsigned char* lds, const Gemm g, const Sched& S, const Epi& E, const int tid) {
;     ...
;         const bool has_next = S.next(ui + 1, nxt);
;         const char* nA = has_next ? S.aptr(nxt) : cA; const char* nB = has_next ? S.bptr(nxt) : cB;
;         for (int t = 0; t < nt; t += 2) {
;             const bool last = (t == nt - 2);
;             const char* a1 = cA + (size_t)(t + 1) * kstep;
;             const char* a2 = last ? nA : cA + (size_t)(t + 2) * kstep; const char* b2 = last ? nB : cB + (size_t)(t + 2) * kstep;
;             const char* a3 = a2 + kstep; const char* b3 = b2 + kstep;
;             if (last && has_next) S.a_ready(nxt);
;             if constexpr (SP2) {
;             PG8_LDB(B0, 0, 0); PG8_LDB(B1, 0, 1); PG8_SCHED; PG8_LDA(At, 0, 0); PG8_STAGE(PG8_SA(1, 1), a1 + hstep, voffA);
;             PG8_WAIT_V(8); PG8_WAIT_L(0); PG8_BAR; PG8_MMA(0, 0, At, B0); PG8_MMA(0, 1, At, B1); PG8_BAR; PG8_SCHED;
;             PG8_LDA(At, 0, 1); PG8_STAGE(PG8_SB(0, 0), b2, voffB); PG8_STAGE(PG8_SB(0, 1), b2 + hstep, voffB); PG8_STAGE(PG8_SA(0, 0), a2, voffA);
;             PG8_WAIT_V(8); PG8_WAIT_L(0); PG8_BAR; PG8_MMA(1, 0, At, B0); PG8_MMA(1, 1, At, B1); PG8_BAR; PG8_SCHED;
.LBB0_338:
	s_ashr_i32 s29, s28, 31
	s_lshl_b64 s[18:19], s[28:29], 19
	s_add_u32 s30, s46, s18
	s_addc_u32 s31, s47, s19
	s_and_b64 s[18:19], s[2:3], exec
	s_cselect_b32 s29, s31, s41
	s_cselect_b32 s62, s30, s40
	s_ashr_i32 s27, s26, 31
	s_lshl_b64 s[18:19], s[26:27], 19
	s_add_u32 s34, s48, s18
	s_addc_u32 s35, s49, s19
	s_and_b64 s[18:19], s[2:3], exec
	s_cselect_b32 s27, s35, s39
	s_cselect_b32 s63, s34, s38
	s_add_u32 s64, s38, 0x100
	s_addc_u32 s65, s39, 0
	s_add_u32 s38, s40, 0x40080
	s_addc_u32 s39, s41, 0
	s_mov_b32 s66, -2
	ds_read_b128 v[150:153], v161
	ds_read_b128 v[172:175], v161 offset:1024
	ds_read_b128 v[176:179], v161 offset:2048
	ds_read_b128 v[180:183], v161 offset:3072
	ds_read_b128 v[184:187], v163
	ds_read_b128 v[192:195], v163 offset:1024
	ds_read_b128 v[196:199], v163 offset:2048
	ds_read_b128 v[200:203], v163 offset:3072
	s_add_u32 s15, s38, 0xfffc0080
	s_addc_u32 s18, s39, -1
	s_cmp_eq_u32 s66, 12
	s_cselect_b32 s43, s29, s18
	s_cselect_b32 s42, s62, s15
	s_cselect_b32 s41, s27, s65
	s_cselect_b32 s40, s63, s64
	v_lshl_add_u64 v[154:155], s[38:39], 0, v[144:145]
	s_add_i32 m0, s51, 0xc000
	ds_read_b128 v[204:207], v167
	ds_read_b128 v[208:211], v167 offset:1024
	ds_read_b128 v[212:215], v167 offset:2048
	ds_read_b128 v[216:219], v167 offset:3072
	ds_read_b128 v[220:223], v167 offset:4096
	ds_read_b128 v[224:227], v167 offset:5120
	ds_read_b128 v[228:231], v167 offset:6144
	ds_read_b128 v[232:235], v167 offset:7168
	global_load_lds_dwordx4 v[154:155], off
	v_lshl_add_u64 v[154:155], s[38:39], 0, v[142:143]
	s_add_i32 m0, s51, 0xe000
	s_nop 0
	global_load_lds_dwordx4 v[154:155], off
	s_waitcnt vmcnt(16)
	s_waitcnt lgkmcnt(0)
	s_barrier
	s_setprio 1
	s_waitcnt lgkmcnt(0)
	v_mfma_f32_16x16x32_bf16 v[126:129], v[150:153], v[204:207], 0
	v_mfma_f32_16x16x32_bf16 v[122:125], v[176:179], v[204:207], 0
	v_mfma_f32_16x16x32_bf16 v[106:109], v[176:179], v[212:215], 0
	v_mfma_f32_16x16x32_bf16 v[110:113], v[150:153], v[212:215], 0
	v_mfma_f32_16x16x32_bf16 v[94:97], v[150:153], v[220:223], 0
	v_mfma_f32_16x16x32_bf16 v[90:93], v[176:179], v[220:223], 0
	v_mfma_f32_16x16x32_bf16 v[74:77], v[176:179], v[228:231], 0
	v_mfma_f32_16x16x32_bf16 v[78:81], v[150:153], v[228:231], 0
	v_mfma_f32_16x16x32_bf16 v[126:129], v[172:175], v[208:211], v[126:129]
	v_mfma_f32_16x16x32_bf16 v[122:125], v[180:183], v[208:211], v[122:125]
	v_mfma_f32_16x16x32_bf16 v[106:109], v[180:183], v[216:219], v[106:109]
	v_mfma_f32_16x16x32_bf16 v[110:113], v[172:175], v[216:219], v[110:113]
	v_mfma_f32_16x16x32_bf16 v[94:97], v[172:175], v[224:227], v[94:97]
	v_mfma_f32_16x16x32_bf16 v[90:93], v[180:183], v[224:227], v[90:93]
	v_mfma_f32_16x16x32_bf16 v[74:77], v[180:183], v[232:235], v[74:77]
	v_mfma_f32_16x16x32_bf16 v[78:81], v[172:175], v[232:235], v[78:81]
	s_setprio 0
	s_setprio 1
	v_mfma_f32_16x16x32_bf16 v[118:121], v[184:187], v[204:207], 0
	v_mfma_f32_16x16x32_bf16 v[114:117], v[196:199], v[204:207], 0
	v_mfma_f32_16x16x32_bf16 v[98:101], v[196:199], v[212:215], 0
	v_mfma_f32_16x16x32_bf16 v[102:105], v[184:187], v[212:215], 0
	v_mfma_f32_16x16x32_bf16 v[86:89], v[184:187], v[220:223], 0
	v_mfma_f32_16x16x32_bf16 v[82:85], v[196:199], v[220:223], 0
	v_mfma_f32_16x16x32_bf16 v[66:69], v[196:199], v[228:231], 0
	v_mfma_f32_16x16x32_bf16 v[70:73], v[184:187], v[228:231], 0
	v_mfma_f32_16x16x32_bf16 v[118:121], v[192:195], v[208:211], v[118:121]
	v_mfma_f32_16x16x32_bf16 v[114:117], v[200:203], v[208:211], v[114:117]
	v_mfma_f32_16x16x32_bf16 v[98:101], v[200:203], v[216:219], v[98:101]
	v_mfma_f32_16x16x32_bf16 v[102:105], v[192:195], v[216:219], v[102:105]
	v_mfma_f32_16x16x32_bf16 v[86:89], v[192:195], v[224:227], v[86:89]
	v_mfma_f32_16x16x32_bf16 v[82:85], v[200:203], v[224:227], v[82:85]
	v_mfma_f32_16x16x32_bf16 v[66:69], v[200:203], v[232:235], v[66:69]
	v_mfma_f32_16x16x32_bf16 v[70:73], v[192:195], v[232:235], v[70:73]
	s_setprio 0
	s_barrier
	s_add_i32 s15, s58, s50
	v_lshl_add_u64 v[154:155], s[40:41], 0, v[132:133]
	s_mov_b32 m0, s15
	ds_read_b128 v[204:207], v167 offset:16384
	ds_read_b128 v[208:211], v167 offset:17408
	ds_read_b128 v[212:215], v167 offset:18432
	ds_read_b128 v[216:219], v167 offset:19456
	ds_read_b128 v[220:223], v167 offset:20480
	ds_read_b128 v[224:227], v167 offset:21504
	ds_read_b128 v[228:231], v167 offset:22528
	ds_read_b128 v[232:235], v167 offset:23552
	global_load_lds_dwordx4 v[154:155], off
	s_add_i32 m0, s15, 0x2000
	s_add_u32 s18, s40, 0x40000
	v_lshl_add_u64 v[158:159], s[40:41], 0, v[136:137]
	s_addc_u32 s19, s41, 0
	s_add_i32 s15, s59, s50
	global_load_lds_dwordx4 v[158:159], off
	v_lshl_add_u64 v[164:165], s[18:19], 0, v[132:133]
	s_mov_b32 m0, s15
	v_lshl_add_u64 v[168:169], s[42:43], 0, v[134:135]
	global_load_lds_dwordx4 v[164:165], off
	v_lshl_add_u64 v[164:165], s[18:19], 0, v[136:137]
	s_add_i32 m0, s15, 0x2000
	s_nop 0
	global_load_lds_dwordx4 v[164:165], off
	v_lshl_add_u64 v[164:165], s[42:43], 0, v[130:131]
	s_mov_b32 m0, s51
	s_nop 0
	global_load_lds_dwordx4 v[164:165], off
	s_mov_b32 m0, s52
	s_nop 0
	global_load_lds_dwordx4 v[168:169], off
	s_waitcnt vmcnt(8)
; #define PG8_STAGE(bufoff, gbase, voff) do { _Pragma("unroll") for (int _i = 0; _i < 2; ++_i) \
;         __builtin_amdgcn_global_load_lds((const unsigned*)((const char*)(gbase) + (voff)[_i]), (PG8_LAS unsigned*)(lds + (bufoff) + ldsw + _i * 8192), 16, 0, 0); } while (0)
; #define PG8_LDA(dst, b, h) do { _Pragma("unroll") for (int m = 0; m < 4; ++m) _Pragma("unroll") for (int k = 0; k < 2; ++k) dst[m][k] = *(const PG8_LAS bf16x8*)(lds + PG8_SA(b, h) + aoff + m * 2048 + k * 1024); } while (0)
; #define PG8_LDB(dst, b, h) do { _Pragma("unroll") for (int n = 0; n < 2; ++n) _Pragma("unroll") for (int k = 0; k < 2; ++k) dst[n][k] = *(const PG8_LAS bf16x8*)(lds + PG8_SB(b, h) + boff + n * 2048 + k * 1024); } while (0)
; #define PG8_MMA(ai, bj, At, Bt) do { __builtin_amdgcn_s_setprio(1); _Pragma("unroll") for (int m = 0; m < 4; ++m) _Pragma("unroll") for (int n = 0; n < 2; ++n) _Pragma("unroll") for (int k = 0; k < 2; ++k) \
;         acc[ai][bj][m][n] = __builtin_amdgcn_mfma_f32_16x16x32_bf16(Bt[n][k], At[m][k], acc[ai][bj][m][n], 0, 0, 0); __builtin_amdgcn_s_setprio(0); } while (0)
; #define PG8_WAIT_V(n) asm volatile("s_waitcnt vmcnt(" #n ")" ::: "memory")
; #define PG8_WAIT_L(n) asm volatile("s_waitcnt lgkmcnt(" #n ")" ::: "memory")
; #define PG8_BAR __builtin_amdgcn_s_barrier()
; #define PG8_SCHED __builtin_amdgcn_sched_barrier(0)
; template <class Epi, class Sched, bool ALIGN_EPI = false, bool SP2 = false>
; __device__ __forceinline__ void gemm_phase(PG8_LAS unsigned char* lds, const Gemm g, const Sched& S, const Epi& E, const int tid) {
;     ...
;             PG8_WAIT_V(8); PG8_WAIT_L(0); PG8_BAR; PG8_MMA(1, 0, At, B0); PG8_MMA(1, 1, At, B1); PG8_BAR; PG8_SCHED;
;             PG8_LDB(B0, 1, 0); PG8_LDB(B1, 1, 1); PG8_SCHED; PG8_LDA(At, 1, 0); PG8_STAGE(PG8_SA(0, 1), a2 + hstep, voffA);
;             PG8_WAIT_V(8); PG8_WAIT_L(0); PG8_BAR; PG8_MMA(0, 0, At, B0); PG8_MMA(0, 1, At, B1); PG8_BAR; PG8_SCHED;
; __device__ __forceinline__ void rstd8(const float* ssq, int row0, int fq, float (&rs)[8]) {
;     ...
; #pragma unroll
;     for (int i = 0; i < 8; ++i) { float s = (pr[i][0] + pr[i][1]) + (pr[i][2] + pr[i][3]); s = xsum16(s); s = xsum32(s); rs[i] = __builtin_amdgcn_rsqf(s * (1.0f / DM) + NORM_EPS); }
	v_add_f32_e32 v6, v6, v7
	v_add_f32_e32 v18, v18, v19
	v_add_f32_e32 v22, v22, v23
	v_add_f32_e32 v34, v34, v35
	v_add_f32_e32 v38, v38, v39
	v_add_f32_e32 v50, v50, v51
	v_add_f32_e32 v54, v54, v55
	v_add_f32_e32 v58, v58, v59
	v_add_f32_e32 v8, v8, v9
	v_add_f32_e32 v20, v20, v21
	v_add_f32_e32 v24, v24, v25
	v_add_f32_e32 v36, v36, v37
	v_add_f32_e32 v40, v40, v41
	v_add_f32_e32 v52, v52, v53
	v_add_f32_e32 v56, v56, v57
	v_add_f32_e32 v60, v60, v61
	v_add_f32_e32 v243, v6, v8
	v_add_f32_e32 v244, v18, v20
	v_add_f32_e32 v245, v22, v24
	v_add_f32_e32 v246, v34, v36
	v_add_f32_e32 v247, v38, v40
	v_add_f32_e32 v248, v50, v52
	v_add_f32_e32 v249, v54, v56
	v_add_f32_e32 v250, v58, v60
	v_mov_b32_e32 v6, v243
	v_mov_b32_e32 v18, v244
	v_mov_b32_e32 v22, v245
	v_mov_b32_e32 v34, v246
	v_mov_b32_e32 v38, v247
	v_mov_b32_e32 v50, v248
	v_mov_b32_e32 v54, v249
	v_mov_b32_e32 v58, v250
	v_permlane16_swap_b32_e32 v243, v6
	v_permlane16_swap_b32_e32 v244, v18
	v_permlane16_swap_b32_e32 v245, v22
	v_permlane16_swap_b32_e32 v246, v34
	v_permlane16_swap_b32_e32 v247, v38
	v_permlane16_swap_b32_e32 v248, v50
	v_permlane16_swap_b32_e32 v249, v54
	v_permlane16_swap_b32_e32 v250, v58
	v_add_f32_e32 v243, v243, v6
	v_add_f32_e32 v244, v244, v18
	v_add_f32_e32 v245, v245, v22
	v_add_f32_e32 v246, v246, v34
	v_add_f32_e32 v247, v247, v38
	v_add_f32_e32 v248, v248, v50
	v_add_f32_e32 v249, v249, v54
	v_add_f32_e32 v250, v250, v58
	v_mov_b32_e32 v6, v243
	v_mov_b32_e32 v18, v244
	v_mov_b32_e32 v22, v245
	v_mov_b32_e32 v34, v246
	v_mov_b32_e32 v38, v247
	v_mov_b32_e32 v50, v248
	v_mov_b32_e32 v54, v249
	v_mov_b32_e32 v58, v250
	v_permlane32_swap_b32_e32 v243, v6
	v_permlane32_swap_b32_e32 v244, v18
	v_permlane32_swap_b32_e32 v245, v22
	v_permlane32_swap_b32_e32 v246, v34
	v_permlane32_swap_b32_e32 v247, v38
	v_permlane32_swap_b32_e32 v248, v50
	v_permlane32_swap_b32_e32 v249, v54
	v_permlane32_swap_b32_e32 v250, v58
	v_add_f32_e32 v243, v243, v6
	v_add_f32_e32 v244, v244, v18
	v_add_f32_e32 v245, v245, v22
	v_add_f32_e32 v246, v246, v34
	v_add_f32_e32 v247, v247, v38
	v_add_f32_e32 v248, v248, v50
	v_add_f32_e32 v249, v249, v54
	v_add_f32_e32 v250, v250, v58
	v_fmamk_f32 v243, v243, 0x3a800000, v171
	v_fmamk_f32 v244, v244, 0x3a800000, v171
	v_fmamk_f32 v245, v245, 0x3a800000, v171
	v_fmamk_f32 v246, v246, 0x3a800000, v171
	v_fmamk_f32 v247, v247, 0x3a800000, v171
	v_fmamk_f32 v248, v248, 0x3a800000, v171
	v_fmamk_f32 v249, v249, 0x3a800000, v171
	v_fmamk_f32 v250, v250, 0x3a800000, v171
	v_rsq_f32_e32 v243, v243
	v_rsq_f32_e32 v244, v244
	v_rsq_f32_e32 v245, v245
	v_rsq_f32_e32 v246, v246
	v_rsq_f32_e32 v247, v247
	v_rsq_f32_e32 v248, v248
	v_rsq_f32_e32 v249, v249
	v_rsq_f32_e32 v250, v250
	s_waitcnt lgkmcnt(0)
	s_barrier
	s_setprio 1
	s_waitcnt lgkmcnt(0)
	v_mfma_f32_16x16x32_bf16 v[62:65], v[150:153], v[204:207], 0
	v_mfma_f32_16x16x32_bf16 v[58:61], v[176:179], v[204:207], 0
	v_mfma_f32_16x16x32_bf16 v[42:45], v[176:179], v[212:215], 0
	v_mfma_f32_16x16x32_bf16 v[46:49], v[150:153], v[212:215], 0
	v_mfma_f32_16x16x32_bf16 v[30:33], v[150:153], v[220:223], 0
	v_mfma_f32_16x16x32_bf16 v[26:29], v[176:179], v[220:223], 0
	v_mfma_f32_16x16x32_bf16 v[10:13], v[176:179], v[228:231], 0
	v_mfma_f32_16x16x32_bf16 v[14:17], v[150:153], v[228:231], 0
	v_mfma_f32_16x16x32_bf16 v[62:65], v[172:175], v[208:211], v[62:65]
	v_mfma_f32_16x16x32_bf16 v[58:61], v[180:183], v[208:211], v[58:61]
	v_mfma_f32_16x16x32_bf16 v[42:45], v[180:183], v[216:219], v[42:45]
	v_mfma_f32_16x16x32_bf16 v[46:49], v[172:175], v[216:219], v[46:49]
	v_mfma_f32_16x16x32_bf16 v[30:33], v[172:175], v[224:227], v[30:33]
	v_mfma_f32_16x16x32_bf16 v[26:29], v[180:183], v[224:227], v[26:29]
	v_mfma_f32_16x16x32_bf16 v[10:13], v[180:183], v[232:235], v[10:13]
	v_mfma_f32_16x16x32_bf16 v[14:17], v[172:175], v[232:235], v[14:17]
	s_setprio 0
	s_setprio 1
	v_mfma_f32_16x16x32_bf16 v[54:57], v[184:187], v[204:207], 0
	v_mfma_f32_16x16x32_bf16 v[50:53], v[196:199], v[204:207], 0
	v_mfma_f32_16x16x32_bf16 v[34:37], v[196:199], v[212:215], 0
	v_mfma_f32_16x16x32_bf16 v[38:41], v[184:187], v[212:215], 0
	v_mfma_f32_16x16x32_bf16 v[22:25], v[184:187], v[220:223], 0
	v_mfma_f32_16x16x32_bf16 v[18:21], v[196:199], v[220:223], 0
	v_mfma_f32_16x16x32_bf16 v[2:5], v[196:199], v[228:231], 0
	v_mfma_f32_16x16x32_bf16 v[6:9], v[184:187], v[228:231], 0
	v_mfma_f32_16x16x32_bf16 v[54:57], v[192:195], v[208:211], v[54:57]
	v_mfma_f32_16x16x32_bf16 v[50:53], v[200:203], v[208:211], v[50:53]
	v_mfma_f32_16x16x32_bf16 v[34:37], v[200:203], v[216:219], v[34:37]
	v_mfma_f32_16x16x32_bf16 v[38:41], v[192:195], v[216:219], v[38:41]
	v_mfma_f32_16x16x32_bf16 v[22:25], v[192:195], v[224:227], v[22:25]
	v_mfma_f32_16x16x32_bf16 v[18:21], v[200:203], v[224:227], v[18:21]
	v_mfma_f32_16x16x32_bf16 v[2:5], v[200:203], v[232:235], v[2:5]
	v_mfma_f32_16x16x32_bf16 v[6:9], v[192:195], v[232:235], v[6:9]
	s_setprio 0
	s_barrier
	s_add_i32 s15, 0, 0x18000
	v_add_u32_e32 v156, s15, v157
	s_add_i32 s67, 0, 0x1c000
	ds_read_b128 v[150:153], v156
	ds_read_b128 v[172:175], v156 offset:1024
	ds_read_b128 v[176:179], v156 offset:2048
	ds_read_b128 v[180:183], v156 offset:3072
	v_add_u32_e32 v156, s67, v157
	ds_read_b128 v[184:187], v156
	ds_read_b128 v[192:195], v156 offset:1024
	ds_read_b128 v[196:199], v156 offset:2048
	ds_read_b128 v[200:203], v156 offset:3072
	s_add_u32 s18, s42, 0x40000
	s_addc_u32 s19, s43, 0
	s_mov_b32 m0, s53
	v_lshl_add_u64 v[188:189], s[18:19], 0, v[130:131]
	ds_read_b128 v[204:207], v167 offset:32768
	ds_read_b128 v[208:211], v167 offset:33792
	ds_read_b128 v[212:215], v167 offset:34816
	ds_read_b128 v[216:219], v167 offset:35840
	ds_read_b128 v[220:223], v167 offset:36864
	ds_read_b128 v[224:227], v167 offset:37888
	ds_read_b128 v[228:231], v167 offset:38912
	ds_read_b128 v[232:235], v167 offset:39936
	global_load_lds_dwordx4 v[188:189], off
	v_lshl_add_u64 v[188:189], s[18:19], 0, v[134:135]
	s_mov_b32 m0, s54
	s_nop 0
	global_load_lds_dwordx4 v[188:189], off
	s_waitcnt vmcnt(8)
	s_waitcnt lgkmcnt(0)
	s_barrier
; #define PG8_STAGE(bufoff, gbase, voff) do { _Pragma("unroll") for (int _i = 0; _i < 2; ++_i) \
;         __builtin_amdgcn_global_load_lds((const unsigned*)((const char*)(gbase) + (voff)[_i]), (PG8_LAS unsigned*)(lds + (bufoff) + ldsw + _i * 8192), 16, 0, 0); } while (0)
; #define PG8_LDA(dst, b, h) do { _Pragma("unroll") for (int m = 0; m < 4; ++m) _Pragma("unroll") for (int k = 0; k < 2; ++k) dst[m][k] = *(const PG8_LAS bf16x8*)(lds + PG8_SA(b, h) + aoff + m * 2048 + k * 1024); } while (0)
; #define PG8_MMA(ai, bj, At, Bt) do { __builtin_amdgcn_s_setprio(1); _Pragma("unroll") for (int m = 0; m < 4; ++m) _Pragma("unroll") for (int n = 0; n < 2; ++n) _Pragma("unroll") for (int k = 0; k < 2; ++k) \
;         acc[ai][bj][m][n] = __builtin_amdgcn_mfma_f32_16x16x32_bf16(Bt[n][k], At[m][k], acc[ai][bj][m][n], 0, 0, 0); __builtin_amdgcn_s_setprio(0); } while (0)
; #define PG8_WAIT_V(n) asm volatile("s_waitcnt vmcnt(" #n ")" ::: "memory")
; #define PG8_WAIT_L(n) asm volatile("s_waitcnt lgkmcnt(" #n ")" ::: "memory")
; #define PG8_BAR __builtin_amdgcn_s_barrier()
; #define PG8_SCHED __builtin_amdgcn_sched_barrier(0)
; template <class Epi, class Sched, bool ALIGN_EPI = false, bool SP2 = false>
; __device__ __forceinline__ void gemm_phase(PG8_LAS unsigned char* lds, const Gemm g, const Sched& S, const Epi& E, const int tid) {
;     ...
;         for (int t = 0; t < nt; t += 2) {
;     ...
;             PG8_WAIT_V(8); PG8_WAIT_L(0); PG8_BAR; PG8_MMA(0, 0, At, B0); PG8_MMA(0, 1, At, B1); PG8_BAR; PG8_SCHED;
;             PG8_LDA(At, 1, 1); PG8_STAGE(PG8_SB(1, 0), b3, voffB); PG8_STAGE(PG8_SB(1, 1), b3 + hstep, voffB); PG8_STAGE(PG8_SA(1, 0), a3, voffA);
;             PG8_WAIT_V(8); PG8_WAIT_L(0); PG8_BAR; PG8_MMA(1, 0, At, B0); PG8_MMA(1, 1, At, B1); PG8_BAR; PG8_SCHED;
	s_setprio 1
	s_waitcnt lgkmcnt(0)
	v_mfma_f32_16x16x32_bf16 v[126:129], v[150:153], v[204:207], v[126:129]
	v_mfma_f32_16x16x32_bf16 v[122:125], v[176:179], v[204:207], v[122:125]
	v_mfma_f32_16x16x32_bf16 v[106:109], v[176:179], v[212:215], v[106:109]
	v_mfma_f32_16x16x32_bf16 v[110:113], v[150:153], v[212:215], v[110:113]
	v_mfma_f32_16x16x32_bf16 v[94:97], v[150:153], v[220:223], v[94:97]
	v_mfma_f32_16x16x32_bf16 v[90:93], v[176:179], v[220:223], v[90:93]
	v_mfma_f32_16x16x32_bf16 v[74:77], v[176:179], v[228:231], v[74:77]
	v_mfma_f32_16x16x32_bf16 v[78:81], v[150:153], v[228:231], v[78:81]
	v_mfma_f32_16x16x32_bf16 v[126:129], v[172:175], v[208:211], v[126:129]
	v_mfma_f32_16x16x32_bf16 v[122:125], v[180:183], v[208:211], v[122:125]
	v_mfma_f32_16x16x32_bf16 v[106:109], v[180:183], v[216:219], v[106:109]
	v_mfma_f32_16x16x32_bf16 v[110:113], v[172:175], v[216:219], v[110:113]
	v_mfma_f32_16x16x32_bf16 v[94:97], v[172:175], v[224:227], v[94:97]
	v_mfma_f32_16x16x32_bf16 v[90:93], v[180:183], v[224:227], v[90:93]
	v_mfma_f32_16x16x32_bf16 v[74:77], v[180:183], v[232:235], v[74:77]
	v_mfma_f32_16x16x32_bf16 v[78:81], v[172:175], v[232:235], v[78:81]
	s_setprio 0
	s_setprio 1
	v_mfma_f32_16x16x32_bf16 v[118:121], v[184:187], v[204:207], v[118:121]
	v_mfma_f32_16x16x32_bf16 v[114:117], v[196:199], v[204:207], v[114:117]
	v_mfma_f32_16x16x32_bf16 v[98:101], v[196:199], v[212:215], v[98:101]
	v_mfma_f32_16x16x32_bf16 v[102:105], v[184:187], v[212:215], v[102:105]
	v_mfma_f32_16x16x32_bf16 v[86:89], v[184:187], v[220:223], v[86:89]
	v_mfma_f32_16x16x32_bf16 v[82:85], v[196:199], v[220:223], v[82:85]
	v_mfma_f32_16x16x32_bf16 v[66:69], v[196:199], v[228:231], v[66:69]
	v_mfma_f32_16x16x32_bf16 v[70:73], v[184:187], v[228:231], v[70:73]
	v_mfma_f32_16x16x32_bf16 v[118:121], v[192:195], v[208:211], v[118:121]
	v_mfma_f32_16x16x32_bf16 v[114:117], v[200:203], v[208:211], v[114:117]
	v_mfma_f32_16x16x32_bf16 v[98:101], v[200:203], v[216:219], v[98:101]
	v_mfma_f32_16x16x32_bf16 v[102:105], v[192:195], v[216:219], v[102:105]
	v_mfma_f32_16x16x32_bf16 v[86:89], v[192:195], v[224:227], v[86:89]
	v_mfma_f32_16x16x32_bf16 v[82:85], v[200:203], v[224:227], v[82:85]
	v_mfma_f32_16x16x32_bf16 v[66:69], v[200:203], v[232:235], v[66:69]
	v_mfma_f32_16x16x32_bf16 v[70:73], v[192:195], v[232:235], v[70:73]
	s_setprio 0
	s_barrier
	s_add_i32 s15, s15, s50
	v_lshl_add_u64 v[154:155], v[154:155], 0, s[8:9]
	s_mov_b32 m0, s15
	ds_read_b128 v[204:207], v167 offset:49152
	ds_read_b128 v[208:211], v167 offset:50176
	ds_read_b128 v[212:215], v167 offset:51200
	ds_read_b128 v[216:219], v167 offset:52224
	ds_read_b128 v[220:223], v167 offset:53248
	ds_read_b128 v[224:227], v167 offset:54272
	ds_read_b128 v[228:231], v167 offset:55296
	ds_read_b128 v[232:235], v167 offset:56320
	global_load_lds_dwordx4 v[154:155], off
	s_add_i32 m0, s15, 0x2000
	s_add_u32 s18, s40, 0x40080
	v_lshl_add_u64 v[154:155], v[158:159], 0, s[8:9]
	s_addc_u32 s19, s41, 0
	s_add_i32 s15, s67, s50
	global_load_lds_dwordx4 v[154:155], off
	v_lshl_add_u64 v[154:155], s[18:19], 0, v[132:133]
	s_mov_b32 m0, s15
	s_nop 0
	global_load_lds_dwordx4 v[154:155], off
	v_lshl_add_u64 v[154:155], s[18:19], 0, v[136:137]
	s_add_i32 m0, s15, 0x2000
	s_nop 0
	global_load_lds_dwordx4 v[154:155], off
	v_lshl_add_u64 v[154:155], v[164:165], 0, s[8:9]
	s_mov_b32 m0, s55
	s_nop 0
	global_load_lds_dwordx4 v[154:155], off
	v_lshl_add_u64 v[154:155], v[168:169], 0, s[8:9]
	s_mov_b32 m0, s56
	s_nop 0
	global_load_lds_dwordx4 v[154:155], off
	s_waitcnt vmcnt(8)
	s_waitcnt lgkmcnt(0)
	s_barrier
	s_setprio 1
	s_waitcnt lgkmcnt(0)
	v_mfma_f32_16x16x32_bf16 v[62:65], v[150:153], v[204:207], v[62:65]
	v_mfma_f32_16x16x32_bf16 v[58:61], v[176:179], v[204:207], v[58:61]
	v_mfma_f32_16x16x32_bf16 v[42:45], v[176:179], v[212:215], v[42:45]
	v_mfma_f32_16x16x32_bf16 v[46:49], v[150:153], v[212:215], v[46:49]
	v_mfma_f32_16x16x32_bf16 v[30:33], v[150:153], v[220:223], v[30:33]
	v_mfma_f32_16x16x32_bf16 v[26:29], v[176:179], v[220:223], v[26:29]
	v_mfma_f32_16x16x32_bf16 v[10:13], v[176:179], v[228:231], v[10:13]
	v_mfma_f32_16x16x32_bf16 v[14:17], v[150:153], v[228:231], v[14:17]
	v_mfma_f32_16x16x32_bf16 v[62:65], v[172:175], v[208:211], v[62:65]
	v_mfma_f32_16x16x32_bf16 v[58:61], v[180:183], v[208:211], v[58:61]
	v_mfma_f32_16x16x32_bf16 v[42:45], v[180:183], v[216:219], v[42:45]
	v_mfma_f32_16x16x32_bf16 v[46:49], v[172:175], v[216:219], v[46:49]
	v_mfma_f32_16x16x32_bf16 v[30:33], v[172:175], v[224:227], v[30:33]
	v_mfma_f32_16x16x32_bf16 v[26:29], v[180:183], v[224:227], v[26:29]
	v_mfma_f32_16x16x32_bf16 v[10:13], v[180:183], v[232:235], v[10:13]
	v_mfma_f32_16x16x32_bf16 v[14:17], v[172:175], v[232:235], v[14:17]
	s_setprio 0
	s_setprio 1
	v_mfma_f32_16x16x32_bf16 v[54:57], v[184:187], v[204:207], v[54:57]
	v_mfma_f32_16x16x32_bf16 v[50:53], v[196:199], v[204:207], v[50:53]
	v_mfma_f32_16x16x32_bf16 v[34:37], v[196:199], v[212:215], v[34:37]
	v_mfma_f32_16x16x32_bf16 v[38:41], v[184:187], v[212:215], v[38:41]
	v_mfma_f32_16x16x32_bf16 v[22:25], v[184:187], v[220:223], v[22:25]
	v_mfma_f32_16x16x32_bf16 v[18:21], v[196:199], v[220:223], v[18:21]
	v_mfma_f32_16x16x32_bf16 v[2:5], v[196:199], v[228:231], v[2:5]
	v_mfma_f32_16x16x32_bf16 v[6:9], v[184:187], v[228:231], v[6:9]
	v_mfma_f32_16x16x32_bf16 v[54:57], v[192:195], v[208:211], v[54:57]
	v_mfma_f32_16x16x32_bf16 v[50:53], v[200:203], v[208:211], v[50:53]
	v_mfma_f32_16x16x32_bf16 v[34:37], v[200:203], v[216:219], v[34:37]
	v_mfma_f32_16x16x32_bf16 v[38:41], v[192:195], v[216:219], v[38:41]
	v_mfma_f32_16x16x32_bf16 v[22:25], v[192:195], v[224:227], v[22:25]
	v_mfma_f32_16x16x32_bf16 v[18:21], v[200:203], v[224:227], v[18:21]
	v_mfma_f32_16x16x32_bf16 v[2:5], v[200:203], v[232:235], v[2:5]
	v_mfma_f32_16x16x32_bf16 v[6:9], v[192:195], v[232:235], v[6:9]
	s_setprio 0
	s_barrier
	s_add_i32 s66, s66, 2
	s_add_u32 s64, s64, 0x100
	s_addc_u32 s65, s65, 0
	s_add_u32 s38, s38, 0x100
	s_addc_u32 s39, s39, 0
; #define PG8_STAGE(bufoff, gbase, voff) do { _Pragma("unroll") for (int _i = 0; _i < 2; ++_i) \
;         __builtin_amdgcn_global_load_lds((const unsigned*)((const char*)(gbase) + (voff)[_i]), (PG8_LAS unsigned*)(lds + (bufoff) + ldsw + _i * 8192), 16, 0, 0); } while (0)
; #define PG8_LDA(dst, b, h) do { _Pragma("unroll") for (int m = 0; m < 4; ++m) _Pragma("unroll") for (int k = 0; k < 2; ++k) dst[m][k] = *(const PG8_LAS bf16x8*)(lds + PG8_SA(b, h) + aoff + m * 2048 + k * 1024); } while (0)
; #define PG8_LDB(dst, b, h) do { _Pragma("unroll") for (int n = 0; n < 2; ++n) _Pragma("unroll") for (int k = 0; k < 2; ++k) dst[n][k] = *(const PG8_LAS bf16x8*)(lds + PG8_SB(b, h) + boff + n * 2048 + k * 1024); } while (0)
; #define PG8_MMA(ai, bj, At, Bt) do { __builtin_amdgcn_s_setprio(1); _Pragma("unroll") for (int m = 0; m < 4; ++m) _Pragma("unroll") for (int n = 0; n < 2; ++n) _Pragma("unroll") for (int k = 0; k < 2; ++k) \
;         acc[ai][bj][m][n] = __builtin_amdgcn_mfma_f32_16x16x32_bf16(Bt[n][k], At[m][k], acc[ai][bj][m][n], 0, 0, 0); __builtin_amdgcn_s_setprio(0); } while (0)
; #define PG8_WAIT_V(n) asm volatile("s_waitcnt vmcnt(" #n ")" ::: "memory")
; #define PG8_BAR __builtin_amdgcn_s_barrier()
; template <class Epi, class Sched, bool ALIGN_EPI = false, bool SP2 = false>
; __device__ __forceinline__ void gemm_phase(PG8_LAS unsigned char* lds, const Gemm g, const Sched& S, const Epi& E, const int tid) {
;     ...
;         for (int t = 0; t < nt; t += 2) {
;             const bool last = (t == nt - 2);
;             const char* a1 = cA + (size_t)(t + 1) * kstep;
;             const char* a2 = last ? nA : cA + (size_t)(t + 2) * kstep; const char* b2 = last ? nB : cB + (size_t)(t + 2) * kstep;
;             const char* a3 = a2 + kstep; const char* b3 = b2 + kstep;
;             if (last && has_next) S.a_ready(nxt);
;             if constexpr (SP2) {
;             PG8_LDB(B0, 0, 0); PG8_LDB(B1, 0, 1); PG8_SCHED; PG8_LDA(At, 0, 0); PG8_STAGE(PG8_SA(1, 1), a1 + hstep, voffA);
;             PG8_WAIT_V(8); PG8_WAIT_L(0); PG8_BAR; PG8_MMA(0, 0, At, B0); PG8_MMA(0, 1, At, B1); PG8_BAR; PG8_SCHED;
;             PG8_LDA(At, 0, 1); PG8_STAGE(PG8_SB(0, 0), b2, voffB); PG8_STAGE(PG8_SB(0, 1), b2 + hstep, voffB); PG8_STAGE(PG8_SA(0, 0), a2, voffA);
;             PG8_WAIT_V(8); PG8_WAIT_L(0); PG8_BAR; PG8_MMA(1, 0, At, B0); PG8_MMA(1, 1, At, B1); PG8_BAR; PG8_SCHED;
.LBB0_339:
	ds_read_b128 v[150:153], v161
	ds_read_b128 v[172:175], v161 offset:1024
	ds_read_b128 v[176:179], v161 offset:2048
	ds_read_b128 v[180:183], v161 offset:3072
	ds_read_b128 v[184:187], v163
	ds_read_b128 v[192:195], v163 offset:1024
	ds_read_b128 v[196:199], v163 offset:2048
	ds_read_b128 v[200:203], v163 offset:3072
	s_add_u32 s15, s38, 0xfffc0080
	s_addc_u32 s18, s39, -1
	s_cmp_eq_u32 s66, 12
	s_cselect_b32 s43, s29, s18
	s_cselect_b32 s42, s62, s15
	s_cselect_b32 s41, s27, s65
	s_cselect_b32 s40, s63, s64
	v_lshl_add_u64 v[154:155], s[38:39], 0, v[144:145]
	s_add_i32 m0, s51, 0xc000
	ds_read_b128 v[204:207], v167
	ds_read_b128 v[208:211], v167 offset:1024
	ds_read_b128 v[212:215], v167 offset:2048
	ds_read_b128 v[216:219], v167 offset:3072
	ds_read_b128 v[220:223], v167 offset:4096
	ds_read_b128 v[224:227], v167 offset:5120
	ds_read_b128 v[228:231], v167 offset:6144
	ds_read_b128 v[232:235], v167 offset:7168
	global_load_lds_dwordx4 v[154:155], off
	v_lshl_add_u64 v[154:155], s[38:39], 0, v[142:143]
	s_add_i32 m0, s51, 0xe000
	s_nop 0
	global_load_lds_dwordx4 v[154:155], off
	s_waitcnt vmcnt(8)
	s_waitcnt lgkmcnt(0)
	s_barrier
	s_setprio 1
	s_waitcnt lgkmcnt(0)
	v_mfma_f32_16x16x32_bf16 v[126:129], v[150:153], v[204:207], v[126:129]
	v_mfma_f32_16x16x32_bf16 v[122:125], v[176:179], v[204:207], v[122:125]
	v_mfma_f32_16x16x32_bf16 v[106:109], v[176:179], v[212:215], v[106:109]
	v_mfma_f32_16x16x32_bf16 v[110:113], v[150:153], v[212:215], v[110:113]
	v_mfma_f32_16x16x32_bf16 v[94:97], v[150:153], v[220:223], v[94:97]
	v_mfma_f32_16x16x32_bf16 v[90:93], v[176:179], v[220:223], v[90:93]
	v_mfma_f32_16x16x32_bf16 v[74:77], v[176:179], v[228:231], v[74:77]
	v_mfma_f32_16x16x32_bf16 v[78:81], v[150:153], v[228:231], v[78:81]
	v_mfma_f32_16x16x32_bf16 v[126:129], v[172:175], v[208:211], v[126:129]
	v_mfma_f32_16x16x32_bf16 v[122:125], v[180:183], v[208:211], v[122:125]
	v_mfma_f32_16x16x32_bf16 v[106:109], v[180:183], v[216:219], v[106:109]
	v_mfma_f32_16x16x32_bf16 v[110:113], v[172:175], v[216:219], v[110:113]
	v_mfma_f32_16x16x32_bf16 v[94:97], v[172:175], v[224:227], v[94:97]
	v_mfma_f32_16x16x32_bf16 v[90:93], v[180:183], v[224:227], v[90:93]
	v_mfma_f32_16x16x32_bf16 v[74:77], v[180:183], v[232:235], v[74:77]
	v_mfma_f32_16x16x32_bf16 v[78:81], v[172:175], v[232:235], v[78:81]
	s_setprio 0
	s_setprio 1
	v_mfma_f32_16x16x32_bf16 v[118:121], v[184:187], v[204:207], v[118:121]
	v_mfma_f32_16x16x32_bf16 v[114:117], v[196:199], v[204:207], v[114:117]
	v_mfma_f32_16x16x32_bf16 v[98:101], v[196:199], v[212:215], v[98:101]
	v_mfma_f32_16x16x32_bf16 v[102:105], v[184:187], v[212:215], v[102:105]
	v_mfma_f32_16x16x32_bf16 v[86:89], v[184:187], v[220:223], v[86:89]
	v_mfma_f32_16x16x32_bf16 v[82:85], v[196:199], v[220:223], v[82:85]
	v_mfma_f32_16x16x32_bf16 v[66:69], v[196:199], v[228:231], v[66:69]
	v_mfma_f32_16x16x32_bf16 v[70:73], v[184:187], v[228:231], v[70:73]
	v_mfma_f32_16x16x32_bf16 v[118:121], v[192:195], v[208:211], v[118:121]
	v_mfma_f32_16x16x32_bf16 v[114:117], v[200:203], v[208:211], v[114:117]
	v_mfma_f32_16x16x32_bf16 v[98:101], v[200:203], v[216:219], v[98:101]
	v_mfma_f32_16x16x32_bf16 v[102:105], v[192:195], v[216:219], v[102:105]
	v_mfma_f32_16x16x32_bf16 v[86:89], v[192:195], v[224:227], v[86:89]
	v_mfma_f32_16x16x32_bf16 v[82:85], v[200:203], v[224:227], v[82:85]
	v_mfma_f32_16x16x32_bf16 v[66:69], v[200:203], v[232:235], v[66:69]
	v_mfma_f32_16x16x32_bf16 v[70:73], v[192:195], v[232:235], v[70:73]
	s_setprio 0
	s_barrier
	s_add_i32 s15, s58, s50
	v_lshl_add_u64 v[154:155], s[40:41], 0, v[132:133]
	s_mov_b32 m0, s15
	ds_read_b128 v[204:207], v167 offset:16384
	ds_read_b128 v[208:211], v167 offset:17408
	ds_read_b128 v[212:215], v167 offset:18432
	ds_read_b128 v[216:219], v167 offset:19456
	ds_read_b128 v[220:223], v167 offset:20480
	ds_read_b128 v[224:227], v167 offset:21504
	ds_read_b128 v[228:231], v167 offset:22528
	ds_read_b128 v[232:235], v167 offset:23552
	global_load_lds_dwordx4 v[154:155], off
	s_add_i32 m0, s15, 0x2000
	s_add_u32 s18, s40, 0x40000
	v_lshl_add_u64 v[158:159], s[40:41], 0, v[136:137]
	s_addc_u32 s19, s41, 0
	s_add_i32 s15, s59, s50
	global_load_lds_dwordx4 v[158:159], off
	v_lshl_add_u64 v[164:165], s[18:19], 0, v[132:133]
	s_mov_b32 m0, s15
	v_lshl_add_u64 v[168:169], s[42:43], 0, v[134:135]
	global_load_lds_dwordx4 v[164:165], off
	v_lshl_add_u64 v[164:165], s[18:19], 0, v[136:137]
	s_add_i32 m0, s15, 0x2000
	s_nop 0
	global_load_lds_dwordx4 v[164:165], off
	v_lshl_add_u64 v[164:165], s[42:43], 0, v[130:131]
	s_mov_b32 m0, s51
	s_nop 0
	global_load_lds_dwordx4 v[164:165], off
	s_mov_b32 m0, s52
	s_nop 0
	global_load_lds_dwordx4 v[168:169], off
	s_waitcnt vmcnt(8)
	s_waitcnt lgkmcnt(0)
	s_barrier
; #define PG8_STAGE(bufoff, gbase, voff) do { _Pragma("unroll") for (int _i = 0; _i < 2; ++_i) \
;         __builtin_amdgcn_global_load_lds((const unsigned*)((const char*)(gbase) + (voff)[_i]), (PG8_LAS unsigned*)(lds + (bufoff) + ldsw + _i * 8192), 16, 0, 0); } while (0)
; #define PG8_LDA(dst, b, h) do { _Pragma("unroll") for (int m = 0; m < 4; ++m) _Pragma("unroll") for (int k = 0; k < 2; ++k) dst[m][k] = *(const PG8_LAS bf16x8*)(lds + PG8_SA(b, h) + aoff + m * 2048 + k * 1024); } while (0)
; #define PG8_LDB(dst, b, h) do { _Pragma("unroll") for (int n = 0; n < 2; ++n) _Pragma("unroll") for (int k = 0; k < 2; ++k) dst[n][k] = *(const PG8_LAS bf16x8*)(lds + PG8_SB(b, h) + boff + n * 2048 + k * 1024); } while (0)
; #define PG8_MMA(ai, bj, At, Bt) do { __builtin_amdgcn_s_setprio(1); _Pragma("unroll") for (int m = 0; m < 4; ++m) _Pragma("unroll") for (int n = 0; n < 2; ++n) _Pragma("unroll") for (int k = 0; k < 2; ++k) \
;         acc[ai][bj][m][n] = __builtin_amdgcn_mfma_f32_16x16x32_bf16(Bt[n][k], At[m][k], acc[ai][bj][m][n], 0, 0, 0); __builtin_amdgcn_s_setprio(0); } while (0)
; #define PG8_WAIT_V(n) asm volatile("s_waitcnt vmcnt(" #n ")" ::: "memory")
; #define PG8_WAIT_L(n) asm volatile("s_waitcnt lgkmcnt(" #n ")" ::: "memory")
; #define PG8_BAR __builtin_amdgcn_s_barrier()
; #define PG8_SCHED __builtin_amdgcn_sched_barrier(0)
; template <class Epi, class Sched, bool ALIGN_EPI = false, bool SP2 = false>
; __device__ __forceinline__ void gemm_phase(PG8_LAS unsigned char* lds, const Gemm g, const Sched& S, const Epi& E, const int tid) {
;     ...
;             PG8_WAIT_V(8); PG8_WAIT_L(0); PG8_BAR; PG8_MMA(1, 0, At, B0); PG8_MMA(1, 1, At, B1); PG8_BAR; PG8_SCHED;
;             PG8_LDB(B0, 1, 0); PG8_LDB(B1, 1, 1); PG8_SCHED; PG8_LDA(At, 1, 0); PG8_STAGE(PG8_SA(0, 1), a2 + hstep, voffA);
;             PG8_WAIT_V(8); PG8_WAIT_L(0); PG8_BAR; PG8_MMA(0, 0, At, B0); PG8_MMA(0, 1, At, B1); PG8_BAR; PG8_SCHED;
	s_setprio 1
	s_waitcnt lgkmcnt(0)
	v_mfma_f32_16x16x32_bf16 v[62:65], v[150:153], v[204:207], v[62:65]
	v_mfma_f32_16x16x32_bf16 v[58:61], v[176:179], v[204:207], v[58:61]
	v_mfma_f32_16x16x32_bf16 v[42:45], v[176:179], v[212:215], v[42:45]
	v_mfma_f32_16x16x32_bf16 v[46:49], v[150:153], v[212:215], v[46:49]
	v_mfma_f32_16x16x32_bf16 v[30:33], v[150:153], v[220:223], v[30:33]
	v_mfma_f32_16x16x32_bf16 v[26:29], v[176:179], v[220:223], v[26:29]
	v_mfma_f32_16x16x32_bf16 v[10:13], v[176:179], v[228:231], v[10:13]
	v_mfma_f32_16x16x32_bf16 v[14:17], v[150:153], v[228:231], v[14:17]
	v_mfma_f32_16x16x32_bf16 v[62:65], v[172:175], v[208:211], v[62:65]
	v_mfma_f32_16x16x32_bf16 v[58:61], v[180:183], v[208:211], v[58:61]
	v_mfma_f32_16x16x32_bf16 v[42:45], v[180:183], v[216:219], v[42:45]
	v_mfma_f32_16x16x32_bf16 v[46:49], v[172:175], v[216:219], v[46:49]
	v_mfma_f32_16x16x32_bf16 v[30:33], v[172:175], v[224:227], v[30:33]
	v_mfma_f32_16x16x32_bf16 v[26:29], v[180:183], v[224:227], v[26:29]
	v_mfma_f32_16x16x32_bf16 v[10:13], v[180:183], v[232:235], v[10:13]
	v_mfma_f32_16x16x32_bf16 v[14:17], v[172:175], v[232:235], v[14:17]
	s_setprio 0
	s_setprio 1
	v_mfma_f32_16x16x32_bf16 v[54:57], v[184:187], v[204:207], v[54:57]
	v_mfma_f32_16x16x32_bf16 v[50:53], v[196:199], v[204:207], v[50:53]
	v_mfma_f32_16x16x32_bf16 v[34:37], v[196:199], v[212:215], v[34:37]
	v_mfma_f32_16x16x32_bf16 v[38:41], v[184:187], v[212:215], v[38:41]
	v_mfma_f32_16x16x32_bf16 v[22:25], v[184:187], v[220:223], v[22:25]
	v_mfma_f32_16x16x32_bf16 v[18:21], v[196:199], v[220:223], v[18:21]
	v_mfma_f32_16x16x32_bf16 v[2:5], v[196:199], v[228:231], v[2:5]
	v_mfma_f32_16x16x32_bf16 v[6:9], v[184:187], v[228:231], v[6:9]
	v_mfma_f32_16x16x32_bf16 v[54:57], v[192:195], v[208:211], v[54:57]
	v_mfma_f32_16x16x32_bf16 v[50:53], v[200:203], v[208:211], v[50:53]
	v_mfma_f32_16x16x32_bf16 v[34:37], v[200:203], v[216:219], v[34:37]
	v_mfma_f32_16x16x32_bf16 v[38:41], v[192:195], v[216:219], v[38:41]
	v_mfma_f32_16x16x32_bf16 v[22:25], v[192:195], v[224:227], v[22:25]
	v_mfma_f32_16x16x32_bf16 v[18:21], v[200:203], v[224:227], v[18:21]
	v_mfma_f32_16x16x32_bf16 v[2:5], v[200:203], v[232:235], v[2:5]
	v_mfma_f32_16x16x32_bf16 v[6:9], v[192:195], v[232:235], v[6:9]
	s_setprio 0
	s_barrier
	s_add_i32 s15, 0, 0x18000
	v_add_u32_e32 v156, s15, v157
	s_add_i32 s67, 0, 0x1c000
	ds_read_b128 v[150:153], v156
	ds_read_b128 v[172:175], v156 offset:1024
	ds_read_b128 v[176:179], v156 offset:2048
	ds_read_b128 v[180:183], v156 offset:3072
	v_add_u32_e32 v156, s67, v157
	ds_read_b128 v[184:187], v156
	ds_read_b128 v[192:195], v156 offset:1024
	ds_read_b128 v[196:199], v156 offset:2048
	ds_read_b128 v[200:203], v156 offset:3072
	s_add_u32 s18, s42, 0x40000
	s_addc_u32 s19, s43, 0
	s_mov_b32 m0, s53
	v_lshl_add_u64 v[188:189], s[18:19], 0, v[130:131]
	ds_read_b128 v[204:207], v167 offset:32768
	ds_read_b128 v[208:211], v167 offset:33792
	ds_read_b128 v[212:215], v167 offset:34816
	ds_read_b128 v[216:219], v167 offset:35840
	ds_read_b128 v[220:223], v167 offset:36864
	ds_read_b128 v[224:227], v167 offset:37888
	ds_read_b128 v[228:231], v167 offset:38912
	ds_read_b128 v[232:235], v167 offset:39936
	global_load_lds_dwordx4 v[188:189], off
	v_lshl_add_u64 v[188:189], s[18:19], 0, v[134:135]
	s_mov_b32 m0, s54
	s_nop 0
	global_load_lds_dwordx4 v[188:189], off
	s_waitcnt vmcnt(8)
	s_waitcnt lgkmcnt(0)
	s_barrier
	s_setprio 1
	s_waitcnt lgkmcnt(0)
	v_mfma_f32_16x16x32_bf16 v[126:129], v[150:153], v[204:207], v[126:129]
	v_mfma_f32_16x16x32_bf16 v[122:125], v[176:179], v[204:207], v[122:125]
	v_mfma_f32_16x16x32_bf16 v[106:109], v[176:179], v[212:215], v[106:109]
	v_mfma_f32_16x16x32_bf16 v[110:113], v[150:153], v[212:215], v[110:113]
	v_mfma_f32_16x16x32_bf16 v[94:97], v[150:153], v[220:223], v[94:97]
	v_mfma_f32_16x16x32_bf16 v[90:93], v[176:179], v[220:223], v[90:93]
	v_mfma_f32_16x16x32_bf16 v[74:77], v[176:179], v[228:231], v[74:77]
	v_mfma_f32_16x16x32_bf16 v[78:81], v[150:153], v[228:231], v[78:81]
	v_mfma_f32_16x16x32_bf16 v[126:129], v[172:175], v[208:211], v[126:129]
	v_mfma_f32_16x16x32_bf16 v[122:125], v[180:183], v[208:211], v[122:125]
	v_mfma_f32_16x16x32_bf16 v[106:109], v[180:183], v[216:219], v[106:109]
	v_mfma_f32_16x16x32_bf16 v[110:113], v[172:175], v[216:219], v[110:113]
	v_mfma_f32_16x16x32_bf16 v[94:97], v[172:175], v[224:227], v[94:97]
	v_mfma_f32_16x16x32_bf16 v[90:93], v[180:183], v[224:227], v[90:93]
	v_mfma_f32_16x16x32_bf16 v[74:77], v[180:183], v[232:235], v[74:77]
	v_mfma_f32_16x16x32_bf16 v[78:81], v[172:175], v[232:235], v[78:81]
	s_setprio 0
	s_setprio 1
	v_mfma_f32_16x16x32_bf16 v[118:121], v[184:187], v[204:207], v[118:121]
	v_mfma_f32_16x16x32_bf16 v[114:117], v[196:199], v[204:207], v[114:117]
	v_mfma_f32_16x16x32_bf16 v[98:101], v[196:199], v[212:215], v[98:101]
	v_mfma_f32_16x16x32_bf16 v[102:105], v[184:187], v[212:215], v[102:105]
	v_mfma_f32_16x16x32_bf16 v[86:89], v[184:187], v[220:223], v[86:89]
	v_mfma_f32_16x16x32_bf16 v[82:85], v[196:199], v[220:223], v[82:85]
	v_mfma_f32_16x16x32_bf16 v[66:69], v[196:199], v[228:231], v[66:69]
	v_mfma_f32_16x16x32_bf16 v[70:73], v[184:187], v[228:231], v[70:73]
	v_mfma_f32_16x16x32_bf16 v[118:121], v[192:195], v[208:211], v[118:121]
	v_mfma_f32_16x16x32_bf16 v[114:117], v[200:203], v[208:211], v[114:117]
	v_mfma_f32_16x16x32_bf16 v[98:101], v[200:203], v[216:219], v[98:101]
	v_mfma_f32_16x16x32_bf16 v[102:105], v[192:195], v[216:219], v[102:105]
	v_mfma_f32_16x16x32_bf16 v[86:89], v[192:195], v[224:227], v[86:89]
	v_mfma_f32_16x16x32_bf16 v[82:85], v[200:203], v[224:227], v[82:85]
	v_mfma_f32_16x16x32_bf16 v[66:69], v[200:203], v[232:235], v[66:69]
	v_mfma_f32_16x16x32_bf16 v[70:73], v[192:195], v[232:235], v[70:73]
	s_setprio 0
	s_barrier
; #define PG8_STAGE(bufoff, gbase, voff) do { _Pragma("unroll") for (int _i = 0; _i < 2; ++_i) \
;         __builtin_amdgcn_global_load_lds((const unsigned*)((const char*)(gbase) + (voff)[_i]), (PG8_LAS unsigned*)(lds + (bufoff) + ldsw + _i * 8192), 16, 0, 0); } while (0)
; #define PG8_LDA(dst, b, h) do { _Pragma("unroll") for (int m = 0; m < 4; ++m) _Pragma("unroll") for (int k = 0; k < 2; ++k) dst[m][k] = *(const PG8_LAS bf16x8*)(lds + PG8_SA(b, h) + aoff + m * 2048 + k * 1024); } while (0)
; #define PG8_MMA(ai, bj, At, Bt) do { __builtin_amdgcn_s_setprio(1); _Pragma("unroll") for (int m = 0; m < 4; ++m) _Pragma("unroll") for (int n = 0; n < 2; ++n) _Pragma("unroll") for (int k = 0; k < 2; ++k) \
;         acc[ai][bj][m][n] = __builtin_amdgcn_mfma_f32_16x16x32_bf16(Bt[n][k], At[m][k], acc[ai][bj][m][n], 0, 0, 0); __builtin_amdgcn_s_setprio(0); } while (0)
; #define PG8_WAIT_V(n) asm volatile("s_waitcnt vmcnt(" #n ")" ::: "memory")
; #define PG8_WAIT_L(n) asm volatile("s_waitcnt lgkmcnt(" #n ")" ::: "memory")
; #define PG8_BAR __builtin_amdgcn_s_barrier()
; #define PG8_SCHED __builtin_amdgcn_sched_barrier(0)
; template <class Epi, class Sched, bool ALIGN_EPI = false, bool SP2 = false>
; __device__ __forceinline__ void gemm_phase(PG8_LAS unsigned char* lds, const Gemm g, const Sched& S, const Epi& E, const int tid) {
;     ...
;             PG8_LDA(At, 1, 1); PG8_STAGE(PG8_SB(1, 0), b3, voffB); PG8_STAGE(PG8_SB(1, 1), b3 + hstep, voffB); PG8_STAGE(PG8_SA(1, 0), a3, voffA);
;             PG8_WAIT_V(8); PG8_WAIT_L(0); PG8_BAR; PG8_MMA(1, 0, At, B0); PG8_MMA(1, 1, At, B1); PG8_BAR; PG8_SCHED;
;     ...
;         if constexpr (ALIGN_EPI) { if (wr == 0) PG8_BAR; }
	s_add_i32 s15, s15, s50
	v_lshl_add_u64 v[154:155], v[154:155], 0, s[8:9]
	s_mov_b32 m0, s15
	ds_read_b128 v[204:207], v167 offset:49152
	ds_read_b128 v[208:211], v167 offset:50176
	ds_read_b128 v[212:215], v167 offset:51200
	ds_read_b128 v[216:219], v167 offset:52224
	ds_read_b128 v[220:223], v167 offset:53248
	ds_read_b128 v[224:227], v167 offset:54272
	ds_read_b128 v[228:231], v167 offset:55296
	ds_read_b128 v[232:235], v167 offset:56320
	global_load_lds_dwordx4 v[154:155], off
	s_add_i32 m0, s15, 0x2000
	s_add_u32 s18, s40, 0x40080
	v_lshl_add_u64 v[154:155], v[158:159], 0, s[8:9]
	s_addc_u32 s19, s41, 0
	s_add_i32 s15, s67, s50
	global_load_lds_dwordx4 v[154:155], off
	v_lshl_add_u64 v[154:155], s[18:19], 0, v[132:133]
	s_mov_b32 m0, s15
	s_nop 0
	global_load_lds_dwordx4 v[154:155], off
	v_lshl_add_u64 v[154:155], s[18:19], 0, v[136:137]
	s_add_i32 m0, s15, 0x2000
	s_nop 0
	global_load_lds_dwordx4 v[154:155], off
	v_lshl_add_u64 v[154:155], v[164:165], 0, s[8:9]
	s_mov_b32 m0, s55
	s_nop 0
	global_load_lds_dwordx4 v[154:155], off
	v_lshl_add_u64 v[154:155], v[168:169], 0, s[8:9]
	s_mov_b32 m0, s56
	s_nop 0
	global_load_lds_dwordx4 v[154:155], off
	s_waitcnt vmcnt(8)
	s_waitcnt lgkmcnt(0)
	s_barrier
	s_setprio 1
	s_waitcnt lgkmcnt(0)
	v_mfma_f32_16x16x32_bf16 v[62:65], v[150:153], v[204:207], v[62:65]
	v_mfma_f32_16x16x32_bf16 v[58:61], v[176:179], v[204:207], v[58:61]
	v_mfma_f32_16x16x32_bf16 v[42:45], v[176:179], v[212:215], v[42:45]
	v_mfma_f32_16x16x32_bf16 v[46:49], v[150:153], v[212:215], v[46:49]
	v_mfma_f32_16x16x32_bf16 v[30:33], v[150:153], v[220:223], v[30:33]
	v_mfma_f32_16x16x32_bf16 v[26:29], v[176:179], v[220:223], v[26:29]
	v_mfma_f32_16x16x32_bf16 v[10:13], v[176:179], v[228:231], v[10:13]
	v_mfma_f32_16x16x32_bf16 v[14:17], v[150:153], v[228:231], v[14:17]
	v_mfma_f32_16x16x32_bf16 v[62:65], v[172:175], v[208:211], v[62:65]
	v_mfma_f32_16x16x32_bf16 v[58:61], v[180:183], v[208:211], v[58:61]
	v_mfma_f32_16x16x32_bf16 v[42:45], v[180:183], v[216:219], v[42:45]
	v_mfma_f32_16x16x32_bf16 v[46:49], v[172:175], v[216:219], v[46:49]
	v_mfma_f32_16x16x32_bf16 v[30:33], v[172:175], v[224:227], v[30:33]
	v_mfma_f32_16x16x32_bf16 v[26:29], v[180:183], v[224:227], v[26:29]
	v_mfma_f32_16x16x32_bf16 v[10:13], v[180:183], v[232:235], v[10:13]
	v_mfma_f32_16x16x32_bf16 v[14:17], v[172:175], v[232:235], v[14:17]
	s_setprio 0
	s_setprio 1
	v_mfma_f32_16x16x32_bf16 v[54:57], v[184:187], v[204:207], v[54:57]
	v_mfma_f32_16x16x32_bf16 v[50:53], v[196:199], v[204:207], v[50:53]
	v_mfma_f32_16x16x32_bf16 v[34:37], v[196:199], v[212:215], v[34:37]
	v_mfma_f32_16x16x32_bf16 v[38:41], v[184:187], v[212:215], v[38:41]
	v_mfma_f32_16x16x32_bf16 v[22:25], v[184:187], v[220:223], v[22:25]
	v_mfma_f32_16x16x32_bf16 v[18:21], v[196:199], v[220:223], v[18:21]
	v_mfma_f32_16x16x32_bf16 v[2:5], v[196:199], v[228:231], v[2:5]
	v_mfma_f32_16x16x32_bf16 v[6:9], v[184:187], v[228:231], v[6:9]
	v_mfma_f32_16x16x32_bf16 v[54:57], v[192:195], v[208:211], v[54:57]
	v_mfma_f32_16x16x32_bf16 v[50:53], v[200:203], v[208:211], v[50:53]
	v_mfma_f32_16x16x32_bf16 v[34:37], v[200:203], v[216:219], v[34:37]
	v_mfma_f32_16x16x32_bf16 v[38:41], v[192:195], v[216:219], v[38:41]
	v_mfma_f32_16x16x32_bf16 v[22:25], v[192:195], v[224:227], v[22:25]
	v_mfma_f32_16x16x32_bf16 v[18:21], v[200:203], v[224:227], v[18:21]
	v_mfma_f32_16x16x32_bf16 v[2:5], v[200:203], v[232:235], v[2:5]
	v_mfma_f32_16x16x32_bf16 v[6:9], v[192:195], v[232:235], v[6:9]
	s_setprio 0
	s_barrier
	s_add_i32 s66, s66, 2
	s_add_u32 s64, s64, 0x100
	s_addc_u32 s65, s65, 0
	s_add_u32 s38, s38, 0x100
	s_addc_u32 s39, s39, 0
	s_cmp_gt_u32 s66, 13
	s_cbranch_scc0 .LBB0_339
	s_and_b64 vcc, exec, s[10:11]
	s_cbranch_vccz .LBB0_342
	s_barrier

; #define PG8_STAGE(bufoff, gbase, voff) do { _Pragma("unroll") for (int _i = 0; _i < 2; ++_i) \
;         __builtin_amdgcn_global_load_lds((const unsigned*)((const char*)(gbase) + (voff)[_i]), (PG8_LAS unsigned*)(lds + (bufoff) + ldsw + _i * 8192), 16, 0, 0); } while (0)
; #define PG8_LDA(dst, b, h) do { _Pragma("unroll") for (int m = 0; m < 4; ++m) _Pragma("unroll") for (int k = 0; k < 2; ++k) dst[m][k] = *(const PG8_LAS bf16x8*)(lds + PG8_SA(b, h) + aoff + m * 2048 + k * 1024); } while (0)
; #define PG8_LDB(dst, b, h) do { _Pragma("unroll") for (int n = 0; n < 2; ++n) _Pragma("unroll") for (int k = 0; k < 2; ++k) dst[n][k] = *(const PG8_LAS bf16x8*)(lds + PG8_SB(b, h) + boff + n * 2048 + k * 1024); } while (0)
; #define PG8_MMA(ai, bj, At, Bt) do { __builtin_amdgcn_s_setprio(1); _Pragma("unroll") for (int m = 0; m < 4; ++m) _Pragma("unroll") for (int n = 0; n < 2; ++n) _Pragma("unroll") for (int k = 0; k < 2; ++k) \
;         acc[ai][bj][m][n] = __builtin_amdgcn_mfma_f32_16x16x32_bf16(Bt[n][k], At[m][k], acc[ai][bj][m][n], 0, 0, 0); __builtin_amdgcn_s_setprio(0); } while (0)
; #define PG8_WAIT_V(n) asm volatile("s_waitcnt vmcnt(" #n ")" ::: "memory")
; #define PG8_WAIT_L(n) asm volatile("s_waitcnt lgkmcnt(" #n ")" ::: "memory")
; #define PG8_BAR __builtin_amdgcn_s_barrier()
; template <class Epi, class Sched, bool ALIGN_EPI = false, bool SP2 = false>
; __device__ __forceinline__ void gemm_phase(PG8_LAS unsigned char* lds, const Gemm g, const Sched& S, const Epi& E, const int tid) {
;     ...
;         for (int t = 0; t < nt; t += 2) {
;             const bool last = (t == nt - 2);
;             const char* a1 = cA + (size_t)(t + 1) * kstep;
;             const char* a2 = last ? nA : cA + (size_t)(t + 2) * kstep; const char* b2 = last ? nB : cB + (size_t)(t + 2) * kstep;
;             const char* a3 = a2 + kstep; const char* b3 = b2 + kstep;
;             if (last && has_next) S.a_ready(nxt);
;             if constexpr (SP2) {
;             PG8_LDB(B0, 0, 0); PG8_LDB(B1, 0, 1); PG8_SCHED; PG8_LDA(At, 0, 0); PG8_STAGE(PG8_SA(1, 1), a1 + hstep, voffA);
;             PG8_WAIT_V(8); PG8_WAIT_L(0); PG8_BAR; PG8_MMA(0, 0, At, B0); PG8_MMA(0, 1, At, B1); PG8_BAR; PG8_SCHED;
;             PG8_LDA(At, 0, 1); PG8_STAGE(PG8_SB(0, 0), b2, voffB); PG8_STAGE(PG8_SB(0, 1), b2 + hstep, voffB); PG8_STAGE(PG8_SA(0, 0), a2, voffA);
.LBB0_422:
	s_add_u32 s45, s8, 0x100
	s_addc_u32 s47, s9, 0
	s_mov_b32 s77, -2
	ds_read_b128 v[130:133], v205
	ds_read_b128 v[134:137], v205 offset:1024
	ds_read_b128 v[138:141], v205 offset:2048
	ds_read_b128 v[142:145], v205 offset:3072
	ds_read_b128 v[146:149], v206
	ds_read_b128 v[150:153], v206 offset:1024
	ds_read_b128 v[154:157], v206 offset:2048
	ds_read_b128 v[158:161], v206 offset:3072
	s_add_u32 s8, s6, 0x100
	s_addc_u32 s9, s7, 0
	s_cmp_eq_u32 s77, 40
	s_cselect_b32 s43, s1, s9
	s_cselect_b32 s42, s0, s8
	s_cselect_b32 s11, s41, s47
	s_cselect_b32 s10, s40, s45
	v_lshl_add_u64 v[220:221], s[6:7], 0, v[176:177]
	s_add_i32 m0, s56, 0xc000
	ds_read_b128 v[182:185], v207
	ds_read_b128 v[186:189], v207 offset:1024
	ds_read_b128 v[192:195], v207 offset:2048
	ds_read_b128 v[196:199], v207 offset:3072
	ds_read_b128 v[200:203], v207 offset:4096
	ds_read_b128 v[208:211], v207 offset:5120
	ds_read_b128 v[212:215], v207 offset:6144
	ds_read_b128 v[216:219], v207 offset:7168
	global_load_lds_dwordx4 v[220:221], off
	v_lshl_add_u64 v[220:221], s[6:7], 0, v[174:175]
	s_add_i32 m0, s56, 0xe000
	s_nop 0
	global_load_lds_dwordx4 v[220:221], off
	s_waitcnt vmcnt(8)
	s_waitcnt lgkmcnt(0)
	s_barrier
	s_setprio 1
	s_waitcnt lgkmcnt(0)
	v_mfma_f32_16x16x32_bf16 v[126:129], v[130:133], v[182:185], 0
	v_mfma_f32_16x16x32_bf16 v[122:125], v[138:141], v[182:185], 0
	v_mfma_f32_16x16x32_bf16 v[106:109], v[138:141], v[192:195], 0
	v_mfma_f32_16x16x32_bf16 v[110:113], v[130:133], v[192:195], 0
	v_mfma_f32_16x16x32_bf16 v[94:97], v[130:133], v[200:203], 0
	v_mfma_f32_16x16x32_bf16 v[90:93], v[138:141], v[200:203], 0
	v_mfma_f32_16x16x32_bf16 v[74:77], v[138:141], v[212:215], 0
	v_mfma_f32_16x16x32_bf16 v[78:81], v[130:133], v[212:215], 0
	v_mfma_f32_16x16x32_bf16 v[126:129], v[134:137], v[186:189], v[126:129]
	v_mfma_f32_16x16x32_bf16 v[122:125], v[142:145], v[186:189], v[122:125]
	v_mfma_f32_16x16x32_bf16 v[106:109], v[142:145], v[196:199], v[106:109]
	v_mfma_f32_16x16x32_bf16 v[110:113], v[134:137], v[196:199], v[110:113]
	v_mfma_f32_16x16x32_bf16 v[94:97], v[134:137], v[208:211], v[94:97]
	v_mfma_f32_16x16x32_bf16 v[90:93], v[142:145], v[208:211], v[90:93]
	v_mfma_f32_16x16x32_bf16 v[74:77], v[142:145], v[216:219], v[74:77]
	v_mfma_f32_16x16x32_bf16 v[78:81], v[134:137], v[216:219], v[78:81]
	s_setprio 0
	s_setprio 1
	v_mfma_f32_16x16x32_bf16 v[118:121], v[146:149], v[182:185], 0
	v_mfma_f32_16x16x32_bf16 v[114:117], v[154:157], v[182:185], 0
	v_mfma_f32_16x16x32_bf16 v[98:101], v[154:157], v[192:195], 0
	v_mfma_f32_16x16x32_bf16 v[102:105], v[146:149], v[192:195], 0
	v_mfma_f32_16x16x32_bf16 v[86:89], v[146:149], v[200:203], 0
	v_mfma_f32_16x16x32_bf16 v[82:85], v[154:157], v[200:203], 0
	v_mfma_f32_16x16x32_bf16 v[66:69], v[154:157], v[212:215], 0
	v_mfma_f32_16x16x32_bf16 v[70:73], v[146:149], v[212:215], 0
	v_mfma_f32_16x16x32_bf16 v[118:121], v[150:153], v[186:189], v[118:121]
	v_mfma_f32_16x16x32_bf16 v[114:117], v[158:161], v[186:189], v[114:117]
	v_mfma_f32_16x16x32_bf16 v[98:101], v[158:161], v[196:199], v[98:101]
	v_mfma_f32_16x16x32_bf16 v[102:105], v[150:153], v[196:199], v[102:105]
	v_mfma_f32_16x16x32_bf16 v[86:89], v[150:153], v[208:211], v[86:89]
	v_mfma_f32_16x16x32_bf16 v[82:85], v[158:161], v[208:211], v[82:85]
	v_mfma_f32_16x16x32_bf16 v[66:69], v[158:161], v[216:219], v[66:69]
	v_mfma_f32_16x16x32_bf16 v[70:73], v[150:153], v[216:219], v[70:73]
	s_setprio 0
	s_barrier
	s_add_i32 s6, s66, s55
	v_lshl_add_u64 v[220:221], s[10:11], 0, v[164:165]
	s_mov_b32 m0, s6
	ds_read_b128 v[182:185], v207 offset:16384
	ds_read_b128 v[186:189], v207 offset:17408
	ds_read_b128 v[192:195], v207 offset:18432
	ds_read_b128 v[196:199], v207 offset:19456
	ds_read_b128 v[200:203], v207 offset:20480
	ds_read_b128 v[208:211], v207 offset:21504
	ds_read_b128 v[212:215], v207 offset:22528
	ds_read_b128 v[216:219], v207 offset:23552
	global_load_lds_dwordx4 v[220:221], off
	s_add_i32 m0, s6, 0x2000
	s_add_u32 s6, s10, 0xb0000
	v_lshl_add_u64 v[222:223], s[10:11], 0, v[168:169]
	s_addc_u32 s7, s11, 0
	s_add_i32 s15, s67, s55
	global_load_lds_dwordx4 v[222:223], off
	v_lshl_add_u64 v[224:225], s[6:7], 0, v[164:165]
	s_mov_b32 m0, s15
	v_lshl_add_u64 v[226:227], s[42:43], 0, v[166:167]
	global_load_lds_dwordx4 v[224:225], off
	v_lshl_add_u64 v[224:225], s[6:7], 0, v[168:169]
	s_add_i32 m0, s15, 0x2000
	s_nop 0
	global_load_lds_dwordx4 v[224:225], off
	v_lshl_add_u64 v[224:225], s[42:43], 0, v[162:163]
	s_mov_b32 m0, s56
	s_nop 0
	global_load_lds_dwordx4 v[224:225], off
	s_mov_b32 m0, s57
	s_nop 0
	global_load_lds_dwordx4 v[226:227], off
	s_waitcnt vmcnt(8)
	s_waitcnt lgkmcnt(0)
	s_barrier
; #define PG8_STAGE(bufoff, gbase, voff) do { _Pragma("unroll") for (int _i = 0; _i < 2; ++_i) \
;         __builtin_amdgcn_global_load_lds((const unsigned*)((const char*)(gbase) + (voff)[_i]), (PG8_LAS unsigned*)(lds + (bufoff) + ldsw + _i * 8192), 16, 0, 0); } while (0)
; #define PG8_LDA(dst, b, h) do { _Pragma("unroll") for (int m = 0; m < 4; ++m) _Pragma("unroll") for (int k = 0; k < 2; ++k) dst[m][k] = *(const PG8_LAS bf16x8*)(lds + PG8_SA(b, h) + aoff + m * 2048 + k * 1024); } while (0)
; #define PG8_LDB(dst, b, h) do { _Pragma("unroll") for (int n = 0; n < 2; ++n) _Pragma("unroll") for (int k = 0; k < 2; ++k) dst[n][k] = *(const PG8_LAS bf16x8*)(lds + PG8_SB(b, h) + boff + n * 2048 + k * 1024); } while (0)
; #define PG8_MMA(ai, bj, At, Bt) do { __builtin_amdgcn_s_setprio(1); _Pragma("unroll") for (int m = 0; m < 4; ++m) _Pragma("unroll") for (int n = 0; n < 2; ++n) _Pragma("unroll") for (int k = 0; k < 2; ++k) \
;         acc[ai][bj][m][n] = __builtin_amdgcn_mfma_f32_16x16x32_bf16(Bt[n][k], At[m][k], acc[ai][bj][m][n], 0, 0, 0); __builtin_amdgcn_s_setprio(0); } while (0)
; #define PG8_WAIT_V(n) asm volatile("s_waitcnt vmcnt(" #n ")" ::: "memory")
; #define PG8_WAIT_L(n) asm volatile("s_waitcnt lgkmcnt(" #n ")" ::: "memory")
; #define PG8_BAR __builtin_amdgcn_s_barrier()
; #define PG8_SCHED __builtin_amdgcn_sched_barrier(0)
; template <class Epi, class Sched, bool ALIGN_EPI = false, bool SP2 = false>
; __device__ __forceinline__ void gemm_phase(PG8_LAS unsigned char* lds, const Gemm g, const Sched& S, const Epi& E, const int tid) {
;     ...
;             PG8_WAIT_V(8); PG8_WAIT_L(0); PG8_BAR; PG8_MMA(1, 0, At, B0); PG8_MMA(1, 1, At, B1); PG8_BAR; PG8_SCHED;
;             PG8_LDB(B0, 1, 0); PG8_LDB(B1, 1, 1); PG8_SCHED; PG8_LDA(At, 1, 0); PG8_STAGE(PG8_SA(0, 1), a2 + hstep, voffA);
;             PG8_WAIT_V(8); PG8_WAIT_L(0); PG8_BAR; PG8_MMA(0, 0, At, B0); PG8_MMA(0, 1, At, B1); PG8_BAR; PG8_SCHED;
	s_setprio 1
	s_waitcnt lgkmcnt(0)
	v_mfma_f32_16x16x32_bf16 v[62:65], v[130:133], v[182:185], 0
	v_mfma_f32_16x16x32_bf16 v[58:61], v[138:141], v[182:185], 0
	v_mfma_f32_16x16x32_bf16 v[42:45], v[138:141], v[192:195], 0
	v_mfma_f32_16x16x32_bf16 v[46:49], v[130:133], v[192:195], 0
	v_mfma_f32_16x16x32_bf16 v[30:33], v[130:133], v[200:203], 0
	v_mfma_f32_16x16x32_bf16 v[26:29], v[138:141], v[200:203], 0
	v_mfma_f32_16x16x32_bf16 v[10:13], v[138:141], v[212:215], 0
	v_mfma_f32_16x16x32_bf16 v[14:17], v[130:133], v[212:215], 0
	v_mfma_f32_16x16x32_bf16 v[62:65], v[134:137], v[186:189], v[62:65]
	v_mfma_f32_16x16x32_bf16 v[58:61], v[142:145], v[186:189], v[58:61]
	v_mfma_f32_16x16x32_bf16 v[42:45], v[142:145], v[196:199], v[42:45]
	v_mfma_f32_16x16x32_bf16 v[46:49], v[134:137], v[196:199], v[46:49]
	v_mfma_f32_16x16x32_bf16 v[30:33], v[134:137], v[208:211], v[30:33]
	v_mfma_f32_16x16x32_bf16 v[26:29], v[142:145], v[208:211], v[26:29]
	v_mfma_f32_16x16x32_bf16 v[10:13], v[142:145], v[216:219], v[10:13]
	v_mfma_f32_16x16x32_bf16 v[14:17], v[134:137], v[216:219], v[14:17]
	s_setprio 0
	s_setprio 1
	v_mfma_f32_16x16x32_bf16 v[54:57], v[146:149], v[182:185], 0
	v_mfma_f32_16x16x32_bf16 v[50:53], v[154:157], v[182:185], 0
	v_mfma_f32_16x16x32_bf16 v[34:37], v[154:157], v[192:195], 0
	v_mfma_f32_16x16x32_bf16 v[38:41], v[146:149], v[192:195], 0
	v_mfma_f32_16x16x32_bf16 v[22:25], v[146:149], v[200:203], 0
	v_mfma_f32_16x16x32_bf16 v[18:21], v[154:157], v[200:203], 0
	v_mfma_f32_16x16x32_bf16 v[2:5], v[154:157], v[212:215], 0
	v_mfma_f32_16x16x32_bf16 v[6:9], v[146:149], v[212:215], 0
	v_mfma_f32_16x16x32_bf16 v[54:57], v[150:153], v[186:189], v[54:57]
	v_mfma_f32_16x16x32_bf16 v[50:53], v[158:161], v[186:189], v[50:53]
	v_mfma_f32_16x16x32_bf16 v[34:37], v[158:161], v[196:199], v[34:37]
	v_mfma_f32_16x16x32_bf16 v[38:41], v[150:153], v[196:199], v[38:41]
	v_mfma_f32_16x16x32_bf16 v[22:25], v[150:153], v[208:211], v[22:25]
	v_mfma_f32_16x16x32_bf16 v[18:21], v[158:161], v[208:211], v[18:21]
	v_mfma_f32_16x16x32_bf16 v[2:5], v[158:161], v[216:219], v[2:5]
	v_mfma_f32_16x16x32_bf16 v[6:9], v[150:153], v[216:219], v[6:9]
	s_setprio 0
	s_barrier
	s_add_i32 s15, 0, 0x18000
	s_add_i32 s18, 0, 0x1c000
	v_add_u32_e32 v142, s15, v204
	v_add_u32_e32 v158, s18, v204
	ds_read_b128 v[130:133], v142
	ds_read_b128 v[134:137], v142 offset:1024
	ds_read_b128 v[138:141], v142 offset:2048
	ds_read_b128 v[142:145], v142 offset:3072
	ds_read_b128 v[146:149], v158
	ds_read_b128 v[150:153], v158 offset:1024
	ds_read_b128 v[154:157], v158 offset:2048
	ds_read_b128 v[158:161], v158 offset:3072
	s_add_u32 s6, s42, 0xb0000
	s_addc_u32 s7, s43, 0
	s_mov_b32 m0, s58
	v_lshl_add_u64 v[228:229], s[6:7], 0, v[162:163]
	ds_read_b128 v[182:185], v207 offset:32768
	ds_read_b128 v[186:189], v207 offset:33792
	ds_read_b128 v[192:195], v207 offset:34816
	ds_read_b128 v[196:199], v207 offset:35840
	ds_read_b128 v[200:203], v207 offset:36864
	ds_read_b128 v[208:211], v207 offset:37888
	ds_read_b128 v[212:215], v207 offset:38912
	ds_read_b128 v[216:219], v207 offset:39936
	global_load_lds_dwordx4 v[228:229], off
	v_lshl_add_u64 v[228:229], s[6:7], 0, v[166:167]
	s_mov_b32 m0, s59
	s_nop 0
	global_load_lds_dwordx4 v[228:229], off
	s_waitcnt vmcnt(8)
	s_waitcnt lgkmcnt(0)
	s_barrier
	s_setprio 1
	s_waitcnt lgkmcnt(0)
	v_mfma_f32_16x16x32_bf16 v[126:129], v[130:133], v[182:185], v[126:129]
	v_mfma_f32_16x16x32_bf16 v[122:125], v[138:141], v[182:185], v[122:125]
	v_mfma_f32_16x16x32_bf16 v[106:109], v[138:141], v[192:195], v[106:109]
	v_mfma_f32_16x16x32_bf16 v[110:113], v[130:133], v[192:195], v[110:113]
	v_mfma_f32_16x16x32_bf16 v[94:97], v[130:133], v[200:203], v[94:97]
	v_mfma_f32_16x16x32_bf16 v[90:93], v[138:141], v[200:203], v[90:93]
	v_mfma_f32_16x16x32_bf16 v[74:77], v[138:141], v[212:215], v[74:77]
	v_mfma_f32_16x16x32_bf16 v[78:81], v[130:133], v[212:215], v[78:81]
	v_mfma_f32_16x16x32_bf16 v[126:129], v[134:137], v[186:189], v[126:129]
	v_mfma_f32_16x16x32_bf16 v[122:125], v[142:145], v[186:189], v[122:125]
	v_mfma_f32_16x16x32_bf16 v[106:109], v[142:145], v[196:199], v[106:109]
	v_mfma_f32_16x16x32_bf16 v[110:113], v[134:137], v[196:199], v[110:113]
	v_mfma_f32_16x16x32_bf16 v[94:97], v[134:137], v[208:211], v[94:97]
	v_mfma_f32_16x16x32_bf16 v[90:93], v[142:145], v[208:211], v[90:93]
	v_mfma_f32_16x16x32_bf16 v[74:77], v[142:145], v[216:219], v[74:77]
	v_mfma_f32_16x16x32_bf16 v[78:81], v[134:137], v[216:219], v[78:81]
	s_setprio 0
	s_setprio 1
	v_mfma_f32_16x16x32_bf16 v[118:121], v[146:149], v[182:185], v[118:121]
	v_mfma_f32_16x16x32_bf16 v[114:117], v[154:157], v[182:185], v[114:117]
	v_mfma_f32_16x16x32_bf16 v[98:101], v[154:157], v[192:195], v[98:101]
	v_mfma_f32_16x16x32_bf16 v[102:105], v[146:149], v[192:195], v[102:105]
	v_mfma_f32_16x16x32_bf16 v[86:89], v[146:149], v[200:203], v[86:89]
	v_mfma_f32_16x16x32_bf16 v[82:85], v[154:157], v[200:203], v[82:85]
	v_mfma_f32_16x16x32_bf16 v[66:69], v[154:157], v[212:215], v[66:69]
	v_mfma_f32_16x16x32_bf16 v[70:73], v[146:149], v[212:215], v[70:73]
	v_mfma_f32_16x16x32_bf16 v[118:121], v[150:153], v[186:189], v[118:121]
	v_mfma_f32_16x16x32_bf16 v[114:117], v[158:161], v[186:189], v[114:117]
	v_mfma_f32_16x16x32_bf16 v[98:101], v[158:161], v[196:199], v[98:101]
	v_mfma_f32_16x16x32_bf16 v[102:105], v[150:153], v[196:199], v[102:105]
	v_mfma_f32_16x16x32_bf16 v[86:89], v[150:153], v[208:211], v[86:89]
	v_mfma_f32_16x16x32_bf16 v[82:85], v[158:161], v[208:211], v[82:85]
	v_mfma_f32_16x16x32_bf16 v[66:69], v[158:161], v[216:219], v[66:69]
	v_mfma_f32_16x16x32_bf16 v[70:73], v[150:153], v[216:219], v[70:73]
	s_setprio 0
	s_barrier
; #define PG8_STAGE(bufoff, gbase, voff) do { _Pragma("unroll") for (int _i = 0; _i < 2; ++_i) \
;         __builtin_amdgcn_global_load_lds((const unsigned*)((const char*)(gbase) + (voff)[_i]), (PG8_LAS unsigned*)(lds + (bufoff) + ldsw + _i * 8192), 16, 0, 0); } while (0)
; #define PG8_LDA(dst, b, h) do { _Pragma("unroll") for (int m = 0; m < 4; ++m) _Pragma("unroll") for (int k = 0; k < 2; ++k) dst[m][k] = *(const PG8_LAS bf16x8*)(lds + PG8_SA(b, h) + aoff + m * 2048 + k * 1024); } while (0)
; #define PG8_LDB(dst, b, h) do { _Pragma("unroll") for (int n = 0; n < 2; ++n) _Pragma("unroll") for (int k = 0; k < 2; ++k) dst[n][k] = *(const PG8_LAS bf16x8*)(lds + PG8_SB(b, h) + boff + n * 2048 + k * 1024); } while (0)
; #define PG8_MMA(ai, bj, At, Bt) do { __builtin_amdgcn_s_setprio(1); _Pragma("unroll") for (int m = 0; m < 4; ++m) _Pragma("unroll") for (int n = 0; n < 2; ++n) _Pragma("unroll") for (int k = 0; k < 2; ++k) \
;         acc[ai][bj][m][n] = __builtin_amdgcn_mfma_f32_16x16x32_bf16(Bt[n][k], At[m][k], acc[ai][bj][m][n], 0, 0, 0); __builtin_amdgcn_s_setprio(0); } while (0)
; #define PG8_WAIT_V(n) asm volatile("s_waitcnt vmcnt(" #n ")" ::: "memory")
; #define PG8_WAIT_L(n) asm volatile("s_waitcnt lgkmcnt(" #n ")" ::: "memory")
; #define PG8_BAR __builtin_amdgcn_s_barrier()
; #define PG8_SCHED __builtin_amdgcn_sched_barrier(0)
; template <class Epi, class Sched, bool ALIGN_EPI = false, bool SP2 = false>
; __device__ __forceinline__ void gemm_phase(PG8_LAS unsigned char* lds, const Gemm g, const Sched& S, const Epi& E, const int tid) {
;     ...
;             PG8_LDB(B0, 0, 0); PG8_LDB(B1, 0, 1); PG8_SCHED; PG8_LDA(At, 0, 0); PG8_STAGE(PG8_SA(1, 1), a1 + hstep, voffA);
;     ...
;             PG8_LDA(At, 1, 1); PG8_STAGE(PG8_SB(1, 0), b3, voffB); PG8_STAGE(PG8_SB(1, 1), b3 + hstep, voffB); PG8_STAGE(PG8_SA(1, 0), a3, voffA);
;             PG8_WAIT_V(8); PG8_WAIT_L(0); PG8_BAR; PG8_MMA(1, 0, At, B0); PG8_MMA(1, 1, At, B1); PG8_BAR; PG8_SCHED;
	s_add_i32 s6, s15, s55
	v_lshl_add_u64 v[220:221], v[220:221], 0, s[36:37]
	s_mov_b32 m0, s6
	ds_read_b128 v[182:185], v207 offset:49152
	ds_read_b128 v[186:189], v207 offset:50176
	ds_read_b128 v[192:195], v207 offset:51200
	ds_read_b128 v[196:199], v207 offset:52224
	ds_read_b128 v[200:203], v207 offset:53248
	ds_read_b128 v[208:211], v207 offset:54272
	ds_read_b128 v[212:215], v207 offset:55296
	ds_read_b128 v[216:219], v207 offset:56320
	global_load_lds_dwordx4 v[220:221], off
	s_add_i32 m0, s6, 0x2000
	s_add_u32 s6, s10, 0xb0080
	v_lshl_add_u64 v[220:221], v[222:223], 0, s[36:37]
	s_addc_u32 s7, s11, 0
	s_add_i32 s10, s18, s55
	global_load_lds_dwordx4 v[220:221], off
	v_lshl_add_u64 v[220:221], s[6:7], 0, v[164:165]
	s_mov_b32 m0, s10
	s_nop 0
	global_load_lds_dwordx4 v[220:221], off
	v_lshl_add_u64 v[220:221], s[6:7], 0, v[168:169]
	s_add_i32 m0, s10, 0x2000
	s_nop 0
	global_load_lds_dwordx4 v[220:221], off
	v_lshl_add_u64 v[220:221], v[224:225], 0, s[36:37]
	s_mov_b32 m0, s61
	s_nop 0
	global_load_lds_dwordx4 v[220:221], off
	v_lshl_add_u64 v[220:221], v[226:227], 0, s[36:37]
	s_mov_b32 m0, s62
	s_nop 0
	global_load_lds_dwordx4 v[220:221], off
	s_waitcnt vmcnt(8)
	s_waitcnt lgkmcnt(0)
	s_barrier
	s_setprio 1
	s_waitcnt lgkmcnt(0)
	v_mfma_f32_16x16x32_bf16 v[62:65], v[130:133], v[182:185], v[62:65]
	v_mfma_f32_16x16x32_bf16 v[58:61], v[138:141], v[182:185], v[58:61]
	v_mfma_f32_16x16x32_bf16 v[42:45], v[138:141], v[192:195], v[42:45]
	v_mfma_f32_16x16x32_bf16 v[46:49], v[130:133], v[192:195], v[46:49]
	v_mfma_f32_16x16x32_bf16 v[30:33], v[130:133], v[200:203], v[30:33]
	v_mfma_f32_16x16x32_bf16 v[26:29], v[138:141], v[200:203], v[26:29]
	v_mfma_f32_16x16x32_bf16 v[10:13], v[138:141], v[212:215], v[10:13]
	v_mfma_f32_16x16x32_bf16 v[14:17], v[130:133], v[212:215], v[14:17]
	v_mfma_f32_16x16x32_bf16 v[62:65], v[134:137], v[186:189], v[62:65]
	v_mfma_f32_16x16x32_bf16 v[58:61], v[142:145], v[186:189], v[58:61]
	v_mfma_f32_16x16x32_bf16 v[42:45], v[142:145], v[196:199], v[42:45]
	v_mfma_f32_16x16x32_bf16 v[46:49], v[134:137], v[196:199], v[46:49]
	v_mfma_f32_16x16x32_bf16 v[30:33], v[134:137], v[208:211], v[30:33]
	v_mfma_f32_16x16x32_bf16 v[26:29], v[142:145], v[208:211], v[26:29]
	v_mfma_f32_16x16x32_bf16 v[10:13], v[142:145], v[216:219], v[10:13]
	v_mfma_f32_16x16x32_bf16 v[14:17], v[134:137], v[216:219], v[14:17]
	s_setprio 0
	s_setprio 1
	v_mfma_f32_16x16x32_bf16 v[54:57], v[146:149], v[182:185], v[54:57]
	v_mfma_f32_16x16x32_bf16 v[50:53], v[154:157], v[182:185], v[50:53]
	v_mfma_f32_16x16x32_bf16 v[34:37], v[154:157], v[192:195], v[34:37]
	v_mfma_f32_16x16x32_bf16 v[38:41], v[146:149], v[192:195], v[38:41]
	v_mfma_f32_16x16x32_bf16 v[22:25], v[146:149], v[200:203], v[22:25]
	v_mfma_f32_16x16x32_bf16 v[18:21], v[154:157], v[200:203], v[18:21]
	v_mfma_f32_16x16x32_bf16 v[2:5], v[154:157], v[212:215], v[2:5]
	v_mfma_f32_16x16x32_bf16 v[6:9], v[146:149], v[212:215], v[6:9]
	v_mfma_f32_16x16x32_bf16 v[54:57], v[150:153], v[186:189], v[54:57]
	v_mfma_f32_16x16x32_bf16 v[50:53], v[158:161], v[186:189], v[50:53]
	v_mfma_f32_16x16x32_bf16 v[34:37], v[158:161], v[196:199], v[34:37]
	v_mfma_f32_16x16x32_bf16 v[38:41], v[150:153], v[196:199], v[38:41]
	v_mfma_f32_16x16x32_bf16 v[22:25], v[150:153], v[208:211], v[22:25]
	v_mfma_f32_16x16x32_bf16 v[18:21], v[158:161], v[208:211], v[18:21]
	v_mfma_f32_16x16x32_bf16 v[2:5], v[158:161], v[216:219], v[2:5]
	v_mfma_f32_16x16x32_bf16 v[6:9], v[150:153], v[216:219], v[6:9]
	s_setprio 0
	s_barrier
	s_add_i32 s77, s77, 2
	s_add_u32 s45, s45, 0x100
	s_addc_u32 s47, s47, 0
	s_mov_b64 s[6:7], s[8:9]
.LBB0_423:
	ds_read_b128 v[130:133], v205
	ds_read_b128 v[134:137], v205 offset:1024
	ds_read_b128 v[138:141], v205 offset:2048
	ds_read_b128 v[142:145], v205 offset:3072
	ds_read_b128 v[146:149], v206
	ds_read_b128 v[150:153], v206 offset:1024
	ds_read_b128 v[154:157], v206 offset:2048
	ds_read_b128 v[158:161], v206 offset:3072
	s_add_u32 s8, s6, 0x100
	s_addc_u32 s9, s7, 0
	s_cmp_eq_u32 s77, 40
	s_cselect_b32 s43, s1, s9
	s_cselect_b32 s42, s0, s8
	s_cselect_b32 s11, s41, s47
	s_cselect_b32 s10, s40, s45
	v_lshl_add_u64 v[220:221], s[6:7], 0, v[176:177]
	s_add_i32 m0, s56, 0xc000
	ds_read_b128 v[182:185], v207
	ds_read_b128 v[186:189], v207 offset:1024
	ds_read_b128 v[192:195], v207 offset:2048
	ds_read_b128 v[196:199], v207 offset:3072
	ds_read_b128 v[200:203], v207 offset:4096
	ds_read_b128 v[208:211], v207 offset:5120
	ds_read_b128 v[212:215], v207 offset:6144
	ds_read_b128 v[216:219], v207 offset:7168
	global_load_lds_dwordx4 v[220:221], off
	v_lshl_add_u64 v[220:221], s[6:7], 0, v[174:175]
	s_add_i32 m0, s56, 0xe000
	s_nop 0
	global_load_lds_dwordx4 v[220:221], off
	s_waitcnt vmcnt(8)
	s_waitcnt lgkmcnt(0)
	s_barrier
; #define PG8_STAGE(bufoff, gbase, voff) do { _Pragma("unroll") for (int _i = 0; _i < 2; ++_i) \
;         __builtin_amdgcn_global_load_lds((const unsigned*)((const char*)(gbase) + (voff)[_i]), (PG8_LAS unsigned*)(lds + (bufoff) + ldsw + _i * 8192), 16, 0, 0); } while (0)
; #define PG8_LDA(dst, b, h) do { _Pragma("unroll") for (int m = 0; m < 4; ++m) _Pragma("unroll") for (int k = 0; k < 2; ++k) dst[m][k] = *(const PG8_LAS bf16x8*)(lds + PG8_SA(b, h) + aoff + m * 2048 + k * 1024); } while (0)
; #define PG8_MMA(ai, bj, At, Bt) do { __builtin_amdgcn_s_setprio(1); _Pragma("unroll") for (int m = 0; m < 4; ++m) _Pragma("unroll") for (int n = 0; n < 2; ++n) _Pragma("unroll") for (int k = 0; k < 2; ++k) \
;         acc[ai][bj][m][n] = __builtin_amdgcn_mfma_f32_16x16x32_bf16(Bt[n][k], At[m][k], acc[ai][bj][m][n], 0, 0, 0); __builtin_amdgcn_s_setprio(0); } while (0)
; #define PG8_WAIT_V(n) asm volatile("s_waitcnt vmcnt(" #n ")" ::: "memory")
; #define PG8_WAIT_L(n) asm volatile("s_waitcnt lgkmcnt(" #n ")" ::: "memory")
; #define PG8_BAR __builtin_amdgcn_s_barrier()
; #define PG8_SCHED __builtin_amdgcn_sched_barrier(0)
; template <class Epi, class Sched, bool ALIGN_EPI = false, bool SP2 = false>
; __device__ __forceinline__ void gemm_phase(PG8_LAS unsigned char* lds, const Gemm g, const Sched& S, const Epi& E, const int tid) {
;     ...
;             PG8_WAIT_V(8); PG8_WAIT_L(0); PG8_BAR; PG8_MMA(0, 0, At, B0); PG8_MMA(0, 1, At, B1); PG8_BAR; PG8_SCHED;
;             PG8_LDA(At, 0, 1); PG8_STAGE(PG8_SB(0, 0), b2, voffB); PG8_STAGE(PG8_SB(0, 1), b2 + hstep, voffB); PG8_STAGE(PG8_SA(0, 0), a2, voffA);
;             PG8_WAIT_V(8); PG8_WAIT_L(0); PG8_BAR; PG8_MMA(1, 0, At, B0); PG8_MMA(1, 1, At, B1); PG8_BAR; PG8_SCHED;
	s_setprio 1
	s_waitcnt lgkmcnt(0)
	v_mfma_f32_16x16x32_bf16 v[126:129], v[130:133], v[182:185], v[126:129]
	v_mfma_f32_16x16x32_bf16 v[122:125], v[138:141], v[182:185], v[122:125]
	v_mfma_f32_16x16x32_bf16 v[106:109], v[138:141], v[192:195], v[106:109]
	v_mfma_f32_16x16x32_bf16 v[110:113], v[130:133], v[192:195], v[110:113]
	v_mfma_f32_16x16x32_bf16 v[94:97], v[130:133], v[200:203], v[94:97]
	v_mfma_f32_16x16x32_bf16 v[90:93], v[138:141], v[200:203], v[90:93]
	v_mfma_f32_16x16x32_bf16 v[74:77], v[138:141], v[212:215], v[74:77]
	v_mfma_f32_16x16x32_bf16 v[78:81], v[130:133], v[212:215], v[78:81]
	v_mfma_f32_16x16x32_bf16 v[126:129], v[134:137], v[186:189], v[126:129]
	v_mfma_f32_16x16x32_bf16 v[122:125], v[142:145], v[186:189], v[122:125]
	v_mfma_f32_16x16x32_bf16 v[106:109], v[142:145], v[196:199], v[106:109]
	v_mfma_f32_16x16x32_bf16 v[110:113], v[134:137], v[196:199], v[110:113]
	v_mfma_f32_16x16x32_bf16 v[94:97], v[134:137], v[208:211], v[94:97]
	v_mfma_f32_16x16x32_bf16 v[90:93], v[142:145], v[208:211], v[90:93]
	v_mfma_f32_16x16x32_bf16 v[74:77], v[142:145], v[216:219], v[74:77]
	v_mfma_f32_16x16x32_bf16 v[78:81], v[134:137], v[216:219], v[78:81]
	s_setprio 0
	s_setprio 1
	v_mfma_f32_16x16x32_bf16 v[118:121], v[146:149], v[182:185], v[118:121]
	v_mfma_f32_16x16x32_bf16 v[114:117], v[154:157], v[182:185], v[114:117]
	v_mfma_f32_16x16x32_bf16 v[98:101], v[154:157], v[192:195], v[98:101]
	v_mfma_f32_16x16x32_bf16 v[102:105], v[146:149], v[192:195], v[102:105]
	v_mfma_f32_16x16x32_bf16 v[86:89], v[146:149], v[200:203], v[86:89]
	v_mfma_f32_16x16x32_bf16 v[82:85], v[154:157], v[200:203], v[82:85]
	v_mfma_f32_16x16x32_bf16 v[66:69], v[154:157], v[212:215], v[66:69]
	v_mfma_f32_16x16x32_bf16 v[70:73], v[146:149], v[212:215], v[70:73]
	v_mfma_f32_16x16x32_bf16 v[118:121], v[150:153], v[186:189], v[118:121]
	v_mfma_f32_16x16x32_bf16 v[114:117], v[158:161], v[186:189], v[114:117]
	v_mfma_f32_16x16x32_bf16 v[98:101], v[158:161], v[196:199], v[98:101]
	v_mfma_f32_16x16x32_bf16 v[102:105], v[150:153], v[196:199], v[102:105]
	v_mfma_f32_16x16x32_bf16 v[86:89], v[150:153], v[208:211], v[86:89]
	v_mfma_f32_16x16x32_bf16 v[82:85], v[158:161], v[208:211], v[82:85]
	v_mfma_f32_16x16x32_bf16 v[66:69], v[158:161], v[216:219], v[66:69]
	v_mfma_f32_16x16x32_bf16 v[70:73], v[150:153], v[216:219], v[70:73]
	s_setprio 0
	s_barrier
	s_add_i32 s6, s66, s55
	v_lshl_add_u64 v[220:221], s[10:11], 0, v[164:165]
	s_mov_b32 m0, s6
	ds_read_b128 v[182:185], v207 offset:16384
	ds_read_b128 v[186:189], v207 offset:17408
	ds_read_b128 v[192:195], v207 offset:18432
	ds_read_b128 v[196:199], v207 offset:19456
	ds_read_b128 v[200:203], v207 offset:20480
	ds_read_b128 v[208:211], v207 offset:21504
	ds_read_b128 v[212:215], v207 offset:22528
	ds_read_b128 v[216:219], v207 offset:23552
	global_load_lds_dwordx4 v[220:221], off
	s_add_i32 m0, s6, 0x2000
	s_add_u32 s6, s10, 0xb0000
	v_lshl_add_u64 v[222:223], s[10:11], 0, v[168:169]
	s_addc_u32 s7, s11, 0
	s_add_i32 s15, s67, s55
	global_load_lds_dwordx4 v[222:223], off
	v_lshl_add_u64 v[224:225], s[6:7], 0, v[164:165]
	s_mov_b32 m0, s15
	v_lshl_add_u64 v[226:227], s[42:43], 0, v[166:167]
	global_load_lds_dwordx4 v[224:225], off
	v_lshl_add_u64 v[224:225], s[6:7], 0, v[168:169]
	s_add_i32 m0, s15, 0x2000
	s_nop 0
	global_load_lds_dwordx4 v[224:225], off
	v_lshl_add_u64 v[224:225], s[42:43], 0, v[162:163]
	s_mov_b32 m0, s56
	s_nop 0
	global_load_lds_dwordx4 v[224:225], off
	s_mov_b32 m0, s57
	s_nop 0
	global_load_lds_dwordx4 v[226:227], off
	s_waitcnt vmcnt(8)
	s_waitcnt lgkmcnt(0)
	s_barrier
	s_setprio 1
	s_waitcnt lgkmcnt(0)
	v_mfma_f32_16x16x32_bf16 v[62:65], v[130:133], v[182:185], v[62:65]
	v_mfma_f32_16x16x32_bf16 v[58:61], v[138:141], v[182:185], v[58:61]
	v_mfma_f32_16x16x32_bf16 v[42:45], v[138:141], v[192:195], v[42:45]
	v_mfma_f32_16x16x32_bf16 v[46:49], v[130:133], v[192:195], v[46:49]
	v_mfma_f32_16x16x32_bf16 v[30:33], v[130:133], v[200:203], v[30:33]
	v_mfma_f32_16x16x32_bf16 v[26:29], v[138:141], v[200:203], v[26:29]
	v_mfma_f32_16x16x32_bf16 v[10:13], v[138:141], v[212:215], v[10:13]
	v_mfma_f32_16x16x32_bf16 v[14:17], v[130:133], v[212:215], v[14:17]
	v_mfma_f32_16x16x32_bf16 v[62:65], v[134:137], v[186:189], v[62:65]
	v_mfma_f32_16x16x32_bf16 v[58:61], v[142:145], v[186:189], v[58:61]
	v_mfma_f32_16x16x32_bf16 v[42:45], v[142:145], v[196:199], v[42:45]
	v_mfma_f32_16x16x32_bf16 v[46:49], v[134:137], v[196:199], v[46:49]
	v_mfma_f32_16x16x32_bf16 v[30:33], v[134:137], v[208:211], v[30:33]
	v_mfma_f32_16x16x32_bf16 v[26:29], v[142:145], v[208:211], v[26:29]
	v_mfma_f32_16x16x32_bf16 v[10:13], v[142:145], v[216:219], v[10:13]
	v_mfma_f32_16x16x32_bf16 v[14:17], v[134:137], v[216:219], v[14:17]
	s_setprio 0
	s_setprio 1
	v_mfma_f32_16x16x32_bf16 v[54:57], v[146:149], v[182:185], v[54:57]
	v_mfma_f32_16x16x32_bf16 v[50:53], v[154:157], v[182:185], v[50:53]
	v_mfma_f32_16x16x32_bf16 v[34:37], v[154:157], v[192:195], v[34:37]
	v_mfma_f32_16x16x32_bf16 v[38:41], v[146:149], v[192:195], v[38:41]
	v_mfma_f32_16x16x32_bf16 v[22:25], v[146:149], v[200:203], v[22:25]
	v_mfma_f32_16x16x32_bf16 v[18:21], v[154:157], v[200:203], v[18:21]
	v_mfma_f32_16x16x32_bf16 v[2:5], v[154:157], v[212:215], v[2:5]
	v_mfma_f32_16x16x32_bf16 v[6:9], v[146:149], v[212:215], v[6:9]
	v_mfma_f32_16x16x32_bf16 v[54:57], v[150:153], v[186:189], v[54:57]
	v_mfma_f32_16x16x32_bf16 v[50:53], v[158:161], v[186:189], v[50:53]
	v_mfma_f32_16x16x32_bf16 v[34:37], v[158:161], v[196:199], v[34:37]
	v_mfma_f32_16x16x32_bf16 v[38:41], v[150:153], v[196:199], v[38:41]
	v_mfma_f32_16x16x32_bf16 v[22:25], v[150:153], v[208:211], v[22:25]
	v_mfma_f32_16x16x32_bf16 v[18:21], v[158:161], v[208:211], v[18:21]
	v_mfma_f32_16x16x32_bf16 v[2:5], v[158:161], v[216:219], v[2:5]
	v_mfma_f32_16x16x32_bf16 v[6:9], v[150:153], v[216:219], v[6:9]
	s_setprio 0
	s_barrier
; #define PG8_STAGE(bufoff, gbase, voff) do { _Pragma("unroll") for (int _i = 0; _i < 2; ++_i) \
;         __builtin_amdgcn_global_load_lds((const unsigned*)((const char*)(gbase) + (voff)[_i]), (PG8_LAS unsigned*)(lds + (bufoff) + ldsw + _i * 8192), 16, 0, 0); } while (0)
; #define PG8_LDA(dst, b, h) do { _Pragma("unroll") for (int m = 0; m < 4; ++m) _Pragma("unroll") for (int k = 0; k < 2; ++k) dst[m][k] = *(const PG8_LAS bf16x8*)(lds + PG8_SA(b, h) + aoff + m * 2048 + k * 1024); } while (0)
; #define PG8_LDB(dst, b, h) do { _Pragma("unroll") for (int n = 0; n < 2; ++n) _Pragma("unroll") for (int k = 0; k < 2; ++k) dst[n][k] = *(const PG8_LAS bf16x8*)(lds + PG8_SB(b, h) + boff + n * 2048 + k * 1024); } while (0)
; #define PG8_MMA(ai, bj, At, Bt) do { __builtin_amdgcn_s_setprio(1); _Pragma("unroll") for (int m = 0; m < 4; ++m) _Pragma("unroll") for (int n = 0; n < 2; ++n) _Pragma("unroll") for (int k = 0; k < 2; ++k) \
;         acc[ai][bj][m][n] = __builtin_amdgcn_mfma_f32_16x16x32_bf16(Bt[n][k], At[m][k], acc[ai][bj][m][n], 0, 0, 0); __builtin_amdgcn_s_setprio(0); } while (0)
; #define PG8_WAIT_V(n) asm volatile("s_waitcnt vmcnt(" #n ")" ::: "memory")
; #define PG8_WAIT_L(n) asm volatile("s_waitcnt lgkmcnt(" #n ")" ::: "memory")
; #define PG8_BAR __builtin_amdgcn_s_barrier()
; #define PG8_SCHED __builtin_amdgcn_sched_barrier(0)
; template <class Epi, class Sched, bool ALIGN_EPI = false, bool SP2 = false>
; __device__ __forceinline__ void gemm_phase(PG8_LAS unsigned char* lds, const Gemm g, const Sched& S, const Epi& E, const int tid) {
;     ...
;             PG8_LDB(B0, 1, 0); PG8_LDB(B1, 1, 1); PG8_SCHED; PG8_LDA(At, 1, 0); PG8_STAGE(PG8_SA(0, 1), a2 + hstep, voffA);
;             PG8_WAIT_V(8); PG8_WAIT_L(0); PG8_BAR; PG8_MMA(0, 0, At, B0); PG8_MMA(0, 1, At, B1); PG8_BAR; PG8_SCHED;
	s_add_i32 s15, 0, 0x18000
	s_add_i32 s18, 0, 0x1c000
	v_add_u32_e32 v142, s15, v204
	v_add_u32_e32 v158, s18, v204
	ds_read_b128 v[130:133], v142
	ds_read_b128 v[134:137], v142 offset:1024
	ds_read_b128 v[138:141], v142 offset:2048
	ds_read_b128 v[142:145], v142 offset:3072
	ds_read_b128 v[146:149], v158
	ds_read_b128 v[150:153], v158 offset:1024
	ds_read_b128 v[154:157], v158 offset:2048
	ds_read_b128 v[158:161], v158 offset:3072
	s_add_u32 s6, s42, 0xb0000
	s_addc_u32 s7, s43, 0
	s_mov_b32 m0, s58
	v_lshl_add_u64 v[228:229], s[6:7], 0, v[162:163]
	ds_read_b128 v[182:185], v207 offset:32768
	ds_read_b128 v[186:189], v207 offset:33792
	ds_read_b128 v[192:195], v207 offset:34816
	ds_read_b128 v[196:199], v207 offset:35840
	ds_read_b128 v[200:203], v207 offset:36864
	ds_read_b128 v[208:211], v207 offset:37888
	ds_read_b128 v[212:215], v207 offset:38912
	ds_read_b128 v[216:219], v207 offset:39936
	global_load_lds_dwordx4 v[228:229], off
	v_lshl_add_u64 v[228:229], s[6:7], 0, v[166:167]
	s_mov_b32 m0, s59
	s_nop 0
	global_load_lds_dwordx4 v[228:229], off
	s_waitcnt vmcnt(8)
	s_waitcnt lgkmcnt(0)
	s_barrier
	s_setprio 1
	s_waitcnt lgkmcnt(0)
	v_mfma_f32_16x16x32_bf16 v[126:129], v[130:133], v[182:185], v[126:129]
	v_mfma_f32_16x16x32_bf16 v[122:125], v[138:141], v[182:185], v[122:125]
	v_mfma_f32_16x16x32_bf16 v[106:109], v[138:141], v[192:195], v[106:109]
	v_mfma_f32_16x16x32_bf16 v[110:113], v[130:133], v[192:195], v[110:113]
	v_mfma_f32_16x16x32_bf16 v[94:97], v[130:133], v[200:203], v[94:97]
	v_mfma_f32_16x16x32_bf16 v[90:93], v[138:141], v[200:203], v[90:93]
	v_mfma_f32_16x16x32_bf16 v[74:77], v[138:141], v[212:215], v[74:77]
	v_mfma_f32_16x16x32_bf16 v[78:81], v[130:133], v[212:215], v[78:81]
	v_mfma_f32_16x16x32_bf16 v[126:129], v[134:137], v[186:189], v[126:129]
	v_mfma_f32_16x16x32_bf16 v[122:125], v[142:145], v[186:189], v[122:125]
	v_mfma_f32_16x16x32_bf16 v[106:109], v[142:145], v[196:199], v[106:109]
	v_mfma_f32_16x16x32_bf16 v[110:113], v[134:137], v[196:199], v[110:113]
	v_mfma_f32_16x16x32_bf16 v[94:97], v[134:137], v[208:211], v[94:97]
	v_mfma_f32_16x16x32_bf16 v[90:93], v[142:145], v[208:211], v[90:93]
	v_mfma_f32_16x16x32_bf16 v[74:77], v[142:145], v[216:219], v[74:77]
	v_mfma_f32_16x16x32_bf16 v[78:81], v[134:137], v[216:219], v[78:81]
	s_setprio 0
	s_setprio 1
	v_mfma_f32_16x16x32_bf16 v[118:121], v[146:149], v[182:185], v[118:121]
	v_mfma_f32_16x16x32_bf16 v[114:117], v[154:157], v[182:185], v[114:117]
	v_mfma_f32_16x16x32_bf16 v[98:101], v[154:157], v[192:195], v[98:101]
	v_mfma_f32_16x16x32_bf16 v[102:105], v[146:149], v[192:195], v[102:105]
	v_mfma_f32_16x16x32_bf16 v[86:89], v[146:149], v[200:203], v[86:89]
	v_mfma_f32_16x16x32_bf16 v[82:85], v[154:157], v[200:203], v[82:85]
	v_mfma_f32_16x16x32_bf16 v[66:69], v[154:157], v[212:215], v[66:69]
	v_mfma_f32_16x16x32_bf16 v[70:73], v[146:149], v[212:215], v[70:73]
	v_mfma_f32_16x16x32_bf16 v[118:121], v[150:153], v[186:189], v[118:121]
	v_mfma_f32_16x16x32_bf16 v[114:117], v[158:161], v[186:189], v[114:117]
	v_mfma_f32_16x16x32_bf16 v[98:101], v[158:161], v[196:199], v[98:101]
	v_mfma_f32_16x16x32_bf16 v[102:105], v[150:153], v[196:199], v[102:105]
	v_mfma_f32_16x16x32_bf16 v[86:89], v[150:153], v[208:211], v[86:89]
	v_mfma_f32_16x16x32_bf16 v[82:85], v[158:161], v[208:211], v[82:85]
	v_mfma_f32_16x16x32_bf16 v[66:69], v[158:161], v[216:219], v[66:69]
	v_mfma_f32_16x16x32_bf16 v[70:73], v[150:153], v[216:219], v[70:73]
	s_setprio 0
	s_barrier
; #define PG8_STAGE(bufoff, gbase, voff) do { _Pragma("unroll") for (int _i = 0; _i < 2; ++_i) \
;         __builtin_amdgcn_global_load_lds((const unsigned*)((const char*)(gbase) + (voff)[_i]), (PG8_LAS unsigned*)(lds + (bufoff) + ldsw + _i * 8192), 16, 0, 0); } while (0)
; #define PG8_LDA(dst, b, h) do { _Pragma("unroll") for (int m = 0; m < 4; ++m) _Pragma("unroll") for (int k = 0; k < 2; ++k) dst[m][k] = *(const PG8_LAS bf16x8*)(lds + PG8_SA(b, h) + aoff + m * 2048 + k * 1024); } while (0)
; #define PG8_MMA(ai, bj, At, Bt) do { __builtin_amdgcn_s_setprio(1); _Pragma("unroll") for (int m = 0; m < 4; ++m) _Pragma("unroll") for (int n = 0; n < 2; ++n) _Pragma("unroll") for (int k = 0; k < 2; ++k) \
;         acc[ai][bj][m][n] = __builtin_amdgcn_mfma_f32_16x16x32_bf16(Bt[n][k], At[m][k], acc[ai][bj][m][n], 0, 0, 0); __builtin_amdgcn_s_setprio(0); } while (0)
; #define PG8_WAIT_V(n) asm volatile("s_waitcnt vmcnt(" #n ")" ::: "memory")
; #define PG8_WAIT_L(n) asm volatile("s_waitcnt lgkmcnt(" #n ")" ::: "memory")
; #define PG8_BAR __builtin_amdgcn_s_barrier()
; #define PG8_SCHED __builtin_amdgcn_sched_barrier(0)
; template <class Epi, class Sched, bool ALIGN_EPI = false, bool SP2 = false>
; __device__ __forceinline__ void gemm_phase(PG8_LAS unsigned char* lds, const Gemm g, const Sched& S, const Epi& E, const int tid) {
;     ...
;             PG8_LDA(At, 1, 1); PG8_STAGE(PG8_SB(1, 0), b3, voffB); PG8_STAGE(PG8_SB(1, 1), b3 + hstep, voffB); PG8_STAGE(PG8_SA(1, 0), a3, voffA);
;             PG8_WAIT_V(8); PG8_WAIT_L(0); PG8_BAR; PG8_MMA(1, 0, At, B0); PG8_MMA(1, 1, At, B1); PG8_BAR; PG8_SCHED;
;     ...
;         if constexpr (ALIGN_EPI) { if (wr == 0) PG8_BAR; }
	s_add_i32 s6, s15, s55
	v_lshl_add_u64 v[220:221], v[220:221], 0, s[36:37]
	s_mov_b32 m0, s6
	ds_read_b128 v[182:185], v207 offset:49152
	ds_read_b128 v[186:189], v207 offset:50176
	ds_read_b128 v[192:195], v207 offset:51200
	ds_read_b128 v[196:199], v207 offset:52224
	ds_read_b128 v[200:203], v207 offset:53248
	ds_read_b128 v[208:211], v207 offset:54272
	ds_read_b128 v[212:215], v207 offset:55296
	ds_read_b128 v[216:219], v207 offset:56320
	global_load_lds_dwordx4 v[220:221], off
	s_add_i32 m0, s6, 0x2000
	s_add_u32 s6, s10, 0xb0080
	v_lshl_add_u64 v[220:221], v[222:223], 0, s[36:37]
	s_addc_u32 s7, s11, 0
	s_add_i32 s10, s18, s55
	global_load_lds_dwordx4 v[220:221], off
	v_lshl_add_u64 v[220:221], s[6:7], 0, v[164:165]
	s_mov_b32 m0, s10
	s_nop 0
	global_load_lds_dwordx4 v[220:221], off
	v_lshl_add_u64 v[220:221], s[6:7], 0, v[168:169]
	s_add_i32 m0, s10, 0x2000
	s_nop 0
	global_load_lds_dwordx4 v[220:221], off
	v_lshl_add_u64 v[220:221], v[224:225], 0, s[36:37]
	s_mov_b32 m0, s61
	s_nop 0
	global_load_lds_dwordx4 v[220:221], off
	v_lshl_add_u64 v[220:221], v[226:227], 0, s[36:37]
	s_mov_b32 m0, s62
	s_nop 0
	global_load_lds_dwordx4 v[220:221], off
	s_waitcnt vmcnt(8)
	s_waitcnt lgkmcnt(0)
	s_barrier
	s_setprio 1
	s_waitcnt lgkmcnt(0)
	v_mfma_f32_16x16x32_bf16 v[62:65], v[130:133], v[182:185], v[62:65]
	v_mfma_f32_16x16x32_bf16 v[58:61], v[138:141], v[182:185], v[58:61]
	v_mfma_f32_16x16x32_bf16 v[42:45], v[138:141], v[192:195], v[42:45]
	v_mfma_f32_16x16x32_bf16 v[46:49], v[130:133], v[192:195], v[46:49]
	v_mfma_f32_16x16x32_bf16 v[30:33], v[130:133], v[200:203], v[30:33]
	v_mfma_f32_16x16x32_bf16 v[26:29], v[138:141], v[200:203], v[26:29]
	v_mfma_f32_16x16x32_bf16 v[10:13], v[138:141], v[212:215], v[10:13]
	v_mfma_f32_16x16x32_bf16 v[14:17], v[130:133], v[212:215], v[14:17]
	v_mfma_f32_16x16x32_bf16 v[62:65], v[134:137], v[186:189], v[62:65]
	v_mfma_f32_16x16x32_bf16 v[58:61], v[142:145], v[186:189], v[58:61]
	v_mfma_f32_16x16x32_bf16 v[42:45], v[142:145], v[196:199], v[42:45]
	v_mfma_f32_16x16x32_bf16 v[46:49], v[134:137], v[196:199], v[46:49]
	v_mfma_f32_16x16x32_bf16 v[30:33], v[134:137], v[208:211], v[30:33]
	v_mfma_f32_16x16x32_bf16 v[26:29], v[142:145], v[208:211], v[26:29]
	v_mfma_f32_16x16x32_bf16 v[10:13], v[142:145], v[216:219], v[10:13]
	v_mfma_f32_16x16x32_bf16 v[14:17], v[134:137], v[216:219], v[14:17]
	s_setprio 0
	s_setprio 1
	v_mfma_f32_16x16x32_bf16 v[54:57], v[146:149], v[182:185], v[54:57]
	v_mfma_f32_16x16x32_bf16 v[50:53], v[154:157], v[182:185], v[50:53]
	v_mfma_f32_16x16x32_bf16 v[34:37], v[154:157], v[192:195], v[34:37]
	v_mfma_f32_16x16x32_bf16 v[38:41], v[146:149], v[192:195], v[38:41]
	v_mfma_f32_16x16x32_bf16 v[22:25], v[146:149], v[200:203], v[22:25]
	v_mfma_f32_16x16x32_bf16 v[18:21], v[154:157], v[200:203], v[18:21]
	v_mfma_f32_16x16x32_bf16 v[2:5], v[154:157], v[212:215], v[2:5]
	v_mfma_f32_16x16x32_bf16 v[6:9], v[146:149], v[212:215], v[6:9]
	v_mfma_f32_16x16x32_bf16 v[54:57], v[150:153], v[186:189], v[54:57]
	v_mfma_f32_16x16x32_bf16 v[50:53], v[158:161], v[186:189], v[50:53]
	v_mfma_f32_16x16x32_bf16 v[34:37], v[158:161], v[196:199], v[34:37]
	v_mfma_f32_16x16x32_bf16 v[38:41], v[150:153], v[196:199], v[38:41]
	v_mfma_f32_16x16x32_bf16 v[22:25], v[150:153], v[208:211], v[22:25]
	v_mfma_f32_16x16x32_bf16 v[18:21], v[158:161], v[208:211], v[18:21]
	v_mfma_f32_16x16x32_bf16 v[2:5], v[158:161], v[216:219], v[2:5]
	v_mfma_f32_16x16x32_bf16 v[6:9], v[150:153], v[216:219], v[6:9]
	s_setprio 0
	s_barrier
	s_add_i32 s77, s77, 2
	s_add_u32 s45, s45, 0x100
	s_addc_u32 s47, s47, 0
	s_cmp_gt_u32 s77, 41
	s_mov_b64 s[6:7], s[8:9]
	s_cbranch_scc0 .LBB0_423
	s_and_b64 vcc, exec, s[38:39]
	s_cbranch_vccz .LBB0_426
	s_barrier

; #define PG8_STAGE(bufoff, gbase, voff) do { _Pragma("unroll") for (int _i = 0; _i < 2; ++_i) \
;         __builtin_amdgcn_global_load_lds((const unsigned*)((const char*)(gbase) + (voff)[_i]), (PG8_LAS unsigned*)(lds + (bufoff) + ldsw + _i * 8192), 16, 0, 0); } while (0)
; #define PG8_LDA(dst, b, h) do { _Pragma("unroll") for (int m = 0; m < 4; ++m) _Pragma("unroll") for (int k = 0; k < 2; ++k) dst[m][k] = *(const PG8_LAS bf16x8*)(lds + PG8_SA(b, h) + aoff + m * 2048 + k * 1024); } while (0)
; #define PG8_LDB(dst, b, h) do { _Pragma("unroll") for (int n = 0; n < 2; ++n) _Pragma("unroll") for (int k = 0; k < 2; ++k) dst[n][k] = *(const PG8_LAS bf16x8*)(lds + PG8_SB(b, h) + boff + n * 2048 + k * 1024); } while (0)
; #define PG8_MMA(ai, bj, At, Bt) do { __builtin_amdgcn_s_setprio(1); _Pragma("unroll") for (int m = 0; m < 4; ++m) _Pragma("unroll") for (int n = 0; n < 2; ++n) _Pragma("unroll") for (int k = 0; k < 2; ++k) \
;         acc[ai][bj][m][n] = __builtin_amdgcn_mfma_f32_16x16x32_bf16(Bt[n][k], At[m][k], acc[ai][bj][m][n], 0, 0, 0); __builtin_amdgcn_s_setprio(0); } while (0)
; #define PG8_WAIT_V(n) asm volatile("s_waitcnt vmcnt(" #n ")" ::: "memory")
; template <class Epi, class Sched, bool ALIGN_EPI = false, bool SP2 = false>
; __device__ __forceinline__ void gemm_phase(PG8_LAS unsigned char* lds, const Gemm g, const Sched& S, const Epi& E, const int tid) {
;     ...
;         const bool has_next = S.next(ui + 1, nxt);
;         const char* nA = has_next ? S.aptr(nxt) : cA; const char* nB = has_next ? S.bptr(nxt) : cB;
;         for (int t = 0; t < nt; t += 2) {
;             const bool last = (t == nt - 2);
;             const char* a1 = cA + (size_t)(t + 1) * kstep;
;             const char* a2 = last ? nA : cA + (size_t)(t + 2) * kstep; const char* b2 = last ? nB : cB + (size_t)(t + 2) * kstep;
;             const char* a3 = a2 + kstep; const char* b3 = b2 + kstep;
;             if (last && has_next) S.a_ready(nxt);
;             if constexpr (SP2) {
;             PG8_LDB(B0, 0, 0); PG8_LDB(B1, 0, 1); PG8_SCHED; PG8_LDA(At, 0, 0); PG8_STAGE(PG8_SA(1, 1), a1 + hstep, voffA);
;             PG8_WAIT_V(8); PG8_WAIT_L(0); PG8_BAR; PG8_MMA(0, 0, At, B0); PG8_MMA(0, 1, At, B1); PG8_BAR; PG8_SCHED;
;             PG8_LDA(At, 0, 1); PG8_STAGE(PG8_SB(0, 0), b2, voffB); PG8_STAGE(PG8_SB(0, 1), b2 + hstep, voffB); PG8_STAGE(PG8_SA(0, 0), a2, voffA);
.LBB0_732:
	s_ashr_i32 s29, s28, 31
	s_lshl_b64 s[18:19], s[28:29], 19
	s_add_u32 s30, s50, s18
	s_addc_u32 s31, s51, s19
	s_and_b64 s[18:19], s[2:3], exec
	s_cselect_b32 s29, s31, s41
	s_cselect_b32 s37, s30, s40
	s_ashr_i32 s27, s26, 31
	s_lshl_b64 s[18:19], s[26:27], 19
	s_add_u32 s34, s52, s18
	s_addc_u32 s35, s53, s19
	s_and_b64 s[18:19], s[2:3], exec
	s_cselect_b32 s27, s35, s39
	s_cselect_b32 s79, s34, s38
	s_add_u32 s80, s38, 0x100
	s_addc_u32 s81, s39, 0
	s_add_u32 s38, s40, 0x40080
	s_addc_u32 s39, s41, 0
	s_mov_b32 s82, -2
	ds_read_b128 v[130:133], v191
	ds_read_b128 v[134:137], v191 offset:1024
	ds_read_b128 v[138:141], v191 offset:2048
	ds_read_b128 v[142:145], v191 offset:3072
	ds_read_b128 v[146:149], v193
	ds_read_b128 v[150:153], v193 offset:1024
	ds_read_b128 v[154:157], v193 offset:2048
	ds_read_b128 v[158:161], v193 offset:3072
	s_add_u32 s15, s38, 0xfffc0080
	s_addc_u32 s18, s39, -1
	s_cmp_eq_u32 s82, 12
	s_cselect_b32 s43, s29, s18
	s_cselect_b32 s42, s37, s15
	s_cselect_b32 s41, s27, s81
	s_cselect_b32 s40, s79, s80
	v_lshl_add_u64 v[194:195], s[38:39], 0, v[180:181]
	s_add_i32 m0, s55, 0xc000
	ds_read_b128 v[186:189], v197
	ds_read_b128 v[198:201], v197 offset:1024
	ds_read_b128 v[206:209], v197 offset:2048
	ds_read_b128 v[212:215], v197 offset:3072
	ds_read_b128 v[216:219], v197 offset:4096
	ds_read_b128 v[220:223], v197 offset:5120
	ds_read_b128 v[224:227], v197 offset:6144
	ds_read_b128 v[228:231], v197 offset:7168
	global_load_lds_dwordx4 v[194:195], off
	v_lshl_add_u64 v[194:195], s[38:39], 0, v[178:179]
	s_add_i32 m0, s55, 0xe000
	s_nop 0
	global_load_lds_dwordx4 v[194:195], off
	s_waitcnt vmcnt(8)
	s_waitcnt lgkmcnt(0)
	s_barrier
	s_setprio 1
	s_waitcnt lgkmcnt(0)
	v_mfma_f32_16x16x32_bf16 v[126:129], v[130:133], v[186:189], 0
	v_mfma_f32_16x16x32_bf16 v[122:125], v[138:141], v[186:189], 0
	v_mfma_f32_16x16x32_bf16 v[106:109], v[138:141], v[206:209], 0
	v_mfma_f32_16x16x32_bf16 v[110:113], v[130:133], v[206:209], 0
	v_mfma_f32_16x16x32_bf16 v[94:97], v[130:133], v[216:219], 0
	v_mfma_f32_16x16x32_bf16 v[90:93], v[138:141], v[216:219], 0
	v_mfma_f32_16x16x32_bf16 v[74:77], v[138:141], v[224:227], 0
	v_mfma_f32_16x16x32_bf16 v[78:81], v[130:133], v[224:227], 0
	v_mfma_f32_16x16x32_bf16 v[126:129], v[134:137], v[198:201], v[126:129]
	v_mfma_f32_16x16x32_bf16 v[122:125], v[142:145], v[198:201], v[122:125]
	v_mfma_f32_16x16x32_bf16 v[106:109], v[142:145], v[212:215], v[106:109]
	v_mfma_f32_16x16x32_bf16 v[110:113], v[134:137], v[212:215], v[110:113]
	v_mfma_f32_16x16x32_bf16 v[94:97], v[134:137], v[220:223], v[94:97]
	v_mfma_f32_16x16x32_bf16 v[90:93], v[142:145], v[220:223], v[90:93]
	v_mfma_f32_16x16x32_bf16 v[74:77], v[142:145], v[228:231], v[74:77]
	v_mfma_f32_16x16x32_bf16 v[78:81], v[134:137], v[228:231], v[78:81]
	s_setprio 0
	s_setprio 1
	v_mfma_f32_16x16x32_bf16 v[118:121], v[146:149], v[186:189], 0
	v_mfma_f32_16x16x32_bf16 v[114:117], v[154:157], v[186:189], 0
	v_mfma_f32_16x16x32_bf16 v[98:101], v[154:157], v[206:209], 0
	v_mfma_f32_16x16x32_bf16 v[102:105], v[146:149], v[206:209], 0
	v_mfma_f32_16x16x32_bf16 v[86:89], v[146:149], v[216:219], 0
	v_mfma_f32_16x16x32_bf16 v[82:85], v[154:157], v[216:219], 0
	v_mfma_f32_16x16x32_bf16 v[66:69], v[154:157], v[224:227], 0
	v_mfma_f32_16x16x32_bf16 v[70:73], v[146:149], v[224:227], 0
	v_mfma_f32_16x16x32_bf16 v[118:121], v[150:153], v[198:201], v[118:121]
	v_mfma_f32_16x16x32_bf16 v[114:117], v[158:161], v[198:201], v[114:117]
	v_mfma_f32_16x16x32_bf16 v[98:101], v[158:161], v[212:215], v[98:101]
	v_mfma_f32_16x16x32_bf16 v[102:105], v[150:153], v[212:215], v[102:105]
	v_mfma_f32_16x16x32_bf16 v[86:89], v[150:153], v[220:223], v[86:89]
	v_mfma_f32_16x16x32_bf16 v[82:85], v[158:161], v[220:223], v[82:85]
	v_mfma_f32_16x16x32_bf16 v[66:69], v[158:161], v[228:231], v[66:69]
	v_mfma_f32_16x16x32_bf16 v[70:73], v[150:153], v[228:231], v[70:73]
	s_setprio 0
	s_barrier
	s_add_i32 s15, s66, s54
	v_lshl_add_u64 v[194:195], s[40:41], 0, v[164:165]
	s_mov_b32 m0, s15
	ds_read_b128 v[186:189], v197 offset:16384
	ds_read_b128 v[198:201], v197 offset:17408
	ds_read_b128 v[206:209], v197 offset:18432
	ds_read_b128 v[212:215], v197 offset:19456
	ds_read_b128 v[216:219], v197 offset:20480
	ds_read_b128 v[220:223], v197 offset:21504
	ds_read_b128 v[224:227], v197 offset:22528
	ds_read_b128 v[228:231], v197 offset:23552
	global_load_lds_dwordx4 v[194:195], off
	s_add_i32 m0, s15, 0x2000
	s_add_u32 s18, s40, 0x40000
	v_lshl_add_u64 v[232:233], s[40:41], 0, v[168:169]
	s_addc_u32 s19, s41, 0
	s_add_i32 s15, s67, s54
	global_load_lds_dwordx4 v[232:233], off
	v_lshl_add_u64 v[234:235], s[18:19], 0, v[164:165]
	s_mov_b32 m0, s15
	v_lshl_add_u64 v[236:237], s[42:43], 0, v[166:167]
	global_load_lds_dwordx4 v[234:235], off
	v_lshl_add_u64 v[234:235], s[18:19], 0, v[168:169]
	s_add_i32 m0, s15, 0x2000
	s_nop 0
	global_load_lds_dwordx4 v[234:235], off
	v_lshl_add_u64 v[234:235], s[42:43], 0, v[162:163]
	s_mov_b32 m0, s55
	s_nop 0
	global_load_lds_dwordx4 v[234:235], off
	s_mov_b32 m0, s56
	s_nop 0
	global_load_lds_dwordx4 v[236:237], off
	s_waitcnt vmcnt(8)
	s_waitcnt lgkmcnt(0)
	s_barrier
; #define PG8_STAGE(bufoff, gbase, voff) do { _Pragma("unroll") for (int _i = 0; _i < 2; ++_i) \
;         __builtin_amdgcn_global_load_lds((const unsigned*)((const char*)(gbase) + (voff)[_i]), (PG8_LAS unsigned*)(lds + (bufoff) + ldsw + _i * 8192), 16, 0, 0); } while (0)
; #define PG8_LDA(dst, b, h) do { _Pragma("unroll") for (int m = 0; m < 4; ++m) _Pragma("unroll") for (int k = 0; k < 2; ++k) dst[m][k] = *(const PG8_LAS bf16x8*)(lds + PG8_SA(b, h) + aoff + m * 2048 + k * 1024); } while (0)
; #define PG8_LDB(dst, b, h) do { _Pragma("unroll") for (int n = 0; n < 2; ++n) _Pragma("unroll") for (int k = 0; k < 2; ++k) dst[n][k] = *(const PG8_LAS bf16x8*)(lds + PG8_SB(b, h) + boff + n * 2048 + k * 1024); } while (0)
; #define PG8_MMA(ai, bj, At, Bt) do { __builtin_amdgcn_s_setprio(1); _Pragma("unroll") for (int m = 0; m < 4; ++m) _Pragma("unroll") for (int n = 0; n < 2; ++n) _Pragma("unroll") for (int k = 0; k < 2; ++k) \
;         acc[ai][bj][m][n] = __builtin_amdgcn_mfma_f32_16x16x32_bf16(Bt[n][k], At[m][k], acc[ai][bj][m][n], 0, 0, 0); __builtin_amdgcn_s_setprio(0); } while (0)
; #define PG8_WAIT_V(n) asm volatile("s_waitcnt vmcnt(" #n ")" ::: "memory")
; #define PG8_WAIT_L(n) asm volatile("s_waitcnt lgkmcnt(" #n ")" ::: "memory")
; #define PG8_BAR __builtin_amdgcn_s_barrier()
; #define PG8_SCHED __builtin_amdgcn_sched_barrier(0)
; template <class Epi, class Sched, bool ALIGN_EPI = false, bool SP2 = false>
; __device__ __forceinline__ void gemm_phase(PG8_LAS unsigned char* lds, const Gemm g, const Sched& S, const Epi& E, const int tid) {
;     ...
;             PG8_WAIT_V(8); PG8_WAIT_L(0); PG8_BAR; PG8_MMA(1, 0, At, B0); PG8_MMA(1, 1, At, B1); PG8_BAR; PG8_SCHED;
;             PG8_LDB(B0, 1, 0); PG8_LDB(B1, 1, 1); PG8_SCHED; PG8_LDA(At, 1, 0); PG8_STAGE(PG8_SA(0, 1), a2 + hstep, voffA);
;             PG8_WAIT_V(8); PG8_WAIT_L(0); PG8_BAR; PG8_MMA(0, 0, At, B0); PG8_MMA(0, 1, At, B1); PG8_BAR; PG8_SCHED;
	s_setprio 1
	s_waitcnt lgkmcnt(0)
	v_mfma_f32_16x16x32_bf16 v[62:65], v[130:133], v[186:189], 0
	v_mfma_f32_16x16x32_bf16 v[58:61], v[138:141], v[186:189], 0
	v_mfma_f32_16x16x32_bf16 v[42:45], v[138:141], v[206:209], 0
	v_mfma_f32_16x16x32_bf16 v[46:49], v[130:133], v[206:209], 0
	v_mfma_f32_16x16x32_bf16 v[30:33], v[130:133], v[216:219], 0
	v_mfma_f32_16x16x32_bf16 v[26:29], v[138:141], v[216:219], 0
	v_mfma_f32_16x16x32_bf16 v[10:13], v[138:141], v[224:227], 0
	v_mfma_f32_16x16x32_bf16 v[14:17], v[130:133], v[224:227], 0
	v_mfma_f32_16x16x32_bf16 v[62:65], v[134:137], v[198:201], v[62:65]
	v_mfma_f32_16x16x32_bf16 v[58:61], v[142:145], v[198:201], v[58:61]
	v_mfma_f32_16x16x32_bf16 v[42:45], v[142:145], v[212:215], v[42:45]
	v_mfma_f32_16x16x32_bf16 v[46:49], v[134:137], v[212:215], v[46:49]
	v_mfma_f32_16x16x32_bf16 v[30:33], v[134:137], v[220:223], v[30:33]
	v_mfma_f32_16x16x32_bf16 v[26:29], v[142:145], v[220:223], v[26:29]
	v_mfma_f32_16x16x32_bf16 v[10:13], v[142:145], v[228:231], v[10:13]
	v_mfma_f32_16x16x32_bf16 v[14:17], v[134:137], v[228:231], v[14:17]
	s_setprio 0
	s_setprio 1
	v_mfma_f32_16x16x32_bf16 v[54:57], v[146:149], v[186:189], 0
	v_mfma_f32_16x16x32_bf16 v[50:53], v[154:157], v[186:189], 0
	v_mfma_f32_16x16x32_bf16 v[34:37], v[154:157], v[206:209], 0
	v_mfma_f32_16x16x32_bf16 v[38:41], v[146:149], v[206:209], 0
	v_mfma_f32_16x16x32_bf16 v[22:25], v[146:149], v[216:219], 0
	v_mfma_f32_16x16x32_bf16 v[18:21], v[154:157], v[216:219], 0
	v_mfma_f32_16x16x32_bf16 v[2:5], v[154:157], v[224:227], 0
	v_mfma_f32_16x16x32_bf16 v[6:9], v[146:149], v[224:227], 0
	v_mfma_f32_16x16x32_bf16 v[54:57], v[150:153], v[198:201], v[54:57]
	v_mfma_f32_16x16x32_bf16 v[50:53], v[158:161], v[198:201], v[50:53]
	v_mfma_f32_16x16x32_bf16 v[34:37], v[158:161], v[212:215], v[34:37]
	v_mfma_f32_16x16x32_bf16 v[38:41], v[150:153], v[212:215], v[38:41]
	v_mfma_f32_16x16x32_bf16 v[22:25], v[150:153], v[220:223], v[22:25]
	v_mfma_f32_16x16x32_bf16 v[18:21], v[158:161], v[220:223], v[18:21]
	v_mfma_f32_16x16x32_bf16 v[2:5], v[158:161], v[228:231], v[2:5]
	v_mfma_f32_16x16x32_bf16 v[6:9], v[150:153], v[228:231], v[6:9]
	s_setprio 0
	s_barrier
	s_add_i32 s15, 0, 0x18000
	s_add_i32 s83, 0, 0x1c000
	v_add_u32_e32 v142, s15, v173
	v_add_u32_e32 v158, s83, v173
	ds_read_b128 v[130:133], v142
	ds_read_b128 v[134:137], v142 offset:1024
	ds_read_b128 v[138:141], v142 offset:2048
	ds_read_b128 v[142:145], v142 offset:3072
	ds_read_b128 v[146:149], v158
	ds_read_b128 v[150:153], v158 offset:1024
	ds_read_b128 v[154:157], v158 offset:2048
	ds_read_b128 v[158:161], v158 offset:3072
	s_add_u32 s18, s42, 0x40000
	s_addc_u32 s19, s43, 0
	s_mov_b32 m0, s57
	v_lshl_add_u64 v[238:239], s[18:19], 0, v[162:163]
	ds_read_b128 v[186:189], v197 offset:32768
	ds_read_b128 v[198:201], v197 offset:33792
	ds_read_b128 v[206:209], v197 offset:34816
	ds_read_b128 v[212:215], v197 offset:35840
	ds_read_b128 v[216:219], v197 offset:36864
	ds_read_b128 v[220:223], v197 offset:37888
	ds_read_b128 v[224:227], v197 offset:38912
	ds_read_b128 v[228:231], v197 offset:39936
	global_load_lds_dwordx4 v[238:239], off
	v_lshl_add_u64 v[238:239], s[18:19], 0, v[166:167]
	s_mov_b32 m0, s58
	s_nop 0
	global_load_lds_dwordx4 v[238:239], off
	s_waitcnt vmcnt(8)
	s_waitcnt lgkmcnt(0)
	s_barrier
	s_setprio 1
	s_waitcnt lgkmcnt(0)
	v_mfma_f32_16x16x32_bf16 v[126:129], v[130:133], v[186:189], v[126:129]
	v_mfma_f32_16x16x32_bf16 v[122:125], v[138:141], v[186:189], v[122:125]
	v_mfma_f32_16x16x32_bf16 v[106:109], v[138:141], v[206:209], v[106:109]
	v_mfma_f32_16x16x32_bf16 v[110:113], v[130:133], v[206:209], v[110:113]
	v_mfma_f32_16x16x32_bf16 v[94:97], v[130:133], v[216:219], v[94:97]
	v_mfma_f32_16x16x32_bf16 v[90:93], v[138:141], v[216:219], v[90:93]
	v_mfma_f32_16x16x32_bf16 v[74:77], v[138:141], v[224:227], v[74:77]
	v_mfma_f32_16x16x32_bf16 v[78:81], v[130:133], v[224:227], v[78:81]
	v_mfma_f32_16x16x32_bf16 v[126:129], v[134:137], v[198:201], v[126:129]
	v_mfma_f32_16x16x32_bf16 v[122:125], v[142:145], v[198:201], v[122:125]
	v_mfma_f32_16x16x32_bf16 v[106:109], v[142:145], v[212:215], v[106:109]
	v_mfma_f32_16x16x32_bf16 v[110:113], v[134:137], v[212:215], v[110:113]
	v_mfma_f32_16x16x32_bf16 v[94:97], v[134:137], v[220:223], v[94:97]
	v_mfma_f32_16x16x32_bf16 v[90:93], v[142:145], v[220:223], v[90:93]
	v_mfma_f32_16x16x32_bf16 v[74:77], v[142:145], v[228:231], v[74:77]
	v_mfma_f32_16x16x32_bf16 v[78:81], v[134:137], v[228:231], v[78:81]
	s_setprio 0
	s_setprio 1
	v_mfma_f32_16x16x32_bf16 v[118:121], v[146:149], v[186:189], v[118:121]
	v_mfma_f32_16x16x32_bf16 v[114:117], v[154:157], v[186:189], v[114:117]
	v_mfma_f32_16x16x32_bf16 v[98:101], v[154:157], v[206:209], v[98:101]
	v_mfma_f32_16x16x32_bf16 v[102:105], v[146:149], v[206:209], v[102:105]
	v_mfma_f32_16x16x32_bf16 v[86:89], v[146:149], v[216:219], v[86:89]
	v_mfma_f32_16x16x32_bf16 v[82:85], v[154:157], v[216:219], v[82:85]
	v_mfma_f32_16x16x32_bf16 v[66:69], v[154:157], v[224:227], v[66:69]
	v_mfma_f32_16x16x32_bf16 v[70:73], v[146:149], v[224:227], v[70:73]
	v_mfma_f32_16x16x32_bf16 v[118:121], v[150:153], v[198:201], v[118:121]
	v_mfma_f32_16x16x32_bf16 v[114:117], v[158:161], v[198:201], v[114:117]
	v_mfma_f32_16x16x32_bf16 v[98:101], v[158:161], v[212:215], v[98:101]
	v_mfma_f32_16x16x32_bf16 v[102:105], v[150:153], v[212:215], v[102:105]
	v_mfma_f32_16x16x32_bf16 v[86:89], v[150:153], v[220:223], v[86:89]
	v_mfma_f32_16x16x32_bf16 v[82:85], v[158:161], v[220:223], v[82:85]
	v_mfma_f32_16x16x32_bf16 v[66:69], v[158:161], v[228:231], v[66:69]
	v_mfma_f32_16x16x32_bf16 v[70:73], v[150:153], v[228:231], v[70:73]
	s_setprio 0
	s_barrier
; #define PG8_STAGE(bufoff, gbase, voff) do { _Pragma("unroll") for (int _i = 0; _i < 2; ++_i) \
;         __builtin_amdgcn_global_load_lds((const unsigned*)((const char*)(gbase) + (voff)[_i]), (PG8_LAS unsigned*)(lds + (bufoff) + ldsw + _i * 8192), 16, 0, 0); } while (0)
; #define PG8_LDA(dst, b, h) do { _Pragma("unroll") for (int m = 0; m < 4; ++m) _Pragma("unroll") for (int k = 0; k < 2; ++k) dst[m][k] = *(const PG8_LAS bf16x8*)(lds + PG8_SA(b, h) + aoff + m * 2048 + k * 1024); } while (0)
; #define PG8_LDB(dst, b, h) do { _Pragma("unroll") for (int n = 0; n < 2; ++n) _Pragma("unroll") for (int k = 0; k < 2; ++k) dst[n][k] = *(const PG8_LAS bf16x8*)(lds + PG8_SB(b, h) + boff + n * 2048 + k * 1024); } while (0)
; #define PG8_MMA(ai, bj, At, Bt) do { __builtin_amdgcn_s_setprio(1); _Pragma("unroll") for (int m = 0; m < 4; ++m) _Pragma("unroll") for (int n = 0; n < 2; ++n) _Pragma("unroll") for (int k = 0; k < 2; ++k) \
;         acc[ai][bj][m][n] = __builtin_amdgcn_mfma_f32_16x16x32_bf16(Bt[n][k], At[m][k], acc[ai][bj][m][n], 0, 0, 0); __builtin_amdgcn_s_setprio(0); } while (0)
; #define PG8_WAIT_V(n) asm volatile("s_waitcnt vmcnt(" #n ")" ::: "memory")
; #define PG8_WAIT_L(n) asm volatile("s_waitcnt lgkmcnt(" #n ")" ::: "memory")
; #define PG8_BAR __builtin_amdgcn_s_barrier()
; #define PG8_SCHED __builtin_amdgcn_sched_barrier(0)
; template <class Epi, class Sched, bool ALIGN_EPI = false, bool SP2 = false>
; __device__ __forceinline__ void gemm_phase(PG8_LAS unsigned char* lds, const Gemm g, const Sched& S, const Epi& E, const int tid) {
;     ...
;             PG8_LDB(B0, 0, 0); PG8_LDB(B1, 0, 1); PG8_SCHED; PG8_LDA(At, 0, 0); PG8_STAGE(PG8_SA(1, 1), a1 + hstep, voffA);
;     ...
;             PG8_LDA(At, 1, 1); PG8_STAGE(PG8_SB(1, 0), b3, voffB); PG8_STAGE(PG8_SB(1, 1), b3 + hstep, voffB); PG8_STAGE(PG8_SA(1, 0), a3, voffA);
;             PG8_WAIT_V(8); PG8_WAIT_L(0); PG8_BAR; PG8_MMA(1, 0, At, B0); PG8_MMA(1, 1, At, B1); PG8_BAR; PG8_SCHED;
	s_add_i32 s15, s15, s54
	v_lshl_add_u64 v[194:195], v[194:195], 0, s[10:11]
	s_mov_b32 m0, s15
	ds_read_b128 v[186:189], v197 offset:49152
	ds_read_b128 v[198:201], v197 offset:50176
	ds_read_b128 v[206:209], v197 offset:51200
	ds_read_b128 v[212:215], v197 offset:52224
	ds_read_b128 v[216:219], v197 offset:53248
	ds_read_b128 v[220:223], v197 offset:54272
	ds_read_b128 v[224:227], v197 offset:55296
	ds_read_b128 v[228:231], v197 offset:56320
	global_load_lds_dwordx4 v[194:195], off
	s_add_i32 m0, s15, 0x2000
	s_add_u32 s18, s40, 0x40080
	v_lshl_add_u64 v[194:195], v[232:233], 0, s[10:11]
	s_addc_u32 s19, s41, 0
	s_add_i32 s15, s83, s54
	global_load_lds_dwordx4 v[194:195], off
	v_lshl_add_u64 v[194:195], s[18:19], 0, v[164:165]
	s_mov_b32 m0, s15
	s_nop 0
	global_load_lds_dwordx4 v[194:195], off
	v_lshl_add_u64 v[194:195], s[18:19], 0, v[168:169]
	s_add_i32 m0, s15, 0x2000
	s_nop 0
	global_load_lds_dwordx4 v[194:195], off
	v_lshl_add_u64 v[194:195], v[234:235], 0, s[10:11]
	s_mov_b32 m0, s61
	s_nop 0
	global_load_lds_dwordx4 v[194:195], off
	v_lshl_add_u64 v[194:195], v[236:237], 0, s[10:11]
	s_mov_b32 m0, s62
	s_nop 0
	global_load_lds_dwordx4 v[194:195], off
	s_waitcnt vmcnt(8)
	s_waitcnt lgkmcnt(0)
	s_barrier
	s_setprio 1
	s_waitcnt lgkmcnt(0)
	v_mfma_f32_16x16x32_bf16 v[62:65], v[130:133], v[186:189], v[62:65]
	v_mfma_f32_16x16x32_bf16 v[58:61], v[138:141], v[186:189], v[58:61]
	v_mfma_f32_16x16x32_bf16 v[42:45], v[138:141], v[206:209], v[42:45]
	v_mfma_f32_16x16x32_bf16 v[46:49], v[130:133], v[206:209], v[46:49]
	v_mfma_f32_16x16x32_bf16 v[30:33], v[130:133], v[216:219], v[30:33]
	v_mfma_f32_16x16x32_bf16 v[26:29], v[138:141], v[216:219], v[26:29]
	v_mfma_f32_16x16x32_bf16 v[10:13], v[138:141], v[224:227], v[10:13]
	v_mfma_f32_16x16x32_bf16 v[14:17], v[130:133], v[224:227], v[14:17]
	v_mfma_f32_16x16x32_bf16 v[62:65], v[134:137], v[198:201], v[62:65]
	v_mfma_f32_16x16x32_bf16 v[58:61], v[142:145], v[198:201], v[58:61]
	v_mfma_f32_16x16x32_bf16 v[42:45], v[142:145], v[212:215], v[42:45]
	v_mfma_f32_16x16x32_bf16 v[46:49], v[134:137], v[212:215], v[46:49]
	v_mfma_f32_16x16x32_bf16 v[30:33], v[134:137], v[220:223], v[30:33]
	v_mfma_f32_16x16x32_bf16 v[26:29], v[142:145], v[220:223], v[26:29]
	v_mfma_f32_16x16x32_bf16 v[10:13], v[142:145], v[228:231], v[10:13]
	v_mfma_f32_16x16x32_bf16 v[14:17], v[134:137], v[228:231], v[14:17]
	s_setprio 0
	s_setprio 1
	v_mfma_f32_16x16x32_bf16 v[54:57], v[146:149], v[186:189], v[54:57]
	v_mfma_f32_16x16x32_bf16 v[50:53], v[154:157], v[186:189], v[50:53]
	v_mfma_f32_16x16x32_bf16 v[34:37], v[154:157], v[206:209], v[34:37]
	v_mfma_f32_16x16x32_bf16 v[38:41], v[146:149], v[206:209], v[38:41]
	v_mfma_f32_16x16x32_bf16 v[22:25], v[146:149], v[216:219], v[22:25]
	v_mfma_f32_16x16x32_bf16 v[18:21], v[154:157], v[216:219], v[18:21]
	v_mfma_f32_16x16x32_bf16 v[2:5], v[154:157], v[224:227], v[2:5]
	v_mfma_f32_16x16x32_bf16 v[6:9], v[146:149], v[224:227], v[6:9]
	v_mfma_f32_16x16x32_bf16 v[54:57], v[150:153], v[198:201], v[54:57]
	v_mfma_f32_16x16x32_bf16 v[50:53], v[158:161], v[198:201], v[50:53]
	v_mfma_f32_16x16x32_bf16 v[34:37], v[158:161], v[212:215], v[34:37]
	v_mfma_f32_16x16x32_bf16 v[38:41], v[150:153], v[212:215], v[38:41]
	v_mfma_f32_16x16x32_bf16 v[22:25], v[150:153], v[220:223], v[22:25]
	v_mfma_f32_16x16x32_bf16 v[18:21], v[158:161], v[220:223], v[18:21]
	v_mfma_f32_16x16x32_bf16 v[2:5], v[158:161], v[228:231], v[2:5]
	v_mfma_f32_16x16x32_bf16 v[6:9], v[150:153], v[228:231], v[6:9]
	s_setprio 0
	s_barrier
	s_add_i32 s82, s82, 2
	s_add_u32 s80, s80, 0x100
	s_addc_u32 s81, s81, 0
	s_add_u32 s38, s38, 0x100
	s_addc_u32 s39, s39, 0
.LBB0_733:
	ds_read_b128 v[130:133], v191
	ds_read_b128 v[134:137], v191 offset:1024
	ds_read_b128 v[138:141], v191 offset:2048
	ds_read_b128 v[142:145], v191 offset:3072
	ds_read_b128 v[146:149], v193
	ds_read_b128 v[150:153], v193 offset:1024
	ds_read_b128 v[154:157], v193 offset:2048
	ds_read_b128 v[158:161], v193 offset:3072
	s_add_u32 s15, s38, 0xfffc0080
	s_addc_u32 s18, s39, -1
	s_cmp_eq_u32 s82, 12
	s_cselect_b32 s43, s29, s18
	s_cselect_b32 s42, s37, s15
	s_cselect_b32 s41, s27, s81
	s_cselect_b32 s40, s79, s80
	v_lshl_add_u64 v[194:195], s[38:39], 0, v[180:181]
	s_add_i32 m0, s55, 0xc000
	ds_read_b128 v[186:189], v197
	ds_read_b128 v[198:201], v197 offset:1024
	ds_read_b128 v[206:209], v197 offset:2048
	ds_read_b128 v[212:215], v197 offset:3072
	ds_read_b128 v[216:219], v197 offset:4096
	ds_read_b128 v[220:223], v197 offset:5120
	ds_read_b128 v[224:227], v197 offset:6144
	ds_read_b128 v[228:231], v197 offset:7168
	global_load_lds_dwordx4 v[194:195], off
	v_lshl_add_u64 v[194:195], s[38:39], 0, v[178:179]
	s_add_i32 m0, s55, 0xe000
	s_nop 0
	global_load_lds_dwordx4 v[194:195], off
	s_waitcnt vmcnt(8)
	s_waitcnt lgkmcnt(0)
	s_barrier
; #define PG8_STAGE(bufoff, gbase, voff) do { _Pragma("unroll") for (int _i = 0; _i < 2; ++_i) \
;         __builtin_amdgcn_global_load_lds((const unsigned*)((const char*)(gbase) + (voff)[_i]), (PG8_LAS unsigned*)(lds + (bufoff) + ldsw + _i * 8192), 16, 0, 0); } while (0)
; #define PG8_LDA(dst, b, h) do { _Pragma("unroll") for (int m = 0; m < 4; ++m) _Pragma("unroll") for (int k = 0; k < 2; ++k) dst[m][k] = *(const PG8_LAS bf16x8*)(lds + PG8_SA(b, h) + aoff + m * 2048 + k * 1024); } while (0)
; #define PG8_MMA(ai, bj, At, Bt) do { __builtin_amdgcn_s_setprio(1); _Pragma("unroll") for (int m = 0; m < 4; ++m) _Pragma("unroll") for (int n = 0; n < 2; ++n) _Pragma("unroll") for (int k = 0; k < 2; ++k) \
;         acc[ai][bj][m][n] = __builtin_amdgcn_mfma_f32_16x16x32_bf16(Bt[n][k], At[m][k], acc[ai][bj][m][n], 0, 0, 0); __builtin_amdgcn_s_setprio(0); } while (0)
; #define PG8_WAIT_V(n) asm volatile("s_waitcnt vmcnt(" #n ")" ::: "memory")
; #define PG8_WAIT_L(n) asm volatile("s_waitcnt lgkmcnt(" #n ")" ::: "memory")
; #define PG8_BAR __builtin_amdgcn_s_barrier()
; #define PG8_SCHED __builtin_amdgcn_sched_barrier(0)
; template <class Epi, class Sched, bool ALIGN_EPI = false, bool SP2 = false>
; __device__ __forceinline__ void gemm_phase(PG8_LAS unsigned char* lds, const Gemm g, const Sched& S, const Epi& E, const int tid) {
;     ...
;             PG8_WAIT_V(8); PG8_WAIT_L(0); PG8_BAR; PG8_MMA(0, 0, At, B0); PG8_MMA(0, 1, At, B1); PG8_BAR; PG8_SCHED;
;             PG8_LDA(At, 0, 1); PG8_STAGE(PG8_SB(0, 0), b2, voffB); PG8_STAGE(PG8_SB(0, 1), b2 + hstep, voffB); PG8_STAGE(PG8_SA(0, 0), a2, voffA);
;             PG8_WAIT_V(8); PG8_WAIT_L(0); PG8_BAR; PG8_MMA(1, 0, At, B0); PG8_MMA(1, 1, At, B1); PG8_BAR; PG8_SCHED;
	s_setprio 1
	s_waitcnt lgkmcnt(0)
	v_mfma_f32_16x16x32_bf16 v[126:129], v[130:133], v[186:189], v[126:129]
	v_mfma_f32_16x16x32_bf16 v[122:125], v[138:141], v[186:189], v[122:125]
	v_mfma_f32_16x16x32_bf16 v[106:109], v[138:141], v[206:209], v[106:109]
	v_mfma_f32_16x16x32_bf16 v[110:113], v[130:133], v[206:209], v[110:113]
	v_mfma_f32_16x16x32_bf16 v[94:97], v[130:133], v[216:219], v[94:97]
	v_mfma_f32_16x16x32_bf16 v[90:93], v[138:141], v[216:219], v[90:93]
	v_mfma_f32_16x16x32_bf16 v[74:77], v[138:141], v[224:227], v[74:77]
	v_mfma_f32_16x16x32_bf16 v[78:81], v[130:133], v[224:227], v[78:81]
	v_mfma_f32_16x16x32_bf16 v[126:129], v[134:137], v[198:201], v[126:129]
	v_mfma_f32_16x16x32_bf16 v[122:125], v[142:145], v[198:201], v[122:125]
	v_mfma_f32_16x16x32_bf16 v[106:109], v[142:145], v[212:215], v[106:109]
	v_mfma_f32_16x16x32_bf16 v[110:113], v[134:137], v[212:215], v[110:113]
	v_mfma_f32_16x16x32_bf16 v[94:97], v[134:137], v[220:223], v[94:97]
	v_mfma_f32_16x16x32_bf16 v[90:93], v[142:145], v[220:223], v[90:93]
	v_mfma_f32_16x16x32_bf16 v[74:77], v[142:145], v[228:231], v[74:77]
	v_mfma_f32_16x16x32_bf16 v[78:81], v[134:137], v[228:231], v[78:81]
	s_setprio 0
	s_setprio 1
	v_mfma_f32_16x16x32_bf16 v[118:121], v[146:149], v[186:189], v[118:121]
	v_mfma_f32_16x16x32_bf16 v[114:117], v[154:157], v[186:189], v[114:117]
	v_mfma_f32_16x16x32_bf16 v[98:101], v[154:157], v[206:209], v[98:101]
	v_mfma_f32_16x16x32_bf16 v[102:105], v[146:149], v[206:209], v[102:105]
	v_mfma_f32_16x16x32_bf16 v[86:89], v[146:149], v[216:219], v[86:89]
	v_mfma_f32_16x16x32_bf16 v[82:85], v[154:157], v[216:219], v[82:85]
	v_mfma_f32_16x16x32_bf16 v[66:69], v[154:157], v[224:227], v[66:69]
	v_mfma_f32_16x16x32_bf16 v[70:73], v[146:149], v[224:227], v[70:73]
	v_mfma_f32_16x16x32_bf16 v[118:121], v[150:153], v[198:201], v[118:121]
	v_mfma_f32_16x16x32_bf16 v[114:117], v[158:161], v[198:201], v[114:117]
	v_mfma_f32_16x16x32_bf16 v[98:101], v[158:161], v[212:215], v[98:101]
	v_mfma_f32_16x16x32_bf16 v[102:105], v[150:153], v[212:215], v[102:105]
	v_mfma_f32_16x16x32_bf16 v[86:89], v[150:153], v[220:223], v[86:89]
	v_mfma_f32_16x16x32_bf16 v[82:85], v[158:161], v[220:223], v[82:85]
	v_mfma_f32_16x16x32_bf16 v[66:69], v[158:161], v[228:231], v[66:69]
	v_mfma_f32_16x16x32_bf16 v[70:73], v[150:153], v[228:231], v[70:73]
	s_setprio 0
	s_barrier
	s_add_i32 s15, s66, s54
	v_lshl_add_u64 v[194:195], s[40:41], 0, v[164:165]
	s_mov_b32 m0, s15
	ds_read_b128 v[186:189], v197 offset:16384
	ds_read_b128 v[198:201], v197 offset:17408
	ds_read_b128 v[206:209], v197 offset:18432
	ds_read_b128 v[212:215], v197 offset:19456
	ds_read_b128 v[216:219], v197 offset:20480
	ds_read_b128 v[220:223], v197 offset:21504
	ds_read_b128 v[224:227], v197 offset:22528
	ds_read_b128 v[228:231], v197 offset:23552
	global_load_lds_dwordx4 v[194:195], off
	s_add_i32 m0, s15, 0x2000
	s_add_u32 s18, s40, 0x40000
	v_lshl_add_u64 v[232:233], s[40:41], 0, v[168:169]
	s_addc_u32 s19, s41, 0
	s_add_i32 s15, s67, s54
	global_load_lds_dwordx4 v[232:233], off
	v_lshl_add_u64 v[234:235], s[18:19], 0, v[164:165]
	s_mov_b32 m0, s15
	v_lshl_add_u64 v[236:237], s[42:43], 0, v[166:167]
	global_load_lds_dwordx4 v[234:235], off
	v_lshl_add_u64 v[234:235], s[18:19], 0, v[168:169]
	s_add_i32 m0, s15, 0x2000
	s_nop 0
	global_load_lds_dwordx4 v[234:235], off
	v_lshl_add_u64 v[234:235], s[42:43], 0, v[162:163]
	s_mov_b32 m0, s55
	s_nop 0
	global_load_lds_dwordx4 v[234:235], off
	s_mov_b32 m0, s56
	s_nop 0
	global_load_lds_dwordx4 v[236:237], off
	s_waitcnt vmcnt(8)
	s_waitcnt lgkmcnt(0)
	s_barrier
	s_setprio 1
	s_waitcnt lgkmcnt(0)
	v_mfma_f32_16x16x32_bf16 v[62:65], v[130:133], v[186:189], v[62:65]
	v_mfma_f32_16x16x32_bf16 v[58:61], v[138:141], v[186:189], v[58:61]
	v_mfma_f32_16x16x32_bf16 v[42:45], v[138:141], v[206:209], v[42:45]
	v_mfma_f32_16x16x32_bf16 v[46:49], v[130:133], v[206:209], v[46:49]
	v_mfma_f32_16x16x32_bf16 v[30:33], v[130:133], v[216:219], v[30:33]
	v_mfma_f32_16x16x32_bf16 v[26:29], v[138:141], v[216:219], v[26:29]
	v_mfma_f32_16x16x32_bf16 v[10:13], v[138:141], v[224:227], v[10:13]
	v_mfma_f32_16x16x32_bf16 v[14:17], v[130:133], v[224:227], v[14:17]
	v_mfma_f32_16x16x32_bf16 v[62:65], v[134:137], v[198:201], v[62:65]
	v_mfma_f32_16x16x32_bf16 v[58:61], v[142:145], v[198:201], v[58:61]
	v_mfma_f32_16x16x32_bf16 v[42:45], v[142:145], v[212:215], v[42:45]
	v_mfma_f32_16x16x32_bf16 v[46:49], v[134:137], v[212:215], v[46:49]
	v_mfma_f32_16x16x32_bf16 v[30:33], v[134:137], v[220:223], v[30:33]
	v_mfma_f32_16x16x32_bf16 v[26:29], v[142:145], v[220:223], v[26:29]
	v_mfma_f32_16x16x32_bf16 v[10:13], v[142:145], v[228:231], v[10:13]
	v_mfma_f32_16x16x32_bf16 v[14:17], v[134:137], v[228:231], v[14:17]
	s_setprio 0
	s_setprio 1
	v_mfma_f32_16x16x32_bf16 v[54:57], v[146:149], v[186:189], v[54:57]
	v_mfma_f32_16x16x32_bf16 v[50:53], v[154:157], v[186:189], v[50:53]
	v_mfma_f32_16x16x32_bf16 v[34:37], v[154:157], v[206:209], v[34:37]
	v_mfma_f32_16x16x32_bf16 v[38:41], v[146:149], v[206:209], v[38:41]
	v_mfma_f32_16x16x32_bf16 v[22:25], v[146:149], v[216:219], v[22:25]
	v_mfma_f32_16x16x32_bf16 v[18:21], v[154:157], v[216:219], v[18:21]
	v_mfma_f32_16x16x32_bf16 v[2:5], v[154:157], v[224:227], v[2:5]
	v_mfma_f32_16x16x32_bf16 v[6:9], v[146:149], v[224:227], v[6:9]
	v_mfma_f32_16x16x32_bf16 v[54:57], v[150:153], v[198:201], v[54:57]
	v_mfma_f32_16x16x32_bf16 v[50:53], v[158:161], v[198:201], v[50:53]
	v_mfma_f32_16x16x32_bf16 v[34:37], v[158:161], v[212:215], v[34:37]
	v_mfma_f32_16x16x32_bf16 v[38:41], v[150:153], v[212:215], v[38:41]
	v_mfma_f32_16x16x32_bf16 v[22:25], v[150:153], v[220:223], v[22:25]
	v_mfma_f32_16x16x32_bf16 v[18:21], v[158:161], v[220:223], v[18:21]
	v_mfma_f32_16x16x32_bf16 v[2:5], v[158:161], v[228:231], v[2:5]
	v_mfma_f32_16x16x32_bf16 v[6:9], v[150:153], v[228:231], v[6:9]
	s_setprio 0
	s_barrier
; #define PG8_STAGE(bufoff, gbase, voff) do { _Pragma("unroll") for (int _i = 0; _i < 2; ++_i) \
;         __builtin_amdgcn_global_load_lds((const unsigned*)((const char*)(gbase) + (voff)[_i]), (PG8_LAS unsigned*)(lds + (bufoff) + ldsw + _i * 8192), 16, 0, 0); } while (0)
; #define PG8_LDA(dst, b, h) do { _Pragma("unroll") for (int m = 0; m < 4; ++m) _Pragma("unroll") for (int k = 0; k < 2; ++k) dst[m][k] = *(const PG8_LAS bf16x8*)(lds + PG8_SA(b, h) + aoff + m * 2048 + k * 1024); } while (0)
; #define PG8_LDB(dst, b, h) do { _Pragma("unroll") for (int n = 0; n < 2; ++n) _Pragma("unroll") for (int k = 0; k < 2; ++k) dst[n][k] = *(const PG8_LAS bf16x8*)(lds + PG8_SB(b, h) + boff + n * 2048 + k * 1024); } while (0)
; #define PG8_MMA(ai, bj, At, Bt) do { __builtin_amdgcn_s_setprio(1); _Pragma("unroll") for (int m = 0; m < 4; ++m) _Pragma("unroll") for (int n = 0; n < 2; ++n) _Pragma("unroll") for (int k = 0; k < 2; ++k) \
;         acc[ai][bj][m][n] = __builtin_amdgcn_mfma_f32_16x16x32_bf16(Bt[n][k], At[m][k], acc[ai][bj][m][n], 0, 0, 0); __builtin_amdgcn_s_setprio(0); } while (0)
; #define PG8_WAIT_V(n) asm volatile("s_waitcnt vmcnt(" #n ")" ::: "memory")
; #define PG8_WAIT_L(n) asm volatile("s_waitcnt lgkmcnt(" #n ")" ::: "memory")
; #define PG8_BAR __builtin_amdgcn_s_barrier()
; #define PG8_SCHED __builtin_amdgcn_sched_barrier(0)
; template <class Epi, class Sched, bool ALIGN_EPI = false, bool SP2 = false>
; __device__ __forceinline__ void gemm_phase(PG8_LAS unsigned char* lds, const Gemm g, const Sched& S, const Epi& E, const int tid) {
;     ...
;             PG8_LDB(B0, 1, 0); PG8_LDB(B1, 1, 1); PG8_SCHED; PG8_LDA(At, 1, 0); PG8_STAGE(PG8_SA(0, 1), a2 + hstep, voffA);
;             PG8_WAIT_V(8); PG8_WAIT_L(0); PG8_BAR; PG8_MMA(0, 0, At, B0); PG8_MMA(0, 1, At, B1); PG8_BAR; PG8_SCHED;
	s_add_i32 s15, 0, 0x18000
	s_add_i32 s83, 0, 0x1c000
	v_add_u32_e32 v142, s15, v173
	v_add_u32_e32 v158, s83, v173
	ds_read_b128 v[130:133], v142
	ds_read_b128 v[134:137], v142 offset:1024
	ds_read_b128 v[138:141], v142 offset:2048
	ds_read_b128 v[142:145], v142 offset:3072
	ds_read_b128 v[146:149], v158
	ds_read_b128 v[150:153], v158 offset:1024
	ds_read_b128 v[154:157], v158 offset:2048
	ds_read_b128 v[158:161], v158 offset:3072
	s_add_u32 s18, s42, 0x40000
	s_addc_u32 s19, s43, 0
	s_mov_b32 m0, s57
	v_lshl_add_u64 v[238:239], s[18:19], 0, v[162:163]
	ds_read_b128 v[186:189], v197 offset:32768
	ds_read_b128 v[198:201], v197 offset:33792
	ds_read_b128 v[206:209], v197 offset:34816
	ds_read_b128 v[212:215], v197 offset:35840
	ds_read_b128 v[216:219], v197 offset:36864
	ds_read_b128 v[220:223], v197 offset:37888
	ds_read_b128 v[224:227], v197 offset:38912
	ds_read_b128 v[228:231], v197 offset:39936
	global_load_lds_dwordx4 v[238:239], off
	v_lshl_add_u64 v[238:239], s[18:19], 0, v[166:167]
	s_mov_b32 m0, s58
	s_nop 0
	global_load_lds_dwordx4 v[238:239], off
	s_waitcnt vmcnt(8)
	s_waitcnt lgkmcnt(0)
	s_barrier
	s_setprio 1
	s_waitcnt lgkmcnt(0)
	v_mfma_f32_16x16x32_bf16 v[126:129], v[130:133], v[186:189], v[126:129]
	v_mfma_f32_16x16x32_bf16 v[122:125], v[138:141], v[186:189], v[122:125]
	v_mfma_f32_16x16x32_bf16 v[106:109], v[138:141], v[206:209], v[106:109]
	v_mfma_f32_16x16x32_bf16 v[110:113], v[130:133], v[206:209], v[110:113]
	v_mfma_f32_16x16x32_bf16 v[94:97], v[130:133], v[216:219], v[94:97]
	v_mfma_f32_16x16x32_bf16 v[90:93], v[138:141], v[216:219], v[90:93]
	v_mfma_f32_16x16x32_bf16 v[74:77], v[138:141], v[224:227], v[74:77]
	v_mfma_f32_16x16x32_bf16 v[78:81], v[130:133], v[224:227], v[78:81]
	v_mfma_f32_16x16x32_bf16 v[126:129], v[134:137], v[198:201], v[126:129]
	v_mfma_f32_16x16x32_bf16 v[122:125], v[142:145], v[198:201], v[122:125]
	v_mfma_f32_16x16x32_bf16 v[106:109], v[142:145], v[212:215], v[106:109]
	v_mfma_f32_16x16x32_bf16 v[110:113], v[134:137], v[212:215], v[110:113]
	v_mfma_f32_16x16x32_bf16 v[94:97], v[134:137], v[220:223], v[94:97]
	v_mfma_f32_16x16x32_bf16 v[90:93], v[142:145], v[220:223], v[90:93]
	v_mfma_f32_16x16x32_bf16 v[74:77], v[142:145], v[228:231], v[74:77]
	v_mfma_f32_16x16x32_bf16 v[78:81], v[134:137], v[228:231], v[78:81]
	s_setprio 0
	s_setprio 1
	v_mfma_f32_16x16x32_bf16 v[118:121], v[146:149], v[186:189], v[118:121]
	v_mfma_f32_16x16x32_bf16 v[114:117], v[154:157], v[186:189], v[114:117]
	v_mfma_f32_16x16x32_bf16 v[98:101], v[154:157], v[206:209], v[98:101]
	v_mfma_f32_16x16x32_bf16 v[102:105], v[146:149], v[206:209], v[102:105]
	v_mfma_f32_16x16x32_bf16 v[86:89], v[146:149], v[216:219], v[86:89]
	v_mfma_f32_16x16x32_bf16 v[82:85], v[154:157], v[216:219], v[82:85]
	v_mfma_f32_16x16x32_bf16 v[66:69], v[154:157], v[224:227], v[66:69]
	v_mfma_f32_16x16x32_bf16 v[70:73], v[146:149], v[224:227], v[70:73]
	v_mfma_f32_16x16x32_bf16 v[118:121], v[150:153], v[198:201], v[118:121]
	v_mfma_f32_16x16x32_bf16 v[114:117], v[158:161], v[198:201], v[114:117]
	v_mfma_f32_16x16x32_bf16 v[98:101], v[158:161], v[212:215], v[98:101]
	v_mfma_f32_16x16x32_bf16 v[102:105], v[150:153], v[212:215], v[102:105]
	v_mfma_f32_16x16x32_bf16 v[86:89], v[150:153], v[220:223], v[86:89]
	v_mfma_f32_16x16x32_bf16 v[82:85], v[158:161], v[220:223], v[82:85]
	v_mfma_f32_16x16x32_bf16 v[66:69], v[158:161], v[228:231], v[66:69]
	v_mfma_f32_16x16x32_bf16 v[70:73], v[150:153], v[228:231], v[70:73]
	s_setprio 0
	s_barrier
; #define PG8_STAGE(bufoff, gbase, voff) do { _Pragma("unroll") for (int _i = 0; _i < 2; ++_i) \
;         __builtin_amdgcn_global_load_lds((const unsigned*)((const char*)(gbase) + (voff)[_i]), (PG8_LAS unsigned*)(lds + (bufoff) + ldsw + _i * 8192), 16, 0, 0); } while (0)
; #define PG8_LDA(dst, b, h) do { _Pragma("unroll") for (int m = 0; m < 4; ++m) _Pragma("unroll") for (int k = 0; k < 2; ++k) dst[m][k] = *(const PG8_LAS bf16x8*)(lds + PG8_SA(b, h) + aoff + m * 2048 + k * 1024); } while (0)
; #define PG8_MMA(ai, bj, At, Bt) do { __builtin_amdgcn_s_setprio(1); _Pragma("unroll") for (int m = 0; m < 4; ++m) _Pragma("unroll") for (int n = 0; n < 2; ++n) _Pragma("unroll") for (int k = 0; k < 2; ++k) \
;         acc[ai][bj][m][n] = __builtin_amdgcn_mfma_f32_16x16x32_bf16(Bt[n][k], At[m][k], acc[ai][bj][m][n], 0, 0, 0); __builtin_amdgcn_s_setprio(0); } while (0)
; #define PG8_WAIT_V(n) asm volatile("s_waitcnt vmcnt(" #n ")" ::: "memory")
; #define PG8_WAIT_L(n) asm volatile("s_waitcnt lgkmcnt(" #n ")" ::: "memory")
; #define PG8_BAR __builtin_amdgcn_s_barrier()
; #define PG8_SCHED __builtin_amdgcn_sched_barrier(0)
; template <class Epi, class Sched, bool ALIGN_EPI = false, bool SP2 = false>
; __device__ __forceinline__ void gemm_phase(PG8_LAS unsigned char* lds, const Gemm g, const Sched& S, const Epi& E, const int tid) {
;     ...
;             PG8_LDA(At, 1, 1); PG8_STAGE(PG8_SB(1, 0), b3, voffB); PG8_STAGE(PG8_SB(1, 1), b3 + hstep, voffB); PG8_STAGE(PG8_SA(1, 0), a3, voffA);
;             PG8_WAIT_V(8); PG8_WAIT_L(0); PG8_BAR; PG8_MMA(1, 0, At, B0); PG8_MMA(1, 1, At, B1); PG8_BAR; PG8_SCHED;
;     ...
;         if constexpr (ALIGN_EPI) { if (wr == 0) PG8_BAR; }
	s_add_i32 s15, s15, s54
	v_lshl_add_u64 v[194:195], v[194:195], 0, s[10:11]
	s_mov_b32 m0, s15
	ds_read_b128 v[186:189], v197 offset:49152
	ds_read_b128 v[198:201], v197 offset:50176
	ds_read_b128 v[206:209], v197 offset:51200
	ds_read_b128 v[212:215], v197 offset:52224
	ds_read_b128 v[216:219], v197 offset:53248
	ds_read_b128 v[220:223], v197 offset:54272
	ds_read_b128 v[224:227], v197 offset:55296
	ds_read_b128 v[228:231], v197 offset:56320
	global_load_lds_dwordx4 v[194:195], off
	s_add_i32 m0, s15, 0x2000
	s_add_u32 s18, s40, 0x40080
	v_lshl_add_u64 v[194:195], v[232:233], 0, s[10:11]
	s_addc_u32 s19, s41, 0
	s_add_i32 s15, s83, s54
	global_load_lds_dwordx4 v[194:195], off
	v_lshl_add_u64 v[194:195], s[18:19], 0, v[164:165]
	s_mov_b32 m0, s15
	s_nop 0
	global_load_lds_dwordx4 v[194:195], off
	v_lshl_add_u64 v[194:195], s[18:19], 0, v[168:169]
	s_add_i32 m0, s15, 0x2000
	s_nop 0
	global_load_lds_dwordx4 v[194:195], off
	v_lshl_add_u64 v[194:195], v[234:235], 0, s[10:11]
	s_mov_b32 m0, s61
	s_nop 0
	global_load_lds_dwordx4 v[194:195], off
	v_lshl_add_u64 v[194:195], v[236:237], 0, s[10:11]
	s_mov_b32 m0, s62
	s_nop 0
	global_load_lds_dwordx4 v[194:195], off
	s_waitcnt vmcnt(8)
	s_waitcnt lgkmcnt(0)
	s_barrier
	s_setprio 1
	s_waitcnt lgkmcnt(0)
	v_mfma_f32_16x16x32_bf16 v[62:65], v[130:133], v[186:189], v[62:65]
	v_mfma_f32_16x16x32_bf16 v[58:61], v[138:141], v[186:189], v[58:61]
	v_mfma_f32_16x16x32_bf16 v[42:45], v[138:141], v[206:209], v[42:45]
	v_mfma_f32_16x16x32_bf16 v[46:49], v[130:133], v[206:209], v[46:49]
	v_mfma_f32_16x16x32_bf16 v[30:33], v[130:133], v[216:219], v[30:33]
	v_mfma_f32_16x16x32_bf16 v[26:29], v[138:141], v[216:219], v[26:29]
	v_mfma_f32_16x16x32_bf16 v[10:13], v[138:141], v[224:227], v[10:13]
	v_mfma_f32_16x16x32_bf16 v[14:17], v[130:133], v[224:227], v[14:17]
	v_mfma_f32_16x16x32_bf16 v[62:65], v[134:137], v[198:201], v[62:65]
	v_mfma_f32_16x16x32_bf16 v[58:61], v[142:145], v[198:201], v[58:61]
	v_mfma_f32_16x16x32_bf16 v[42:45], v[142:145], v[212:215], v[42:45]
	v_mfma_f32_16x16x32_bf16 v[46:49], v[134:137], v[212:215], v[46:49]
	v_mfma_f32_16x16x32_bf16 v[30:33], v[134:137], v[220:223], v[30:33]
	v_mfma_f32_16x16x32_bf16 v[26:29], v[142:145], v[220:223], v[26:29]
	v_mfma_f32_16x16x32_bf16 v[10:13], v[142:145], v[228:231], v[10:13]
	v_mfma_f32_16x16x32_bf16 v[14:17], v[134:137], v[228:231], v[14:17]
	s_setprio 0
	s_setprio 1
	v_mfma_f32_16x16x32_bf16 v[54:57], v[146:149], v[186:189], v[54:57]
	v_mfma_f32_16x16x32_bf16 v[50:53], v[154:157], v[186:189], v[50:53]
	v_mfma_f32_16x16x32_bf16 v[34:37], v[154:157], v[206:209], v[34:37]
	v_mfma_f32_16x16x32_bf16 v[38:41], v[146:149], v[206:209], v[38:41]
	v_mfma_f32_16x16x32_bf16 v[22:25], v[146:149], v[216:219], v[22:25]
	v_mfma_f32_16x16x32_bf16 v[18:21], v[154:157], v[216:219], v[18:21]
	v_mfma_f32_16x16x32_bf16 v[2:5], v[154:157], v[224:227], v[2:5]
	v_mfma_f32_16x16x32_bf16 v[6:9], v[146:149], v[224:227], v[6:9]
	v_mfma_f32_16x16x32_bf16 v[54:57], v[150:153], v[198:201], v[54:57]
	v_mfma_f32_16x16x32_bf16 v[50:53], v[158:161], v[198:201], v[50:53]
	v_mfma_f32_16x16x32_bf16 v[34:37], v[158:161], v[212:215], v[34:37]
	v_mfma_f32_16x16x32_bf16 v[38:41], v[150:153], v[212:215], v[38:41]
	v_mfma_f32_16x16x32_bf16 v[22:25], v[150:153], v[220:223], v[22:25]
	v_mfma_f32_16x16x32_bf16 v[18:21], v[158:161], v[220:223], v[18:21]
	v_mfma_f32_16x16x32_bf16 v[2:5], v[158:161], v[228:231], v[2:5]
	v_mfma_f32_16x16x32_bf16 v[6:9], v[150:153], v[228:231], v[6:9]
	s_setprio 0
	s_barrier
	s_add_i32 s82, s82, 2
	s_add_u32 s80, s80, 0x100
	s_addc_u32 s81, s81, 0
	s_add_u32 s38, s38, 0x100
	s_addc_u32 s39, s39, 0
	s_cmp_gt_u32 s82, 13
	s_cbranch_scc0 .LBB0_733
	s_and_b64 vcc, exec, s[24:25]
	s_cbranch_vccz .LBB0_736
	s_barrier

; #define PG8_STAGE(bufoff, gbase, voff) do { _Pragma("unroll") for (int _i = 0; _i < 2; ++_i) \
;         __builtin_amdgcn_global_load_lds((const unsigned*)((const char*)(gbase) + (voff)[_i]), (PG8_LAS unsigned*)(lds + (bufoff) + ldsw + _i * 8192), 16, 0, 0); } while (0)
; #define PG8_LDA(dst, b, h) do { _Pragma("unroll") for (int m = 0; m < 4; ++m) _Pragma("unroll") for (int k = 0; k < 2; ++k) dst[m][k] = *(const PG8_LAS bf16x8*)(lds + PG8_SA(b, h) + aoff + m * 2048 + k * 1024); } while (0)
; #define PG8_LDB(dst, b, h) do { _Pragma("unroll") for (int n = 0; n < 2; ++n) _Pragma("unroll") for (int k = 0; k < 2; ++k) dst[n][k] = *(const PG8_LAS bf16x8*)(lds + PG8_SB(b, h) + boff + n * 2048 + k * 1024); } while (0)
; #define PG8_MMA(ai, bj, At, Bt) do { __builtin_amdgcn_s_setprio(1); _Pragma("unroll") for (int m = 0; m < 4; ++m) _Pragma("unroll") for (int n = 0; n < 2; ++n) _Pragma("unroll") for (int k = 0; k < 2; ++k) \
;         acc[ai][bj][m][n] = __builtin_amdgcn_mfma_f32_16x16x32_bf16(Bt[n][k], At[m][k], acc[ai][bj][m][n], 0, 0, 0); __builtin_amdgcn_s_setprio(0); } while (0)
; #define PG8_WAIT_V(n) asm volatile("s_waitcnt vmcnt(" #n ")" ::: "memory")
; #define PG8_WAIT_L(n) asm volatile("s_waitcnt lgkmcnt(" #n ")" ::: "memory")
; #define PG8_BAR __builtin_amdgcn_s_barrier()
; template <class Epi, class Sched, bool ALIGN_EPI = false, bool SP2 = false>
; __device__ __forceinline__ void gemm_phase(PG8_LAS unsigned char* lds, const Gemm g, const Sched& S, const Epi& E, const int tid) {
;     ...
;         for (int t = 0; t < nt; t += 2) {
;             const bool last = (t == nt - 2);
;             const char* a1 = cA + (size_t)(t + 1) * kstep;
;             const char* a2 = last ? nA : cA + (size_t)(t + 2) * kstep; const char* b2 = last ? nB : cB + (size_t)(t + 2) * kstep;
;             const char* a3 = a2 + kstep; const char* b3 = b2 + kstep;
;             if (last && has_next) S.a_ready(nxt);
;             if constexpr (SP2) {
;             PG8_LDB(B0, 0, 0); PG8_LDB(B1, 0, 1); PG8_SCHED; PG8_LDA(At, 0, 0); PG8_STAGE(PG8_SA(1, 1), a1 + hstep, voffA);
;             PG8_WAIT_V(8); PG8_WAIT_L(0); PG8_BAR; PG8_MMA(0, 0, At, B0); PG8_MMA(0, 1, At, B1); PG8_BAR; PG8_SCHED;
;             PG8_LDA(At, 0, 1); PG8_STAGE(PG8_SB(0, 0), b2, voffB); PG8_STAGE(PG8_SB(0, 1), b2 + hstep, voffB); PG8_STAGE(PG8_SA(0, 0), a2, voffA);
.LBB0_1121:
	s_add_u32 s5, s56, 0x100
	s_addc_u32 s49, s57, 0
	s_add_u32 s56, s58, 0x40080
	s_addc_u32 s57, s59, 0
	s_mov_b32 s51, -2
	ds_read_b128 v[130:133], v139
	ds_read_b128 v[134:137], v139 offset:1024
	ds_read_b128 v[162:165], v139 offset:2048
	ds_read_b128 v[166:169], v139 offset:3072
	ds_read_b128 v[176:179], v173
	ds_read_b128 v[180:183], v173 offset:1024
	ds_read_b128 v[184:187], v173 offset:2048
	ds_read_b128 v[192:195], v173 offset:3072
	s_add_u32 s15, s56, 0xfffc0080
	s_addc_u32 s18, s57, -1
	s_cmp_eq_u32 s51, 12
	s_cselect_b32 s61, s1, s18
	s_cselect_b32 s60, s0, s15
	s_cselect_b32 s59, s53, s49
	s_cselect_b32 s58, s52, s5
	v_lshl_add_u64 v[170:171], s[56:57], 0, v[156:157]
	s_add_i32 m0, s67, 0xc000
	ds_read_b128 v[196:199], v174
	ds_read_b128 v[200:203], v174 offset:1024
	ds_read_b128 v[204:207], v174 offset:2048
	ds_read_b128 v[208:211], v174 offset:3072
	ds_read_b128 v[212:215], v174 offset:4096
	ds_read_b128 v[216:219], v174 offset:5120
	ds_read_b128 v[220:223], v174 offset:6144
	ds_read_b128 v[224:227], v174 offset:7168
	global_load_lds_dwordx4 v[170:171], off
	v_lshl_add_u64 v[170:171], s[56:57], 0, v[154:155]
	s_add_i32 m0, s67, 0xe000
	s_nop 0
	global_load_lds_dwordx4 v[170:171], off
	s_waitcnt vmcnt(8)
	s_waitcnt lgkmcnt(0)
	s_barrier
	s_setprio 1
	s_waitcnt lgkmcnt(0)
	v_mfma_f32_16x16x32_bf16 v[126:129], v[130:133], v[196:199], 0
	v_mfma_f32_16x16x32_bf16 v[122:125], v[162:165], v[196:199], 0
	v_mfma_f32_16x16x32_bf16 v[106:109], v[162:165], v[204:207], 0
	v_mfma_f32_16x16x32_bf16 v[110:113], v[130:133], v[204:207], 0
	v_mfma_f32_16x16x32_bf16 v[94:97], v[130:133], v[212:215], 0
	v_mfma_f32_16x16x32_bf16 v[90:93], v[162:165], v[212:215], 0
	v_mfma_f32_16x16x32_bf16 v[74:77], v[162:165], v[220:223], 0
	v_mfma_f32_16x16x32_bf16 v[78:81], v[130:133], v[220:223], 0
	v_mfma_f32_16x16x32_bf16 v[126:129], v[134:137], v[200:203], v[126:129]
	v_mfma_f32_16x16x32_bf16 v[122:125], v[166:169], v[200:203], v[122:125]
	v_mfma_f32_16x16x32_bf16 v[106:109], v[166:169], v[208:211], v[106:109]
	v_mfma_f32_16x16x32_bf16 v[110:113], v[134:137], v[208:211], v[110:113]
	v_mfma_f32_16x16x32_bf16 v[94:97], v[134:137], v[216:219], v[94:97]
	v_mfma_f32_16x16x32_bf16 v[90:93], v[166:169], v[216:219], v[90:93]
	v_mfma_f32_16x16x32_bf16 v[74:77], v[166:169], v[224:227], v[74:77]
	v_mfma_f32_16x16x32_bf16 v[78:81], v[134:137], v[224:227], v[78:81]
	s_setprio 0
	s_setprio 1
	v_mfma_f32_16x16x32_bf16 v[118:121], v[176:179], v[196:199], 0
	v_mfma_f32_16x16x32_bf16 v[114:117], v[184:187], v[196:199], 0
	v_mfma_f32_16x16x32_bf16 v[98:101], v[184:187], v[204:207], 0
	v_mfma_f32_16x16x32_bf16 v[102:105], v[176:179], v[204:207], 0
	v_mfma_f32_16x16x32_bf16 v[86:89], v[176:179], v[212:215], 0
	v_mfma_f32_16x16x32_bf16 v[82:85], v[184:187], v[212:215], 0
	v_mfma_f32_16x16x32_bf16 v[66:69], v[184:187], v[220:223], 0
	v_mfma_f32_16x16x32_bf16 v[70:73], v[176:179], v[220:223], 0
	v_mfma_f32_16x16x32_bf16 v[118:121], v[180:183], v[200:203], v[118:121]
	v_mfma_f32_16x16x32_bf16 v[114:117], v[192:195], v[200:203], v[114:117]
	v_mfma_f32_16x16x32_bf16 v[98:101], v[192:195], v[208:211], v[98:101]
	v_mfma_f32_16x16x32_bf16 v[102:105], v[180:183], v[208:211], v[102:105]
	v_mfma_f32_16x16x32_bf16 v[86:89], v[180:183], v[216:219], v[86:89]
	v_mfma_f32_16x16x32_bf16 v[82:85], v[192:195], v[216:219], v[82:85]
	v_mfma_f32_16x16x32_bf16 v[66:69], v[192:195], v[224:227], v[66:69]
	v_mfma_f32_16x16x32_bf16 v[70:73], v[180:183], v[224:227], v[70:73]
	s_setprio 0
	s_barrier
	s_add_i32 s15, s86, s66
	v_lshl_add_u64 v[170:171], s[58:59], 0, v[142:143]
	s_mov_b32 m0, s15
	ds_read_b128 v[196:199], v174 offset:16384
	ds_read_b128 v[200:203], v174 offset:17408
	ds_read_b128 v[204:207], v174 offset:18432
	ds_read_b128 v[208:211], v174 offset:19456
	ds_read_b128 v[212:215], v174 offset:20480
	ds_read_b128 v[216:219], v174 offset:21504
	ds_read_b128 v[220:223], v174 offset:22528
	ds_read_b128 v[224:227], v174 offset:23552
	global_load_lds_dwordx4 v[170:171], off
	s_add_i32 m0, s15, 0x2000
	s_add_u32 s18, s58, 0x40000
	v_lshl_add_u64 v[188:189], s[58:59], 0, v[146:147]
	s_addc_u32 s19, s59, 0
	s_add_i32 s15, s87, s66
	global_load_lds_dwordx4 v[188:189], off
	v_lshl_add_u64 v[228:229], s[18:19], 0, v[142:143]
	s_mov_b32 m0, s15
	v_lshl_add_u64 v[230:231], s[60:61], 0, v[144:145]
	global_load_lds_dwordx4 v[228:229], off
	v_lshl_add_u64 v[228:229], s[18:19], 0, v[146:147]
	s_add_i32 m0, s15, 0x2000
	s_nop 0
	global_load_lds_dwordx4 v[228:229], off
	v_lshl_add_u64 v[228:229], s[60:61], 0, v[140:141]
	s_mov_b32 m0, s67
	s_nop 0
	global_load_lds_dwordx4 v[228:229], off
	s_mov_b32 m0, s68
	s_nop 0
	global_load_lds_dwordx4 v[230:231], off
	s_waitcnt vmcnt(8)
	s_waitcnt lgkmcnt(0)
	s_barrier
; #define PG8_STAGE(bufoff, gbase, voff) do { _Pragma("unroll") for (int _i = 0; _i < 2; ++_i) \
;         __builtin_amdgcn_global_load_lds((const unsigned*)((const char*)(gbase) + (voff)[_i]), (PG8_LAS unsigned*)(lds + (bufoff) + ldsw + _i * 8192), 16, 0, 0); } while (0)
; #define PG8_LDA(dst, b, h) do { _Pragma("unroll") for (int m = 0; m < 4; ++m) _Pragma("unroll") for (int k = 0; k < 2; ++k) dst[m][k] = *(const PG8_LAS bf16x8*)(lds + PG8_SA(b, h) + aoff + m * 2048 + k * 1024); } while (0)
; #define PG8_LDB(dst, b, h) do { _Pragma("unroll") for (int n = 0; n < 2; ++n) _Pragma("unroll") for (int k = 0; k < 2; ++k) dst[n][k] = *(const PG8_LAS bf16x8*)(lds + PG8_SB(b, h) + boff + n * 2048 + k * 1024); } while (0)
; #define PG8_MMA(ai, bj, At, Bt) do { __builtin_amdgcn_s_setprio(1); _Pragma("unroll") for (int m = 0; m < 4; ++m) _Pragma("unroll") for (int n = 0; n < 2; ++n) _Pragma("unroll") for (int k = 0; k < 2; ++k) \
;         acc[ai][bj][m][n] = __builtin_amdgcn_mfma_f32_16x16x32_bf16(Bt[n][k], At[m][k], acc[ai][bj][m][n], 0, 0, 0); __builtin_amdgcn_s_setprio(0); } while (0)
; #define PG8_WAIT_V(n) asm volatile("s_waitcnt vmcnt(" #n ")" ::: "memory")
; #define PG8_WAIT_L(n) asm volatile("s_waitcnt lgkmcnt(" #n ")" ::: "memory")
; #define PG8_BAR __builtin_amdgcn_s_barrier()
; #define PG8_SCHED __builtin_amdgcn_sched_barrier(0)
; template <class Epi, class Sched, bool ALIGN_EPI = false, bool SP2 = false>
; __device__ __forceinline__ void gemm_phase(PG8_LAS unsigned char* lds, const Gemm g, const Sched& S, const Epi& E, const int tid) {
;     ...
;             PG8_WAIT_V(8); PG8_WAIT_L(0); PG8_BAR; PG8_MMA(1, 0, At, B0); PG8_MMA(1, 1, At, B1); PG8_BAR; PG8_SCHED;
;             PG8_LDB(B0, 1, 0); PG8_LDB(B1, 1, 1); PG8_SCHED; PG8_LDA(At, 1, 0); PG8_STAGE(PG8_SA(0, 1), a2 + hstep, voffA);
;             PG8_WAIT_V(8); PG8_WAIT_L(0); PG8_BAR; PG8_MMA(0, 0, At, B0); PG8_MMA(0, 1, At, B1); PG8_BAR; PG8_SCHED;
	s_setprio 1
	s_waitcnt lgkmcnt(0)
	v_mfma_f32_16x16x32_bf16 v[62:65], v[130:133], v[196:199], 0
	v_mfma_f32_16x16x32_bf16 v[58:61], v[162:165], v[196:199], 0
	v_mfma_f32_16x16x32_bf16 v[42:45], v[162:165], v[204:207], 0
	v_mfma_f32_16x16x32_bf16 v[46:49], v[130:133], v[204:207], 0
	v_mfma_f32_16x16x32_bf16 v[30:33], v[130:133], v[212:215], 0
	v_mfma_f32_16x16x32_bf16 v[26:29], v[162:165], v[212:215], 0
	v_mfma_f32_16x16x32_bf16 v[10:13], v[162:165], v[220:223], 0
	v_mfma_f32_16x16x32_bf16 v[14:17], v[130:133], v[220:223], 0
	v_mfma_f32_16x16x32_bf16 v[62:65], v[134:137], v[200:203], v[62:65]
	v_mfma_f32_16x16x32_bf16 v[58:61], v[166:169], v[200:203], v[58:61]
	v_mfma_f32_16x16x32_bf16 v[42:45], v[166:169], v[208:211], v[42:45]
	v_mfma_f32_16x16x32_bf16 v[46:49], v[134:137], v[208:211], v[46:49]
	v_mfma_f32_16x16x32_bf16 v[30:33], v[134:137], v[216:219], v[30:33]
	v_mfma_f32_16x16x32_bf16 v[26:29], v[166:169], v[216:219], v[26:29]
	v_mfma_f32_16x16x32_bf16 v[10:13], v[166:169], v[224:227], v[10:13]
	v_mfma_f32_16x16x32_bf16 v[14:17], v[134:137], v[224:227], v[14:17]
	s_setprio 0
	s_setprio 1
	v_mfma_f32_16x16x32_bf16 v[54:57], v[176:179], v[196:199], 0
	v_mfma_f32_16x16x32_bf16 v[50:53], v[184:187], v[196:199], 0
	v_mfma_f32_16x16x32_bf16 v[34:37], v[184:187], v[204:207], 0
	v_mfma_f32_16x16x32_bf16 v[38:41], v[176:179], v[204:207], 0
	v_mfma_f32_16x16x32_bf16 v[22:25], v[176:179], v[212:215], 0
	v_mfma_f32_16x16x32_bf16 v[18:21], v[184:187], v[212:215], 0
	v_mfma_f32_16x16x32_bf16 v[2:5], v[184:187], v[220:223], 0
	v_mfma_f32_16x16x32_bf16 v[6:9], v[176:179], v[220:223], 0
	v_mfma_f32_16x16x32_bf16 v[54:57], v[180:183], v[200:203], v[54:57]
	v_mfma_f32_16x16x32_bf16 v[50:53], v[192:195], v[200:203], v[50:53]
	v_mfma_f32_16x16x32_bf16 v[34:37], v[192:195], v[208:211], v[34:37]
	v_mfma_f32_16x16x32_bf16 v[38:41], v[180:183], v[208:211], v[38:41]
	v_mfma_f32_16x16x32_bf16 v[22:25], v[180:183], v[216:219], v[22:25]
	v_mfma_f32_16x16x32_bf16 v[18:21], v[192:195], v[216:219], v[18:21]
	v_mfma_f32_16x16x32_bf16 v[2:5], v[192:195], v[224:227], v[2:5]
	v_mfma_f32_16x16x32_bf16 v[6:9], v[180:183], v[224:227], v[6:9]
	s_setprio 0
	s_barrier
	s_add_i32 s15, 0, 0x18000
	s_add_i32 s62, 0, 0x1c000
	v_add_u32_e32 v166, s15, v172
	v_add_u32_e32 v191, s62, v172
	ds_read_b128 v[130:133], v166
	ds_read_b128 v[134:137], v166 offset:1024
	ds_read_b128 v[162:165], v166 offset:2048
	ds_read_b128 v[166:169], v166 offset:3072
	ds_read_b128 v[176:179], v191
	ds_read_b128 v[180:183], v191 offset:1024
	ds_read_b128 v[184:187], v191 offset:2048
	ds_read_b128 v[192:195], v191 offset:3072
	s_add_u32 s18, s60, 0x40000
	s_addc_u32 s19, s61, 0
	s_mov_b32 m0, s69
	v_lshl_add_u64 v[232:233], s[18:19], 0, v[140:141]
	ds_read_b128 v[196:199], v174 offset:32768
	ds_read_b128 v[200:203], v174 offset:33792
	ds_read_b128 v[204:207], v174 offset:34816
	ds_read_b128 v[208:211], v174 offset:35840
	ds_read_b128 v[212:215], v174 offset:36864
	ds_read_b128 v[216:219], v174 offset:37888
	ds_read_b128 v[220:223], v174 offset:38912
	ds_read_b128 v[224:227], v174 offset:39936
	global_load_lds_dwordx4 v[232:233], off
	v_lshl_add_u64 v[232:233], s[18:19], 0, v[144:145]
	s_mov_b32 m0, s71
	s_nop 0
	global_load_lds_dwordx4 v[232:233], off
	s_waitcnt vmcnt(8)
	s_waitcnt lgkmcnt(0)
	s_barrier
	s_setprio 1
	s_waitcnt lgkmcnt(0)
	v_mfma_f32_16x16x32_bf16 v[126:129], v[130:133], v[196:199], v[126:129]
	v_mfma_f32_16x16x32_bf16 v[122:125], v[162:165], v[196:199], v[122:125]
	v_mfma_f32_16x16x32_bf16 v[106:109], v[162:165], v[204:207], v[106:109]
	v_mfma_f32_16x16x32_bf16 v[110:113], v[130:133], v[204:207], v[110:113]
	v_mfma_f32_16x16x32_bf16 v[94:97], v[130:133], v[212:215], v[94:97]
	v_mfma_f32_16x16x32_bf16 v[90:93], v[162:165], v[212:215], v[90:93]
	v_mfma_f32_16x16x32_bf16 v[74:77], v[162:165], v[220:223], v[74:77]
	v_mfma_f32_16x16x32_bf16 v[78:81], v[130:133], v[220:223], v[78:81]
	v_mfma_f32_16x16x32_bf16 v[126:129], v[134:137], v[200:203], v[126:129]
	v_mfma_f32_16x16x32_bf16 v[122:125], v[166:169], v[200:203], v[122:125]
	v_mfma_f32_16x16x32_bf16 v[106:109], v[166:169], v[208:211], v[106:109]
	v_mfma_f32_16x16x32_bf16 v[110:113], v[134:137], v[208:211], v[110:113]
	v_mfma_f32_16x16x32_bf16 v[94:97], v[134:137], v[216:219], v[94:97]
	v_mfma_f32_16x16x32_bf16 v[90:93], v[166:169], v[216:219], v[90:93]
	v_mfma_f32_16x16x32_bf16 v[74:77], v[166:169], v[224:227], v[74:77]
	v_mfma_f32_16x16x32_bf16 v[78:81], v[134:137], v[224:227], v[78:81]
	s_setprio 0
	s_setprio 1
	v_mfma_f32_16x16x32_bf16 v[118:121], v[176:179], v[196:199], v[118:121]
	v_mfma_f32_16x16x32_bf16 v[114:117], v[184:187], v[196:199], v[114:117]
	v_mfma_f32_16x16x32_bf16 v[98:101], v[184:187], v[204:207], v[98:101]
	v_mfma_f32_16x16x32_bf16 v[102:105], v[176:179], v[204:207], v[102:105]
	v_mfma_f32_16x16x32_bf16 v[86:89], v[176:179], v[212:215], v[86:89]
	v_mfma_f32_16x16x32_bf16 v[82:85], v[184:187], v[212:215], v[82:85]
	v_mfma_f32_16x16x32_bf16 v[66:69], v[184:187], v[220:223], v[66:69]
	v_mfma_f32_16x16x32_bf16 v[70:73], v[176:179], v[220:223], v[70:73]
	v_mfma_f32_16x16x32_bf16 v[118:121], v[180:183], v[200:203], v[118:121]
	v_mfma_f32_16x16x32_bf16 v[114:117], v[192:195], v[200:203], v[114:117]
	v_mfma_f32_16x16x32_bf16 v[98:101], v[192:195], v[208:211], v[98:101]
	v_mfma_f32_16x16x32_bf16 v[102:105], v[180:183], v[208:211], v[102:105]
	v_mfma_f32_16x16x32_bf16 v[86:89], v[180:183], v[216:219], v[86:89]
	v_mfma_f32_16x16x32_bf16 v[82:85], v[192:195], v[216:219], v[82:85]
	v_mfma_f32_16x16x32_bf16 v[66:69], v[192:195], v[224:227], v[66:69]
	v_mfma_f32_16x16x32_bf16 v[70:73], v[180:183], v[224:227], v[70:73]
	s_setprio 0
	s_barrier
; #define PG8_STAGE(bufoff, gbase, voff) do { _Pragma("unroll") for (int _i = 0; _i < 2; ++_i) \
;         __builtin_amdgcn_global_load_lds((const unsigned*)((const char*)(gbase) + (voff)[_i]), (PG8_LAS unsigned*)(lds + (bufoff) + ldsw + _i * 8192), 16, 0, 0); } while (0)
; #define PG8_LDA(dst, b, h) do { _Pragma("unroll") for (int m = 0; m < 4; ++m) _Pragma("unroll") for (int k = 0; k < 2; ++k) dst[m][k] = *(const PG8_LAS bf16x8*)(lds + PG8_SA(b, h) + aoff + m * 2048 + k * 1024); } while (0)
; #define PG8_LDB(dst, b, h) do { _Pragma("unroll") for (int n = 0; n < 2; ++n) _Pragma("unroll") for (int k = 0; k < 2; ++k) dst[n][k] = *(const PG8_LAS bf16x8*)(lds + PG8_SB(b, h) + boff + n * 2048 + k * 1024); } while (0)
; #define PG8_MMA(ai, bj, At, Bt) do { __builtin_amdgcn_s_setprio(1); _Pragma("unroll") for (int m = 0; m < 4; ++m) _Pragma("unroll") for (int n = 0; n < 2; ++n) _Pragma("unroll") for (int k = 0; k < 2; ++k) \
;         acc[ai][bj][m][n] = __builtin_amdgcn_mfma_f32_16x16x32_bf16(Bt[n][k], At[m][k], acc[ai][bj][m][n], 0, 0, 0); __builtin_amdgcn_s_setprio(0); } while (0)
; #define PG8_WAIT_V(n) asm volatile("s_waitcnt vmcnt(" #n ")" ::: "memory")
; #define PG8_WAIT_L(n) asm volatile("s_waitcnt lgkmcnt(" #n ")" ::: "memory")
; #define PG8_BAR __builtin_amdgcn_s_barrier()
; #define PG8_SCHED __builtin_amdgcn_sched_barrier(0)
; template <class Epi, class Sched, bool ALIGN_EPI = false, bool SP2 = false>
; __device__ __forceinline__ void gemm_phase(PG8_LAS unsigned char* lds, const Gemm g, const Sched& S, const Epi& E, const int tid) {
;     ...
;             PG8_LDB(B0, 0, 0); PG8_LDB(B1, 0, 1); PG8_SCHED; PG8_LDA(At, 0, 0); PG8_STAGE(PG8_SA(1, 1), a1 + hstep, voffA);
;     ...
;             PG8_LDA(At, 1, 1); PG8_STAGE(PG8_SB(1, 0), b3, voffB); PG8_STAGE(PG8_SB(1, 1), b3 + hstep, voffB); PG8_STAGE(PG8_SA(1, 0), a3, voffA);
;             PG8_WAIT_V(8); PG8_WAIT_L(0); PG8_BAR; PG8_MMA(1, 0, At, B0); PG8_MMA(1, 1, At, B1); PG8_BAR; PG8_SCHED;
	s_add_i32 s15, s15, s66
	v_lshl_add_u64 v[170:171], v[170:171], 0, s[44:45]
	s_mov_b32 m0, s15
	ds_read_b128 v[196:199], v174 offset:49152
	ds_read_b128 v[200:203], v174 offset:50176
	ds_read_b128 v[204:207], v174 offset:51200
	ds_read_b128 v[208:211], v174 offset:52224
	ds_read_b128 v[212:215], v174 offset:53248
	ds_read_b128 v[216:219], v174 offset:54272
	ds_read_b128 v[220:223], v174 offset:55296
	ds_read_b128 v[224:227], v174 offset:56320
	global_load_lds_dwordx4 v[170:171], off
	s_add_i32 m0, s15, 0x2000
	s_add_u32 s18, s58, 0x40080
	v_lshl_add_u64 v[170:171], v[188:189], 0, s[44:45]
	s_addc_u32 s19, s59, 0
	s_add_i32 s15, s62, s66
	global_load_lds_dwordx4 v[170:171], off
	v_lshl_add_u64 v[170:171], s[18:19], 0, v[142:143]
	s_mov_b32 m0, s15
	s_nop 0
	global_load_lds_dwordx4 v[170:171], off
	v_lshl_add_u64 v[170:171], s[18:19], 0, v[146:147]
	s_add_i32 m0, s15, 0x2000
	s_nop 0
	global_load_lds_dwordx4 v[170:171], off
	v_lshl_add_u64 v[170:171], v[228:229], 0, s[44:45]
	s_mov_b32 m0, s77
	s_nop 0
	global_load_lds_dwordx4 v[170:171], off
	v_lshl_add_u64 v[170:171], v[230:231], 0, s[44:45]
	s_mov_b32 m0, s78
	s_nop 0
	global_load_lds_dwordx4 v[170:171], off
	s_waitcnt vmcnt(8)
	s_waitcnt lgkmcnt(0)
	s_barrier
	s_setprio 1
	s_waitcnt lgkmcnt(0)
	v_mfma_f32_16x16x32_bf16 v[62:65], v[130:133], v[196:199], v[62:65]
	v_mfma_f32_16x16x32_bf16 v[58:61], v[162:165], v[196:199], v[58:61]
	v_mfma_f32_16x16x32_bf16 v[42:45], v[162:165], v[204:207], v[42:45]
	v_mfma_f32_16x16x32_bf16 v[46:49], v[130:133], v[204:207], v[46:49]
	v_mfma_f32_16x16x32_bf16 v[30:33], v[130:133], v[212:215], v[30:33]
	v_mfma_f32_16x16x32_bf16 v[26:29], v[162:165], v[212:215], v[26:29]
	v_mfma_f32_16x16x32_bf16 v[10:13], v[162:165], v[220:223], v[10:13]
	v_mfma_f32_16x16x32_bf16 v[14:17], v[130:133], v[220:223], v[14:17]
	v_mfma_f32_16x16x32_bf16 v[62:65], v[134:137], v[200:203], v[62:65]
	v_mfma_f32_16x16x32_bf16 v[58:61], v[166:169], v[200:203], v[58:61]
	v_mfma_f32_16x16x32_bf16 v[42:45], v[166:169], v[208:211], v[42:45]
	v_mfma_f32_16x16x32_bf16 v[46:49], v[134:137], v[208:211], v[46:49]
	v_mfma_f32_16x16x32_bf16 v[30:33], v[134:137], v[216:219], v[30:33]
	v_mfma_f32_16x16x32_bf16 v[26:29], v[166:169], v[216:219], v[26:29]
	v_mfma_f32_16x16x32_bf16 v[10:13], v[166:169], v[224:227], v[10:13]
	v_mfma_f32_16x16x32_bf16 v[14:17], v[134:137], v[224:227], v[14:17]
	s_setprio 0
	s_setprio 1
	v_mfma_f32_16x16x32_bf16 v[54:57], v[176:179], v[196:199], v[54:57]
	v_mfma_f32_16x16x32_bf16 v[50:53], v[184:187], v[196:199], v[50:53]
	v_mfma_f32_16x16x32_bf16 v[34:37], v[184:187], v[204:207], v[34:37]
	v_mfma_f32_16x16x32_bf16 v[38:41], v[176:179], v[204:207], v[38:41]
	v_mfma_f32_16x16x32_bf16 v[22:25], v[176:179], v[212:215], v[22:25]
	v_mfma_f32_16x16x32_bf16 v[18:21], v[184:187], v[212:215], v[18:21]
	v_mfma_f32_16x16x32_bf16 v[2:5], v[184:187], v[220:223], v[2:5]
	v_mfma_f32_16x16x32_bf16 v[6:9], v[176:179], v[220:223], v[6:9]
	v_mfma_f32_16x16x32_bf16 v[54:57], v[180:183], v[200:203], v[54:57]
	v_mfma_f32_16x16x32_bf16 v[50:53], v[192:195], v[200:203], v[50:53]
	v_mfma_f32_16x16x32_bf16 v[34:37], v[192:195], v[208:211], v[34:37]
	v_mfma_f32_16x16x32_bf16 v[38:41], v[180:183], v[208:211], v[38:41]
	v_mfma_f32_16x16x32_bf16 v[22:25], v[180:183], v[216:219], v[22:25]
	v_mfma_f32_16x16x32_bf16 v[18:21], v[192:195], v[216:219], v[18:21]
	v_mfma_f32_16x16x32_bf16 v[2:5], v[192:195], v[224:227], v[2:5]
	v_mfma_f32_16x16x32_bf16 v[6:9], v[180:183], v[224:227], v[6:9]
	s_setprio 0
	s_barrier
	s_add_i32 s51, s51, 2
	s_add_u32 s5, s5, 0x100
	s_addc_u32 s49, s49, 0
	s_add_u32 s56, s56, 0x100
	s_addc_u32 s57, s57, 0
.LBB0_1122:
	ds_read_b128 v[130:133], v139
	ds_read_b128 v[134:137], v139 offset:1024
	ds_read_b128 v[162:165], v139 offset:2048
	ds_read_b128 v[166:169], v139 offset:3072
	ds_read_b128 v[176:179], v173
	ds_read_b128 v[180:183], v173 offset:1024
	ds_read_b128 v[184:187], v173 offset:2048
	ds_read_b128 v[192:195], v173 offset:3072
	s_add_u32 s15, s56, 0xfffc0080
	s_addc_u32 s18, s57, -1
	s_cmp_eq_u32 s51, 12
	s_cselect_b32 s61, s1, s18
	s_cselect_b32 s60, s0, s15
	s_cselect_b32 s59, s53, s49
	s_cselect_b32 s58, s52, s5
	v_lshl_add_u64 v[170:171], s[56:57], 0, v[156:157]
	s_add_i32 m0, s67, 0xc000
	ds_read_b128 v[196:199], v174
	ds_read_b128 v[200:203], v174 offset:1024
	ds_read_b128 v[204:207], v174 offset:2048
	ds_read_b128 v[208:211], v174 offset:3072
	ds_read_b128 v[212:215], v174 offset:4096
	ds_read_b128 v[216:219], v174 offset:5120
	ds_read_b128 v[220:223], v174 offset:6144
	ds_read_b128 v[224:227], v174 offset:7168
	global_load_lds_dwordx4 v[170:171], off
	v_lshl_add_u64 v[170:171], s[56:57], 0, v[154:155]
	s_add_i32 m0, s67, 0xe000
	s_nop 0
	global_load_lds_dwordx4 v[170:171], off
	s_waitcnt vmcnt(8)
	s_waitcnt lgkmcnt(0)
	s_barrier
; #define PG8_STAGE(bufoff, gbase, voff) do { _Pragma("unroll") for (int _i = 0; _i < 2; ++_i) \
;         __builtin_amdgcn_global_load_lds((const unsigned*)((const char*)(gbase) + (voff)[_i]), (PG8_LAS unsigned*)(lds + (bufoff) + ldsw + _i * 8192), 16, 0, 0); } while (0)
; #define PG8_LDA(dst, b, h) do { _Pragma("unroll") for (int m = 0; m < 4; ++m) _Pragma("unroll") for (int k = 0; k < 2; ++k) dst[m][k] = *(const PG8_LAS bf16x8*)(lds + PG8_SA(b, h) + aoff + m * 2048 + k * 1024); } while (0)
; #define PG8_MMA(ai, bj, At, Bt) do { __builtin_amdgcn_s_setprio(1); _Pragma("unroll") for (int m = 0; m < 4; ++m) _Pragma("unroll") for (int n = 0; n < 2; ++n) _Pragma("unroll") for (int k = 0; k < 2; ++k) \
;         acc[ai][bj][m][n] = __builtin_amdgcn_mfma_f32_16x16x32_bf16(Bt[n][k], At[m][k], acc[ai][bj][m][n], 0, 0, 0); __builtin_amdgcn_s_setprio(0); } while (0)
; #define PG8_WAIT_V(n) asm volatile("s_waitcnt vmcnt(" #n ")" ::: "memory")
; #define PG8_WAIT_L(n) asm volatile("s_waitcnt lgkmcnt(" #n ")" ::: "memory")
; #define PG8_BAR __builtin_amdgcn_s_barrier()
; #define PG8_SCHED __builtin_amdgcn_sched_barrier(0)
; template <class Epi, class Sched, bool ALIGN_EPI = false, bool SP2 = false>
; __device__ __forceinline__ void gemm_phase(PG8_LAS unsigned char* lds, const Gemm g, const Sched& S, const Epi& E, const int tid) {
;     ...
;             PG8_WAIT_V(8); PG8_WAIT_L(0); PG8_BAR; PG8_MMA(0, 0, At, B0); PG8_MMA(0, 1, At, B1); PG8_BAR; PG8_SCHED;
;             PG8_LDA(At, 0, 1); PG8_STAGE(PG8_SB(0, 0), b2, voffB); PG8_STAGE(PG8_SB(0, 1), b2 + hstep, voffB); PG8_STAGE(PG8_SA(0, 0), a2, voffA);
;             PG8_WAIT_V(8); PG8_WAIT_L(0); PG8_BAR; PG8_MMA(1, 0, At, B0); PG8_MMA(1, 1, At, B1); PG8_BAR; PG8_SCHED;
	s_setprio 1
	s_waitcnt lgkmcnt(0)
	v_mfma_f32_16x16x32_bf16 v[126:129], v[130:133], v[196:199], v[126:129]
	v_mfma_f32_16x16x32_bf16 v[122:125], v[162:165], v[196:199], v[122:125]
	v_mfma_f32_16x16x32_bf16 v[106:109], v[162:165], v[204:207], v[106:109]
	v_mfma_f32_16x16x32_bf16 v[110:113], v[130:133], v[204:207], v[110:113]
	v_mfma_f32_16x16x32_bf16 v[94:97], v[130:133], v[212:215], v[94:97]
	v_mfma_f32_16x16x32_bf16 v[90:93], v[162:165], v[212:215], v[90:93]
	v_mfma_f32_16x16x32_bf16 v[74:77], v[162:165], v[220:223], v[74:77]
	v_mfma_f32_16x16x32_bf16 v[78:81], v[130:133], v[220:223], v[78:81]
	v_mfma_f32_16x16x32_bf16 v[126:129], v[134:137], v[200:203], v[126:129]
	v_mfma_f32_16x16x32_bf16 v[122:125], v[166:169], v[200:203], v[122:125]
	v_mfma_f32_16x16x32_bf16 v[106:109], v[166:169], v[208:211], v[106:109]
	v_mfma_f32_16x16x32_bf16 v[110:113], v[134:137], v[208:211], v[110:113]
	v_mfma_f32_16x16x32_bf16 v[94:97], v[134:137], v[216:219], v[94:97]
	v_mfma_f32_16x16x32_bf16 v[90:93], v[166:169], v[216:219], v[90:93]
	v_mfma_f32_16x16x32_bf16 v[74:77], v[166:169], v[224:227], v[74:77]
	v_mfma_f32_16x16x32_bf16 v[78:81], v[134:137], v[224:227], v[78:81]
	s_setprio 0
	s_setprio 1
	v_mfma_f32_16x16x32_bf16 v[118:121], v[176:179], v[196:199], v[118:121]
	v_mfma_f32_16x16x32_bf16 v[114:117], v[184:187], v[196:199], v[114:117]
	v_mfma_f32_16x16x32_bf16 v[98:101], v[184:187], v[204:207], v[98:101]
	v_mfma_f32_16x16x32_bf16 v[102:105], v[176:179], v[204:207], v[102:105]
	v_mfma_f32_16x16x32_bf16 v[86:89], v[176:179], v[212:215], v[86:89]
	v_mfma_f32_16x16x32_bf16 v[82:85], v[184:187], v[212:215], v[82:85]
	v_mfma_f32_16x16x32_bf16 v[66:69], v[184:187], v[220:223], v[66:69]
	v_mfma_f32_16x16x32_bf16 v[70:73], v[176:179], v[220:223], v[70:73]
	v_mfma_f32_16x16x32_bf16 v[118:121], v[180:183], v[200:203], v[118:121]
	v_mfma_f32_16x16x32_bf16 v[114:117], v[192:195], v[200:203], v[114:117]
	v_mfma_f32_16x16x32_bf16 v[98:101], v[192:195], v[208:211], v[98:101]
	v_mfma_f32_16x16x32_bf16 v[102:105], v[180:183], v[208:211], v[102:105]
	v_mfma_f32_16x16x32_bf16 v[86:89], v[180:183], v[216:219], v[86:89]
	v_mfma_f32_16x16x32_bf16 v[82:85], v[192:195], v[216:219], v[82:85]
	v_mfma_f32_16x16x32_bf16 v[66:69], v[192:195], v[224:227], v[66:69]
	v_mfma_f32_16x16x32_bf16 v[70:73], v[180:183], v[224:227], v[70:73]
	s_setprio 0
	s_barrier
	s_add_i32 s15, s86, s66
	v_lshl_add_u64 v[170:171], s[58:59], 0, v[142:143]
	s_mov_b32 m0, s15
	ds_read_b128 v[196:199], v174 offset:16384
	ds_read_b128 v[200:203], v174 offset:17408
	ds_read_b128 v[204:207], v174 offset:18432
	ds_read_b128 v[208:211], v174 offset:19456
	ds_read_b128 v[212:215], v174 offset:20480
	ds_read_b128 v[216:219], v174 offset:21504
	ds_read_b128 v[220:223], v174 offset:22528
	ds_read_b128 v[224:227], v174 offset:23552
	global_load_lds_dwordx4 v[170:171], off
	s_add_i32 m0, s15, 0x2000
	s_add_u32 s18, s58, 0x40000
	v_lshl_add_u64 v[188:189], s[58:59], 0, v[146:147]
	s_addc_u32 s19, s59, 0
	s_add_i32 s15, s87, s66
	global_load_lds_dwordx4 v[188:189], off
	v_lshl_add_u64 v[228:229], s[18:19], 0, v[142:143]
	s_mov_b32 m0, s15
	v_lshl_add_u64 v[230:231], s[60:61], 0, v[144:145]
	global_load_lds_dwordx4 v[228:229], off
	v_lshl_add_u64 v[228:229], s[18:19], 0, v[146:147]
	s_add_i32 m0, s15, 0x2000
	s_nop 0
	global_load_lds_dwordx4 v[228:229], off
	v_lshl_add_u64 v[228:229], s[60:61], 0, v[140:141]
	s_mov_b32 m0, s67
	s_nop 0
	global_load_lds_dwordx4 v[228:229], off
	s_mov_b32 m0, s68
	s_nop 0
	global_load_lds_dwordx4 v[230:231], off
	s_waitcnt vmcnt(8)
	s_waitcnt lgkmcnt(0)
	s_barrier
	s_setprio 1
	s_waitcnt lgkmcnt(0)
	v_mfma_f32_16x16x32_bf16 v[62:65], v[130:133], v[196:199], v[62:65]
	v_mfma_f32_16x16x32_bf16 v[58:61], v[162:165], v[196:199], v[58:61]
	v_mfma_f32_16x16x32_bf16 v[42:45], v[162:165], v[204:207], v[42:45]
	v_mfma_f32_16x16x32_bf16 v[46:49], v[130:133], v[204:207], v[46:49]
	v_mfma_f32_16x16x32_bf16 v[30:33], v[130:133], v[212:215], v[30:33]
	v_mfma_f32_16x16x32_bf16 v[26:29], v[162:165], v[212:215], v[26:29]
	v_mfma_f32_16x16x32_bf16 v[10:13], v[162:165], v[220:223], v[10:13]
	v_mfma_f32_16x16x32_bf16 v[14:17], v[130:133], v[220:223], v[14:17]
	v_mfma_f32_16x16x32_bf16 v[62:65], v[134:137], v[200:203], v[62:65]
	v_mfma_f32_16x16x32_bf16 v[58:61], v[166:169], v[200:203], v[58:61]
	v_mfma_f32_16x16x32_bf16 v[42:45], v[166:169], v[208:211], v[42:45]
	v_mfma_f32_16x16x32_bf16 v[46:49], v[134:137], v[208:211], v[46:49]
	v_mfma_f32_16x16x32_bf16 v[30:33], v[134:137], v[216:219], v[30:33]
	v_mfma_f32_16x16x32_bf16 v[26:29], v[166:169], v[216:219], v[26:29]
	v_mfma_f32_16x16x32_bf16 v[10:13], v[166:169], v[224:227], v[10:13]
	v_mfma_f32_16x16x32_bf16 v[14:17], v[134:137], v[224:227], v[14:17]
	s_setprio 0
	s_setprio 1
	v_mfma_f32_16x16x32_bf16 v[54:57], v[176:179], v[196:199], v[54:57]
	v_mfma_f32_16x16x32_bf16 v[50:53], v[184:187], v[196:199], v[50:53]
	v_mfma_f32_16x16x32_bf16 v[34:37], v[184:187], v[204:207], v[34:37]
	v_mfma_f32_16x16x32_bf16 v[38:41], v[176:179], v[204:207], v[38:41]
	v_mfma_f32_16x16x32_bf16 v[22:25], v[176:179], v[212:215], v[22:25]
	v_mfma_f32_16x16x32_bf16 v[18:21], v[184:187], v[212:215], v[18:21]
	v_mfma_f32_16x16x32_bf16 v[2:5], v[184:187], v[220:223], v[2:5]
	v_mfma_f32_16x16x32_bf16 v[6:9], v[176:179], v[220:223], v[6:9]
	v_mfma_f32_16x16x32_bf16 v[54:57], v[180:183], v[200:203], v[54:57]
	v_mfma_f32_16x16x32_bf16 v[50:53], v[192:195], v[200:203], v[50:53]
	v_mfma_f32_16x16x32_bf16 v[34:37], v[192:195], v[208:211], v[34:37]
	v_mfma_f32_16x16x32_bf16 v[38:41], v[180:183], v[208:211], v[38:41]
	v_mfma_f32_16x16x32_bf16 v[22:25], v[180:183], v[216:219], v[22:25]
	v_mfma_f32_16x16x32_bf16 v[18:21], v[192:195], v[216:219], v[18:21]
	v_mfma_f32_16x16x32_bf16 v[2:5], v[192:195], v[224:227], v[2:5]
	v_mfma_f32_16x16x32_bf16 v[6:9], v[180:183], v[224:227], v[6:9]
	s_setprio 0
	s_barrier
; #define PG8_STAGE(bufoff, gbase, voff) do { _Pragma("unroll") for (int _i = 0; _i < 2; ++_i) \
;         __builtin_amdgcn_global_load_lds((const unsigned*)((const char*)(gbase) + (voff)[_i]), (PG8_LAS unsigned*)(lds + (bufoff) + ldsw + _i * 8192), 16, 0, 0); } while (0)
; #define PG8_LDA(dst, b, h) do { _Pragma("unroll") for (int m = 0; m < 4; ++m) _Pragma("unroll") for (int k = 0; k < 2; ++k) dst[m][k] = *(const PG8_LAS bf16x8*)(lds + PG8_SA(b, h) + aoff + m * 2048 + k * 1024); } while (0)
; #define PG8_LDB(dst, b, h) do { _Pragma("unroll") for (int n = 0; n < 2; ++n) _Pragma("unroll") for (int k = 0; k < 2; ++k) dst[n][k] = *(const PG8_LAS bf16x8*)(lds + PG8_SB(b, h) + boff + n * 2048 + k * 1024); } while (0)
; #define PG8_MMA(ai, bj, At, Bt) do { __builtin_amdgcn_s_setprio(1); _Pragma("unroll") for (int m = 0; m < 4; ++m) _Pragma("unroll") for (int n = 0; n < 2; ++n) _Pragma("unroll") for (int k = 0; k < 2; ++k) \
;         acc[ai][bj][m][n] = __builtin_amdgcn_mfma_f32_16x16x32_bf16(Bt[n][k], At[m][k], acc[ai][bj][m][n], 0, 0, 0); __builtin_amdgcn_s_setprio(0); } while (0)
; #define PG8_WAIT_V(n) asm volatile("s_waitcnt vmcnt(" #n ")" ::: "memory")
; #define PG8_WAIT_L(n) asm volatile("s_waitcnt lgkmcnt(" #n ")" ::: "memory")
; #define PG8_BAR __builtin_amdgcn_s_barrier()
; #define PG8_SCHED __builtin_amdgcn_sched_barrier(0)
; template <class Epi, class Sched, bool ALIGN_EPI = false, bool SP2 = false>
; __device__ __forceinline__ void gemm_phase(PG8_LAS unsigned char* lds, const Gemm g, const Sched& S, const Epi& E, const int tid) {
;     ...
;             PG8_LDB(B0, 1, 0); PG8_LDB(B1, 1, 1); PG8_SCHED; PG8_LDA(At, 1, 0); PG8_STAGE(PG8_SA(0, 1), a2 + hstep, voffA);
;             PG8_WAIT_V(8); PG8_WAIT_L(0); PG8_BAR; PG8_MMA(0, 0, At, B0); PG8_MMA(0, 1, At, B1); PG8_BAR; PG8_SCHED;
	s_add_i32 s15, 0, 0x18000
	s_add_i32 s62, 0, 0x1c000
	v_add_u32_e32 v166, s15, v172
	v_add_u32_e32 v191, s62, v172
	ds_read_b128 v[130:133], v166
	ds_read_b128 v[134:137], v166 offset:1024
	ds_read_b128 v[162:165], v166 offset:2048
	ds_read_b128 v[166:169], v166 offset:3072
	ds_read_b128 v[176:179], v191
	ds_read_b128 v[180:183], v191 offset:1024
	ds_read_b128 v[184:187], v191 offset:2048
	ds_read_b128 v[192:195], v191 offset:3072
	s_add_u32 s18, s60, 0x40000
	s_addc_u32 s19, s61, 0
	s_mov_b32 m0, s69
	v_lshl_add_u64 v[232:233], s[18:19], 0, v[140:141]
	ds_read_b128 v[196:199], v174 offset:32768
	ds_read_b128 v[200:203], v174 offset:33792
	ds_read_b128 v[204:207], v174 offset:34816
	ds_read_b128 v[208:211], v174 offset:35840
	ds_read_b128 v[212:215], v174 offset:36864
	ds_read_b128 v[216:219], v174 offset:37888
	ds_read_b128 v[220:223], v174 offset:38912
	ds_read_b128 v[224:227], v174 offset:39936
	global_load_lds_dwordx4 v[232:233], off
	v_lshl_add_u64 v[232:233], s[18:19], 0, v[144:145]
	s_mov_b32 m0, s71
	s_nop 0
	global_load_lds_dwordx4 v[232:233], off
	s_waitcnt vmcnt(8)
	s_waitcnt lgkmcnt(0)
	s_barrier
	s_setprio 1
	s_waitcnt lgkmcnt(0)
	v_mfma_f32_16x16x32_bf16 v[126:129], v[130:133], v[196:199], v[126:129]
	v_mfma_f32_16x16x32_bf16 v[122:125], v[162:165], v[196:199], v[122:125]
	v_mfma_f32_16x16x32_bf16 v[106:109], v[162:165], v[204:207], v[106:109]
	v_mfma_f32_16x16x32_bf16 v[110:113], v[130:133], v[204:207], v[110:113]
	v_mfma_f32_16x16x32_bf16 v[94:97], v[130:133], v[212:215], v[94:97]
	v_mfma_f32_16x16x32_bf16 v[90:93], v[162:165], v[212:215], v[90:93]
	v_mfma_f32_16x16x32_bf16 v[74:77], v[162:165], v[220:223], v[74:77]
	v_mfma_f32_16x16x32_bf16 v[78:81], v[130:133], v[220:223], v[78:81]
	v_mfma_f32_16x16x32_bf16 v[126:129], v[134:137], v[200:203], v[126:129]
	v_mfma_f32_16x16x32_bf16 v[122:125], v[166:169], v[200:203], v[122:125]
	v_mfma_f32_16x16x32_bf16 v[106:109], v[166:169], v[208:211], v[106:109]
	v_mfma_f32_16x16x32_bf16 v[110:113], v[134:137], v[208:211], v[110:113]
	v_mfma_f32_16x16x32_bf16 v[94:97], v[134:137], v[216:219], v[94:97]
	v_mfma_f32_16x16x32_bf16 v[90:93], v[166:169], v[216:219], v[90:93]
	v_mfma_f32_16x16x32_bf16 v[74:77], v[166:169], v[224:227], v[74:77]
	v_mfma_f32_16x16x32_bf16 v[78:81], v[134:137], v[224:227], v[78:81]
	s_setprio 0
	s_setprio 1
	v_mfma_f32_16x16x32_bf16 v[118:121], v[176:179], v[196:199], v[118:121]
	v_mfma_f32_16x16x32_bf16 v[114:117], v[184:187], v[196:199], v[114:117]
	v_mfma_f32_16x16x32_bf16 v[98:101], v[184:187], v[204:207], v[98:101]
	v_mfma_f32_16x16x32_bf16 v[102:105], v[176:179], v[204:207], v[102:105]
	v_mfma_f32_16x16x32_bf16 v[86:89], v[176:179], v[212:215], v[86:89]
	v_mfma_f32_16x16x32_bf16 v[82:85], v[184:187], v[212:215], v[82:85]
	v_mfma_f32_16x16x32_bf16 v[66:69], v[184:187], v[220:223], v[66:69]
	v_mfma_f32_16x16x32_bf16 v[70:73], v[176:179], v[220:223], v[70:73]
	v_mfma_f32_16x16x32_bf16 v[118:121], v[180:183], v[200:203], v[118:121]
	v_mfma_f32_16x16x32_bf16 v[114:117], v[192:195], v[200:203], v[114:117]
	v_mfma_f32_16x16x32_bf16 v[98:101], v[192:195], v[208:211], v[98:101]
	v_mfma_f32_16x16x32_bf16 v[102:105], v[180:183], v[208:211], v[102:105]
	v_mfma_f32_16x16x32_bf16 v[86:89], v[180:183], v[216:219], v[86:89]
	v_mfma_f32_16x16x32_bf16 v[82:85], v[192:195], v[216:219], v[82:85]
	v_mfma_f32_16x16x32_bf16 v[66:69], v[192:195], v[224:227], v[66:69]
	v_mfma_f32_16x16x32_bf16 v[70:73], v[180:183], v[224:227], v[70:73]
	s_setprio 0
	s_barrier
; #define PG8_STAGE(bufoff, gbase, voff) do { _Pragma("unroll") for (int _i = 0; _i < 2; ++_i) \
;         __builtin_amdgcn_global_load_lds((const unsigned*)((const char*)(gbase) + (voff)[_i]), (PG8_LAS unsigned*)(lds + (bufoff) + ldsw + _i * 8192), 16, 0, 0); } while (0)
; #define PG8_LDA(dst, b, h) do { _Pragma("unroll") for (int m = 0; m < 4; ++m) _Pragma("unroll") for (int k = 0; k < 2; ++k) dst[m][k] = *(const PG8_LAS bf16x8*)(lds + PG8_SA(b, h) + aoff + m * 2048 + k * 1024); } while (0)
; #define PG8_MMA(ai, bj, At, Bt) do { __builtin_amdgcn_s_setprio(1); _Pragma("unroll") for (int m = 0; m < 4; ++m) _Pragma("unroll") for (int n = 0; n < 2; ++n) _Pragma("unroll") for (int k = 0; k < 2; ++k) \
;         acc[ai][bj][m][n] = __builtin_amdgcn_mfma_f32_16x16x32_bf16(Bt[n][k], At[m][k], acc[ai][bj][m][n], 0, 0, 0); __builtin_amdgcn_s_setprio(0); } while (0)
; #define PG8_WAIT_V(n) asm volatile("s_waitcnt vmcnt(" #n ")" ::: "memory")
; #define PG8_WAIT_L(n) asm volatile("s_waitcnt lgkmcnt(" #n ")" ::: "memory")
; #define PG8_BAR __builtin_amdgcn_s_barrier()
; #define PG8_SCHED __builtin_amdgcn_sched_barrier(0)
; template <class Epi, class Sched, bool ALIGN_EPI = false, bool SP2 = false>
; __device__ __forceinline__ void gemm_phase(PG8_LAS unsigned char* lds, const Gemm g, const Sched& S, const Epi& E, const int tid) {
;     ...
;             PG8_LDA(At, 1, 1); PG8_STAGE(PG8_SB(1, 0), b3, voffB); PG8_STAGE(PG8_SB(1, 1), b3 + hstep, voffB); PG8_STAGE(PG8_SA(1, 0), a3, voffA);
;             PG8_WAIT_V(8); PG8_WAIT_L(0); PG8_BAR; PG8_MMA(1, 0, At, B0); PG8_MMA(1, 1, At, B1); PG8_BAR; PG8_SCHED;
;     ...
;         if constexpr (ALIGN_EPI) { if (wr == 0) PG8_BAR; }
	s_add_i32 s15, s15, s66
	v_lshl_add_u64 v[170:171], v[170:171], 0, s[44:45]
	s_mov_b32 m0, s15
	ds_read_b128 v[196:199], v174 offset:49152
	ds_read_b128 v[200:203], v174 offset:50176
	ds_read_b128 v[204:207], v174 offset:51200
	ds_read_b128 v[208:211], v174 offset:52224
	ds_read_b128 v[212:215], v174 offset:53248
	ds_read_b128 v[216:219], v174 offset:54272
	ds_read_b128 v[220:223], v174 offset:55296
	ds_read_b128 v[224:227], v174 offset:56320
	global_load_lds_dwordx4 v[170:171], off
	s_add_i32 m0, s15, 0x2000
	s_add_u32 s18, s58, 0x40080
	v_lshl_add_u64 v[170:171], v[188:189], 0, s[44:45]
	s_addc_u32 s19, s59, 0
	s_add_i32 s15, s62, s66
	global_load_lds_dwordx4 v[170:171], off
	v_lshl_add_u64 v[170:171], s[18:19], 0, v[142:143]
	s_mov_b32 m0, s15
	s_nop 0
	global_load_lds_dwordx4 v[170:171], off
	v_lshl_add_u64 v[170:171], s[18:19], 0, v[146:147]
	s_add_i32 m0, s15, 0x2000
	s_nop 0
	global_load_lds_dwordx4 v[170:171], off
	v_lshl_add_u64 v[170:171], v[228:229], 0, s[44:45]
	s_mov_b32 m0, s77
	s_nop 0
	global_load_lds_dwordx4 v[170:171], off
	v_lshl_add_u64 v[170:171], v[230:231], 0, s[44:45]
	s_mov_b32 m0, s78
	s_nop 0
	global_load_lds_dwordx4 v[170:171], off
	s_waitcnt vmcnt(8)
	s_waitcnt lgkmcnt(0)
	s_barrier
	s_setprio 1
	s_waitcnt lgkmcnt(0)
	v_mfma_f32_16x16x32_bf16 v[62:65], v[130:133], v[196:199], v[62:65]
	v_mfma_f32_16x16x32_bf16 v[58:61], v[162:165], v[196:199], v[58:61]
	v_mfma_f32_16x16x32_bf16 v[42:45], v[162:165], v[204:207], v[42:45]
	v_mfma_f32_16x16x32_bf16 v[46:49], v[130:133], v[204:207], v[46:49]
	v_mfma_f32_16x16x32_bf16 v[30:33], v[130:133], v[212:215], v[30:33]
	v_mfma_f32_16x16x32_bf16 v[26:29], v[162:165], v[212:215], v[26:29]
	v_mfma_f32_16x16x32_bf16 v[10:13], v[162:165], v[220:223], v[10:13]
	v_mfma_f32_16x16x32_bf16 v[14:17], v[130:133], v[220:223], v[14:17]
	v_mfma_f32_16x16x32_bf16 v[62:65], v[134:137], v[200:203], v[62:65]
	v_mfma_f32_16x16x32_bf16 v[58:61], v[166:169], v[200:203], v[58:61]
	v_mfma_f32_16x16x32_bf16 v[42:45], v[166:169], v[208:211], v[42:45]
	v_mfma_f32_16x16x32_bf16 v[46:49], v[134:137], v[208:211], v[46:49]
	v_mfma_f32_16x16x32_bf16 v[30:33], v[134:137], v[216:219], v[30:33]
	v_mfma_f32_16x16x32_bf16 v[26:29], v[166:169], v[216:219], v[26:29]
	v_mfma_f32_16x16x32_bf16 v[10:13], v[166:169], v[224:227], v[10:13]
	v_mfma_f32_16x16x32_bf16 v[14:17], v[134:137], v[224:227], v[14:17]
	s_setprio 0
	s_setprio 1
	v_mfma_f32_16x16x32_bf16 v[54:57], v[176:179], v[196:199], v[54:57]
	v_mfma_f32_16x16x32_bf16 v[50:53], v[184:187], v[196:199], v[50:53]
	v_mfma_f32_16x16x32_bf16 v[34:37], v[184:187], v[204:207], v[34:37]
	v_mfma_f32_16x16x32_bf16 v[38:41], v[176:179], v[204:207], v[38:41]
	v_mfma_f32_16x16x32_bf16 v[22:25], v[176:179], v[212:215], v[22:25]
	v_mfma_f32_16x16x32_bf16 v[18:21], v[184:187], v[212:215], v[18:21]
	v_mfma_f32_16x16x32_bf16 v[2:5], v[184:187], v[220:223], v[2:5]
	v_mfma_f32_16x16x32_bf16 v[6:9], v[176:179], v[220:223], v[6:9]
	v_mfma_f32_16x16x32_bf16 v[54:57], v[180:183], v[200:203], v[54:57]
	v_mfma_f32_16x16x32_bf16 v[50:53], v[192:195], v[200:203], v[50:53]
	v_mfma_f32_16x16x32_bf16 v[34:37], v[192:195], v[208:211], v[34:37]
	v_mfma_f32_16x16x32_bf16 v[38:41], v[180:183], v[208:211], v[38:41]
	v_mfma_f32_16x16x32_bf16 v[22:25], v[180:183], v[216:219], v[22:25]
	v_mfma_f32_16x16x32_bf16 v[18:21], v[192:195], v[216:219], v[18:21]
	v_mfma_f32_16x16x32_bf16 v[2:5], v[192:195], v[224:227], v[2:5]
	v_mfma_f32_16x16x32_bf16 v[6:9], v[180:183], v[224:227], v[6:9]
	s_setprio 0
	s_barrier
	s_add_i32 s51, s51, 2
	s_add_u32 s5, s5, 0x100
	s_addc_u32 s49, s49, 0
	s_add_u32 s56, s56, 0x100
	s_addc_u32 s57, s57, 0
	s_cmp_gt_u32 s51, 13
	s_cbranch_scc0 .LBB0_1122
	s_and_b64 vcc, exec, s[46:47]
	s_cbranch_vccz .LBB0_1125
	s_barrier

; #define PG8_STAGE(bufoff, gbase, voff) do { _Pragma("unroll") for (int _i = 0; _i < 2; ++_i) \
;         __builtin_amdgcn_global_load_lds((const unsigned*)((const char*)(gbase) + (voff)[_i]), (PG8_LAS unsigned*)(lds + (bufoff) + ldsw + _i * 8192), 16, 0, 0); } while (0)
; #define PG8_LDA(dst, b, h) do { _Pragma("unroll") for (int m = 0; m < 4; ++m) _Pragma("unroll") for (int k = 0; k < 2; ++k) dst[m][k] = *(const PG8_LAS bf16x8*)(lds + PG8_SA(b, h) + aoff + m * 2048 + k * 1024); } while (0)
; #define PG8_LDB(dst, b, h) do { _Pragma("unroll") for (int n = 0; n < 2; ++n) _Pragma("unroll") for (int k = 0; k < 2; ++k) dst[n][k] = *(const PG8_LAS bf16x8*)(lds + PG8_SB(b, h) + boff + n * 2048 + k * 1024); } while (0)
; #define PG8_WAIT_V(n) asm volatile("s_waitcnt vmcnt(" #n ")" ::: "memory")
; #define PG8_WAIT_L(n) asm volatile("s_waitcnt lgkmcnt(" #n ")" ::: "memory")
; #define PG8_BAR __builtin_amdgcn_s_barrier()
; #define PG8_SCHED __builtin_amdgcn_sched_barrier(0)
; template <class Epi, class Sched, bool ALIGN_EPI = false, bool SP2 = false>
; __device__ __forceinline__ void gemm_phase(PG8_LAS unsigned char* lds, const Gemm g, const Sched& S, const Epi& E, const int tid) {
;     ...
;         const bool has_next = S.next(ui + 1, nxt);
;         const char* nA = has_next ? S.aptr(nxt) : cA; const char* nB = has_next ? S.bptr(nxt) : cB;
;         for (int t = 0; t < nt; t += 2) {
;             const bool last = (t == nt - 2);
;             const char* a1 = cA + (size_t)(t + 1) * kstep;
;             const char* a2 = last ? nA : cA + (size_t)(t + 2) * kstep; const char* b2 = last ? nB : cB + (size_t)(t + 2) * kstep;
;             const char* a3 = a2 + kstep; const char* b3 = b2 + kstep;
;             if (last && has_next) S.a_ready(nxt);
;             if constexpr (SP2) {
;             PG8_LDB(B0, 0, 0); PG8_LDB(B1, 0, 1); PG8_SCHED; PG8_LDA(At, 0, 0); PG8_STAGE(PG8_SA(1, 1), a1 + hstep, voffA);
;             PG8_WAIT_V(8); PG8_WAIT_L(0); PG8_BAR; PG8_MMA(0, 0, At, B0); PG8_MMA(0, 1, At, B1); PG8_BAR; PG8_SCHED;
;             PG8_LDA(At, 0, 1); PG8_STAGE(PG8_SB(0, 0), b2, voffB); PG8_STAGE(PG8_SB(0, 1), b2 + hstep, voffB); PG8_STAGE(PG8_SA(0, 0), a2, voffA);
;             PG8_WAIT_V(8); PG8_WAIT_L(0); PG8_BAR; PG8_MMA(1, 0, At, B0); PG8_MMA(1, 1, At, B1); PG8_BAR; PG8_SCHED;
.LBB0_1373:
	s_ashr_i32 s39, s38, 31
	s_lshl_b64 s[18:19], s[38:39], 19
	s_add_u32 s40, s52, s18
	s_addc_u32 s41, s53, s19
	s_and_b64 s[18:19], s[4:5], exec
	s_cselect_b32 s7, s41, s11
	s_cselect_b32 s39, s40, s10
	s_ashr_i32 s37, s36, 31
	s_lshl_b64 s[18:19], s[36:37], 19
	s_add_u32 s42, s54, s18
	s_addc_u32 s43, s55, s19
	s_and_b64 s[18:19], s[4:5], exec
	s_cselect_b32 s37, s43, s9
	s_cselect_b32 s45, s42, s8
	s_add_u32 s48, s8, 0x100
	s_addc_u32 s49, s9, 0
	s_add_u32 s8, s10, 0x40080
	s_addc_u32 s9, s11, 0
	s_mov_b32 s76, -2
	ds_read_b128 v[130:133], v204
	ds_read_b128 v[134:137], v204 offset:1024
	ds_read_b128 v[138:141], v204 offset:2048
	ds_read_b128 v[142:145], v204 offset:3072
	ds_read_b128 v[146:149], v205
	ds_read_b128 v[150:153], v205 offset:1024
	ds_read_b128 v[154:157], v205 offset:2048
	ds_read_b128 v[158:161], v205 offset:3072
	s_add_u32 s10, s8, 0xfffc0080
	s_addc_u32 s11, s9, -1
	s_cmp_eq_u32 s76, 12
	s_cselect_b32 s47, s7, s11
	s_cselect_b32 s46, s39, s10
	s_cselect_b32 s11, s37, s49
	s_cselect_b32 s10, s45, s48
	v_lshl_add_u64 v[220:221], s[8:9], 0, v[176:177]
	s_add_i32 m0, s57, 0xc000
	ds_read_b128 v[182:185], v206
	ds_read_b128 v[186:189], v206 offset:1024
	ds_read_b128 v[192:195], v206 offset:2048
	ds_read_b128 v[196:199], v206 offset:3072
	ds_read_b128 v[200:203], v206 offset:4096
	ds_read_b128 v[208:211], v206 offset:5120
	ds_read_b128 v[212:215], v206 offset:6144
	ds_read_b128 v[216:219], v206 offset:7168
	global_load_lds_dwordx4 v[220:221], off
	v_lshl_add_u64 v[220:221], s[8:9], 0, v[174:175]
	s_add_i32 m0, s57, 0xe000
	s_nop 0
	global_load_lds_dwordx4 v[220:221], off
	s_waitcnt vmcnt(8)
	s_waitcnt lgkmcnt(0)
	s_barrier
	s_setprio 1
	s_waitcnt lgkmcnt(0)
	v_mfma_f32_16x16x32_bf16 v[126:129], v[130:133], v[182:185], 0
	v_mfma_f32_16x16x32_bf16 v[122:125], v[138:141], v[182:185], 0
	v_mfma_f32_16x16x32_bf16 v[106:109], v[138:141], v[192:195], 0
	v_mfma_f32_16x16x32_bf16 v[110:113], v[130:133], v[192:195], 0
	v_mfma_f32_16x16x32_bf16 v[94:97], v[130:133], v[200:203], 0
	v_mfma_f32_16x16x32_bf16 v[90:93], v[138:141], v[200:203], 0
	v_mfma_f32_16x16x32_bf16 v[74:77], v[138:141], v[212:215], 0
	v_mfma_f32_16x16x32_bf16 v[78:81], v[130:133], v[212:215], 0
	v_mfma_f32_16x16x32_bf16 v[126:129], v[134:137], v[186:189], v[126:129]
	v_mfma_f32_16x16x32_bf16 v[122:125], v[142:145], v[186:189], v[122:125]
	v_mfma_f32_16x16x32_bf16 v[106:109], v[142:145], v[196:199], v[106:109]
	v_mfma_f32_16x16x32_bf16 v[110:113], v[134:137], v[196:199], v[110:113]
	v_mfma_f32_16x16x32_bf16 v[94:97], v[134:137], v[208:211], v[94:97]
	v_mfma_f32_16x16x32_bf16 v[90:93], v[142:145], v[208:211], v[90:93]
	v_mfma_f32_16x16x32_bf16 v[74:77], v[142:145], v[216:219], v[74:77]
	v_mfma_f32_16x16x32_bf16 v[78:81], v[134:137], v[216:219], v[78:81]
	s_setprio 0
	s_setprio 1
	v_mfma_f32_16x16x32_bf16 v[118:121], v[146:149], v[182:185], 0
	v_mfma_f32_16x16x32_bf16 v[114:117], v[154:157], v[182:185], 0
	v_mfma_f32_16x16x32_bf16 v[98:101], v[154:157], v[192:195], 0
	v_mfma_f32_16x16x32_bf16 v[102:105], v[146:149], v[192:195], 0
	v_mfma_f32_16x16x32_bf16 v[86:89], v[146:149], v[200:203], 0
	v_mfma_f32_16x16x32_bf16 v[82:85], v[154:157], v[200:203], 0
	v_mfma_f32_16x16x32_bf16 v[66:69], v[154:157], v[212:215], 0
	v_mfma_f32_16x16x32_bf16 v[70:73], v[146:149], v[212:215], 0
	v_mfma_f32_16x16x32_bf16 v[118:121], v[150:153], v[186:189], v[118:121]
	v_mfma_f32_16x16x32_bf16 v[114:117], v[158:161], v[186:189], v[114:117]
	v_mfma_f32_16x16x32_bf16 v[98:101], v[158:161], v[196:199], v[98:101]
	v_mfma_f32_16x16x32_bf16 v[102:105], v[150:153], v[196:199], v[102:105]
	v_mfma_f32_16x16x32_bf16 v[86:89], v[150:153], v[208:211], v[86:89]
	v_mfma_f32_16x16x32_bf16 v[82:85], v[158:161], v[208:211], v[82:85]
	v_mfma_f32_16x16x32_bf16 v[66:69], v[158:161], v[216:219], v[66:69]
	v_mfma_f32_16x16x32_bf16 v[70:73], v[150:153], v[216:219], v[70:73]
	s_setprio 0
	s_barrier
	s_add_i32 s15, s67, s56
	v_lshl_add_u64 v[220:221], s[10:11], 0, v[164:165]
	s_mov_b32 m0, s15
	ds_read_b128 v[182:185], v206 offset:16384
	ds_read_b128 v[186:189], v206 offset:17408
	ds_read_b128 v[192:195], v206 offset:18432
	ds_read_b128 v[196:199], v206 offset:19456
	ds_read_b128 v[200:203], v206 offset:20480
	ds_read_b128 v[208:211], v206 offset:21504
	ds_read_b128 v[212:215], v206 offset:22528
	ds_read_b128 v[216:219], v206 offset:23552
	global_load_lds_dwordx4 v[220:221], off
	s_add_i32 m0, s15, 0x2000
	s_add_u32 s18, s10, 0x40000
	v_lshl_add_u64 v[222:223], s[10:11], 0, v[168:169]
	s_addc_u32 s19, s11, 0
	s_add_i32 s15, s68, s56
	global_load_lds_dwordx4 v[222:223], off
	v_lshl_add_u64 v[224:225], s[18:19], 0, v[164:165]
	s_mov_b32 m0, s15
	v_lshl_add_u64 v[226:227], s[46:47], 0, v[166:167]
	global_load_lds_dwordx4 v[224:225], off
	v_lshl_add_u64 v[224:225], s[18:19], 0, v[168:169]
	s_add_i32 m0, s15, 0x2000
	s_nop 0
	global_load_lds_dwordx4 v[224:225], off
	v_lshl_add_u64 v[224:225], s[46:47], 0, v[162:163]
	s_mov_b32 m0, s57
	s_nop 0
	global_load_lds_dwordx4 v[224:225], off
	s_mov_b32 m0, s58
	s_nop 0
	global_load_lds_dwordx4 v[226:227], off
	s_waitcnt vmcnt(8)
	s_waitcnt lgkmcnt(0)
	s_barrier
; #define PG8_STAGE(bufoff, gbase, voff) do { _Pragma("unroll") for (int _i = 0; _i < 2; ++_i) \
;         __builtin_amdgcn_global_load_lds((const unsigned*)((const char*)(gbase) + (voff)[_i]), (PG8_LAS unsigned*)(lds + (bufoff) + ldsw + _i * 8192), 16, 0, 0); } while (0)
; #define PG8_LDA(dst, b, h) do { _Pragma("unroll") for (int m = 0; m < 4; ++m) _Pragma("unroll") for (int k = 0; k < 2; ++k) dst[m][k] = *(const PG8_LAS bf16x8*)(lds + PG8_SA(b, h) + aoff + m * 2048 + k * 1024); } while (0)
; #define PG8_LDB(dst, b, h) do { _Pragma("unroll") for (int n = 0; n < 2; ++n) _Pragma("unroll") for (int k = 0; k < 2; ++k) dst[n][k] = *(const PG8_LAS bf16x8*)(lds + PG8_SB(b, h) + boff + n * 2048 + k * 1024); } while (0)
; #define PG8_MMA(ai, bj, At, Bt) do { __builtin_amdgcn_s_setprio(1); _Pragma("unroll") for (int m = 0; m < 4; ++m) _Pragma("unroll") for (int n = 0; n < 2; ++n) _Pragma("unroll") for (int k = 0; k < 2; ++k) \
;         acc[ai][bj][m][n] = __builtin_amdgcn_mfma_f32_16x16x32_bf16(Bt[n][k], At[m][k], acc[ai][bj][m][n], 0, 0, 0); __builtin_amdgcn_s_setprio(0); } while (0)
; #define PG8_WAIT_V(n) asm volatile("s_waitcnt vmcnt(" #n ")" ::: "memory")
; #define PG8_WAIT_L(n) asm volatile("s_waitcnt lgkmcnt(" #n ")" ::: "memory")
; #define PG8_BAR __builtin_amdgcn_s_barrier()
; #define PG8_SCHED __builtin_amdgcn_sched_barrier(0)
; template <class Epi, class Sched, bool ALIGN_EPI = false, bool SP2 = false>
; __device__ __forceinline__ void gemm_phase(PG8_LAS unsigned char* lds, const Gemm g, const Sched& S, const Epi& E, const int tid) {
;     ...
;             PG8_WAIT_V(8); PG8_WAIT_L(0); PG8_BAR; PG8_MMA(1, 0, At, B0); PG8_MMA(1, 1, At, B1); PG8_BAR; PG8_SCHED;
;             PG8_LDB(B0, 1, 0); PG8_LDB(B1, 1, 1); PG8_SCHED; PG8_LDA(At, 1, 0); PG8_STAGE(PG8_SA(0, 1), a2 + hstep, voffA);
;             PG8_WAIT_V(8); PG8_WAIT_L(0); PG8_BAR; PG8_MMA(0, 0, At, B0); PG8_MMA(0, 1, At, B1); PG8_BAR; PG8_SCHED;
	s_setprio 1
	s_waitcnt lgkmcnt(0)
	v_mfma_f32_16x16x32_bf16 v[62:65], v[130:133], v[182:185], 0
	v_mfma_f32_16x16x32_bf16 v[58:61], v[138:141], v[182:185], 0
	v_mfma_f32_16x16x32_bf16 v[42:45], v[138:141], v[192:195], 0
	v_mfma_f32_16x16x32_bf16 v[46:49], v[130:133], v[192:195], 0
	v_mfma_f32_16x16x32_bf16 v[30:33], v[130:133], v[200:203], 0
	v_mfma_f32_16x16x32_bf16 v[26:29], v[138:141], v[200:203], 0
	v_mfma_f32_16x16x32_bf16 v[10:13], v[138:141], v[212:215], 0
	v_mfma_f32_16x16x32_bf16 v[14:17], v[130:133], v[212:215], 0
	v_mfma_f32_16x16x32_bf16 v[62:65], v[134:137], v[186:189], v[62:65]
	v_mfma_f32_16x16x32_bf16 v[58:61], v[142:145], v[186:189], v[58:61]
	v_mfma_f32_16x16x32_bf16 v[42:45], v[142:145], v[196:199], v[42:45]
	v_mfma_f32_16x16x32_bf16 v[46:49], v[134:137], v[196:199], v[46:49]
	v_mfma_f32_16x16x32_bf16 v[30:33], v[134:137], v[208:211], v[30:33]
	v_mfma_f32_16x16x32_bf16 v[26:29], v[142:145], v[208:211], v[26:29]
	v_mfma_f32_16x16x32_bf16 v[10:13], v[142:145], v[216:219], v[10:13]
	v_mfma_f32_16x16x32_bf16 v[14:17], v[134:137], v[216:219], v[14:17]
	s_setprio 0
	s_setprio 1
	v_mfma_f32_16x16x32_bf16 v[54:57], v[146:149], v[182:185], 0
	v_mfma_f32_16x16x32_bf16 v[50:53], v[154:157], v[182:185], 0
	v_mfma_f32_16x16x32_bf16 v[34:37], v[154:157], v[192:195], 0
	v_mfma_f32_16x16x32_bf16 v[38:41], v[146:149], v[192:195], 0
	v_mfma_f32_16x16x32_bf16 v[22:25], v[146:149], v[200:203], 0
	v_mfma_f32_16x16x32_bf16 v[18:21], v[154:157], v[200:203], 0
	v_mfma_f32_16x16x32_bf16 v[2:5], v[154:157], v[212:215], 0
	v_mfma_f32_16x16x32_bf16 v[6:9], v[146:149], v[212:215], 0
	v_mfma_f32_16x16x32_bf16 v[54:57], v[150:153], v[186:189], v[54:57]
	v_mfma_f32_16x16x32_bf16 v[50:53], v[158:161], v[186:189], v[50:53]
	v_mfma_f32_16x16x32_bf16 v[34:37], v[158:161], v[196:199], v[34:37]
	v_mfma_f32_16x16x32_bf16 v[38:41], v[150:153], v[196:199], v[38:41]
	v_mfma_f32_16x16x32_bf16 v[22:25], v[150:153], v[208:211], v[22:25]
	v_mfma_f32_16x16x32_bf16 v[18:21], v[158:161], v[208:211], v[18:21]
	v_mfma_f32_16x16x32_bf16 v[2:5], v[158:161], v[216:219], v[2:5]
	v_mfma_f32_16x16x32_bf16 v[6:9], v[150:153], v[216:219], v[6:9]
	s_setprio 0
	s_barrier
	s_add_i32 s15, 0, 0x18000
	s_add_i32 s77, 0, 0x1c000
	v_add_u32_e32 v142, s15, v191
	v_add_u32_e32 v158, s77, v191
	ds_read_b128 v[130:133], v142
	ds_read_b128 v[134:137], v142 offset:1024
	ds_read_b128 v[138:141], v142 offset:2048
	ds_read_b128 v[142:145], v142 offset:3072
	ds_read_b128 v[146:149], v158
	ds_read_b128 v[150:153], v158 offset:1024
	ds_read_b128 v[154:157], v158 offset:2048
	ds_read_b128 v[158:161], v158 offset:3072
	s_add_u32 s18, s46, 0x40000
	s_addc_u32 s19, s47, 0
	s_mov_b32 m0, s59
	v_lshl_add_u64 v[228:229], s[18:19], 0, v[162:163]
	ds_read_b128 v[182:185], v206 offset:32768
	ds_read_b128 v[186:189], v206 offset:33792
	ds_read_b128 v[192:195], v206 offset:34816
	ds_read_b128 v[196:199], v206 offset:35840
	ds_read_b128 v[200:203], v206 offset:36864
	ds_read_b128 v[208:211], v206 offset:37888
	ds_read_b128 v[212:215], v206 offset:38912
	ds_read_b128 v[216:219], v206 offset:39936
	global_load_lds_dwordx4 v[228:229], off
	v_lshl_add_u64 v[228:229], s[18:19], 0, v[166:167]
	s_mov_b32 m0, s60
	s_nop 0
	global_load_lds_dwordx4 v[228:229], off
	s_waitcnt vmcnt(8)
	s_waitcnt lgkmcnt(0)
	s_barrier
	s_setprio 1
	s_waitcnt lgkmcnt(0)
	v_mfma_f32_16x16x32_bf16 v[126:129], v[130:133], v[182:185], v[126:129]
	v_mfma_f32_16x16x32_bf16 v[122:125], v[138:141], v[182:185], v[122:125]
	v_mfma_f32_16x16x32_bf16 v[106:109], v[138:141], v[192:195], v[106:109]
	v_mfma_f32_16x16x32_bf16 v[110:113], v[130:133], v[192:195], v[110:113]
	v_mfma_f32_16x16x32_bf16 v[94:97], v[130:133], v[200:203], v[94:97]
	v_mfma_f32_16x16x32_bf16 v[90:93], v[138:141], v[200:203], v[90:93]
	v_mfma_f32_16x16x32_bf16 v[74:77], v[138:141], v[212:215], v[74:77]
	v_mfma_f32_16x16x32_bf16 v[78:81], v[130:133], v[212:215], v[78:81]
	v_mfma_f32_16x16x32_bf16 v[126:129], v[134:137], v[186:189], v[126:129]
	v_mfma_f32_16x16x32_bf16 v[122:125], v[142:145], v[186:189], v[122:125]
	v_mfma_f32_16x16x32_bf16 v[106:109], v[142:145], v[196:199], v[106:109]
	v_mfma_f32_16x16x32_bf16 v[110:113], v[134:137], v[196:199], v[110:113]
	v_mfma_f32_16x16x32_bf16 v[94:97], v[134:137], v[208:211], v[94:97]
	v_mfma_f32_16x16x32_bf16 v[90:93], v[142:145], v[208:211], v[90:93]
	v_mfma_f32_16x16x32_bf16 v[74:77], v[142:145], v[216:219], v[74:77]
	v_mfma_f32_16x16x32_bf16 v[78:81], v[134:137], v[216:219], v[78:81]
	s_setprio 0
	s_setprio 1
	v_mfma_f32_16x16x32_bf16 v[118:121], v[146:149], v[182:185], v[118:121]
	v_mfma_f32_16x16x32_bf16 v[114:117], v[154:157], v[182:185], v[114:117]
	v_mfma_f32_16x16x32_bf16 v[98:101], v[154:157], v[192:195], v[98:101]
	v_mfma_f32_16x16x32_bf16 v[102:105], v[146:149], v[192:195], v[102:105]
	v_mfma_f32_16x16x32_bf16 v[86:89], v[146:149], v[200:203], v[86:89]
	v_mfma_f32_16x16x32_bf16 v[82:85], v[154:157], v[200:203], v[82:85]
	v_mfma_f32_16x16x32_bf16 v[66:69], v[154:157], v[212:215], v[66:69]
	v_mfma_f32_16x16x32_bf16 v[70:73], v[146:149], v[212:215], v[70:73]
	v_mfma_f32_16x16x32_bf16 v[118:121], v[150:153], v[186:189], v[118:121]
	v_mfma_f32_16x16x32_bf16 v[114:117], v[158:161], v[186:189], v[114:117]
	v_mfma_f32_16x16x32_bf16 v[98:101], v[158:161], v[196:199], v[98:101]
	v_mfma_f32_16x16x32_bf16 v[102:105], v[150:153], v[196:199], v[102:105]
	v_mfma_f32_16x16x32_bf16 v[86:89], v[150:153], v[208:211], v[86:89]
	v_mfma_f32_16x16x32_bf16 v[82:85], v[158:161], v[208:211], v[82:85]
	v_mfma_f32_16x16x32_bf16 v[66:69], v[158:161], v[216:219], v[66:69]
	v_mfma_f32_16x16x32_bf16 v[70:73], v[150:153], v[216:219], v[70:73]
	s_setprio 0
	s_barrier
; #define PG8_STAGE(bufoff, gbase, voff) do { _Pragma("unroll") for (int _i = 0; _i < 2; ++_i) \
;         __builtin_amdgcn_global_load_lds((const unsigned*)((const char*)(gbase) + (voff)[_i]), (PG8_LAS unsigned*)(lds + (bufoff) + ldsw + _i * 8192), 16, 0, 0); } while (0)
; #define PG8_LDA(dst, b, h) do { _Pragma("unroll") for (int m = 0; m < 4; ++m) _Pragma("unroll") for (int k = 0; k < 2; ++k) dst[m][k] = *(const PG8_LAS bf16x8*)(lds + PG8_SA(b, h) + aoff + m * 2048 + k * 1024); } while (0)
; #define PG8_LDB(dst, b, h) do { _Pragma("unroll") for (int n = 0; n < 2; ++n) _Pragma("unroll") for (int k = 0; k < 2; ++k) dst[n][k] = *(const PG8_LAS bf16x8*)(lds + PG8_SB(b, h) + boff + n * 2048 + k * 1024); } while (0)
; #define PG8_MMA(ai, bj, At, Bt) do { __builtin_amdgcn_s_setprio(1); _Pragma("unroll") for (int m = 0; m < 4; ++m) _Pragma("unroll") for (int n = 0; n < 2; ++n) _Pragma("unroll") for (int k = 0; k < 2; ++k) \
;         acc[ai][bj][m][n] = __builtin_amdgcn_mfma_f32_16x16x32_bf16(Bt[n][k], At[m][k], acc[ai][bj][m][n], 0, 0, 0); __builtin_amdgcn_s_setprio(0); } while (0)
; #define PG8_WAIT_V(n) asm volatile("s_waitcnt vmcnt(" #n ")" ::: "memory")
; #define PG8_WAIT_L(n) asm volatile("s_waitcnt lgkmcnt(" #n ")" ::: "memory")
; #define PG8_BAR __builtin_amdgcn_s_barrier()
; #define PG8_SCHED __builtin_amdgcn_sched_barrier(0)
; template <class Epi, class Sched, bool ALIGN_EPI = false, bool SP2 = false>
; __device__ __forceinline__ void gemm_phase(PG8_LAS unsigned char* lds, const Gemm g, const Sched& S, const Epi& E, const int tid) {
;     ...
;             PG8_LDB(B0, 0, 0); PG8_LDB(B1, 0, 1); PG8_SCHED; PG8_LDA(At, 0, 0); PG8_STAGE(PG8_SA(1, 1), a1 + hstep, voffA);
;             PG8_WAIT_V(8); PG8_WAIT_L(0); PG8_BAR; PG8_MMA(0, 0, At, B0); PG8_MMA(0, 1, At, B1); PG8_BAR; PG8_SCHED;
;     ...
;             PG8_LDA(At, 1, 1); PG8_STAGE(PG8_SB(1, 0), b3, voffB); PG8_STAGE(PG8_SB(1, 1), b3 + hstep, voffB); PG8_STAGE(PG8_SA(1, 0), a3, voffA);
;             PG8_WAIT_V(8); PG8_WAIT_L(0); PG8_BAR; PG8_MMA(1, 0, At, B0); PG8_MMA(1, 1, At, B1); PG8_BAR; PG8_SCHED;
	s_add_i32 s15, s15, s56
	v_lshl_add_u64 v[220:221], v[220:221], 0, s[30:31]
	s_mov_b32 m0, s15
	ds_read_b128 v[182:185], v206 offset:49152
	ds_read_b128 v[186:189], v206 offset:50176
	ds_read_b128 v[192:195], v206 offset:51200
	ds_read_b128 v[196:199], v206 offset:52224
	ds_read_b128 v[200:203], v206 offset:53248
	ds_read_b128 v[208:211], v206 offset:54272
	ds_read_b128 v[212:215], v206 offset:55296
	ds_read_b128 v[216:219], v206 offset:56320
	global_load_lds_dwordx4 v[220:221], off
	s_add_i32 m0, s15, 0x2000
	s_add_u32 s10, s10, 0x40080
	v_lshl_add_u64 v[220:221], v[222:223], 0, s[30:31]
	s_addc_u32 s11, s11, 0
	s_add_i32 s15, s77, s56
	global_load_lds_dwordx4 v[220:221], off
	v_lshl_add_u64 v[220:221], s[10:11], 0, v[164:165]
	s_mov_b32 m0, s15
	s_nop 0
	global_load_lds_dwordx4 v[220:221], off
	v_lshl_add_u64 v[220:221], s[10:11], 0, v[168:169]
	s_add_i32 m0, s15, 0x2000
	s_nop 0
	global_load_lds_dwordx4 v[220:221], off
	v_lshl_add_u64 v[220:221], v[224:225], 0, s[30:31]
	s_mov_b32 m0, s62
	s_nop 0
	global_load_lds_dwordx4 v[220:221], off
	v_lshl_add_u64 v[220:221], v[226:227], 0, s[30:31]
	s_mov_b32 m0, s63
	s_nop 0
	global_load_lds_dwordx4 v[220:221], off
	s_waitcnt vmcnt(8)
	s_waitcnt lgkmcnt(0)
	s_barrier
	s_setprio 1
	s_waitcnt lgkmcnt(0)
	v_mfma_f32_16x16x32_bf16 v[62:65], v[130:133], v[182:185], v[62:65]
	v_mfma_f32_16x16x32_bf16 v[58:61], v[138:141], v[182:185], v[58:61]
	v_mfma_f32_16x16x32_bf16 v[42:45], v[138:141], v[192:195], v[42:45]
	v_mfma_f32_16x16x32_bf16 v[46:49], v[130:133], v[192:195], v[46:49]
	v_mfma_f32_16x16x32_bf16 v[30:33], v[130:133], v[200:203], v[30:33]
	v_mfma_f32_16x16x32_bf16 v[26:29], v[138:141], v[200:203], v[26:29]
	v_mfma_f32_16x16x32_bf16 v[10:13], v[138:141], v[212:215], v[10:13]
	v_mfma_f32_16x16x32_bf16 v[14:17], v[130:133], v[212:215], v[14:17]
	v_mfma_f32_16x16x32_bf16 v[62:65], v[134:137], v[186:189], v[62:65]
	v_mfma_f32_16x16x32_bf16 v[58:61], v[142:145], v[186:189], v[58:61]
	v_mfma_f32_16x16x32_bf16 v[42:45], v[142:145], v[196:199], v[42:45]
	v_mfma_f32_16x16x32_bf16 v[46:49], v[134:137], v[196:199], v[46:49]
	v_mfma_f32_16x16x32_bf16 v[30:33], v[134:137], v[208:211], v[30:33]
	v_mfma_f32_16x16x32_bf16 v[26:29], v[142:145], v[208:211], v[26:29]
	v_mfma_f32_16x16x32_bf16 v[10:13], v[142:145], v[216:219], v[10:13]
	v_mfma_f32_16x16x32_bf16 v[14:17], v[134:137], v[216:219], v[14:17]
	s_setprio 0
	s_setprio 1
	v_mfma_f32_16x16x32_bf16 v[54:57], v[146:149], v[182:185], v[54:57]
	v_mfma_f32_16x16x32_bf16 v[50:53], v[154:157], v[182:185], v[50:53]
	v_mfma_f32_16x16x32_bf16 v[34:37], v[154:157], v[192:195], v[34:37]
	v_mfma_f32_16x16x32_bf16 v[38:41], v[146:149], v[192:195], v[38:41]
	v_mfma_f32_16x16x32_bf16 v[22:25], v[146:149], v[200:203], v[22:25]
	v_mfma_f32_16x16x32_bf16 v[18:21], v[154:157], v[200:203], v[18:21]
	v_mfma_f32_16x16x32_bf16 v[2:5], v[154:157], v[212:215], v[2:5]
	v_mfma_f32_16x16x32_bf16 v[6:9], v[146:149], v[212:215], v[6:9]
	v_mfma_f32_16x16x32_bf16 v[54:57], v[150:153], v[186:189], v[54:57]
	v_mfma_f32_16x16x32_bf16 v[50:53], v[158:161], v[186:189], v[50:53]
	v_mfma_f32_16x16x32_bf16 v[34:37], v[158:161], v[196:199], v[34:37]
	v_mfma_f32_16x16x32_bf16 v[38:41], v[150:153], v[196:199], v[38:41]
	v_mfma_f32_16x16x32_bf16 v[22:25], v[150:153], v[208:211], v[22:25]
	v_mfma_f32_16x16x32_bf16 v[18:21], v[158:161], v[208:211], v[18:21]
	v_mfma_f32_16x16x32_bf16 v[2:5], v[158:161], v[216:219], v[2:5]
	v_mfma_f32_16x16x32_bf16 v[6:9], v[150:153], v[216:219], v[6:9]
	s_setprio 0
	s_barrier
	s_add_i32 s76, s76, 2
	s_add_u32 s48, s48, 0x100
	s_addc_u32 s49, s49, 0
	s_add_u32 s8, s8, 0x100
	s_addc_u32 s9, s9, 0
.LBB0_1374:
	ds_read_b128 v[130:133], v204
	ds_read_b128 v[134:137], v204 offset:1024
	ds_read_b128 v[138:141], v204 offset:2048
	ds_read_b128 v[142:145], v204 offset:3072
	ds_read_b128 v[146:149], v205
	ds_read_b128 v[150:153], v205 offset:1024
	ds_read_b128 v[154:157], v205 offset:2048
	ds_read_b128 v[158:161], v205 offset:3072
	s_add_u32 s10, s8, 0xfffc0080
	s_addc_u32 s11, s9, -1
	s_cmp_eq_u32 s76, 12
	s_cselect_b32 s47, s7, s11
	s_cselect_b32 s46, s39, s10
	s_cselect_b32 s11, s37, s49
	s_cselect_b32 s10, s45, s48
	v_lshl_add_u64 v[220:221], s[8:9], 0, v[176:177]
	s_add_i32 m0, s57, 0xc000
	ds_read_b128 v[182:185], v206
	ds_read_b128 v[186:189], v206 offset:1024
	ds_read_b128 v[192:195], v206 offset:2048
	ds_read_b128 v[196:199], v206 offset:3072
	ds_read_b128 v[200:203], v206 offset:4096
	ds_read_b128 v[208:211], v206 offset:5120
	ds_read_b128 v[212:215], v206 offset:6144
	ds_read_b128 v[216:219], v206 offset:7168
	global_load_lds_dwordx4 v[220:221], off
	v_lshl_add_u64 v[220:221], s[8:9], 0, v[174:175]
	s_add_i32 m0, s57, 0xe000
	s_nop 0
	global_load_lds_dwordx4 v[220:221], off
	s_waitcnt vmcnt(8)
	s_waitcnt lgkmcnt(0)
	s_barrier
; #define PG8_STAGE(bufoff, gbase, voff) do { _Pragma("unroll") for (int _i = 0; _i < 2; ++_i) \
;         __builtin_amdgcn_global_load_lds((const unsigned*)((const char*)(gbase) + (voff)[_i]), (PG8_LAS unsigned*)(lds + (bufoff) + ldsw + _i * 8192), 16, 0, 0); } while (0)
; #define PG8_LDA(dst, b, h) do { _Pragma("unroll") for (int m = 0; m < 4; ++m) _Pragma("unroll") for (int k = 0; k < 2; ++k) dst[m][k] = *(const PG8_LAS bf16x8*)(lds + PG8_SA(b, h) + aoff + m * 2048 + k * 1024); } while (0)
; #define PG8_MMA(ai, bj, At, Bt) do { __builtin_amdgcn_s_setprio(1); _Pragma("unroll") for (int m = 0; m < 4; ++m) _Pragma("unroll") for (int n = 0; n < 2; ++n) _Pragma("unroll") for (int k = 0; k < 2; ++k) \
;         acc[ai][bj][m][n] = __builtin_amdgcn_mfma_f32_16x16x32_bf16(Bt[n][k], At[m][k], acc[ai][bj][m][n], 0, 0, 0); __builtin_amdgcn_s_setprio(0); } while (0)
; #define PG8_WAIT_V(n) asm volatile("s_waitcnt vmcnt(" #n ")" ::: "memory")
; #define PG8_WAIT_L(n) asm volatile("s_waitcnt lgkmcnt(" #n ")" ::: "memory")
; #define PG8_BAR __builtin_amdgcn_s_barrier()
; #define PG8_SCHED __builtin_amdgcn_sched_barrier(0)
; template <class Epi, class Sched, bool ALIGN_EPI = false, bool SP2 = false>
; __device__ __forceinline__ void gemm_phase(PG8_LAS unsigned char* lds, const Gemm g, const Sched& S, const Epi& E, const int tid) {
;     ...
;             PG8_WAIT_V(8); PG8_WAIT_L(0); PG8_BAR; PG8_MMA(0, 0, At, B0); PG8_MMA(0, 1, At, B1); PG8_BAR; PG8_SCHED;
;             PG8_LDA(At, 0, 1); PG8_STAGE(PG8_SB(0, 0), b2, voffB); PG8_STAGE(PG8_SB(0, 1), b2 + hstep, voffB); PG8_STAGE(PG8_SA(0, 0), a2, voffA);
;             PG8_WAIT_V(8); PG8_WAIT_L(0); PG8_BAR; PG8_MMA(1, 0, At, B0); PG8_MMA(1, 1, At, B1); PG8_BAR; PG8_SCHED;
	s_setprio 1
	s_waitcnt lgkmcnt(0)
	v_mfma_f32_16x16x32_bf16 v[126:129], v[130:133], v[182:185], v[126:129]
	v_mfma_f32_16x16x32_bf16 v[122:125], v[138:141], v[182:185], v[122:125]
	v_mfma_f32_16x16x32_bf16 v[106:109], v[138:141], v[192:195], v[106:109]
	v_mfma_f32_16x16x32_bf16 v[110:113], v[130:133], v[192:195], v[110:113]
	v_mfma_f32_16x16x32_bf16 v[94:97], v[130:133], v[200:203], v[94:97]
	v_mfma_f32_16x16x32_bf16 v[90:93], v[138:141], v[200:203], v[90:93]
	v_mfma_f32_16x16x32_bf16 v[74:77], v[138:141], v[212:215], v[74:77]
	v_mfma_f32_16x16x32_bf16 v[78:81], v[130:133], v[212:215], v[78:81]
	v_mfma_f32_16x16x32_bf16 v[126:129], v[134:137], v[186:189], v[126:129]
	v_mfma_f32_16x16x32_bf16 v[122:125], v[142:145], v[186:189], v[122:125]
	v_mfma_f32_16x16x32_bf16 v[106:109], v[142:145], v[196:199], v[106:109]
	v_mfma_f32_16x16x32_bf16 v[110:113], v[134:137], v[196:199], v[110:113]
	v_mfma_f32_16x16x32_bf16 v[94:97], v[134:137], v[208:211], v[94:97]
	v_mfma_f32_16x16x32_bf16 v[90:93], v[142:145], v[208:211], v[90:93]
	v_mfma_f32_16x16x32_bf16 v[74:77], v[142:145], v[216:219], v[74:77]
	v_mfma_f32_16x16x32_bf16 v[78:81], v[134:137], v[216:219], v[78:81]
	s_setprio 0
	s_setprio 1
	v_mfma_f32_16x16x32_bf16 v[118:121], v[146:149], v[182:185], v[118:121]
	v_mfma_f32_16x16x32_bf16 v[114:117], v[154:157], v[182:185], v[114:117]
	v_mfma_f32_16x16x32_bf16 v[98:101], v[154:157], v[192:195], v[98:101]
	v_mfma_f32_16x16x32_bf16 v[102:105], v[146:149], v[192:195], v[102:105]
	v_mfma_f32_16x16x32_bf16 v[86:89], v[146:149], v[200:203], v[86:89]
	v_mfma_f32_16x16x32_bf16 v[82:85], v[154:157], v[200:203], v[82:85]
	v_mfma_f32_16x16x32_bf16 v[66:69], v[154:157], v[212:215], v[66:69]
	v_mfma_f32_16x16x32_bf16 v[70:73], v[146:149], v[212:215], v[70:73]
	v_mfma_f32_16x16x32_bf16 v[118:121], v[150:153], v[186:189], v[118:121]
	v_mfma_f32_16x16x32_bf16 v[114:117], v[158:161], v[186:189], v[114:117]
	v_mfma_f32_16x16x32_bf16 v[98:101], v[158:161], v[196:199], v[98:101]
	v_mfma_f32_16x16x32_bf16 v[102:105], v[150:153], v[196:199], v[102:105]
	v_mfma_f32_16x16x32_bf16 v[86:89], v[150:153], v[208:211], v[86:89]
	v_mfma_f32_16x16x32_bf16 v[82:85], v[158:161], v[208:211], v[82:85]
	v_mfma_f32_16x16x32_bf16 v[66:69], v[158:161], v[216:219], v[66:69]
	v_mfma_f32_16x16x32_bf16 v[70:73], v[150:153], v[216:219], v[70:73]
	s_setprio 0
	s_barrier
	s_add_i32 s15, s67, s56
	v_lshl_add_u64 v[220:221], s[10:11], 0, v[164:165]
	s_mov_b32 m0, s15
	ds_read_b128 v[182:185], v206 offset:16384
	ds_read_b128 v[186:189], v206 offset:17408
	ds_read_b128 v[192:195], v206 offset:18432
	ds_read_b128 v[196:199], v206 offset:19456
	ds_read_b128 v[200:203], v206 offset:20480
	ds_read_b128 v[208:211], v206 offset:21504
	ds_read_b128 v[212:215], v206 offset:22528
	ds_read_b128 v[216:219], v206 offset:23552
	global_load_lds_dwordx4 v[220:221], off
	s_add_i32 m0, s15, 0x2000
	s_add_u32 s18, s10, 0x40000
	v_lshl_add_u64 v[222:223], s[10:11], 0, v[168:169]
	s_addc_u32 s19, s11, 0
	s_add_i32 s15, s68, s56
	global_load_lds_dwordx4 v[222:223], off
	v_lshl_add_u64 v[224:225], s[18:19], 0, v[164:165]
	s_mov_b32 m0, s15
	v_lshl_add_u64 v[226:227], s[46:47], 0, v[166:167]
	global_load_lds_dwordx4 v[224:225], off
	v_lshl_add_u64 v[224:225], s[18:19], 0, v[168:169]
	s_add_i32 m0, s15, 0x2000
	s_nop 0
	global_load_lds_dwordx4 v[224:225], off
	v_lshl_add_u64 v[224:225], s[46:47], 0, v[162:163]
	s_mov_b32 m0, s57
	s_nop 0
	global_load_lds_dwordx4 v[224:225], off
	s_mov_b32 m0, s58
	s_nop 0
	global_load_lds_dwordx4 v[226:227], off
	s_waitcnt vmcnt(8)
	s_waitcnt lgkmcnt(0)
	s_barrier
	s_setprio 1
	s_waitcnt lgkmcnt(0)
	v_mfma_f32_16x16x32_bf16 v[62:65], v[130:133], v[182:185], v[62:65]
	v_mfma_f32_16x16x32_bf16 v[58:61], v[138:141], v[182:185], v[58:61]
	v_mfma_f32_16x16x32_bf16 v[42:45], v[138:141], v[192:195], v[42:45]
	v_mfma_f32_16x16x32_bf16 v[46:49], v[130:133], v[192:195], v[46:49]
	v_mfma_f32_16x16x32_bf16 v[30:33], v[130:133], v[200:203], v[30:33]
	v_mfma_f32_16x16x32_bf16 v[26:29], v[138:141], v[200:203], v[26:29]
	v_mfma_f32_16x16x32_bf16 v[10:13], v[138:141], v[212:215], v[10:13]
	v_mfma_f32_16x16x32_bf16 v[14:17], v[130:133], v[212:215], v[14:17]
	v_mfma_f32_16x16x32_bf16 v[62:65], v[134:137], v[186:189], v[62:65]
	v_mfma_f32_16x16x32_bf16 v[58:61], v[142:145], v[186:189], v[58:61]
	v_mfma_f32_16x16x32_bf16 v[42:45], v[142:145], v[196:199], v[42:45]
	v_mfma_f32_16x16x32_bf16 v[46:49], v[134:137], v[196:199], v[46:49]
	v_mfma_f32_16x16x32_bf16 v[30:33], v[134:137], v[208:211], v[30:33]
	v_mfma_f32_16x16x32_bf16 v[26:29], v[142:145], v[208:211], v[26:29]
	v_mfma_f32_16x16x32_bf16 v[10:13], v[142:145], v[216:219], v[10:13]
	v_mfma_f32_16x16x32_bf16 v[14:17], v[134:137], v[216:219], v[14:17]
	s_setprio 0
	s_setprio 1
	v_mfma_f32_16x16x32_bf16 v[54:57], v[146:149], v[182:185], v[54:57]
	v_mfma_f32_16x16x32_bf16 v[50:53], v[154:157], v[182:185], v[50:53]
	v_mfma_f32_16x16x32_bf16 v[34:37], v[154:157], v[192:195], v[34:37]
	v_mfma_f32_16x16x32_bf16 v[38:41], v[146:149], v[192:195], v[38:41]
	v_mfma_f32_16x16x32_bf16 v[22:25], v[146:149], v[200:203], v[22:25]
	v_mfma_f32_16x16x32_bf16 v[18:21], v[154:157], v[200:203], v[18:21]
	v_mfma_f32_16x16x32_bf16 v[2:5], v[154:157], v[212:215], v[2:5]
	v_mfma_f32_16x16x32_bf16 v[6:9], v[146:149], v[212:215], v[6:9]
	v_mfma_f32_16x16x32_bf16 v[54:57], v[150:153], v[186:189], v[54:57]
	v_mfma_f32_16x16x32_bf16 v[50:53], v[158:161], v[186:189], v[50:53]
	v_mfma_f32_16x16x32_bf16 v[34:37], v[158:161], v[196:199], v[34:37]
	v_mfma_f32_16x16x32_bf16 v[38:41], v[150:153], v[196:199], v[38:41]
	v_mfma_f32_16x16x32_bf16 v[22:25], v[150:153], v[208:211], v[22:25]
	v_mfma_f32_16x16x32_bf16 v[18:21], v[158:161], v[208:211], v[18:21]
	v_mfma_f32_16x16x32_bf16 v[2:5], v[158:161], v[216:219], v[2:5]
	v_mfma_f32_16x16x32_bf16 v[6:9], v[150:153], v[216:219], v[6:9]
	s_setprio 0
	s_barrier
; #define PG8_STAGE(bufoff, gbase, voff) do { _Pragma("unroll") for (int _i = 0; _i < 2; ++_i) \
;         __builtin_amdgcn_global_load_lds((const unsigned*)((const char*)(gbase) + (voff)[_i]), (PG8_LAS unsigned*)(lds + (bufoff) + ldsw + _i * 8192), 16, 0, 0); } while (0)
; #define PG8_LDA(dst, b, h) do { _Pragma("unroll") for (int m = 0; m < 4; ++m) _Pragma("unroll") for (int k = 0; k < 2; ++k) dst[m][k] = *(const PG8_LAS bf16x8*)(lds + PG8_SA(b, h) + aoff + m * 2048 + k * 1024); } while (0)
; #define PG8_LDB(dst, b, h) do { _Pragma("unroll") for (int n = 0; n < 2; ++n) _Pragma("unroll") for (int k = 0; k < 2; ++k) dst[n][k] = *(const PG8_LAS bf16x8*)(lds + PG8_SB(b, h) + boff + n * 2048 + k * 1024); } while (0)
; #define PG8_MMA(ai, bj, At, Bt) do { __builtin_amdgcn_s_setprio(1); _Pragma("unroll") for (int m = 0; m < 4; ++m) _Pragma("unroll") for (int n = 0; n < 2; ++n) _Pragma("unroll") for (int k = 0; k < 2; ++k) \
;         acc[ai][bj][m][n] = __builtin_amdgcn_mfma_f32_16x16x32_bf16(Bt[n][k], At[m][k], acc[ai][bj][m][n], 0, 0, 0); __builtin_amdgcn_s_setprio(0); } while (0)
; #define PG8_WAIT_V(n) asm volatile("s_waitcnt vmcnt(" #n ")" ::: "memory")
; #define PG8_WAIT_L(n) asm volatile("s_waitcnt lgkmcnt(" #n ")" ::: "memory")
; #define PG8_BAR __builtin_amdgcn_s_barrier()
; #define PG8_SCHED __builtin_amdgcn_sched_barrier(0)
; template <class Epi, class Sched, bool ALIGN_EPI = false, bool SP2 = false>
; __device__ __forceinline__ void gemm_phase(PG8_LAS unsigned char* lds, const Gemm g, const Sched& S, const Epi& E, const int tid) {
;     ...
;             PG8_LDB(B0, 1, 0); PG8_LDB(B1, 1, 1); PG8_SCHED; PG8_LDA(At, 1, 0); PG8_STAGE(PG8_SA(0, 1), a2 + hstep, voffA);
;             PG8_WAIT_V(8); PG8_WAIT_L(0); PG8_BAR; PG8_MMA(0, 0, At, B0); PG8_MMA(0, 1, At, B1); PG8_BAR; PG8_SCHED;
	s_add_i32 s15, 0, 0x18000
	s_add_i32 s77, 0, 0x1c000
	v_add_u32_e32 v142, s15, v191
	v_add_u32_e32 v158, s77, v191
	ds_read_b128 v[130:133], v142
	ds_read_b128 v[134:137], v142 offset:1024
	ds_read_b128 v[138:141], v142 offset:2048
	ds_read_b128 v[142:145], v142 offset:3072
	ds_read_b128 v[146:149], v158
	ds_read_b128 v[150:153], v158 offset:1024
	ds_read_b128 v[154:157], v158 offset:2048
	ds_read_b128 v[158:161], v158 offset:3072
	s_add_u32 s18, s46, 0x40000
	s_addc_u32 s19, s47, 0
	s_mov_b32 m0, s59
	v_lshl_add_u64 v[228:229], s[18:19], 0, v[162:163]
	ds_read_b128 v[182:185], v206 offset:32768
	ds_read_b128 v[186:189], v206 offset:33792
	ds_read_b128 v[192:195], v206 offset:34816
	ds_read_b128 v[196:199], v206 offset:35840
	ds_read_b128 v[200:203], v206 offset:36864
	ds_read_b128 v[208:211], v206 offset:37888
	ds_read_b128 v[212:215], v206 offset:38912
	ds_read_b128 v[216:219], v206 offset:39936
	global_load_lds_dwordx4 v[228:229], off
	v_lshl_add_u64 v[228:229], s[18:19], 0, v[166:167]
	s_mov_b32 m0, s60
	s_nop 0
	global_load_lds_dwordx4 v[228:229], off
	s_waitcnt vmcnt(8)
	s_waitcnt lgkmcnt(0)
	s_barrier
	s_setprio 1
	s_waitcnt lgkmcnt(0)
	v_mfma_f32_16x16x32_bf16 v[126:129], v[130:133], v[182:185], v[126:129]
	v_mfma_f32_16x16x32_bf16 v[122:125], v[138:141], v[182:185], v[122:125]
	v_mfma_f32_16x16x32_bf16 v[106:109], v[138:141], v[192:195], v[106:109]
	v_mfma_f32_16x16x32_bf16 v[110:113], v[130:133], v[192:195], v[110:113]
	v_mfma_f32_16x16x32_bf16 v[94:97], v[130:133], v[200:203], v[94:97]
	v_mfma_f32_16x16x32_bf16 v[90:93], v[138:141], v[200:203], v[90:93]
	v_mfma_f32_16x16x32_bf16 v[74:77], v[138:141], v[212:215], v[74:77]
	v_mfma_f32_16x16x32_bf16 v[78:81], v[130:133], v[212:215], v[78:81]
	v_mfma_f32_16x16x32_bf16 v[126:129], v[134:137], v[186:189], v[126:129]
	v_mfma_f32_16x16x32_bf16 v[122:125], v[142:145], v[186:189], v[122:125]
	v_mfma_f32_16x16x32_bf16 v[106:109], v[142:145], v[196:199], v[106:109]
	v_mfma_f32_16x16x32_bf16 v[110:113], v[134:137], v[196:199], v[110:113]
	v_mfma_f32_16x16x32_bf16 v[94:97], v[134:137], v[208:211], v[94:97]
	v_mfma_f32_16x16x32_bf16 v[90:93], v[142:145], v[208:211], v[90:93]
	v_mfma_f32_16x16x32_bf16 v[74:77], v[142:145], v[216:219], v[74:77]
	v_mfma_f32_16x16x32_bf16 v[78:81], v[134:137], v[216:219], v[78:81]
	s_setprio 0
	s_setprio 1
	v_mfma_f32_16x16x32_bf16 v[118:121], v[146:149], v[182:185], v[118:121]
	v_mfma_f32_16x16x32_bf16 v[114:117], v[154:157], v[182:185], v[114:117]
	v_mfma_f32_16x16x32_bf16 v[98:101], v[154:157], v[192:195], v[98:101]
	v_mfma_f32_16x16x32_bf16 v[102:105], v[146:149], v[192:195], v[102:105]
	v_mfma_f32_16x16x32_bf16 v[86:89], v[146:149], v[200:203], v[86:89]
	v_mfma_f32_16x16x32_bf16 v[82:85], v[154:157], v[200:203], v[82:85]
	v_mfma_f32_16x16x32_bf16 v[66:69], v[154:157], v[212:215], v[66:69]
	v_mfma_f32_16x16x32_bf16 v[70:73], v[146:149], v[212:215], v[70:73]
	v_mfma_f32_16x16x32_bf16 v[118:121], v[150:153], v[186:189], v[118:121]
	v_mfma_f32_16x16x32_bf16 v[114:117], v[158:161], v[186:189], v[114:117]
	v_mfma_f32_16x16x32_bf16 v[98:101], v[158:161], v[196:199], v[98:101]
	v_mfma_f32_16x16x32_bf16 v[102:105], v[150:153], v[196:199], v[102:105]
	v_mfma_f32_16x16x32_bf16 v[86:89], v[150:153], v[208:211], v[86:89]
	v_mfma_f32_16x16x32_bf16 v[82:85], v[158:161], v[208:211], v[82:85]
	v_mfma_f32_16x16x32_bf16 v[66:69], v[158:161], v[216:219], v[66:69]
	v_mfma_f32_16x16x32_bf16 v[70:73], v[150:153], v[216:219], v[70:73]
	s_setprio 0
	s_barrier
; #define PG8_STAGE(bufoff, gbase, voff) do { _Pragma("unroll") for (int _i = 0; _i < 2; ++_i) \
;         __builtin_amdgcn_global_load_lds((const unsigned*)((const char*)(gbase) + (voff)[_i]), (PG8_LAS unsigned*)(lds + (bufoff) + ldsw + _i * 8192), 16, 0, 0); } while (0)
; #define PG8_LDA(dst, b, h) do { _Pragma("unroll") for (int m = 0; m < 4; ++m) _Pragma("unroll") for (int k = 0; k < 2; ++k) dst[m][k] = *(const PG8_LAS bf16x8*)(lds + PG8_SA(b, h) + aoff + m * 2048 + k * 1024); } while (0)
; #define PG8_MMA(ai, bj, At, Bt) do { __builtin_amdgcn_s_setprio(1); _Pragma("unroll") for (int m = 0; m < 4; ++m) _Pragma("unroll") for (int n = 0; n < 2; ++n) _Pragma("unroll") for (int k = 0; k < 2; ++k) \
;         acc[ai][bj][m][n] = __builtin_amdgcn_mfma_f32_16x16x32_bf16(Bt[n][k], At[m][k], acc[ai][bj][m][n], 0, 0, 0); __builtin_amdgcn_s_setprio(0); } while (0)
; #define PG8_WAIT_V(n) asm volatile("s_waitcnt vmcnt(" #n ")" ::: "memory")
; #define PG8_WAIT_L(n) asm volatile("s_waitcnt lgkmcnt(" #n ")" ::: "memory")
; #define PG8_BAR __builtin_amdgcn_s_barrier()
; #define PG8_SCHED __builtin_amdgcn_sched_barrier(0)
; template <class Epi, class Sched, bool ALIGN_EPI = false, bool SP2 = false>
; __device__ __forceinline__ void gemm_phase(PG8_LAS unsigned char* lds, const Gemm g, const Sched& S, const Epi& E, const int tid) {
;     ...
;             PG8_LDA(At, 1, 1); PG8_STAGE(PG8_SB(1, 0), b3, voffB); PG8_STAGE(PG8_SB(1, 1), b3 + hstep, voffB); PG8_STAGE(PG8_SA(1, 0), a3, voffA);
;             PG8_WAIT_V(8); PG8_WAIT_L(0); PG8_BAR; PG8_MMA(1, 0, At, B0); PG8_MMA(1, 1, At, B1); PG8_BAR; PG8_SCHED;
;     ...
;         if constexpr (ALIGN_EPI) { if (wr == 0) PG8_BAR; }
	s_add_i32 s15, s15, s56
	v_lshl_add_u64 v[220:221], v[220:221], 0, s[30:31]
	s_mov_b32 m0, s15
	ds_read_b128 v[182:185], v206 offset:49152
	ds_read_b128 v[186:189], v206 offset:50176
	ds_read_b128 v[192:195], v206 offset:51200
	ds_read_b128 v[196:199], v206 offset:52224
	ds_read_b128 v[200:203], v206 offset:53248
	ds_read_b128 v[208:211], v206 offset:54272
	ds_read_b128 v[212:215], v206 offset:55296
	ds_read_b128 v[216:219], v206 offset:56320
	global_load_lds_dwordx4 v[220:221], off
	s_add_i32 m0, s15, 0x2000
	s_add_u32 s10, s10, 0x40080
	v_lshl_add_u64 v[220:221], v[222:223], 0, s[30:31]
	s_addc_u32 s11, s11, 0
	s_add_i32 s15, s77, s56
	global_load_lds_dwordx4 v[220:221], off
	v_lshl_add_u64 v[220:221], s[10:11], 0, v[164:165]
	s_mov_b32 m0, s15
	s_nop 0
	global_load_lds_dwordx4 v[220:221], off
	v_lshl_add_u64 v[220:221], s[10:11], 0, v[168:169]
	s_add_i32 m0, s15, 0x2000
	s_nop 0
	global_load_lds_dwordx4 v[220:221], off
	v_lshl_add_u64 v[220:221], v[224:225], 0, s[30:31]
	s_mov_b32 m0, s62
	s_nop 0
	global_load_lds_dwordx4 v[220:221], off
	v_lshl_add_u64 v[220:221], v[226:227], 0, s[30:31]
	s_mov_b32 m0, s63
	s_nop 0
	global_load_lds_dwordx4 v[220:221], off
	s_waitcnt vmcnt(8)
	s_waitcnt lgkmcnt(0)
	s_barrier
	s_setprio 1
	s_waitcnt lgkmcnt(0)
	v_mfma_f32_16x16x32_bf16 v[62:65], v[130:133], v[182:185], v[62:65]
	v_mfma_f32_16x16x32_bf16 v[58:61], v[138:141], v[182:185], v[58:61]
	v_mfma_f32_16x16x32_bf16 v[42:45], v[138:141], v[192:195], v[42:45]
	v_mfma_f32_16x16x32_bf16 v[46:49], v[130:133], v[192:195], v[46:49]
	v_mfma_f32_16x16x32_bf16 v[30:33], v[130:133], v[200:203], v[30:33]
	v_mfma_f32_16x16x32_bf16 v[26:29], v[138:141], v[200:203], v[26:29]
	v_mfma_f32_16x16x32_bf16 v[10:13], v[138:141], v[212:215], v[10:13]
	v_mfma_f32_16x16x32_bf16 v[14:17], v[130:133], v[212:215], v[14:17]
	v_mfma_f32_16x16x32_bf16 v[62:65], v[134:137], v[186:189], v[62:65]
	v_mfma_f32_16x16x32_bf16 v[58:61], v[142:145], v[186:189], v[58:61]
	v_mfma_f32_16x16x32_bf16 v[42:45], v[142:145], v[196:199], v[42:45]
	v_mfma_f32_16x16x32_bf16 v[46:49], v[134:137], v[196:199], v[46:49]
	v_mfma_f32_16x16x32_bf16 v[30:33], v[134:137], v[208:211], v[30:33]
	v_mfma_f32_16x16x32_bf16 v[26:29], v[142:145], v[208:211], v[26:29]
	v_mfma_f32_16x16x32_bf16 v[10:13], v[142:145], v[216:219], v[10:13]
	v_mfma_f32_16x16x32_bf16 v[14:17], v[134:137], v[216:219], v[14:17]
	s_setprio 0
	s_setprio 1
	v_mfma_f32_16x16x32_bf16 v[54:57], v[146:149], v[182:185], v[54:57]
	v_mfma_f32_16x16x32_bf16 v[50:53], v[154:157], v[182:185], v[50:53]
	v_mfma_f32_16x16x32_bf16 v[34:37], v[154:157], v[192:195], v[34:37]
	v_mfma_f32_16x16x32_bf16 v[38:41], v[146:149], v[192:195], v[38:41]
	v_mfma_f32_16x16x32_bf16 v[22:25], v[146:149], v[200:203], v[22:25]
	v_mfma_f32_16x16x32_bf16 v[18:21], v[154:157], v[200:203], v[18:21]
	v_mfma_f32_16x16x32_bf16 v[2:5], v[154:157], v[212:215], v[2:5]
	v_mfma_f32_16x16x32_bf16 v[6:9], v[146:149], v[212:215], v[6:9]
	v_mfma_f32_16x16x32_bf16 v[54:57], v[150:153], v[186:189], v[54:57]
	v_mfma_f32_16x16x32_bf16 v[50:53], v[158:161], v[186:189], v[50:53]
	v_mfma_f32_16x16x32_bf16 v[34:37], v[158:161], v[196:199], v[34:37]
	v_mfma_f32_16x16x32_bf16 v[38:41], v[150:153], v[196:199], v[38:41]
	v_mfma_f32_16x16x32_bf16 v[22:25], v[150:153], v[208:211], v[22:25]
	v_mfma_f32_16x16x32_bf16 v[18:21], v[158:161], v[208:211], v[18:21]
	v_mfma_f32_16x16x32_bf16 v[2:5], v[158:161], v[216:219], v[2:5]
	v_mfma_f32_16x16x32_bf16 v[6:9], v[150:153], v[216:219], v[6:9]
	s_setprio 0
	s_barrier
	s_add_i32 s76, s76, 2
	s_add_u32 s48, s48, 0x100
	s_addc_u32 s49, s49, 0
	s_add_u32 s8, s8, 0x100
	s_addc_u32 s9, s9, 0
	s_cmp_gt_u32 s76, 13
	s_cbranch_scc0 .LBB0_1374
	s_and_b64 vcc, exec, s[34:35]
	s_cbranch_vccz .LBB0_1377
	s_barrier

; #define PG8_STAGE(bufoff, gbase, voff) do { _Pragma("unroll") for (int _i = 0; _i < 2; ++_i) \
;         __builtin_amdgcn_global_load_lds((const unsigned*)((const char*)(gbase) + (voff)[_i]), (PG8_LAS unsigned*)(lds + (bufoff) + ldsw + _i * 8192), 16, 0, 0); } while (0)
; #define PG8_LDA(dst, b, h) do { _Pragma("unroll") for (int m = 0; m < 4; ++m) _Pragma("unroll") for (int k = 0; k < 2; ++k) dst[m][k] = *(const PG8_LAS bf16x8*)(lds + PG8_SA(b, h) + aoff + m * 2048 + k * 1024); } while (0)
; #define PG8_LDB(dst, b, h) do { _Pragma("unroll") for (int n = 0; n < 2; ++n) _Pragma("unroll") for (int k = 0; k < 2; ++k) dst[n][k] = *(const PG8_LAS bf16x8*)(lds + PG8_SB(b, h) + boff + n * 2048 + k * 1024); } while (0)
; #define PG8_WAIT_V(n) asm volatile("s_waitcnt vmcnt(" #n ")" ::: "memory")
; #define PG8_WAIT_L(n) asm volatile("s_waitcnt lgkmcnt(" #n ")" ::: "memory")
; #define PG8_BAR __builtin_amdgcn_s_barrier()
; #define PG8_SCHED __builtin_amdgcn_sched_barrier(0)
; template <class Epi, class Sched, bool ALIGN_EPI = false, bool SP2 = false>
; __device__ __forceinline__ void gemm_phase(PG8_LAS unsigned char* lds, const Gemm g, const Sched& S, const Epi& E, const int tid) {
;     ...
;         const bool has_next = S.next(ui + 1, nxt);
;         const char* nA = has_next ? S.aptr(nxt) : cA; const char* nB = has_next ? S.bptr(nxt) : cB;
;         for (int t = 0; t < nt; t += 2) {
;             const bool last = (t == nt - 2);
;             const char* a1 = cA + (size_t)(t + 1) * kstep;
;             const char* a2 = last ? nA : cA + (size_t)(t + 2) * kstep; const char* b2 = last ? nB : cB + (size_t)(t + 2) * kstep;
;             const char* a3 = a2 + kstep; const char* b3 = b2 + kstep;
;             if (last && has_next) S.a_ready(nxt);
;             if constexpr (SP2) {
;             PG8_LDB(B0, 0, 0); PG8_LDB(B1, 0, 1); PG8_SCHED; PG8_LDA(At, 0, 0); PG8_STAGE(PG8_SA(1, 1), a1 + hstep, voffA);
;             PG8_WAIT_V(8); PG8_WAIT_L(0); PG8_BAR; PG8_MMA(0, 0, At, B0); PG8_MMA(0, 1, At, B1); PG8_BAR; PG8_SCHED;
;             PG8_LDA(At, 0, 1); PG8_STAGE(PG8_SB(0, 0), b2, voffB); PG8_STAGE(PG8_SB(0, 1), b2 + hstep, voffB); PG8_STAGE(PG8_SA(0, 0), a2, voffA);
;             PG8_WAIT_V(8); PG8_WAIT_L(0); PG8_BAR; PG8_MMA(1, 0, At, B0); PG8_MMA(1, 1, At, B1); PG8_BAR; PG8_SCHED;
.LBB0_5219:
	s_add_u32 s43, s8, 0x100
	s_addc_u32 s45, s9, 0
	s_mov_b32 s74, -2
	ds_read_b128 v[130:133], v204
	ds_read_b128 v[134:137], v204 offset:1024
	ds_read_b128 v[138:141], v204 offset:2048
	ds_read_b128 v[142:145], v204 offset:3072
	ds_read_b128 v[146:149], v205
	ds_read_b128 v[150:153], v205 offset:1024
	ds_read_b128 v[154:157], v205 offset:2048
	ds_read_b128 v[158:161], v205 offset:3072
	s_add_u32 s8, s6, 0x100
	s_addc_u32 s9, s7, 0
	s_cmp_eq_u32 s74, 40
	s_cselect_b32 s41, s1, s9
	s_cselect_b32 s40, s0, s8
	s_cselect_b32 s11, s39, s45
	s_cselect_b32 s10, s38, s43
	v_lshl_add_u64 v[220:221], s[6:7], 0, v[176:177]
	s_add_i32 m0, s53, 0xc000
	ds_read_b128 v[182:185], v206
	ds_read_b128 v[186:189], v206 offset:1024
	ds_read_b128 v[192:195], v206 offset:2048
	ds_read_b128 v[196:199], v206 offset:3072
	ds_read_b128 v[200:203], v206 offset:4096
	ds_read_b128 v[208:211], v206 offset:5120
	ds_read_b128 v[212:215], v206 offset:6144
	ds_read_b128 v[216:219], v206 offset:7168
	global_load_lds_dwordx4 v[220:221], off
	v_lshl_add_u64 v[220:221], s[6:7], 0, v[174:175]
	s_add_i32 m0, s53, 0xe000
	s_nop 0
	global_load_lds_dwordx4 v[220:221], off
	s_waitcnt vmcnt(8)
	s_waitcnt lgkmcnt(0)
	s_barrier
	s_setprio 1
	s_waitcnt lgkmcnt(0)
	v_mfma_f32_16x16x32_bf16 v[126:129], v[130:133], v[182:185], 0
	v_mfma_f32_16x16x32_bf16 v[122:125], v[138:141], v[182:185], 0
	v_mfma_f32_16x16x32_bf16 v[106:109], v[138:141], v[192:195], 0
	v_mfma_f32_16x16x32_bf16 v[110:113], v[130:133], v[192:195], 0
	v_mfma_f32_16x16x32_bf16 v[94:97], v[130:133], v[200:203], 0
	v_mfma_f32_16x16x32_bf16 v[90:93], v[138:141], v[200:203], 0
	v_mfma_f32_16x16x32_bf16 v[74:77], v[138:141], v[212:215], 0
	v_mfma_f32_16x16x32_bf16 v[78:81], v[130:133], v[212:215], 0
	v_mfma_f32_16x16x32_bf16 v[126:129], v[134:137], v[186:189], v[126:129]
	v_mfma_f32_16x16x32_bf16 v[122:125], v[142:145], v[186:189], v[122:125]
	v_mfma_f32_16x16x32_bf16 v[106:109], v[142:145], v[196:199], v[106:109]
	v_mfma_f32_16x16x32_bf16 v[110:113], v[134:137], v[196:199], v[110:113]
	v_mfma_f32_16x16x32_bf16 v[94:97], v[134:137], v[208:211], v[94:97]
	v_mfma_f32_16x16x32_bf16 v[90:93], v[142:145], v[208:211], v[90:93]
	v_mfma_f32_16x16x32_bf16 v[74:77], v[142:145], v[216:219], v[74:77]
	v_mfma_f32_16x16x32_bf16 v[78:81], v[134:137], v[216:219], v[78:81]
	s_setprio 0
	s_setprio 1
	v_mfma_f32_16x16x32_bf16 v[118:121], v[146:149], v[182:185], 0
	v_mfma_f32_16x16x32_bf16 v[114:117], v[154:157], v[182:185], 0
	v_mfma_f32_16x16x32_bf16 v[98:101], v[154:157], v[192:195], 0
	v_mfma_f32_16x16x32_bf16 v[102:105], v[146:149], v[192:195], 0
	v_mfma_f32_16x16x32_bf16 v[86:89], v[146:149], v[200:203], 0
	v_mfma_f32_16x16x32_bf16 v[82:85], v[154:157], v[200:203], 0
	v_mfma_f32_16x16x32_bf16 v[66:69], v[154:157], v[212:215], 0
	v_mfma_f32_16x16x32_bf16 v[70:73], v[146:149], v[212:215], 0
	v_mfma_f32_16x16x32_bf16 v[118:121], v[150:153], v[186:189], v[118:121]
	v_mfma_f32_16x16x32_bf16 v[114:117], v[158:161], v[186:189], v[114:117]
	v_mfma_f32_16x16x32_bf16 v[98:101], v[158:161], v[196:199], v[98:101]
	v_mfma_f32_16x16x32_bf16 v[102:105], v[150:153], v[196:199], v[102:105]
	v_mfma_f32_16x16x32_bf16 v[86:89], v[150:153], v[208:211], v[86:89]
	v_mfma_f32_16x16x32_bf16 v[82:85], v[158:161], v[208:211], v[82:85]
	v_mfma_f32_16x16x32_bf16 v[66:69], v[158:161], v[216:219], v[66:69]
	v_mfma_f32_16x16x32_bf16 v[70:73], v[150:153], v[216:219], v[70:73]
	s_setprio 0
	s_barrier
	s_add_i32 s6, s63, s52
	v_lshl_add_u64 v[220:221], s[10:11], 0, v[164:165]
	s_mov_b32 m0, s6
	ds_read_b128 v[182:185], v206 offset:16384
	ds_read_b128 v[186:189], v206 offset:17408
	ds_read_b128 v[192:195], v206 offset:18432
	ds_read_b128 v[196:199], v206 offset:19456
	ds_read_b128 v[200:203], v206 offset:20480
	ds_read_b128 v[208:211], v206 offset:21504
	ds_read_b128 v[212:215], v206 offset:22528
	ds_read_b128 v[216:219], v206 offset:23552
	global_load_lds_dwordx4 v[220:221], off
	s_add_i32 m0, s6, 0x2000
	s_add_u32 s6, s10, 0xb0000
	v_lshl_add_u64 v[222:223], s[10:11], 0, v[168:169]
	s_addc_u32 s7, s11, 0
	s_add_i32 s15, s64, s52
	global_load_lds_dwordx4 v[222:223], off
	v_lshl_add_u64 v[224:225], s[6:7], 0, v[164:165]
	s_mov_b32 m0, s15
	v_lshl_add_u64 v[226:227], s[40:41], 0, v[166:167]
	global_load_lds_dwordx4 v[224:225], off
	v_lshl_add_u64 v[224:225], s[6:7], 0, v[168:169]
	s_add_i32 m0, s15, 0x2000
	s_nop 0
	global_load_lds_dwordx4 v[224:225], off
	v_lshl_add_u64 v[224:225], s[40:41], 0, v[162:163]
	s_mov_b32 m0, s53
	s_nop 0
	global_load_lds_dwordx4 v[224:225], off
	s_mov_b32 m0, s54
	s_nop 0
	global_load_lds_dwordx4 v[226:227], off
	s_waitcnt vmcnt(8)
	s_waitcnt lgkmcnt(0)
	s_barrier
; #define PG8_STAGE(bufoff, gbase, voff) do { _Pragma("unroll") for (int _i = 0; _i < 2; ++_i) \
;         __builtin_amdgcn_global_load_lds((const unsigned*)((const char*)(gbase) + (voff)[_i]), (PG8_LAS unsigned*)(lds + (bufoff) + ldsw + _i * 8192), 16, 0, 0); } while (0)
; #define PG8_LDA(dst, b, h) do { _Pragma("unroll") for (int m = 0; m < 4; ++m) _Pragma("unroll") for (int k = 0; k < 2; ++k) dst[m][k] = *(const PG8_LAS bf16x8*)(lds + PG8_SA(b, h) + aoff + m * 2048 + k * 1024); } while (0)
; #define PG8_LDB(dst, b, h) do { _Pragma("unroll") for (int n = 0; n < 2; ++n) _Pragma("unroll") for (int k = 0; k < 2; ++k) dst[n][k] = *(const PG8_LAS bf16x8*)(lds + PG8_SB(b, h) + boff + n * 2048 + k * 1024); } while (0)
; #define PG8_MMA(ai, bj, At, Bt) do { __builtin_amdgcn_s_setprio(1); _Pragma("unroll") for (int m = 0; m < 4; ++m) _Pragma("unroll") for (int n = 0; n < 2; ++n) _Pragma("unroll") for (int k = 0; k < 2; ++k) \
;         acc[ai][bj][m][n] = __builtin_amdgcn_mfma_f32_16x16x32_bf16(Bt[n][k], At[m][k], acc[ai][bj][m][n], 0, 0, 0); __builtin_amdgcn_s_setprio(0); } while (0)
; #define PG8_WAIT_V(n) asm volatile("s_waitcnt vmcnt(" #n ")" ::: "memory")
; #define PG8_WAIT_L(n) asm volatile("s_waitcnt lgkmcnt(" #n ")" ::: "memory")
; #define PG8_BAR __builtin_amdgcn_s_barrier()
; #define PG8_SCHED __builtin_amdgcn_sched_barrier(0)
; template <class Epi, class Sched, bool ALIGN_EPI = false, bool SP2 = false>
; __device__ __forceinline__ void gemm_phase(PG8_LAS unsigned char* lds, const Gemm g, const Sched& S, const Epi& E, const int tid) {
;     ...
;             PG8_WAIT_V(8); PG8_WAIT_L(0); PG8_BAR; PG8_MMA(1, 0, At, B0); PG8_MMA(1, 1, At, B1); PG8_BAR; PG8_SCHED;
;             PG8_LDB(B0, 1, 0); PG8_LDB(B1, 1, 1); PG8_SCHED; PG8_LDA(At, 1, 0); PG8_STAGE(PG8_SA(0, 1), a2 + hstep, voffA);
;             PG8_WAIT_V(8); PG8_WAIT_L(0); PG8_BAR; PG8_MMA(0, 0, At, B0); PG8_MMA(0, 1, At, B1); PG8_BAR; PG8_SCHED;
	s_setprio 1
	s_waitcnt lgkmcnt(0)
	v_mfma_f32_16x16x32_bf16 v[62:65], v[130:133], v[182:185], 0
	v_mfma_f32_16x16x32_bf16 v[58:61], v[138:141], v[182:185], 0
	v_mfma_f32_16x16x32_bf16 v[42:45], v[138:141], v[192:195], 0
	v_mfma_f32_16x16x32_bf16 v[46:49], v[130:133], v[192:195], 0
	v_mfma_f32_16x16x32_bf16 v[30:33], v[130:133], v[200:203], 0
	v_mfma_f32_16x16x32_bf16 v[26:29], v[138:141], v[200:203], 0
	v_mfma_f32_16x16x32_bf16 v[10:13], v[138:141], v[212:215], 0
	v_mfma_f32_16x16x32_bf16 v[14:17], v[130:133], v[212:215], 0
	v_mfma_f32_16x16x32_bf16 v[62:65], v[134:137], v[186:189], v[62:65]
	v_mfma_f32_16x16x32_bf16 v[58:61], v[142:145], v[186:189], v[58:61]
	v_mfma_f32_16x16x32_bf16 v[42:45], v[142:145], v[196:199], v[42:45]
	v_mfma_f32_16x16x32_bf16 v[46:49], v[134:137], v[196:199], v[46:49]
	v_mfma_f32_16x16x32_bf16 v[30:33], v[134:137], v[208:211], v[30:33]
	v_mfma_f32_16x16x32_bf16 v[26:29], v[142:145], v[208:211], v[26:29]
	v_mfma_f32_16x16x32_bf16 v[10:13], v[142:145], v[216:219], v[10:13]
	v_mfma_f32_16x16x32_bf16 v[14:17], v[134:137], v[216:219], v[14:17]
	s_setprio 0
	s_setprio 1
	v_mfma_f32_16x16x32_bf16 v[54:57], v[146:149], v[182:185], 0
	v_mfma_f32_16x16x32_bf16 v[50:53], v[154:157], v[182:185], 0
	v_mfma_f32_16x16x32_bf16 v[34:37], v[154:157], v[192:195], 0
	v_mfma_f32_16x16x32_bf16 v[38:41], v[146:149], v[192:195], 0
	v_mfma_f32_16x16x32_bf16 v[22:25], v[146:149], v[200:203], 0
	v_mfma_f32_16x16x32_bf16 v[18:21], v[154:157], v[200:203], 0
	v_mfma_f32_16x16x32_bf16 v[2:5], v[154:157], v[212:215], 0
	v_mfma_f32_16x16x32_bf16 v[6:9], v[146:149], v[212:215], 0
	v_mfma_f32_16x16x32_bf16 v[54:57], v[150:153], v[186:189], v[54:57]
	v_mfma_f32_16x16x32_bf16 v[50:53], v[158:161], v[186:189], v[50:53]
	v_mfma_f32_16x16x32_bf16 v[34:37], v[158:161], v[196:199], v[34:37]
	v_mfma_f32_16x16x32_bf16 v[38:41], v[150:153], v[196:199], v[38:41]
	v_mfma_f32_16x16x32_bf16 v[22:25], v[150:153], v[208:211], v[22:25]
	v_mfma_f32_16x16x32_bf16 v[18:21], v[158:161], v[208:211], v[18:21]
	v_mfma_f32_16x16x32_bf16 v[2:5], v[158:161], v[216:219], v[2:5]
	v_mfma_f32_16x16x32_bf16 v[6:9], v[150:153], v[216:219], v[6:9]
	s_setprio 0
	s_barrier
	s_add_i32 s15, 0, 0x18000
	s_add_i32 s18, 0, 0x1c000
	v_add_u32_e32 v142, s15, v191
	v_add_u32_e32 v158, s18, v191
	ds_read_b128 v[130:133], v142
	ds_read_b128 v[134:137], v142 offset:1024
	ds_read_b128 v[138:141], v142 offset:2048
	ds_read_b128 v[142:145], v142 offset:3072
	ds_read_b128 v[146:149], v158
	ds_read_b128 v[150:153], v158 offset:1024
	ds_read_b128 v[154:157], v158 offset:2048
	ds_read_b128 v[158:161], v158 offset:3072
	s_add_u32 s6, s40, 0xb0000
	s_addc_u32 s7, s41, 0
	s_mov_b32 m0, s55
	v_lshl_add_u64 v[228:229], s[6:7], 0, v[162:163]
	ds_read_b128 v[182:185], v206 offset:32768
	ds_read_b128 v[186:189], v206 offset:33792
	ds_read_b128 v[192:195], v206 offset:34816
	ds_read_b128 v[196:199], v206 offset:35840
	ds_read_b128 v[200:203], v206 offset:36864
	ds_read_b128 v[208:211], v206 offset:37888
	ds_read_b128 v[212:215], v206 offset:38912
	ds_read_b128 v[216:219], v206 offset:39936
	global_load_lds_dwordx4 v[228:229], off
	v_lshl_add_u64 v[228:229], s[6:7], 0, v[166:167]
	s_mov_b32 m0, s56
	s_nop 0
	global_load_lds_dwordx4 v[228:229], off
	s_waitcnt vmcnt(8)
	s_waitcnt lgkmcnt(0)
	s_barrier
	s_setprio 1
	s_waitcnt lgkmcnt(0)
	v_mfma_f32_16x16x32_bf16 v[126:129], v[130:133], v[182:185], v[126:129]
	v_mfma_f32_16x16x32_bf16 v[122:125], v[138:141], v[182:185], v[122:125]
	v_mfma_f32_16x16x32_bf16 v[106:109], v[138:141], v[192:195], v[106:109]
	v_mfma_f32_16x16x32_bf16 v[110:113], v[130:133], v[192:195], v[110:113]
	v_mfma_f32_16x16x32_bf16 v[94:97], v[130:133], v[200:203], v[94:97]
	v_mfma_f32_16x16x32_bf16 v[90:93], v[138:141], v[200:203], v[90:93]
	v_mfma_f32_16x16x32_bf16 v[74:77], v[138:141], v[212:215], v[74:77]
	v_mfma_f32_16x16x32_bf16 v[78:81], v[130:133], v[212:215], v[78:81]
	v_mfma_f32_16x16x32_bf16 v[126:129], v[134:137], v[186:189], v[126:129]
	v_mfma_f32_16x16x32_bf16 v[122:125], v[142:145], v[186:189], v[122:125]
	v_mfma_f32_16x16x32_bf16 v[106:109], v[142:145], v[196:199], v[106:109]
	v_mfma_f32_16x16x32_bf16 v[110:113], v[134:137], v[196:199], v[110:113]
	v_mfma_f32_16x16x32_bf16 v[94:97], v[134:137], v[208:211], v[94:97]
	v_mfma_f32_16x16x32_bf16 v[90:93], v[142:145], v[208:211], v[90:93]
	v_mfma_f32_16x16x32_bf16 v[74:77], v[142:145], v[216:219], v[74:77]
	v_mfma_f32_16x16x32_bf16 v[78:81], v[134:137], v[216:219], v[78:81]
	s_setprio 0
	s_setprio 1
	v_mfma_f32_16x16x32_bf16 v[118:121], v[146:149], v[182:185], v[118:121]
	v_mfma_f32_16x16x32_bf16 v[114:117], v[154:157], v[182:185], v[114:117]
	v_mfma_f32_16x16x32_bf16 v[98:101], v[154:157], v[192:195], v[98:101]
	v_mfma_f32_16x16x32_bf16 v[102:105], v[146:149], v[192:195], v[102:105]
	v_mfma_f32_16x16x32_bf16 v[86:89], v[146:149], v[200:203], v[86:89]
	v_mfma_f32_16x16x32_bf16 v[82:85], v[154:157], v[200:203], v[82:85]
	v_mfma_f32_16x16x32_bf16 v[66:69], v[154:157], v[212:215], v[66:69]
	v_mfma_f32_16x16x32_bf16 v[70:73], v[146:149], v[212:215], v[70:73]
	v_mfma_f32_16x16x32_bf16 v[118:121], v[150:153], v[186:189], v[118:121]
	v_mfma_f32_16x16x32_bf16 v[114:117], v[158:161], v[186:189], v[114:117]
	v_mfma_f32_16x16x32_bf16 v[98:101], v[158:161], v[196:199], v[98:101]
	v_mfma_f32_16x16x32_bf16 v[102:105], v[150:153], v[196:199], v[102:105]
	v_mfma_f32_16x16x32_bf16 v[86:89], v[150:153], v[208:211], v[86:89]
	v_mfma_f32_16x16x32_bf16 v[82:85], v[158:161], v[208:211], v[82:85]
	v_mfma_f32_16x16x32_bf16 v[66:69], v[158:161], v[216:219], v[66:69]
	v_mfma_f32_16x16x32_bf16 v[70:73], v[150:153], v[216:219], v[70:73]
	s_setprio 0
	s_barrier
; #define PG8_STAGE(bufoff, gbase, voff) do { _Pragma("unroll") for (int _i = 0; _i < 2; ++_i) \
;         __builtin_amdgcn_global_load_lds((const unsigned*)((const char*)(gbase) + (voff)[_i]), (PG8_LAS unsigned*)(lds + (bufoff) + ldsw + _i * 8192), 16, 0, 0); } while (0)
; #define PG8_LDA(dst, b, h) do { _Pragma("unroll") for (int m = 0; m < 4; ++m) _Pragma("unroll") for (int k = 0; k < 2; ++k) dst[m][k] = *(const PG8_LAS bf16x8*)(lds + PG8_SA(b, h) + aoff + m * 2048 + k * 1024); } while (0)
; #define PG8_LDB(dst, b, h) do { _Pragma("unroll") for (int n = 0; n < 2; ++n) _Pragma("unroll") for (int k = 0; k < 2; ++k) dst[n][k] = *(const PG8_LAS bf16x8*)(lds + PG8_SB(b, h) + boff + n * 2048 + k * 1024); } while (0)
; #define PG8_MMA(ai, bj, At, Bt) do { __builtin_amdgcn_s_setprio(1); _Pragma("unroll") for (int m = 0; m < 4; ++m) _Pragma("unroll") for (int n = 0; n < 2; ++n) _Pragma("unroll") for (int k = 0; k < 2; ++k) \
;         acc[ai][bj][m][n] = __builtin_amdgcn_mfma_f32_16x16x32_bf16(Bt[n][k], At[m][k], acc[ai][bj][m][n], 0, 0, 0); __builtin_amdgcn_s_setprio(0); } while (0)
; #define PG8_WAIT_V(n) asm volatile("s_waitcnt vmcnt(" #n ")" ::: "memory")
; #define PG8_WAIT_L(n) asm volatile("s_waitcnt lgkmcnt(" #n ")" ::: "memory")
; #define PG8_BAR __builtin_amdgcn_s_barrier()
; #define PG8_SCHED __builtin_amdgcn_sched_barrier(0)
; template <class Epi, class Sched, bool ALIGN_EPI = false, bool SP2 = false>
; __device__ __forceinline__ void gemm_phase(PG8_LAS unsigned char* lds, const Gemm g, const Sched& S, const Epi& E, const int tid) {
;     ...
;             PG8_LDB(B0, 0, 0); PG8_LDB(B1, 0, 1); PG8_SCHED; PG8_LDA(At, 0, 0); PG8_STAGE(PG8_SA(1, 1), a1 + hstep, voffA);
;             PG8_WAIT_V(8); PG8_WAIT_L(0); PG8_BAR; PG8_MMA(0, 0, At, B0); PG8_MMA(0, 1, At, B1); PG8_BAR; PG8_SCHED;
;     ...
;             PG8_LDA(At, 1, 1); PG8_STAGE(PG8_SB(1, 0), b3, voffB); PG8_STAGE(PG8_SB(1, 1), b3 + hstep, voffB); PG8_STAGE(PG8_SA(1, 0), a3, voffA);
;             PG8_WAIT_V(8); PG8_WAIT_L(0); PG8_BAR; PG8_MMA(1, 0, At, B0); PG8_MMA(1, 1, At, B1); PG8_BAR; PG8_SCHED;
	s_add_i32 s6, s15, s52
	v_lshl_add_u64 v[220:221], v[220:221], 0, s[34:35]
	s_mov_b32 m0, s6
	ds_read_b128 v[182:185], v206 offset:49152
	ds_read_b128 v[186:189], v206 offset:50176
	ds_read_b128 v[192:195], v206 offset:51200
	ds_read_b128 v[196:199], v206 offset:52224
	ds_read_b128 v[200:203], v206 offset:53248
	ds_read_b128 v[208:211], v206 offset:54272
	ds_read_b128 v[212:215], v206 offset:55296
	ds_read_b128 v[216:219], v206 offset:56320
	global_load_lds_dwordx4 v[220:221], off
	s_add_i32 m0, s6, 0x2000
	s_add_u32 s6, s10, 0xb0080
	v_lshl_add_u64 v[220:221], v[222:223], 0, s[34:35]
	s_addc_u32 s7, s11, 0
	s_add_i32 s10, s18, s52
	global_load_lds_dwordx4 v[220:221], off
	v_lshl_add_u64 v[220:221], s[6:7], 0, v[164:165]
	s_mov_b32 m0, s10
	s_nop 0
	global_load_lds_dwordx4 v[220:221], off
	v_lshl_add_u64 v[220:221], s[6:7], 0, v[168:169]
	s_add_i32 m0, s10, 0x2000
	s_nop 0
	global_load_lds_dwordx4 v[220:221], off
	v_lshl_add_u64 v[220:221], v[224:225], 0, s[34:35]
	s_mov_b32 m0, s58
	s_nop 0
	global_load_lds_dwordx4 v[220:221], off
	v_lshl_add_u64 v[220:221], v[226:227], 0, s[34:35]
	s_mov_b32 m0, s59
	s_nop 0
	global_load_lds_dwordx4 v[220:221], off
	s_waitcnt vmcnt(8)
	s_waitcnt lgkmcnt(0)
	s_barrier
	s_setprio 1
	s_waitcnt lgkmcnt(0)
	v_mfma_f32_16x16x32_bf16 v[62:65], v[130:133], v[182:185], v[62:65]
	v_mfma_f32_16x16x32_bf16 v[58:61], v[138:141], v[182:185], v[58:61]
	v_mfma_f32_16x16x32_bf16 v[42:45], v[138:141], v[192:195], v[42:45]
	v_mfma_f32_16x16x32_bf16 v[46:49], v[130:133], v[192:195], v[46:49]
	v_mfma_f32_16x16x32_bf16 v[30:33], v[130:133], v[200:203], v[30:33]
	v_mfma_f32_16x16x32_bf16 v[26:29], v[138:141], v[200:203], v[26:29]
	v_mfma_f32_16x16x32_bf16 v[10:13], v[138:141], v[212:215], v[10:13]
	v_mfma_f32_16x16x32_bf16 v[14:17], v[130:133], v[212:215], v[14:17]
	v_mfma_f32_16x16x32_bf16 v[62:65], v[134:137], v[186:189], v[62:65]
	v_mfma_f32_16x16x32_bf16 v[58:61], v[142:145], v[186:189], v[58:61]
	v_mfma_f32_16x16x32_bf16 v[42:45], v[142:145], v[196:199], v[42:45]
	v_mfma_f32_16x16x32_bf16 v[46:49], v[134:137], v[196:199], v[46:49]
	v_mfma_f32_16x16x32_bf16 v[30:33], v[134:137], v[208:211], v[30:33]
	v_mfma_f32_16x16x32_bf16 v[26:29], v[142:145], v[208:211], v[26:29]
	v_mfma_f32_16x16x32_bf16 v[10:13], v[142:145], v[216:219], v[10:13]
	v_mfma_f32_16x16x32_bf16 v[14:17], v[134:137], v[216:219], v[14:17]
	s_setprio 0
	s_setprio 1
	v_mfma_f32_16x16x32_bf16 v[54:57], v[146:149], v[182:185], v[54:57]
	v_mfma_f32_16x16x32_bf16 v[50:53], v[154:157], v[182:185], v[50:53]
	v_mfma_f32_16x16x32_bf16 v[34:37], v[154:157], v[192:195], v[34:37]
	v_mfma_f32_16x16x32_bf16 v[38:41], v[146:149], v[192:195], v[38:41]
	v_mfma_f32_16x16x32_bf16 v[22:25], v[146:149], v[200:203], v[22:25]
	v_mfma_f32_16x16x32_bf16 v[18:21], v[154:157], v[200:203], v[18:21]
	v_mfma_f32_16x16x32_bf16 v[2:5], v[154:157], v[212:215], v[2:5]
	v_mfma_f32_16x16x32_bf16 v[6:9], v[146:149], v[212:215], v[6:9]
	v_mfma_f32_16x16x32_bf16 v[54:57], v[150:153], v[186:189], v[54:57]
	v_mfma_f32_16x16x32_bf16 v[50:53], v[158:161], v[186:189], v[50:53]
	v_mfma_f32_16x16x32_bf16 v[34:37], v[158:161], v[196:199], v[34:37]
	v_mfma_f32_16x16x32_bf16 v[38:41], v[150:153], v[196:199], v[38:41]
	v_mfma_f32_16x16x32_bf16 v[22:25], v[150:153], v[208:211], v[22:25]
	v_mfma_f32_16x16x32_bf16 v[18:21], v[158:161], v[208:211], v[18:21]
	v_mfma_f32_16x16x32_bf16 v[2:5], v[158:161], v[216:219], v[2:5]
	v_mfma_f32_16x16x32_bf16 v[6:9], v[150:153], v[216:219], v[6:9]
	s_setprio 0
	s_barrier
	s_add_i32 s74, s74, 2
	s_add_u32 s43, s43, 0x100
	s_addc_u32 s45, s45, 0
	s_mov_b64 s[6:7], s[8:9]
.LBB0_5220:
	ds_read_b128 v[130:133], v204
	ds_read_b128 v[134:137], v204 offset:1024
	ds_read_b128 v[138:141], v204 offset:2048
	ds_read_b128 v[142:145], v204 offset:3072
	ds_read_b128 v[146:149], v205
	ds_read_b128 v[150:153], v205 offset:1024
	ds_read_b128 v[154:157], v205 offset:2048
	ds_read_b128 v[158:161], v205 offset:3072
	s_add_u32 s8, s6, 0x100
	s_addc_u32 s9, s7, 0
	s_cmp_eq_u32 s74, 40
	s_cselect_b32 s41, s1, s9
	s_cselect_b32 s40, s0, s8
	s_cselect_b32 s11, s39, s45
	s_cselect_b32 s10, s38, s43
	v_lshl_add_u64 v[220:221], s[6:7], 0, v[176:177]
	s_add_i32 m0, s53, 0xc000
	ds_read_b128 v[182:185], v206
	ds_read_b128 v[186:189], v206 offset:1024
	ds_read_b128 v[192:195], v206 offset:2048
	ds_read_b128 v[196:199], v206 offset:3072
	ds_read_b128 v[200:203], v206 offset:4096
	ds_read_b128 v[208:211], v206 offset:5120
	ds_read_b128 v[212:215], v206 offset:6144
	ds_read_b128 v[216:219], v206 offset:7168
	global_load_lds_dwordx4 v[220:221], off
	v_lshl_add_u64 v[220:221], s[6:7], 0, v[174:175]
	s_add_i32 m0, s53, 0xe000
	s_nop 0
	global_load_lds_dwordx4 v[220:221], off
	s_waitcnt vmcnt(8)
	s_waitcnt lgkmcnt(0)
	s_barrier
; #define PG8_STAGE(bufoff, gbase, voff) do { _Pragma("unroll") for (int _i = 0; _i < 2; ++_i) \
;         __builtin_amdgcn_global_load_lds((const unsigned*)((const char*)(gbase) + (voff)[_i]), (PG8_LAS unsigned*)(lds + (bufoff) + ldsw + _i * 8192), 16, 0, 0); } while (0)
; #define PG8_LDA(dst, b, h) do { _Pragma("unroll") for (int m = 0; m < 4; ++m) _Pragma("unroll") for (int k = 0; k < 2; ++k) dst[m][k] = *(const PG8_LAS bf16x8*)(lds + PG8_SA(b, h) + aoff + m * 2048 + k * 1024); } while (0)
; #define PG8_MMA(ai, bj, At, Bt) do { __builtin_amdgcn_s_setprio(1); _Pragma("unroll") for (int m = 0; m < 4; ++m) _Pragma("unroll") for (int n = 0; n < 2; ++n) _Pragma("unroll") for (int k = 0; k < 2; ++k) \
;         acc[ai][bj][m][n] = __builtin_amdgcn_mfma_f32_16x16x32_bf16(Bt[n][k], At[m][k], acc[ai][bj][m][n], 0, 0, 0); __builtin_amdgcn_s_setprio(0); } while (0)
; #define PG8_WAIT_V(n) asm volatile("s_waitcnt vmcnt(" #n ")" ::: "memory")
; #define PG8_WAIT_L(n) asm volatile("s_waitcnt lgkmcnt(" #n ")" ::: "memory")
; #define PG8_BAR __builtin_amdgcn_s_barrier()
; #define PG8_SCHED __builtin_amdgcn_sched_barrier(0)
; template <class Epi, class Sched, bool ALIGN_EPI = false, bool SP2 = false>
; __device__ __forceinline__ void gemm_phase(PG8_LAS unsigned char* lds, const Gemm g, const Sched& S, const Epi& E, const int tid) {
;     ...
;             PG8_WAIT_V(8); PG8_WAIT_L(0); PG8_BAR; PG8_MMA(0, 0, At, B0); PG8_MMA(0, 1, At, B1); PG8_BAR; PG8_SCHED;
;             PG8_LDA(At, 0, 1); PG8_STAGE(PG8_SB(0, 0), b2, voffB); PG8_STAGE(PG8_SB(0, 1), b2 + hstep, voffB); PG8_STAGE(PG8_SA(0, 0), a2, voffA);
;             PG8_WAIT_V(8); PG8_WAIT_L(0); PG8_BAR; PG8_MMA(1, 0, At, B0); PG8_MMA(1, 1, At, B1); PG8_BAR; PG8_SCHED;
	s_setprio 1
	s_waitcnt lgkmcnt(0)
	v_mfma_f32_16x16x32_bf16 v[126:129], v[130:133], v[182:185], v[126:129]
	v_mfma_f32_16x16x32_bf16 v[122:125], v[138:141], v[182:185], v[122:125]
	v_mfma_f32_16x16x32_bf16 v[106:109], v[138:141], v[192:195], v[106:109]
	v_mfma_f32_16x16x32_bf16 v[110:113], v[130:133], v[192:195], v[110:113]
	v_mfma_f32_16x16x32_bf16 v[94:97], v[130:133], v[200:203], v[94:97]
	v_mfma_f32_16x16x32_bf16 v[90:93], v[138:141], v[200:203], v[90:93]
	v_mfma_f32_16x16x32_bf16 v[74:77], v[138:141], v[212:215], v[74:77]
	v_mfma_f32_16x16x32_bf16 v[78:81], v[130:133], v[212:215], v[78:81]
	v_mfma_f32_16x16x32_bf16 v[126:129], v[134:137], v[186:189], v[126:129]
	v_mfma_f32_16x16x32_bf16 v[122:125], v[142:145], v[186:189], v[122:125]
	v_mfma_f32_16x16x32_bf16 v[106:109], v[142:145], v[196:199], v[106:109]
	v_mfma_f32_16x16x32_bf16 v[110:113], v[134:137], v[196:199], v[110:113]
	v_mfma_f32_16x16x32_bf16 v[94:97], v[134:137], v[208:211], v[94:97]
	v_mfma_f32_16x16x32_bf16 v[90:93], v[142:145], v[208:211], v[90:93]
	v_mfma_f32_16x16x32_bf16 v[74:77], v[142:145], v[216:219], v[74:77]
	v_mfma_f32_16x16x32_bf16 v[78:81], v[134:137], v[216:219], v[78:81]
	s_setprio 0
	s_setprio 1
	v_mfma_f32_16x16x32_bf16 v[118:121], v[146:149], v[182:185], v[118:121]
	v_mfma_f32_16x16x32_bf16 v[114:117], v[154:157], v[182:185], v[114:117]
	v_mfma_f32_16x16x32_bf16 v[98:101], v[154:157], v[192:195], v[98:101]
	v_mfma_f32_16x16x32_bf16 v[102:105], v[146:149], v[192:195], v[102:105]
	v_mfma_f32_16x16x32_bf16 v[86:89], v[146:149], v[200:203], v[86:89]
	v_mfma_f32_16x16x32_bf16 v[82:85], v[154:157], v[200:203], v[82:85]
	v_mfma_f32_16x16x32_bf16 v[66:69], v[154:157], v[212:215], v[66:69]
	v_mfma_f32_16x16x32_bf16 v[70:73], v[146:149], v[212:215], v[70:73]
	v_mfma_f32_16x16x32_bf16 v[118:121], v[150:153], v[186:189], v[118:121]
	v_mfma_f32_16x16x32_bf16 v[114:117], v[158:161], v[186:189], v[114:117]
	v_mfma_f32_16x16x32_bf16 v[98:101], v[158:161], v[196:199], v[98:101]
	v_mfma_f32_16x16x32_bf16 v[102:105], v[150:153], v[196:199], v[102:105]
	v_mfma_f32_16x16x32_bf16 v[86:89], v[150:153], v[208:211], v[86:89]
	v_mfma_f32_16x16x32_bf16 v[82:85], v[158:161], v[208:211], v[82:85]
	v_mfma_f32_16x16x32_bf16 v[66:69], v[158:161], v[216:219], v[66:69]
	v_mfma_f32_16x16x32_bf16 v[70:73], v[150:153], v[216:219], v[70:73]
	s_setprio 0
	s_barrier
	s_add_i32 s6, s63, s52
	v_lshl_add_u64 v[220:221], s[10:11], 0, v[164:165]
	s_mov_b32 m0, s6
	ds_read_b128 v[182:185], v206 offset:16384
	ds_read_b128 v[186:189], v206 offset:17408
	ds_read_b128 v[192:195], v206 offset:18432
	ds_read_b128 v[196:199], v206 offset:19456
	ds_read_b128 v[200:203], v206 offset:20480
	ds_read_b128 v[208:211], v206 offset:21504
	ds_read_b128 v[212:215], v206 offset:22528
	ds_read_b128 v[216:219], v206 offset:23552
	global_load_lds_dwordx4 v[220:221], off
	s_add_i32 m0, s6, 0x2000
	s_add_u32 s6, s10, 0xb0000
	v_lshl_add_u64 v[222:223], s[10:11], 0, v[168:169]
	s_addc_u32 s7, s11, 0
	s_add_i32 s15, s64, s52
	global_load_lds_dwordx4 v[222:223], off
	v_lshl_add_u64 v[224:225], s[6:7], 0, v[164:165]
	s_mov_b32 m0, s15
	v_lshl_add_u64 v[226:227], s[40:41], 0, v[166:167]
	global_load_lds_dwordx4 v[224:225], off
	v_lshl_add_u64 v[224:225], s[6:7], 0, v[168:169]
	s_add_i32 m0, s15, 0x2000
	s_nop 0
	global_load_lds_dwordx4 v[224:225], off
	v_lshl_add_u64 v[224:225], s[40:41], 0, v[162:163]
	s_mov_b32 m0, s53
	s_nop 0
	global_load_lds_dwordx4 v[224:225], off
	s_mov_b32 m0, s54
	s_nop 0
	global_load_lds_dwordx4 v[226:227], off
	s_waitcnt vmcnt(8)
	s_waitcnt lgkmcnt(0)
	s_barrier
	s_setprio 1
	s_waitcnt lgkmcnt(0)
	v_mfma_f32_16x16x32_bf16 v[62:65], v[130:133], v[182:185], v[62:65]
	v_mfma_f32_16x16x32_bf16 v[58:61], v[138:141], v[182:185], v[58:61]
	v_mfma_f32_16x16x32_bf16 v[42:45], v[138:141], v[192:195], v[42:45]
	v_mfma_f32_16x16x32_bf16 v[46:49], v[130:133], v[192:195], v[46:49]
	v_mfma_f32_16x16x32_bf16 v[30:33], v[130:133], v[200:203], v[30:33]
	v_mfma_f32_16x16x32_bf16 v[26:29], v[138:141], v[200:203], v[26:29]
	v_mfma_f32_16x16x32_bf16 v[10:13], v[138:141], v[212:215], v[10:13]
	v_mfma_f32_16x16x32_bf16 v[14:17], v[130:133], v[212:215], v[14:17]
	v_mfma_f32_16x16x32_bf16 v[62:65], v[134:137], v[186:189], v[62:65]
	v_mfma_f32_16x16x32_bf16 v[58:61], v[142:145], v[186:189], v[58:61]
	v_mfma_f32_16x16x32_bf16 v[42:45], v[142:145], v[196:199], v[42:45]
	v_mfma_f32_16x16x32_bf16 v[46:49], v[134:137], v[196:199], v[46:49]
	v_mfma_f32_16x16x32_bf16 v[30:33], v[134:137], v[208:211], v[30:33]
	v_mfma_f32_16x16x32_bf16 v[26:29], v[142:145], v[208:211], v[26:29]
	v_mfma_f32_16x16x32_bf16 v[10:13], v[142:145], v[216:219], v[10:13]
	v_mfma_f32_16x16x32_bf16 v[14:17], v[134:137], v[216:219], v[14:17]
	s_setprio 0
	s_setprio 1
	v_mfma_f32_16x16x32_bf16 v[54:57], v[146:149], v[182:185], v[54:57]
	v_mfma_f32_16x16x32_bf16 v[50:53], v[154:157], v[182:185], v[50:53]
	v_mfma_f32_16x16x32_bf16 v[34:37], v[154:157], v[192:195], v[34:37]
	v_mfma_f32_16x16x32_bf16 v[38:41], v[146:149], v[192:195], v[38:41]
	v_mfma_f32_16x16x32_bf16 v[22:25], v[146:149], v[200:203], v[22:25]
	v_mfma_f32_16x16x32_bf16 v[18:21], v[154:157], v[200:203], v[18:21]
	v_mfma_f32_16x16x32_bf16 v[2:5], v[154:157], v[212:215], v[2:5]
	v_mfma_f32_16x16x32_bf16 v[6:9], v[146:149], v[212:215], v[6:9]
	v_mfma_f32_16x16x32_bf16 v[54:57], v[150:153], v[186:189], v[54:57]
	v_mfma_f32_16x16x32_bf16 v[50:53], v[158:161], v[186:189], v[50:53]
	v_mfma_f32_16x16x32_bf16 v[34:37], v[158:161], v[196:199], v[34:37]
	v_mfma_f32_16x16x32_bf16 v[38:41], v[150:153], v[196:199], v[38:41]
	v_mfma_f32_16x16x32_bf16 v[22:25], v[150:153], v[208:211], v[22:25]
	v_mfma_f32_16x16x32_bf16 v[18:21], v[158:161], v[208:211], v[18:21]
	v_mfma_f32_16x16x32_bf16 v[2:5], v[158:161], v[216:219], v[2:5]
	v_mfma_f32_16x16x32_bf16 v[6:9], v[150:153], v[216:219], v[6:9]
	s_setprio 0
	s_barrier
; #define PG8_STAGE(bufoff, gbase, voff) do { _Pragma("unroll") for (int _i = 0; _i < 2; ++_i) \
;         __builtin_amdgcn_global_load_lds((const unsigned*)((const char*)(gbase) + (voff)[_i]), (PG8_LAS unsigned*)(lds + (bufoff) + ldsw + _i * 8192), 16, 0, 0); } while (0)
; #define PG8_LDA(dst, b, h) do { _Pragma("unroll") for (int m = 0; m < 4; ++m) _Pragma("unroll") for (int k = 0; k < 2; ++k) dst[m][k] = *(const PG8_LAS bf16x8*)(lds + PG8_SA(b, h) + aoff + m * 2048 + k * 1024); } while (0)
; #define PG8_LDB(dst, b, h) do { _Pragma("unroll") for (int n = 0; n < 2; ++n) _Pragma("unroll") for (int k = 0; k < 2; ++k) dst[n][k] = *(const PG8_LAS bf16x8*)(lds + PG8_SB(b, h) + boff + n * 2048 + k * 1024); } while (0)
; #define PG8_MMA(ai, bj, At, Bt) do { __builtin_amdgcn_s_setprio(1); _Pragma("unroll") for (int m = 0; m < 4; ++m) _Pragma("unroll") for (int n = 0; n < 2; ++n) _Pragma("unroll") for (int k = 0; k < 2; ++k) \
;         acc[ai][bj][m][n] = __builtin_amdgcn_mfma_f32_16x16x32_bf16(Bt[n][k], At[m][k], acc[ai][bj][m][n], 0, 0, 0); __builtin_amdgcn_s_setprio(0); } while (0)
; #define PG8_WAIT_V(n) asm volatile("s_waitcnt vmcnt(" #n ")" ::: "memory")
; #define PG8_WAIT_L(n) asm volatile("s_waitcnt lgkmcnt(" #n ")" ::: "memory")
; #define PG8_BAR __builtin_amdgcn_s_barrier()
; #define PG8_SCHED __builtin_amdgcn_sched_barrier(0)
; template <class Epi, class Sched, bool ALIGN_EPI = false, bool SP2 = false>
; __device__ __forceinline__ void gemm_phase(PG8_LAS unsigned char* lds, const Gemm g, const Sched& S, const Epi& E, const int tid) {
;     ...
;             PG8_LDB(B0, 1, 0); PG8_LDB(B1, 1, 1); PG8_SCHED; PG8_LDA(At, 1, 0); PG8_STAGE(PG8_SA(0, 1), a2 + hstep, voffA);
;             PG8_WAIT_V(8); PG8_WAIT_L(0); PG8_BAR; PG8_MMA(0, 0, At, B0); PG8_MMA(0, 1, At, B1); PG8_BAR; PG8_SCHED;
	s_add_i32 s15, 0, 0x18000
	s_add_i32 s18, 0, 0x1c000
	v_add_u32_e32 v142, s15, v191
	v_add_u32_e32 v158, s18, v191
	ds_read_b128 v[130:133], v142
	ds_read_b128 v[134:137], v142 offset:1024
	ds_read_b128 v[138:141], v142 offset:2048
	ds_read_b128 v[142:145], v142 offset:3072
	ds_read_b128 v[146:149], v158
	ds_read_b128 v[150:153], v158 offset:1024
	ds_read_b128 v[154:157], v158 offset:2048
	ds_read_b128 v[158:161], v158 offset:3072
	s_add_u32 s6, s40, 0xb0000
	s_addc_u32 s7, s41, 0
	s_mov_b32 m0, s55
	v_lshl_add_u64 v[228:229], s[6:7], 0, v[162:163]
	ds_read_b128 v[182:185], v206 offset:32768
	ds_read_b128 v[186:189], v206 offset:33792
	ds_read_b128 v[192:195], v206 offset:34816
	ds_read_b128 v[196:199], v206 offset:35840
	ds_read_b128 v[200:203], v206 offset:36864
	ds_read_b128 v[208:211], v206 offset:37888
	ds_read_b128 v[212:215], v206 offset:38912
	ds_read_b128 v[216:219], v206 offset:39936
	global_load_lds_dwordx4 v[228:229], off
	v_lshl_add_u64 v[228:229], s[6:7], 0, v[166:167]
	s_mov_b32 m0, s56
	s_nop 0
	global_load_lds_dwordx4 v[228:229], off
	s_waitcnt vmcnt(8)
	s_waitcnt lgkmcnt(0)
	s_barrier
	s_setprio 1
	s_waitcnt lgkmcnt(0)
	v_mfma_f32_16x16x32_bf16 v[126:129], v[130:133], v[182:185], v[126:129]
	v_mfma_f32_16x16x32_bf16 v[122:125], v[138:141], v[182:185], v[122:125]
	v_mfma_f32_16x16x32_bf16 v[106:109], v[138:141], v[192:195], v[106:109]
	v_mfma_f32_16x16x32_bf16 v[110:113], v[130:133], v[192:195], v[110:113]
	v_mfma_f32_16x16x32_bf16 v[94:97], v[130:133], v[200:203], v[94:97]
	v_mfma_f32_16x16x32_bf16 v[90:93], v[138:141], v[200:203], v[90:93]
	v_mfma_f32_16x16x32_bf16 v[74:77], v[138:141], v[212:215], v[74:77]
	v_mfma_f32_16x16x32_bf16 v[78:81], v[130:133], v[212:215], v[78:81]
	v_mfma_f32_16x16x32_bf16 v[126:129], v[134:137], v[186:189], v[126:129]
	v_mfma_f32_16x16x32_bf16 v[122:125], v[142:145], v[186:189], v[122:125]
	v_mfma_f32_16x16x32_bf16 v[106:109], v[142:145], v[196:199], v[106:109]
	v_mfma_f32_16x16x32_bf16 v[110:113], v[134:137], v[196:199], v[110:113]
	v_mfma_f32_16x16x32_bf16 v[94:97], v[134:137], v[208:211], v[94:97]
	v_mfma_f32_16x16x32_bf16 v[90:93], v[142:145], v[208:211], v[90:93]
	v_mfma_f32_16x16x32_bf16 v[74:77], v[142:145], v[216:219], v[74:77]
	v_mfma_f32_16x16x32_bf16 v[78:81], v[134:137], v[216:219], v[78:81]
	s_setprio 0
	s_setprio 1
	v_mfma_f32_16x16x32_bf16 v[118:121], v[146:149], v[182:185], v[118:121]
	v_mfma_f32_16x16x32_bf16 v[114:117], v[154:157], v[182:185], v[114:117]
	v_mfma_f32_16x16x32_bf16 v[98:101], v[154:157], v[192:195], v[98:101]
	v_mfma_f32_16x16x32_bf16 v[102:105], v[146:149], v[192:195], v[102:105]
	v_mfma_f32_16x16x32_bf16 v[86:89], v[146:149], v[200:203], v[86:89]
	v_mfma_f32_16x16x32_bf16 v[82:85], v[154:157], v[200:203], v[82:85]
	v_mfma_f32_16x16x32_bf16 v[66:69], v[154:157], v[212:215], v[66:69]
	v_mfma_f32_16x16x32_bf16 v[70:73], v[146:149], v[212:215], v[70:73]
	v_mfma_f32_16x16x32_bf16 v[118:121], v[150:153], v[186:189], v[118:121]
	v_mfma_f32_16x16x32_bf16 v[114:117], v[158:161], v[186:189], v[114:117]
	v_mfma_f32_16x16x32_bf16 v[98:101], v[158:161], v[196:199], v[98:101]
	v_mfma_f32_16x16x32_bf16 v[102:105], v[150:153], v[196:199], v[102:105]
	v_mfma_f32_16x16x32_bf16 v[86:89], v[150:153], v[208:211], v[86:89]
	v_mfma_f32_16x16x32_bf16 v[82:85], v[158:161], v[208:211], v[82:85]
	v_mfma_f32_16x16x32_bf16 v[66:69], v[158:161], v[216:219], v[66:69]
	v_mfma_f32_16x16x32_bf16 v[70:73], v[150:153], v[216:219], v[70:73]
	s_setprio 0
	s_barrier
; #define PG8_STAGE(bufoff, gbase, voff) do { _Pragma("unroll") for (int _i = 0; _i < 2; ++_i) \
;         __builtin_amdgcn_global_load_lds((const unsigned*)((const char*)(gbase) + (voff)[_i]), (PG8_LAS unsigned*)(lds + (bufoff) + ldsw + _i * 8192), 16, 0, 0); } while (0)
; #define PG8_LDA(dst, b, h) do { _Pragma("unroll") for (int m = 0; m < 4; ++m) _Pragma("unroll") for (int k = 0; k < 2; ++k) dst[m][k] = *(const PG8_LAS bf16x8*)(lds + PG8_SA(b, h) + aoff + m * 2048 + k * 1024); } while (0)
; #define PG8_MMA(ai, bj, At, Bt) do { __builtin_amdgcn_s_setprio(1); _Pragma("unroll") for (int m = 0; m < 4; ++m) _Pragma("unroll") for (int n = 0; n < 2; ++n) _Pragma("unroll") for (int k = 0; k < 2; ++k) \
;         acc[ai][bj][m][n] = __builtin_amdgcn_mfma_f32_16x16x32_bf16(Bt[n][k], At[m][k], acc[ai][bj][m][n], 0, 0, 0); __builtin_amdgcn_s_setprio(0); } while (0)
; #define PG8_WAIT_V(n) asm volatile("s_waitcnt vmcnt(" #n ")" ::: "memory")
; #define PG8_WAIT_L(n) asm volatile("s_waitcnt lgkmcnt(" #n ")" ::: "memory")
; #define PG8_BAR __builtin_amdgcn_s_barrier()
; #define PG8_SCHED __builtin_amdgcn_sched_barrier(0)
; template <class Epi, class Sched, bool ALIGN_EPI = false, bool SP2 = false>
; __device__ __forceinline__ void gemm_phase(PG8_LAS unsigned char* lds, const Gemm g, const Sched& S, const Epi& E, const int tid) {
;     ...
;             PG8_LDA(At, 1, 1); PG8_STAGE(PG8_SB(1, 0), b3, voffB); PG8_STAGE(PG8_SB(1, 1), b3 + hstep, voffB); PG8_STAGE(PG8_SA(1, 0), a3, voffA);
;             PG8_WAIT_V(8); PG8_WAIT_L(0); PG8_BAR; PG8_MMA(1, 0, At, B0); PG8_MMA(1, 1, At, B1); PG8_BAR; PG8_SCHED;
;     ...
;         if constexpr (ALIGN_EPI) { if (wr == 0) PG8_BAR; }
	s_add_i32 s6, s15, s52
	v_lshl_add_u64 v[220:221], v[220:221], 0, s[34:35]
	s_mov_b32 m0, s6
	ds_read_b128 v[182:185], v206 offset:49152
	ds_read_b128 v[186:189], v206 offset:50176
	ds_read_b128 v[192:195], v206 offset:51200
	ds_read_b128 v[196:199], v206 offset:52224
	ds_read_b128 v[200:203], v206 offset:53248
	ds_read_b128 v[208:211], v206 offset:54272
	ds_read_b128 v[212:215], v206 offset:55296
	ds_read_b128 v[216:219], v206 offset:56320
	global_load_lds_dwordx4 v[220:221], off
	s_add_i32 m0, s6, 0x2000
	s_add_u32 s6, s10, 0xb0080
	v_lshl_add_u64 v[220:221], v[222:223], 0, s[34:35]
	s_addc_u32 s7, s11, 0
	s_add_i32 s10, s18, s52
	global_load_lds_dwordx4 v[220:221], off
	v_lshl_add_u64 v[220:221], s[6:7], 0, v[164:165]
	s_mov_b32 m0, s10
	s_nop 0
	global_load_lds_dwordx4 v[220:221], off
	v_lshl_add_u64 v[220:221], s[6:7], 0, v[168:169]
	s_add_i32 m0, s10, 0x2000
	s_nop 0
	global_load_lds_dwordx4 v[220:221], off
	v_lshl_add_u64 v[220:221], v[224:225], 0, s[34:35]
	s_mov_b32 m0, s58
	s_nop 0
	global_load_lds_dwordx4 v[220:221], off
	v_lshl_add_u64 v[220:221], v[226:227], 0, s[34:35]
	s_mov_b32 m0, s59
	s_nop 0
	global_load_lds_dwordx4 v[220:221], off
	s_waitcnt vmcnt(8)
	s_waitcnt lgkmcnt(0)
	s_barrier
	s_setprio 1
	s_waitcnt lgkmcnt(0)
	v_mfma_f32_16x16x32_bf16 v[62:65], v[130:133], v[182:185], v[62:65]
	v_mfma_f32_16x16x32_bf16 v[58:61], v[138:141], v[182:185], v[58:61]
	v_mfma_f32_16x16x32_bf16 v[42:45], v[138:141], v[192:195], v[42:45]
	v_mfma_f32_16x16x32_bf16 v[46:49], v[130:133], v[192:195], v[46:49]
	v_mfma_f32_16x16x32_bf16 v[30:33], v[130:133], v[200:203], v[30:33]
	v_mfma_f32_16x16x32_bf16 v[26:29], v[138:141], v[200:203], v[26:29]
	v_mfma_f32_16x16x32_bf16 v[10:13], v[138:141], v[212:215], v[10:13]
	v_mfma_f32_16x16x32_bf16 v[14:17], v[130:133], v[212:215], v[14:17]
	v_mfma_f32_16x16x32_bf16 v[62:65], v[134:137], v[186:189], v[62:65]
	v_mfma_f32_16x16x32_bf16 v[58:61], v[142:145], v[186:189], v[58:61]
	v_mfma_f32_16x16x32_bf16 v[42:45], v[142:145], v[196:199], v[42:45]
	v_mfma_f32_16x16x32_bf16 v[46:49], v[134:137], v[196:199], v[46:49]
	v_mfma_f32_16x16x32_bf16 v[30:33], v[134:137], v[208:211], v[30:33]
	v_mfma_f32_16x16x32_bf16 v[26:29], v[142:145], v[208:211], v[26:29]
	v_mfma_f32_16x16x32_bf16 v[10:13], v[142:145], v[216:219], v[10:13]
	v_mfma_f32_16x16x32_bf16 v[14:17], v[134:137], v[216:219], v[14:17]
	s_setprio 0
	s_setprio 1
	v_mfma_f32_16x16x32_bf16 v[54:57], v[146:149], v[182:185], v[54:57]
	v_mfma_f32_16x16x32_bf16 v[50:53], v[154:157], v[182:185], v[50:53]
	v_mfma_f32_16x16x32_bf16 v[34:37], v[154:157], v[192:195], v[34:37]
	v_mfma_f32_16x16x32_bf16 v[38:41], v[146:149], v[192:195], v[38:41]
	v_mfma_f32_16x16x32_bf16 v[22:25], v[146:149], v[200:203], v[22:25]
	v_mfma_f32_16x16x32_bf16 v[18:21], v[154:157], v[200:203], v[18:21]
	v_mfma_f32_16x16x32_bf16 v[2:5], v[154:157], v[212:215], v[2:5]
	v_mfma_f32_16x16x32_bf16 v[6:9], v[146:149], v[212:215], v[6:9]
	v_mfma_f32_16x16x32_bf16 v[54:57], v[150:153], v[186:189], v[54:57]
	v_mfma_f32_16x16x32_bf16 v[50:53], v[158:161], v[186:189], v[50:53]
	v_mfma_f32_16x16x32_bf16 v[34:37], v[158:161], v[196:199], v[34:37]
	v_mfma_f32_16x16x32_bf16 v[38:41], v[150:153], v[196:199], v[38:41]
	v_mfma_f32_16x16x32_bf16 v[22:25], v[150:153], v[208:211], v[22:25]
	v_mfma_f32_16x16x32_bf16 v[18:21], v[158:161], v[208:211], v[18:21]
	v_mfma_f32_16x16x32_bf16 v[2:5], v[158:161], v[216:219], v[2:5]
	v_mfma_f32_16x16x32_bf16 v[6:9], v[150:153], v[216:219], v[6:9]
	s_setprio 0
	s_barrier
	s_add_i32 s74, s74, 2
	s_add_u32 s43, s43, 0x100
	s_addc_u32 s45, s45, 0
	s_cmp_gt_u32 s74, 41
	s_mov_b64 s[6:7], s[8:9]
	s_cbranch_scc0 .LBB0_5220
	s_and_b64 vcc, exec, s[36:37]
	s_cbranch_vccz .LBB0_5223
	s_barrier

; #define PG8_STAGE(bufoff, gbase, voff) do { _Pragma("unroll") for (int _i = 0; _i < 2; ++_i) \
;         __builtin_amdgcn_global_load_lds((const unsigned*)((const char*)(gbase) + (voff)[_i]), (PG8_LAS unsigned*)(lds + (bufoff) + ldsw + _i * 8192), 16, 0, 0); } while (0)
; #define PG8_LDA(dst, b, h) do { _Pragma("unroll") for (int m = 0; m < 4; ++m) _Pragma("unroll") for (int k = 0; k < 2; ++k) dst[m][k] = *(const PG8_LAS bf16x8*)(lds + PG8_SA(b, h) + aoff + m * 2048 + k * 1024); } while (0)
; #define PG8_LDB(dst, b, h) do { _Pragma("unroll") for (int n = 0; n < 2; ++n) _Pragma("unroll") for (int k = 0; k < 2; ++k) dst[n][k] = *(const PG8_LAS bf16x8*)(lds + PG8_SB(b, h) + boff + n * 2048 + k * 1024); } while (0)
; #define PG8_WAIT_V(n) asm volatile("s_waitcnt vmcnt(" #n ")" ::: "memory")
; #define PG8_WAIT_L(n) asm volatile("s_waitcnt lgkmcnt(" #n ")" ::: "memory")
; #define PG8_BAR __builtin_amdgcn_s_barrier()
; #define PG8_SCHED __builtin_amdgcn_sched_barrier(0)
; template <class Epi, class Sched, bool ALIGN_EPI = false, bool SP2 = false>
; __device__ __forceinline__ void gemm_phase(PG8_LAS unsigned char* lds, const Gemm g, const Sched& S, const Epi& E, const int tid) {
;     ...
;         const bool has_next = S.next(ui + 1, nxt);
;         const char* nA = has_next ? S.aptr(nxt) : cA; const char* nB = has_next ? S.bptr(nxt) : cB;
;         for (int t = 0; t < nt; t += 2) {
;             const bool last = (t == nt - 2);
;             const char* a1 = cA + (size_t)(t + 1) * kstep;
;             const char* a2 = last ? nA : cA + (size_t)(t + 2) * kstep; const char* b2 = last ? nB : cB + (size_t)(t + 2) * kstep;
;             const char* a3 = a2 + kstep; const char* b3 = b2 + kstep;
;             if (last && has_next) S.a_ready(nxt);
;             if constexpr (SP2) {
;             PG8_LDB(B0, 0, 0); PG8_LDB(B1, 0, 1); PG8_SCHED; PG8_LDA(At, 0, 0); PG8_STAGE(PG8_SA(1, 1), a1 + hstep, voffA);
;             PG8_WAIT_V(8); PG8_WAIT_L(0); PG8_BAR; PG8_MMA(0, 0, At, B0); PG8_MMA(0, 1, At, B1); PG8_BAR; PG8_SCHED;
;             PG8_LDA(At, 0, 1); PG8_STAGE(PG8_SB(0, 0), b2, voffB); PG8_STAGE(PG8_SB(0, 1), b2 + hstep, voffB); PG8_STAGE(PG8_SA(0, 0), a2, voffA);
;             PG8_WAIT_V(8); PG8_WAIT_L(0); PG8_BAR; PG8_MMA(1, 0, At, B0); PG8_MMA(1, 1, At, B1); PG8_BAR; PG8_SCHED;
.LBB0_5776:
	s_add_u32 s5, s54, 0x100
	s_addc_u32 s47, s55, 0
	s_add_u32 s54, s56, 0x40080
	s_addc_u32 s55, s57, 0
	s_mov_b32 s49, -2
	ds_read_b128 v[130:133], v171
	ds_read_b128 v[134:137], v171 offset:1024
	ds_read_b128 v[160:163], v171 offset:2048
	ds_read_b128 v[164:167], v171 offset:3072
	ds_read_b128 v[176:179], v172
	ds_read_b128 v[180:183], v172 offset:1024
	ds_read_b128 v[184:187], v172 offset:2048
	ds_read_b128 v[192:195], v172 offset:3072
	s_add_u32 s15, s54, 0xfffc0080
	s_addc_u32 s18, s55, -1
	s_cmp_eq_u32 s49, 12
	s_cselect_b32 s59, s1, s18
	s_cselect_b32 s58, s0, s15
	s_cselect_b32 s57, s51, s47
	s_cselect_b32 s56, s50, s5
	v_lshl_add_u64 v[168:169], s[54:55], 0, v[154:155]
	s_add_i32 m0, s64, 0xc000
	ds_read_b128 v[196:199], v173
	ds_read_b128 v[200:203], v173 offset:1024
	ds_read_b128 v[204:207], v173 offset:2048
	ds_read_b128 v[208:211], v173 offset:3072
	ds_read_b128 v[212:215], v173 offset:4096
	ds_read_b128 v[216:219], v173 offset:5120
	ds_read_b128 v[220:223], v173 offset:6144
	ds_read_b128 v[224:227], v173 offset:7168
	global_load_lds_dwordx4 v[168:169], off
	v_lshl_add_u64 v[168:169], s[54:55], 0, v[152:153]
	s_add_i32 m0, s64, 0xe000
	s_nop 0
	global_load_lds_dwordx4 v[168:169], off
	s_waitcnt vmcnt(8)
	s_waitcnt lgkmcnt(0)
	s_barrier
	s_setprio 1
	s_waitcnt lgkmcnt(0)
	v_mfma_f32_16x16x32_bf16 v[126:129], v[130:133], v[196:199], 0
	v_mfma_f32_16x16x32_bf16 v[122:125], v[160:163], v[196:199], 0
	v_mfma_f32_16x16x32_bf16 v[106:109], v[160:163], v[204:207], 0
	v_mfma_f32_16x16x32_bf16 v[110:113], v[130:133], v[204:207], 0
	v_mfma_f32_16x16x32_bf16 v[94:97], v[130:133], v[212:215], 0
	v_mfma_f32_16x16x32_bf16 v[90:93], v[160:163], v[212:215], 0
	v_mfma_f32_16x16x32_bf16 v[74:77], v[160:163], v[220:223], 0
	v_mfma_f32_16x16x32_bf16 v[78:81], v[130:133], v[220:223], 0
	v_mfma_f32_16x16x32_bf16 v[126:129], v[134:137], v[200:203], v[126:129]
	v_mfma_f32_16x16x32_bf16 v[122:125], v[164:167], v[200:203], v[122:125]
	v_mfma_f32_16x16x32_bf16 v[106:109], v[164:167], v[208:211], v[106:109]
	v_mfma_f32_16x16x32_bf16 v[110:113], v[134:137], v[208:211], v[110:113]
	v_mfma_f32_16x16x32_bf16 v[94:97], v[134:137], v[216:219], v[94:97]
	v_mfma_f32_16x16x32_bf16 v[90:93], v[164:167], v[216:219], v[90:93]
	v_mfma_f32_16x16x32_bf16 v[74:77], v[164:167], v[224:227], v[74:77]
	v_mfma_f32_16x16x32_bf16 v[78:81], v[134:137], v[224:227], v[78:81]
	s_setprio 0
	s_setprio 1
	v_mfma_f32_16x16x32_bf16 v[118:121], v[176:179], v[196:199], 0
	v_mfma_f32_16x16x32_bf16 v[114:117], v[184:187], v[196:199], 0
	v_mfma_f32_16x16x32_bf16 v[98:101], v[184:187], v[204:207], 0
	v_mfma_f32_16x16x32_bf16 v[102:105], v[176:179], v[204:207], 0
	v_mfma_f32_16x16x32_bf16 v[86:89], v[176:179], v[212:215], 0
	v_mfma_f32_16x16x32_bf16 v[82:85], v[184:187], v[212:215], 0
	v_mfma_f32_16x16x32_bf16 v[66:69], v[184:187], v[220:223], 0
	v_mfma_f32_16x16x32_bf16 v[70:73], v[176:179], v[220:223], 0
	v_mfma_f32_16x16x32_bf16 v[118:121], v[180:183], v[200:203], v[118:121]
	v_mfma_f32_16x16x32_bf16 v[114:117], v[192:195], v[200:203], v[114:117]
	v_mfma_f32_16x16x32_bf16 v[98:101], v[192:195], v[208:211], v[98:101]
	v_mfma_f32_16x16x32_bf16 v[102:105], v[180:183], v[208:211], v[102:105]
	v_mfma_f32_16x16x32_bf16 v[86:89], v[180:183], v[216:219], v[86:89]
	v_mfma_f32_16x16x32_bf16 v[82:85], v[192:195], v[216:219], v[82:85]
	v_mfma_f32_16x16x32_bf16 v[66:69], v[192:195], v[224:227], v[66:69]
	v_mfma_f32_16x16x32_bf16 v[70:73], v[180:183], v[224:227], v[70:73]
	s_setprio 0
	s_barrier
	s_add_i32 s15, s83, s63
	v_lshl_add_u64 v[168:169], s[56:57], 0, v[140:141]
	s_mov_b32 m0, s15
	ds_read_b128 v[196:199], v173 offset:16384
	ds_read_b128 v[200:203], v173 offset:17408
	ds_read_b128 v[204:207], v173 offset:18432
	ds_read_b128 v[208:211], v173 offset:19456
	ds_read_b128 v[212:215], v173 offset:20480
	ds_read_b128 v[216:219], v173 offset:21504
	ds_read_b128 v[220:223], v173 offset:22528
	ds_read_b128 v[224:227], v173 offset:23552
	global_load_lds_dwordx4 v[168:169], off
	s_add_i32 m0, s15, 0x2000
	s_add_u32 s18, s56, 0x40000
	v_lshl_add_u64 v[188:189], s[56:57], 0, v[144:145]
	s_addc_u32 s19, s57, 0
	s_add_i32 s15, s84, s63
	global_load_lds_dwordx4 v[188:189], off
	v_lshl_add_u64 v[228:229], s[18:19], 0, v[140:141]
	s_mov_b32 m0, s15
	v_lshl_add_u64 v[230:231], s[58:59], 0, v[142:143]
	global_load_lds_dwordx4 v[228:229], off
	v_lshl_add_u64 v[228:229], s[18:19], 0, v[144:145]
	s_add_i32 m0, s15, 0x2000
	s_nop 0
	global_load_lds_dwordx4 v[228:229], off
	v_lshl_add_u64 v[228:229], s[58:59], 0, v[138:139]
	s_mov_b32 m0, s64
	s_nop 0
	global_load_lds_dwordx4 v[228:229], off
	s_mov_b32 m0, s65
	s_nop 0
	global_load_lds_dwordx4 v[230:231], off
	s_waitcnt vmcnt(8)
	s_waitcnt lgkmcnt(0)
	s_barrier
; #define PG8_STAGE(bufoff, gbase, voff) do { _Pragma("unroll") for (int _i = 0; _i < 2; ++_i) \
;         __builtin_amdgcn_global_load_lds((const unsigned*)((const char*)(gbase) + (voff)[_i]), (PG8_LAS unsigned*)(lds + (bufoff) + ldsw + _i * 8192), 16, 0, 0); } while (0)
; #define PG8_LDA(dst, b, h) do { _Pragma("unroll") for (int m = 0; m < 4; ++m) _Pragma("unroll") for (int k = 0; k < 2; ++k) dst[m][k] = *(const PG8_LAS bf16x8*)(lds + PG8_SA(b, h) + aoff + m * 2048 + k * 1024); } while (0)
; #define PG8_LDB(dst, b, h) do { _Pragma("unroll") for (int n = 0; n < 2; ++n) _Pragma("unroll") for (int k = 0; k < 2; ++k) dst[n][k] = *(const PG8_LAS bf16x8*)(lds + PG8_SB(b, h) + boff + n * 2048 + k * 1024); } while (0)
; #define PG8_MMA(ai, bj, At, Bt) do { __builtin_amdgcn_s_setprio(1); _Pragma("unroll") for (int m = 0; m < 4; ++m) _Pragma("unroll") for (int n = 0; n < 2; ++n) _Pragma("unroll") for (int k = 0; k < 2; ++k) \
;         acc[ai][bj][m][n] = __builtin_amdgcn_mfma_f32_16x16x32_bf16(Bt[n][k], At[m][k], acc[ai][bj][m][n], 0, 0, 0); __builtin_amdgcn_s_setprio(0); } while (0)
; #define PG8_WAIT_V(n) asm volatile("s_waitcnt vmcnt(" #n ")" ::: "memory")
; #define PG8_WAIT_L(n) asm volatile("s_waitcnt lgkmcnt(" #n ")" ::: "memory")
; #define PG8_BAR __builtin_amdgcn_s_barrier()
; #define PG8_SCHED __builtin_amdgcn_sched_barrier(0)
; template <class Epi, class Sched, bool ALIGN_EPI = false, bool SP2 = false>
; __device__ __forceinline__ void gemm_phase(PG8_LAS unsigned char* lds, const Gemm g, const Sched& S, const Epi& E, const int tid) {
;     ...
;             PG8_WAIT_V(8); PG8_WAIT_L(0); PG8_BAR; PG8_MMA(1, 0, At, B0); PG8_MMA(1, 1, At, B1); PG8_BAR; PG8_SCHED;
;             PG8_LDB(B0, 1, 0); PG8_LDB(B1, 1, 1); PG8_SCHED; PG8_LDA(At, 1, 0); PG8_STAGE(PG8_SA(0, 1), a2 + hstep, voffA);
;             PG8_WAIT_V(8); PG8_WAIT_L(0); PG8_BAR; PG8_MMA(0, 0, At, B0); PG8_MMA(0, 1, At, B1); PG8_BAR; PG8_SCHED;
	s_setprio 1
	s_waitcnt lgkmcnt(0)
	v_mfma_f32_16x16x32_bf16 v[62:65], v[130:133], v[196:199], 0
	v_mfma_f32_16x16x32_bf16 v[58:61], v[160:163], v[196:199], 0
	v_mfma_f32_16x16x32_bf16 v[42:45], v[160:163], v[204:207], 0
	v_mfma_f32_16x16x32_bf16 v[46:49], v[130:133], v[204:207], 0
	v_mfma_f32_16x16x32_bf16 v[30:33], v[130:133], v[212:215], 0
	v_mfma_f32_16x16x32_bf16 v[26:29], v[160:163], v[212:215], 0
	v_mfma_f32_16x16x32_bf16 v[10:13], v[160:163], v[220:223], 0
	v_mfma_f32_16x16x32_bf16 v[14:17], v[130:133], v[220:223], 0
	v_mfma_f32_16x16x32_bf16 v[62:65], v[134:137], v[200:203], v[62:65]
	v_mfma_f32_16x16x32_bf16 v[58:61], v[164:167], v[200:203], v[58:61]
	v_mfma_f32_16x16x32_bf16 v[42:45], v[164:167], v[208:211], v[42:45]
	v_mfma_f32_16x16x32_bf16 v[46:49], v[134:137], v[208:211], v[46:49]
	v_mfma_f32_16x16x32_bf16 v[30:33], v[134:137], v[216:219], v[30:33]
	v_mfma_f32_16x16x32_bf16 v[26:29], v[164:167], v[216:219], v[26:29]
	v_mfma_f32_16x16x32_bf16 v[10:13], v[164:167], v[224:227], v[10:13]
	v_mfma_f32_16x16x32_bf16 v[14:17], v[134:137], v[224:227], v[14:17]
	s_setprio 0
	s_setprio 1
	v_mfma_f32_16x16x32_bf16 v[54:57], v[176:179], v[196:199], 0
	v_mfma_f32_16x16x32_bf16 v[50:53], v[184:187], v[196:199], 0
	v_mfma_f32_16x16x32_bf16 v[34:37], v[184:187], v[204:207], 0
	v_mfma_f32_16x16x32_bf16 v[38:41], v[176:179], v[204:207], 0
	v_mfma_f32_16x16x32_bf16 v[22:25], v[176:179], v[212:215], 0
	v_mfma_f32_16x16x32_bf16 v[18:21], v[184:187], v[212:215], 0
	v_mfma_f32_16x16x32_bf16 v[2:5], v[184:187], v[220:223], 0
	v_mfma_f32_16x16x32_bf16 v[6:9], v[176:179], v[220:223], 0
	v_mfma_f32_16x16x32_bf16 v[54:57], v[180:183], v[200:203], v[54:57]
	v_mfma_f32_16x16x32_bf16 v[50:53], v[192:195], v[200:203], v[50:53]
	v_mfma_f32_16x16x32_bf16 v[34:37], v[192:195], v[208:211], v[34:37]
	v_mfma_f32_16x16x32_bf16 v[38:41], v[180:183], v[208:211], v[38:41]
	v_mfma_f32_16x16x32_bf16 v[22:25], v[180:183], v[216:219], v[22:25]
	v_mfma_f32_16x16x32_bf16 v[18:21], v[192:195], v[216:219], v[18:21]
	v_mfma_f32_16x16x32_bf16 v[2:5], v[192:195], v[224:227], v[2:5]
	v_mfma_f32_16x16x32_bf16 v[6:9], v[180:183], v[224:227], v[6:9]
	s_setprio 0
	s_barrier
	s_add_i32 s15, 0, 0x18000
	s_add_i32 s60, 0, 0x1c000
	v_add_u32_e32 v164, s15, v170
	v_add_u32_e32 v175, s60, v170
	ds_read_b128 v[130:133], v164
	ds_read_b128 v[134:137], v164 offset:1024
	ds_read_b128 v[160:163], v164 offset:2048
	ds_read_b128 v[164:167], v164 offset:3072
	ds_read_b128 v[176:179], v175
	ds_read_b128 v[180:183], v175 offset:1024
	ds_read_b128 v[184:187], v175 offset:2048
	ds_read_b128 v[192:195], v175 offset:3072
	s_add_u32 s18, s58, 0x40000
	s_addc_u32 s19, s59, 0
	s_mov_b32 m0, s66
	v_lshl_add_u64 v[232:233], s[18:19], 0, v[138:139]
	ds_read_b128 v[196:199], v173 offset:32768
	ds_read_b128 v[200:203], v173 offset:33792
	ds_read_b128 v[204:207], v173 offset:34816
	ds_read_b128 v[208:211], v173 offset:35840
	ds_read_b128 v[212:215], v173 offset:36864
	ds_read_b128 v[216:219], v173 offset:37888
	ds_read_b128 v[220:223], v173 offset:38912
	ds_read_b128 v[224:227], v173 offset:39936
	global_load_lds_dwordx4 v[232:233], off
	v_lshl_add_u64 v[232:233], s[18:19], 0, v[142:143]
	s_mov_b32 m0, s67
	s_nop 0
	global_load_lds_dwordx4 v[232:233], off
	s_waitcnt vmcnt(8)
	s_waitcnt lgkmcnt(0)
	s_barrier
	s_setprio 1
	s_waitcnt lgkmcnt(0)
	v_mfma_f32_16x16x32_bf16 v[126:129], v[130:133], v[196:199], v[126:129]
	v_mfma_f32_16x16x32_bf16 v[122:125], v[160:163], v[196:199], v[122:125]
	v_mfma_f32_16x16x32_bf16 v[106:109], v[160:163], v[204:207], v[106:109]
	v_mfma_f32_16x16x32_bf16 v[110:113], v[130:133], v[204:207], v[110:113]
	v_mfma_f32_16x16x32_bf16 v[94:97], v[130:133], v[212:215], v[94:97]
	v_mfma_f32_16x16x32_bf16 v[90:93], v[160:163], v[212:215], v[90:93]
	v_mfma_f32_16x16x32_bf16 v[74:77], v[160:163], v[220:223], v[74:77]
	v_mfma_f32_16x16x32_bf16 v[78:81], v[130:133], v[220:223], v[78:81]
	v_mfma_f32_16x16x32_bf16 v[126:129], v[134:137], v[200:203], v[126:129]
	v_mfma_f32_16x16x32_bf16 v[122:125], v[164:167], v[200:203], v[122:125]
	v_mfma_f32_16x16x32_bf16 v[106:109], v[164:167], v[208:211], v[106:109]
	v_mfma_f32_16x16x32_bf16 v[110:113], v[134:137], v[208:211], v[110:113]
	v_mfma_f32_16x16x32_bf16 v[94:97], v[134:137], v[216:219], v[94:97]
	v_mfma_f32_16x16x32_bf16 v[90:93], v[164:167], v[216:219], v[90:93]
	v_mfma_f32_16x16x32_bf16 v[74:77], v[164:167], v[224:227], v[74:77]
	v_mfma_f32_16x16x32_bf16 v[78:81], v[134:137], v[224:227], v[78:81]
	s_setprio 0
	s_setprio 1
	v_mfma_f32_16x16x32_bf16 v[118:121], v[176:179], v[196:199], v[118:121]
	v_mfma_f32_16x16x32_bf16 v[114:117], v[184:187], v[196:199], v[114:117]
	v_mfma_f32_16x16x32_bf16 v[98:101], v[184:187], v[204:207], v[98:101]
	v_mfma_f32_16x16x32_bf16 v[102:105], v[176:179], v[204:207], v[102:105]
	v_mfma_f32_16x16x32_bf16 v[86:89], v[176:179], v[212:215], v[86:89]
	v_mfma_f32_16x16x32_bf16 v[82:85], v[184:187], v[212:215], v[82:85]
	v_mfma_f32_16x16x32_bf16 v[66:69], v[184:187], v[220:223], v[66:69]
	v_mfma_f32_16x16x32_bf16 v[70:73], v[176:179], v[220:223], v[70:73]
	v_mfma_f32_16x16x32_bf16 v[118:121], v[180:183], v[200:203], v[118:121]
	v_mfma_f32_16x16x32_bf16 v[114:117], v[192:195], v[200:203], v[114:117]
	v_mfma_f32_16x16x32_bf16 v[98:101], v[192:195], v[208:211], v[98:101]
	v_mfma_f32_16x16x32_bf16 v[102:105], v[180:183], v[208:211], v[102:105]
	v_mfma_f32_16x16x32_bf16 v[86:89], v[180:183], v[216:219], v[86:89]
	v_mfma_f32_16x16x32_bf16 v[82:85], v[192:195], v[216:219], v[82:85]
	v_mfma_f32_16x16x32_bf16 v[66:69], v[192:195], v[224:227], v[66:69]
	v_mfma_f32_16x16x32_bf16 v[70:73], v[180:183], v[224:227], v[70:73]
	s_setprio 0
	s_barrier
; #define PG8_STAGE(bufoff, gbase, voff) do { _Pragma("unroll") for (int _i = 0; _i < 2; ++_i) \
;         __builtin_amdgcn_global_load_lds((const unsigned*)((const char*)(gbase) + (voff)[_i]), (PG8_LAS unsigned*)(lds + (bufoff) + ldsw + _i * 8192), 16, 0, 0); } while (0)
; #define PG8_LDA(dst, b, h) do { _Pragma("unroll") for (int m = 0; m < 4; ++m) _Pragma("unroll") for (int k = 0; k < 2; ++k) dst[m][k] = *(const PG8_LAS bf16x8*)(lds + PG8_SA(b, h) + aoff + m * 2048 + k * 1024); } while (0)
; #define PG8_LDB(dst, b, h) do { _Pragma("unroll") for (int n = 0; n < 2; ++n) _Pragma("unroll") for (int k = 0; k < 2; ++k) dst[n][k] = *(const PG8_LAS bf16x8*)(lds + PG8_SB(b, h) + boff + n * 2048 + k * 1024); } while (0)
; #define PG8_MMA(ai, bj, At, Bt) do { __builtin_amdgcn_s_setprio(1); _Pragma("unroll") for (int m = 0; m < 4; ++m) _Pragma("unroll") for (int n = 0; n < 2; ++n) _Pragma("unroll") for (int k = 0; k < 2; ++k) \
;         acc[ai][bj][m][n] = __builtin_amdgcn_mfma_f32_16x16x32_bf16(Bt[n][k], At[m][k], acc[ai][bj][m][n], 0, 0, 0); __builtin_amdgcn_s_setprio(0); } while (0)
; #define PG8_WAIT_V(n) asm volatile("s_waitcnt vmcnt(" #n ")" ::: "memory")
; #define PG8_WAIT_L(n) asm volatile("s_waitcnt lgkmcnt(" #n ")" ::: "memory")
; #define PG8_BAR __builtin_amdgcn_s_barrier()
; #define PG8_SCHED __builtin_amdgcn_sched_barrier(0)
; template <class Epi, class Sched, bool ALIGN_EPI = false, bool SP2 = false>
; __device__ __forceinline__ void gemm_phase(PG8_LAS unsigned char* lds, const Gemm g, const Sched& S, const Epi& E, const int tid) {
;     ...
;             PG8_LDB(B0, 0, 0); PG8_LDB(B1, 0, 1); PG8_SCHED; PG8_LDA(At, 0, 0); PG8_STAGE(PG8_SA(1, 1), a1 + hstep, voffA);
;             PG8_WAIT_V(8); PG8_WAIT_L(0); PG8_BAR; PG8_MMA(0, 0, At, B0); PG8_MMA(0, 1, At, B1); PG8_BAR; PG8_SCHED;
;     ...
;             PG8_LDA(At, 1, 1); PG8_STAGE(PG8_SB(1, 0), b3, voffB); PG8_STAGE(PG8_SB(1, 1), b3 + hstep, voffB); PG8_STAGE(PG8_SA(1, 0), a3, voffA);
;             PG8_WAIT_V(8); PG8_WAIT_L(0); PG8_BAR; PG8_MMA(1, 0, At, B0); PG8_MMA(1, 1, At, B1); PG8_BAR; PG8_SCHED;
	s_add_i32 s15, s15, s63
	v_lshl_add_u64 v[168:169], v[168:169], 0, s[42:43]
	s_mov_b32 m0, s15
	ds_read_b128 v[196:199], v173 offset:49152
	ds_read_b128 v[200:203], v173 offset:50176
	ds_read_b128 v[204:207], v173 offset:51200
	ds_read_b128 v[208:211], v173 offset:52224
	ds_read_b128 v[212:215], v173 offset:53248
	ds_read_b128 v[216:219], v173 offset:54272
	ds_read_b128 v[220:223], v173 offset:55296
	ds_read_b128 v[224:227], v173 offset:56320
	global_load_lds_dwordx4 v[168:169], off
	s_add_i32 m0, s15, 0x2000
	s_add_u32 s18, s56, 0x40080
	v_lshl_add_u64 v[168:169], v[188:189], 0, s[42:43]
	s_addc_u32 s19, s57, 0
	s_add_i32 s15, s60, s63
	global_load_lds_dwordx4 v[168:169], off
	v_lshl_add_u64 v[168:169], s[18:19], 0, v[140:141]
	s_mov_b32 m0, s15
	s_nop 0
	global_load_lds_dwordx4 v[168:169], off
	v_lshl_add_u64 v[168:169], s[18:19], 0, v[144:145]
	s_add_i32 m0, s15, 0x2000
	s_nop 0
	global_load_lds_dwordx4 v[168:169], off
	v_lshl_add_u64 v[168:169], v[228:229], 0, s[42:43]
	s_mov_b32 m0, s74
	s_nop 0
	global_load_lds_dwordx4 v[168:169], off
	v_lshl_add_u64 v[168:169], v[230:231], 0, s[42:43]
	s_mov_b32 m0, s75
	s_nop 0
	global_load_lds_dwordx4 v[168:169], off
	s_waitcnt vmcnt(8)
	s_waitcnt lgkmcnt(0)
	s_barrier
	s_setprio 1
	s_waitcnt lgkmcnt(0)
	v_mfma_f32_16x16x32_bf16 v[62:65], v[130:133], v[196:199], v[62:65]
	v_mfma_f32_16x16x32_bf16 v[58:61], v[160:163], v[196:199], v[58:61]
	v_mfma_f32_16x16x32_bf16 v[42:45], v[160:163], v[204:207], v[42:45]
	v_mfma_f32_16x16x32_bf16 v[46:49], v[130:133], v[204:207], v[46:49]
	v_mfma_f32_16x16x32_bf16 v[30:33], v[130:133], v[212:215], v[30:33]
	v_mfma_f32_16x16x32_bf16 v[26:29], v[160:163], v[212:215], v[26:29]
	v_mfma_f32_16x16x32_bf16 v[10:13], v[160:163], v[220:223], v[10:13]
	v_mfma_f32_16x16x32_bf16 v[14:17], v[130:133], v[220:223], v[14:17]
	v_mfma_f32_16x16x32_bf16 v[62:65], v[134:137], v[200:203], v[62:65]
	v_mfma_f32_16x16x32_bf16 v[58:61], v[164:167], v[200:203], v[58:61]
	v_mfma_f32_16x16x32_bf16 v[42:45], v[164:167], v[208:211], v[42:45]
	v_mfma_f32_16x16x32_bf16 v[46:49], v[134:137], v[208:211], v[46:49]
	v_mfma_f32_16x16x32_bf16 v[30:33], v[134:137], v[216:219], v[30:33]
	v_mfma_f32_16x16x32_bf16 v[26:29], v[164:167], v[216:219], v[26:29]
	v_mfma_f32_16x16x32_bf16 v[10:13], v[164:167], v[224:227], v[10:13]
	v_mfma_f32_16x16x32_bf16 v[14:17], v[134:137], v[224:227], v[14:17]
	s_setprio 0
	s_setprio 1
	v_mfma_f32_16x16x32_bf16 v[54:57], v[176:179], v[196:199], v[54:57]
	v_mfma_f32_16x16x32_bf16 v[50:53], v[184:187], v[196:199], v[50:53]
	v_mfma_f32_16x16x32_bf16 v[34:37], v[184:187], v[204:207], v[34:37]
	v_mfma_f32_16x16x32_bf16 v[38:41], v[176:179], v[204:207], v[38:41]
	v_mfma_f32_16x16x32_bf16 v[22:25], v[176:179], v[212:215], v[22:25]
	v_mfma_f32_16x16x32_bf16 v[18:21], v[184:187], v[212:215], v[18:21]
	v_mfma_f32_16x16x32_bf16 v[2:5], v[184:187], v[220:223], v[2:5]
	v_mfma_f32_16x16x32_bf16 v[6:9], v[176:179], v[220:223], v[6:9]
	v_mfma_f32_16x16x32_bf16 v[54:57], v[180:183], v[200:203], v[54:57]
	v_mfma_f32_16x16x32_bf16 v[50:53], v[192:195], v[200:203], v[50:53]
	v_mfma_f32_16x16x32_bf16 v[34:37], v[192:195], v[208:211], v[34:37]
	v_mfma_f32_16x16x32_bf16 v[38:41], v[180:183], v[208:211], v[38:41]
	v_mfma_f32_16x16x32_bf16 v[22:25], v[180:183], v[216:219], v[22:25]
	v_mfma_f32_16x16x32_bf16 v[18:21], v[192:195], v[216:219], v[18:21]
	v_mfma_f32_16x16x32_bf16 v[2:5], v[192:195], v[224:227], v[2:5]
	v_mfma_f32_16x16x32_bf16 v[6:9], v[180:183], v[224:227], v[6:9]
	s_setprio 0
	s_barrier
	s_add_i32 s49, s49, 2
	s_add_u32 s5, s5, 0x100
	s_addc_u32 s47, s47, 0
	s_add_u32 s54, s54, 0x100
	s_addc_u32 s55, s55, 0
.LBB0_5777:
	ds_read_b128 v[130:133], v171
	ds_read_b128 v[134:137], v171 offset:1024
	ds_read_b128 v[160:163], v171 offset:2048
	ds_read_b128 v[164:167], v171 offset:3072
	ds_read_b128 v[176:179], v172
	ds_read_b128 v[180:183], v172 offset:1024
	ds_read_b128 v[184:187], v172 offset:2048
	ds_read_b128 v[192:195], v172 offset:3072
	s_add_u32 s15, s54, 0xfffc0080
	s_addc_u32 s18, s55, -1
	s_cmp_eq_u32 s49, 12
	s_cselect_b32 s59, s1, s18
	s_cselect_b32 s58, s0, s15
	s_cselect_b32 s57, s51, s47
	s_cselect_b32 s56, s50, s5
	v_lshl_add_u64 v[168:169], s[54:55], 0, v[154:155]
	s_add_i32 m0, s64, 0xc000
	ds_read_b128 v[196:199], v173
	ds_read_b128 v[200:203], v173 offset:1024
	ds_read_b128 v[204:207], v173 offset:2048
	ds_read_b128 v[208:211], v173 offset:3072
	ds_read_b128 v[212:215], v173 offset:4096
	ds_read_b128 v[216:219], v173 offset:5120
	ds_read_b128 v[220:223], v173 offset:6144
	ds_read_b128 v[224:227], v173 offset:7168
	global_load_lds_dwordx4 v[168:169], off
	v_lshl_add_u64 v[168:169], s[54:55], 0, v[152:153]
	s_add_i32 m0, s64, 0xe000
	s_nop 0
	global_load_lds_dwordx4 v[168:169], off
	s_waitcnt vmcnt(8)
	s_waitcnt lgkmcnt(0)
	s_barrier
; #define PG8_STAGE(bufoff, gbase, voff) do { _Pragma("unroll") for (int _i = 0; _i < 2; ++_i) \
;         __builtin_amdgcn_global_load_lds((const unsigned*)((const char*)(gbase) + (voff)[_i]), (PG8_LAS unsigned*)(lds + (bufoff) + ldsw + _i * 8192), 16, 0, 0); } while (0)
; #define PG8_LDA(dst, b, h) do { _Pragma("unroll") for (int m = 0; m < 4; ++m) _Pragma("unroll") for (int k = 0; k < 2; ++k) dst[m][k] = *(const PG8_LAS bf16x8*)(lds + PG8_SA(b, h) + aoff + m * 2048 + k * 1024); } while (0)
; #define PG8_MMA(ai, bj, At, Bt) do { __builtin_amdgcn_s_setprio(1); _Pragma("unroll") for (int m = 0; m < 4; ++m) _Pragma("unroll") for (int n = 0; n < 2; ++n) _Pragma("unroll") for (int k = 0; k < 2; ++k) \
;         acc[ai][bj][m][n] = __builtin_amdgcn_mfma_f32_16x16x32_bf16(Bt[n][k], At[m][k], acc[ai][bj][m][n], 0, 0, 0); __builtin_amdgcn_s_setprio(0); } while (0)
; #define PG8_WAIT_V(n) asm volatile("s_waitcnt vmcnt(" #n ")" ::: "memory")
; #define PG8_WAIT_L(n) asm volatile("s_waitcnt lgkmcnt(" #n ")" ::: "memory")
; #define PG8_BAR __builtin_amdgcn_s_barrier()
; #define PG8_SCHED __builtin_amdgcn_sched_barrier(0)
; template <class Epi, class Sched, bool ALIGN_EPI = false, bool SP2 = false>
; __device__ __forceinline__ void gemm_phase(PG8_LAS unsigned char* lds, const Gemm g, const Sched& S, const Epi& E, const int tid) {
;     ...
;             PG8_WAIT_V(8); PG8_WAIT_L(0); PG8_BAR; PG8_MMA(0, 0, At, B0); PG8_MMA(0, 1, At, B1); PG8_BAR; PG8_SCHED;
;             PG8_LDA(At, 0, 1); PG8_STAGE(PG8_SB(0, 0), b2, voffB); PG8_STAGE(PG8_SB(0, 1), b2 + hstep, voffB); PG8_STAGE(PG8_SA(0, 0), a2, voffA);
;             PG8_WAIT_V(8); PG8_WAIT_L(0); PG8_BAR; PG8_MMA(1, 0, At, B0); PG8_MMA(1, 1, At, B1); PG8_BAR; PG8_SCHED;
	s_setprio 1
	s_waitcnt lgkmcnt(0)
	v_mfma_f32_16x16x32_bf16 v[126:129], v[130:133], v[196:199], v[126:129]
	v_mfma_f32_16x16x32_bf16 v[122:125], v[160:163], v[196:199], v[122:125]
	v_mfma_f32_16x16x32_bf16 v[106:109], v[160:163], v[204:207], v[106:109]
	v_mfma_f32_16x16x32_bf16 v[110:113], v[130:133], v[204:207], v[110:113]
	v_mfma_f32_16x16x32_bf16 v[94:97], v[130:133], v[212:215], v[94:97]
	v_mfma_f32_16x16x32_bf16 v[90:93], v[160:163], v[212:215], v[90:93]
	v_mfma_f32_16x16x32_bf16 v[74:77], v[160:163], v[220:223], v[74:77]
	v_mfma_f32_16x16x32_bf16 v[78:81], v[130:133], v[220:223], v[78:81]
	v_mfma_f32_16x16x32_bf16 v[126:129], v[134:137], v[200:203], v[126:129]
	v_mfma_f32_16x16x32_bf16 v[122:125], v[164:167], v[200:203], v[122:125]
	v_mfma_f32_16x16x32_bf16 v[106:109], v[164:167], v[208:211], v[106:109]
	v_mfma_f32_16x16x32_bf16 v[110:113], v[134:137], v[208:211], v[110:113]
	v_mfma_f32_16x16x32_bf16 v[94:97], v[134:137], v[216:219], v[94:97]
	v_mfma_f32_16x16x32_bf16 v[90:93], v[164:167], v[216:219], v[90:93]
	v_mfma_f32_16x16x32_bf16 v[74:77], v[164:167], v[224:227], v[74:77]
	v_mfma_f32_16x16x32_bf16 v[78:81], v[134:137], v[224:227], v[78:81]
	s_setprio 0
	s_setprio 1
	v_mfma_f32_16x16x32_bf16 v[118:121], v[176:179], v[196:199], v[118:121]
	v_mfma_f32_16x16x32_bf16 v[114:117], v[184:187], v[196:199], v[114:117]
	v_mfma_f32_16x16x32_bf16 v[98:101], v[184:187], v[204:207], v[98:101]
	v_mfma_f32_16x16x32_bf16 v[102:105], v[176:179], v[204:207], v[102:105]
	v_mfma_f32_16x16x32_bf16 v[86:89], v[176:179], v[212:215], v[86:89]
	v_mfma_f32_16x16x32_bf16 v[82:85], v[184:187], v[212:215], v[82:85]
	v_mfma_f32_16x16x32_bf16 v[66:69], v[184:187], v[220:223], v[66:69]
	v_mfma_f32_16x16x32_bf16 v[70:73], v[176:179], v[220:223], v[70:73]
	v_mfma_f32_16x16x32_bf16 v[118:121], v[180:183], v[200:203], v[118:121]
	v_mfma_f32_16x16x32_bf16 v[114:117], v[192:195], v[200:203], v[114:117]
	v_mfma_f32_16x16x32_bf16 v[98:101], v[192:195], v[208:211], v[98:101]
	v_mfma_f32_16x16x32_bf16 v[102:105], v[180:183], v[208:211], v[102:105]
	v_mfma_f32_16x16x32_bf16 v[86:89], v[180:183], v[216:219], v[86:89]
	v_mfma_f32_16x16x32_bf16 v[82:85], v[192:195], v[216:219], v[82:85]
	v_mfma_f32_16x16x32_bf16 v[66:69], v[192:195], v[224:227], v[66:69]
	v_mfma_f32_16x16x32_bf16 v[70:73], v[180:183], v[224:227], v[70:73]
	s_setprio 0
	s_barrier
	s_add_i32 s15, s83, s63
	v_lshl_add_u64 v[168:169], s[56:57], 0, v[140:141]
	s_mov_b32 m0, s15
	ds_read_b128 v[196:199], v173 offset:16384
	ds_read_b128 v[200:203], v173 offset:17408
	ds_read_b128 v[204:207], v173 offset:18432
	ds_read_b128 v[208:211], v173 offset:19456
	ds_read_b128 v[212:215], v173 offset:20480
	ds_read_b128 v[216:219], v173 offset:21504
	ds_read_b128 v[220:223], v173 offset:22528
	ds_read_b128 v[224:227], v173 offset:23552
	global_load_lds_dwordx4 v[168:169], off
	s_add_i32 m0, s15, 0x2000
	s_add_u32 s18, s56, 0x40000
	v_lshl_add_u64 v[188:189], s[56:57], 0, v[144:145]
	s_addc_u32 s19, s57, 0
	s_add_i32 s15, s84, s63
	global_load_lds_dwordx4 v[188:189], off
	v_lshl_add_u64 v[228:229], s[18:19], 0, v[140:141]
	s_mov_b32 m0, s15
	v_lshl_add_u64 v[230:231], s[58:59], 0, v[142:143]
	global_load_lds_dwordx4 v[228:229], off
	v_lshl_add_u64 v[228:229], s[18:19], 0, v[144:145]
	s_add_i32 m0, s15, 0x2000
	s_nop 0
	global_load_lds_dwordx4 v[228:229], off
	v_lshl_add_u64 v[228:229], s[58:59], 0, v[138:139]
	s_mov_b32 m0, s64
	s_nop 0
	global_load_lds_dwordx4 v[228:229], off
	s_mov_b32 m0, s65
	s_nop 0
	global_load_lds_dwordx4 v[230:231], off
	s_waitcnt vmcnt(8)
	s_waitcnt lgkmcnt(0)
	s_barrier
	s_setprio 1
	s_waitcnt lgkmcnt(0)
	v_mfma_f32_16x16x32_bf16 v[62:65], v[130:133], v[196:199], v[62:65]
	v_mfma_f32_16x16x32_bf16 v[58:61], v[160:163], v[196:199], v[58:61]
	v_mfma_f32_16x16x32_bf16 v[42:45], v[160:163], v[204:207], v[42:45]
	v_mfma_f32_16x16x32_bf16 v[46:49], v[130:133], v[204:207], v[46:49]
	v_mfma_f32_16x16x32_bf16 v[30:33], v[130:133], v[212:215], v[30:33]
	v_mfma_f32_16x16x32_bf16 v[26:29], v[160:163], v[212:215], v[26:29]
	v_mfma_f32_16x16x32_bf16 v[10:13], v[160:163], v[220:223], v[10:13]
	v_mfma_f32_16x16x32_bf16 v[14:17], v[130:133], v[220:223], v[14:17]
	v_mfma_f32_16x16x32_bf16 v[62:65], v[134:137], v[200:203], v[62:65]
	v_mfma_f32_16x16x32_bf16 v[58:61], v[164:167], v[200:203], v[58:61]
	v_mfma_f32_16x16x32_bf16 v[42:45], v[164:167], v[208:211], v[42:45]
	v_mfma_f32_16x16x32_bf16 v[46:49], v[134:137], v[208:211], v[46:49]
	v_mfma_f32_16x16x32_bf16 v[30:33], v[134:137], v[216:219], v[30:33]
	v_mfma_f32_16x16x32_bf16 v[26:29], v[164:167], v[216:219], v[26:29]
	v_mfma_f32_16x16x32_bf16 v[10:13], v[164:167], v[224:227], v[10:13]
	v_mfma_f32_16x16x32_bf16 v[14:17], v[134:137], v[224:227], v[14:17]
	s_setprio 0
	s_setprio 1
	v_mfma_f32_16x16x32_bf16 v[54:57], v[176:179], v[196:199], v[54:57]
	v_mfma_f32_16x16x32_bf16 v[50:53], v[184:187], v[196:199], v[50:53]
	v_mfma_f32_16x16x32_bf16 v[34:37], v[184:187], v[204:207], v[34:37]
	v_mfma_f32_16x16x32_bf16 v[38:41], v[176:179], v[204:207], v[38:41]
	v_mfma_f32_16x16x32_bf16 v[22:25], v[176:179], v[212:215], v[22:25]
	v_mfma_f32_16x16x32_bf16 v[18:21], v[184:187], v[212:215], v[18:21]
	v_mfma_f32_16x16x32_bf16 v[2:5], v[184:187], v[220:223], v[2:5]
	v_mfma_f32_16x16x32_bf16 v[6:9], v[176:179], v[220:223], v[6:9]
	v_mfma_f32_16x16x32_bf16 v[54:57], v[180:183], v[200:203], v[54:57]
	v_mfma_f32_16x16x32_bf16 v[50:53], v[192:195], v[200:203], v[50:53]
	v_mfma_f32_16x16x32_bf16 v[34:37], v[192:195], v[208:211], v[34:37]
	v_mfma_f32_16x16x32_bf16 v[38:41], v[180:183], v[208:211], v[38:41]
	v_mfma_f32_16x16x32_bf16 v[22:25], v[180:183], v[216:219], v[22:25]
	v_mfma_f32_16x16x32_bf16 v[18:21], v[192:195], v[216:219], v[18:21]
	v_mfma_f32_16x16x32_bf16 v[2:5], v[192:195], v[224:227], v[2:5]
	v_mfma_f32_16x16x32_bf16 v[6:9], v[180:183], v[224:227], v[6:9]
	s_setprio 0
	s_barrier
; #define PG8_STAGE(bufoff, gbase, voff) do { _Pragma("unroll") for (int _i = 0; _i < 2; ++_i) \
;         __builtin_amdgcn_global_load_lds((const unsigned*)((const char*)(gbase) + (voff)[_i]), (PG8_LAS unsigned*)(lds + (bufoff) + ldsw + _i * 8192), 16, 0, 0); } while (0)
; #define PG8_LDA(dst, b, h) do { _Pragma("unroll") for (int m = 0; m < 4; ++m) _Pragma("unroll") for (int k = 0; k < 2; ++k) dst[m][k] = *(const PG8_LAS bf16x8*)(lds + PG8_SA(b, h) + aoff + m * 2048 + k * 1024); } while (0)
; #define PG8_LDB(dst, b, h) do { _Pragma("unroll") for (int n = 0; n < 2; ++n) _Pragma("unroll") for (int k = 0; k < 2; ++k) dst[n][k] = *(const PG8_LAS bf16x8*)(lds + PG8_SB(b, h) + boff + n * 2048 + k * 1024); } while (0)
; #define PG8_MMA(ai, bj, At, Bt) do { __builtin_amdgcn_s_setprio(1); _Pragma("unroll") for (int m = 0; m < 4; ++m) _Pragma("unroll") for (int n = 0; n < 2; ++n) _Pragma("unroll") for (int k = 0; k < 2; ++k) \
;         acc[ai][bj][m][n] = __builtin_amdgcn_mfma_f32_16x16x32_bf16(Bt[n][k], At[m][k], acc[ai][bj][m][n], 0, 0, 0); __builtin_amdgcn_s_setprio(0); } while (0)
; #define PG8_WAIT_V(n) asm volatile("s_waitcnt vmcnt(" #n ")" ::: "memory")
; #define PG8_WAIT_L(n) asm volatile("s_waitcnt lgkmcnt(" #n ")" ::: "memory")
; #define PG8_BAR __builtin_amdgcn_s_barrier()
; #define PG8_SCHED __builtin_amdgcn_sched_barrier(0)
; template <class Epi, class Sched, bool ALIGN_EPI = false, bool SP2 = false>
; __device__ __forceinline__ void gemm_phase(PG8_LAS unsigned char* lds, const Gemm g, const Sched& S, const Epi& E, const int tid) {
;     ...
;             PG8_LDB(B0, 1, 0); PG8_LDB(B1, 1, 1); PG8_SCHED; PG8_LDA(At, 1, 0); PG8_STAGE(PG8_SA(0, 1), a2 + hstep, voffA);
;             PG8_WAIT_V(8); PG8_WAIT_L(0); PG8_BAR; PG8_MMA(0, 0, At, B0); PG8_MMA(0, 1, At, B1); PG8_BAR; PG8_SCHED;
	s_add_i32 s15, 0, 0x18000
	s_add_i32 s60, 0, 0x1c000
	v_add_u32_e32 v164, s15, v170
	v_add_u32_e32 v175, s60, v170
	ds_read_b128 v[130:133], v164
	ds_read_b128 v[134:137], v164 offset:1024
	ds_read_b128 v[160:163], v164 offset:2048
	ds_read_b128 v[164:167], v164 offset:3072
	ds_read_b128 v[176:179], v175
	ds_read_b128 v[180:183], v175 offset:1024
	ds_read_b128 v[184:187], v175 offset:2048
	ds_read_b128 v[192:195], v175 offset:3072
	s_add_u32 s18, s58, 0x40000
	s_addc_u32 s19, s59, 0
	s_mov_b32 m0, s66
	v_lshl_add_u64 v[232:233], s[18:19], 0, v[138:139]
	ds_read_b128 v[196:199], v173 offset:32768
	ds_read_b128 v[200:203], v173 offset:33792
	ds_read_b128 v[204:207], v173 offset:34816
	ds_read_b128 v[208:211], v173 offset:35840
	ds_read_b128 v[212:215], v173 offset:36864
	ds_read_b128 v[216:219], v173 offset:37888
	ds_read_b128 v[220:223], v173 offset:38912
	ds_read_b128 v[224:227], v173 offset:39936
	global_load_lds_dwordx4 v[232:233], off
	v_lshl_add_u64 v[232:233], s[18:19], 0, v[142:143]
	s_mov_b32 m0, s67
	s_nop 0
	global_load_lds_dwordx4 v[232:233], off
	s_waitcnt vmcnt(8)
	s_waitcnt lgkmcnt(0)
	s_barrier
	s_setprio 1
	s_waitcnt lgkmcnt(0)
	v_mfma_f32_16x16x32_bf16 v[126:129], v[130:133], v[196:199], v[126:129]
	v_mfma_f32_16x16x32_bf16 v[122:125], v[160:163], v[196:199], v[122:125]
	v_mfma_f32_16x16x32_bf16 v[106:109], v[160:163], v[204:207], v[106:109]
	v_mfma_f32_16x16x32_bf16 v[110:113], v[130:133], v[204:207], v[110:113]
	v_mfma_f32_16x16x32_bf16 v[94:97], v[130:133], v[212:215], v[94:97]
	v_mfma_f32_16x16x32_bf16 v[90:93], v[160:163], v[212:215], v[90:93]
	v_mfma_f32_16x16x32_bf16 v[74:77], v[160:163], v[220:223], v[74:77]
	v_mfma_f32_16x16x32_bf16 v[78:81], v[130:133], v[220:223], v[78:81]
	v_mfma_f32_16x16x32_bf16 v[126:129], v[134:137], v[200:203], v[126:129]
	v_mfma_f32_16x16x32_bf16 v[122:125], v[164:167], v[200:203], v[122:125]
	v_mfma_f32_16x16x32_bf16 v[106:109], v[164:167], v[208:211], v[106:109]
	v_mfma_f32_16x16x32_bf16 v[110:113], v[134:137], v[208:211], v[110:113]
	v_mfma_f32_16x16x32_bf16 v[94:97], v[134:137], v[216:219], v[94:97]
	v_mfma_f32_16x16x32_bf16 v[90:93], v[164:167], v[216:219], v[90:93]
	v_mfma_f32_16x16x32_bf16 v[74:77], v[164:167], v[224:227], v[74:77]
	v_mfma_f32_16x16x32_bf16 v[78:81], v[134:137], v[224:227], v[78:81]
	s_setprio 0
	s_setprio 1
	v_mfma_f32_16x16x32_bf16 v[118:121], v[176:179], v[196:199], v[118:121]
	v_mfma_f32_16x16x32_bf16 v[114:117], v[184:187], v[196:199], v[114:117]
	v_mfma_f32_16x16x32_bf16 v[98:101], v[184:187], v[204:207], v[98:101]
	v_mfma_f32_16x16x32_bf16 v[102:105], v[176:179], v[204:207], v[102:105]
	v_mfma_f32_16x16x32_bf16 v[86:89], v[176:179], v[212:215], v[86:89]
	v_mfma_f32_16x16x32_bf16 v[82:85], v[184:187], v[212:215], v[82:85]
	v_mfma_f32_16x16x32_bf16 v[66:69], v[184:187], v[220:223], v[66:69]
	v_mfma_f32_16x16x32_bf16 v[70:73], v[176:179], v[220:223], v[70:73]
	v_mfma_f32_16x16x32_bf16 v[118:121], v[180:183], v[200:203], v[118:121]
	v_mfma_f32_16x16x32_bf16 v[114:117], v[192:195], v[200:203], v[114:117]
	v_mfma_f32_16x16x32_bf16 v[98:101], v[192:195], v[208:211], v[98:101]
	v_mfma_f32_16x16x32_bf16 v[102:105], v[180:183], v[208:211], v[102:105]
	v_mfma_f32_16x16x32_bf16 v[86:89], v[180:183], v[216:219], v[86:89]
	v_mfma_f32_16x16x32_bf16 v[82:85], v[192:195], v[216:219], v[82:85]
	v_mfma_f32_16x16x32_bf16 v[66:69], v[192:195], v[224:227], v[66:69]
	v_mfma_f32_16x16x32_bf16 v[70:73], v[180:183], v[224:227], v[70:73]
	s_setprio 0
	s_barrier
; #define PG8_STAGE(bufoff, gbase, voff) do { _Pragma("unroll") for (int _i = 0; _i < 2; ++_i) \
;         __builtin_amdgcn_global_load_lds((const unsigned*)((const char*)(gbase) + (voff)[_i]), (PG8_LAS unsigned*)(lds + (bufoff) + ldsw + _i * 8192), 16, 0, 0); } while (0)
; #define PG8_LDA(dst, b, h) do { _Pragma("unroll") for (int m = 0; m < 4; ++m) _Pragma("unroll") for (int k = 0; k < 2; ++k) dst[m][k] = *(const PG8_LAS bf16x8*)(lds + PG8_SA(b, h) + aoff + m * 2048 + k * 1024); } while (0)
; #define PG8_MMA(ai, bj, At, Bt) do { __builtin_amdgcn_s_setprio(1); _Pragma("unroll") for (int m = 0; m < 4; ++m) _Pragma("unroll") for (int n = 0; n < 2; ++n) _Pragma("unroll") for (int k = 0; k < 2; ++k) \
;         acc[ai][bj][m][n] = __builtin_amdgcn_mfma_f32_16x16x32_bf16(Bt[n][k], At[m][k], acc[ai][bj][m][n], 0, 0, 0); __builtin_amdgcn_s_setprio(0); } while (0)
; #define PG8_WAIT_V(n) asm volatile("s_waitcnt vmcnt(" #n ")" ::: "memory")
; #define PG8_WAIT_L(n) asm volatile("s_waitcnt lgkmcnt(" #n ")" ::: "memory")
; #define PG8_BAR __builtin_amdgcn_s_barrier()
; #define PG8_SCHED __builtin_amdgcn_sched_barrier(0)
; template <class Epi, class Sched, bool ALIGN_EPI = false, bool SP2 = false>
; __device__ __forceinline__ void gemm_phase(PG8_LAS unsigned char* lds, const Gemm g, const Sched& S, const Epi& E, const int tid) {
;     ...
;             PG8_LDA(At, 1, 1); PG8_STAGE(PG8_SB(1, 0), b3, voffB); PG8_STAGE(PG8_SB(1, 1), b3 + hstep, voffB); PG8_STAGE(PG8_SA(1, 0), a3, voffA);
;             PG8_WAIT_V(8); PG8_WAIT_L(0); PG8_BAR; PG8_MMA(1, 0, At, B0); PG8_MMA(1, 1, At, B1); PG8_BAR; PG8_SCHED;
;     ...
;         if constexpr (ALIGN_EPI) { if (wr == 0) PG8_BAR; }
	s_add_i32 s15, s15, s63
	v_lshl_add_u64 v[168:169], v[168:169], 0, s[42:43]
	s_mov_b32 m0, s15
	ds_read_b128 v[196:199], v173 offset:49152
	ds_read_b128 v[200:203], v173 offset:50176
	ds_read_b128 v[204:207], v173 offset:51200
	ds_read_b128 v[208:211], v173 offset:52224
	ds_read_b128 v[212:215], v173 offset:53248
	ds_read_b128 v[216:219], v173 offset:54272
	ds_read_b128 v[220:223], v173 offset:55296
	ds_read_b128 v[224:227], v173 offset:56320
	global_load_lds_dwordx4 v[168:169], off
	s_add_i32 m0, s15, 0x2000
	s_add_u32 s18, s56, 0x40080
	v_lshl_add_u64 v[168:169], v[188:189], 0, s[42:43]
	s_addc_u32 s19, s57, 0
	s_add_i32 s15, s60, s63
	global_load_lds_dwordx4 v[168:169], off
	v_lshl_add_u64 v[168:169], s[18:19], 0, v[140:141]
	s_mov_b32 m0, s15
	s_nop 0
	global_load_lds_dwordx4 v[168:169], off
	v_lshl_add_u64 v[168:169], s[18:19], 0, v[144:145]
	s_add_i32 m0, s15, 0x2000
	s_nop 0
	global_load_lds_dwordx4 v[168:169], off
	v_lshl_add_u64 v[168:169], v[228:229], 0, s[42:43]
	s_mov_b32 m0, s74
	s_nop 0
	global_load_lds_dwordx4 v[168:169], off
	v_lshl_add_u64 v[168:169], v[230:231], 0, s[42:43]
	s_mov_b32 m0, s75
	s_nop 0
	global_load_lds_dwordx4 v[168:169], off
	s_waitcnt vmcnt(8)
	s_waitcnt lgkmcnt(0)
	s_barrier
	s_setprio 1
	s_waitcnt lgkmcnt(0)
	v_mfma_f32_16x16x32_bf16 v[62:65], v[130:133], v[196:199], v[62:65]
	v_mfma_f32_16x16x32_bf16 v[58:61], v[160:163], v[196:199], v[58:61]
	v_mfma_f32_16x16x32_bf16 v[42:45], v[160:163], v[204:207], v[42:45]
	v_mfma_f32_16x16x32_bf16 v[46:49], v[130:133], v[204:207], v[46:49]
	v_mfma_f32_16x16x32_bf16 v[30:33], v[130:133], v[212:215], v[30:33]
	v_mfma_f32_16x16x32_bf16 v[26:29], v[160:163], v[212:215], v[26:29]
	v_mfma_f32_16x16x32_bf16 v[10:13], v[160:163], v[220:223], v[10:13]
	v_mfma_f32_16x16x32_bf16 v[14:17], v[130:133], v[220:223], v[14:17]
	v_mfma_f32_16x16x32_bf16 v[62:65], v[134:137], v[200:203], v[62:65]
	v_mfma_f32_16x16x32_bf16 v[58:61], v[164:167], v[200:203], v[58:61]
	v_mfma_f32_16x16x32_bf16 v[42:45], v[164:167], v[208:211], v[42:45]
	v_mfma_f32_16x16x32_bf16 v[46:49], v[134:137], v[208:211], v[46:49]
	v_mfma_f32_16x16x32_bf16 v[30:33], v[134:137], v[216:219], v[30:33]
	v_mfma_f32_16x16x32_bf16 v[26:29], v[164:167], v[216:219], v[26:29]
	v_mfma_f32_16x16x32_bf16 v[10:13], v[164:167], v[224:227], v[10:13]
	v_mfma_f32_16x16x32_bf16 v[14:17], v[134:137], v[224:227], v[14:17]
	s_setprio 0
	s_setprio 1
	v_mfma_f32_16x16x32_bf16 v[54:57], v[176:179], v[196:199], v[54:57]
	v_mfma_f32_16x16x32_bf16 v[50:53], v[184:187], v[196:199], v[50:53]
	v_mfma_f32_16x16x32_bf16 v[34:37], v[184:187], v[204:207], v[34:37]
	v_mfma_f32_16x16x32_bf16 v[38:41], v[176:179], v[204:207], v[38:41]
	v_mfma_f32_16x16x32_bf16 v[22:25], v[176:179], v[212:215], v[22:25]
	v_mfma_f32_16x16x32_bf16 v[18:21], v[184:187], v[212:215], v[18:21]
	v_mfma_f32_16x16x32_bf16 v[2:5], v[184:187], v[220:223], v[2:5]
	v_mfma_f32_16x16x32_bf16 v[6:9], v[176:179], v[220:223], v[6:9]
	v_mfma_f32_16x16x32_bf16 v[54:57], v[180:183], v[200:203], v[54:57]
	v_mfma_f32_16x16x32_bf16 v[50:53], v[192:195], v[200:203], v[50:53]
	v_mfma_f32_16x16x32_bf16 v[34:37], v[192:195], v[208:211], v[34:37]
	v_mfma_f32_16x16x32_bf16 v[38:41], v[180:183], v[208:211], v[38:41]
	v_mfma_f32_16x16x32_bf16 v[22:25], v[180:183], v[216:219], v[22:25]
	v_mfma_f32_16x16x32_bf16 v[18:21], v[192:195], v[216:219], v[18:21]
	v_mfma_f32_16x16x32_bf16 v[2:5], v[192:195], v[224:227], v[2:5]
	v_mfma_f32_16x16x32_bf16 v[6:9], v[180:183], v[224:227], v[6:9]
	s_setprio 0
	s_barrier
	s_add_i32 s49, s49, 2
	s_add_u32 s5, s5, 0x100
	s_addc_u32 s47, s47, 0
	s_add_u32 s54, s54, 0x100
	s_addc_u32 s55, s55, 0
	s_cmp_gt_u32 s49, 13
	s_cbranch_scc0 .LBB0_5777
	s_and_b64 vcc, exec, s[44:45]
	s_cbranch_vccz .LBB0_5780
	s_barrier
